# v028 + GEMM K-loops: first iteration peeled (C=0 MFMAs instead of zeroing), DMAs drained right after the K-loop, and the first iteration's two vmcnt(8) waits skipped when that drain happened (no waiti
# speedup vs baseline: 1.0176x; 1.0152x over previous
; #define PG8_STAGE(bufoff, gbase, voff) do { _Pragma("unroll") for (int _i = 0; _i < 2; ++_i) \
;         __builtin_amdgcn_global_load_lds((const unsigned*)((const char*)(gbase) + (voff)[_i]), (LAS unsigned*)(lds + (bufoff) + ldsw + _i * 8192), 16, 0, 0); } while (0)
; #define PG8_WAIT_V(n) asm volatile("s_waitcnt vmcnt(" #n ")" ::: "memory")
; #define PG8_BAR __builtin_amdgcn_s_barrier()
; template <class Epi, class Sched>
; DI void gemm_phase(LAS unsigned char* lds, const Gemm g, const Sched& S, const Epi& E) {
;     const int tid = threadIdx.x, wid = __builtin_amdgcn_readfirstlane(tid >> 6), lane = tid & 63, wr = wid >> 2, wc = wid & 3, fr = lane & 15, fq = lane >> 4;
;     const int K = g.K, nt = K / BK;
;     unsigned voffA[2], voffB[2];
; #pragma unroll
;     for (int i = 0; i < 2; ++i) { int R, C; stage_rc(tid * 16 + i * 8192, R, C); const int Rb = Epi::PERM ? ((R & ~31) + perm32(R & 31)) : R;
;         voffA[i] = (unsigned)(R * g.lda + C) * 2u; voffB[i] = (unsigned)(Rb * g.ldb + C) * 2u; }
;     const size_t kstep = (size_t)(BK * 2);
;     const size_t hstepA = (size_t)HALF * g.lda * 2, hstepB = (size_t)HALF * g.ldb * 2;
;     const size_t tstepA = 2 * hstepA, tstepB = 2 * hstepB;
;     const unsigned ldsw = (unsigned)wid * 1024u;
;     const int aoff = lds_byte(wr * 64 + fr, fq * 8), boff = lds_byte(wc * 32 + fr, fq * 8);
;     ...
;     PG8_STAGE(PG8_SB(0, 0), cB, voffB); PG8_STAGE(PG8_SB(0, 1), cB + hstepB, voffB); PG8_STAGE(PG8_SA(0, 0), cA, voffA); PG8_STAGE(PG8_SA(0, 1), cA + hstepA, voffA);
;     if (wr == 1) PG8_BAR;
;     PG8_WAIT_V(2); PG8_BAR;
;     PG8_STAGE(PG8_SB(1, 0), cB + kstep, voffB); PG8_STAGE(PG8_SA(1, 0), cA + kstep, voffA); PG8_STAGE(PG8_SB(1, 1), cB + hstepB + kstep, voffB);
;     PG8_WAIT_V(6); PG8_BAR;
.LBB0_173:
	s_add_u32 s10, s24, 0xc000000
	s_addc_u32 s11, s25, 0
	s_lshl_b32 s12, s12, 5
	s_and_b32 s34, s12, 0x60
	s_lshl_b32 s19, s18, 13
	s_lshl_b32 s35, s34, 7
	s_add_u32 s12, s24, 0x3400000
	s_waitcnt lgkmcnt(0)
	s_mov_b64 s[16:17], 0x80
	s_addc_u32 s13, s25, 0
	s_add_i32 m0, s49, 0x18000
	v_lshl_add_u64 v[8:9], v[8:9], 0, s[16:17]
	s_waitcnt vmcnt(2)
	s_barrier
	global_load_lds_dwordx4 v[8:9], off
	v_lshl_add_u64 v[6:7], v[6:7], 0, s[16:17]
	s_add_i32 m0, s49, 0x1a000
	s_add_i32 s54, s49, 0x8000
	s_add_i32 s55, s49, 0xa000
	global_load_lds_dwordx4 v[6:7], off
	v_lshl_add_u64 v[2:3], v[2:3], 0, s[16:17]
	s_mov_b32 m0, s54
	s_add_u32 s20, s42, 0x40080
	global_load_lds_dwordx4 v[2:3], off
	v_lshl_add_u64 v[2:3], v[4:5], 0, s[16:17]
	s_mov_b32 m0, s55
	s_addc_u32 s21, s43, 0
	global_load_lds_dwordx4 v[2:3], off
	s_add_i32 m0, s49, 0x1c000
	v_lshl_add_u64 v[2:3], s[20:21], 0, v[134:135]
	global_load_lds_dwordx4 v[2:3], off
	v_lshl_add_u64 v[2:3], s[20:21], 0, v[130:131]
	s_add_i32 m0, s49, 0x1e000
	s_sext_i32_i16 s60, s4
	global_load_lds_dwordx4 v[2:3], off
	v_and_b32_e32 v2, 15, v184
	v_lshlrev_b32_e32 v3, 1, v13
	v_lshlrev_b32_e32 v4, 2, v184
	v_lshlrev_b32_e32 v5, 6, v184
	s_movk_i32 s4, 0x3c0
	v_lshl_or_b32 v147, s18, 6, v2
	v_lshl_or_b32 v2, v2, 6, v3
	v_and_b32_e32 v4, 32, v4
	v_and_or_b32 v3, v5, s4, v3
	v_bitop3_b32 v158, s35, v3, v4 bitop3:0xf6
	v_lshlrev_b32_e32 v3, 8, v184
	v_bitop3_b32 v2, v2, s19, v4 bitop3:0xde
	v_and_b32_e32 v3, 0x38000, v3
	v_lshlrev_b32_e32 v4, 11, v14
	v_or3_b32 v3, v11, v3, v4
	v_add_u32_e32 v138, v3, v12
	v_lshlrev_b32_e32 v3, 4, v10
	s_waitcnt vmcnt(6)
	s_cmpk_lt_u32 s5, 0x100
	v_and_b32_e32 v3, 0x78000, v3
	s_cselect_b64 s[18:19], -1, 0
	v_or3_b32 v3, v11, v3, v4
	s_add_i32 s57, 0, 0x10000
	s_add_i32 s58, 0, 0x14000
	s_ashr_i32 s56, s3, 31
	v_or_b32_e32 v159, s34, v13
	v_mov_b32_e32 v139, v135
	v_add_u32_e32 v140, v3, v12
	v_mov_b32_e32 v141, v135
	v_mov_b64_e32 v[142:143], 0x1600
	v_mov_b64_e32 v[144:145], 0x15ff
	v_add_u32_e32 v160, 0, v2
	v_mov_b32_e32 v161, 0x358637bd
	s_movk_i32 s59, 0x1600
	v_add_u32_e32 v162, s57, v158
	v_add_u32_e32 v163, s58, v158
	s_barrier
	s_mov_b32 s99, 0
	s_branch .LBB0_176

;     DI bool next(int i, Unit& u) const { if (i > 0 || c >= 64) return false; u.pm = c & 31; u.pn = 0; u.src = c >> 5; return true; }
; #define PG8_STAGE(bufoff, gbase, voff) do { _Pragma("unroll") for (int _i = 0; _i < 2; ++_i) \
;         __builtin_amdgcn_global_load_lds((const unsigned*)((const char*)(gbase) + (voff)[_i]), (LAS unsigned*)(lds + (bufoff) + ldsw + _i * 8192), 16, 0, 0); } while (0)
; #define PG8_LDA(dst, b, h) do { _Pragma("unroll") for (int m = 0; m < 4; ++m) _Pragma("unroll") for (int k = 0; k < 2; ++k) dst[m][k] = *(const LAS bf16x8*)(lds + PG8_SA(b, h) + aoff + m * 2048 + k * 1024); } while (0)
; #define PG8_LDB(dst, b, h) do { _Pragma("unroll") for (int n = 0; n < 2; ++n) _Pragma("unroll") for (int k = 0; k < 2; ++k) dst[n][k] = *(const LAS bf16x8*)(lds + PG8_SB(b, h) + boff + n * 2048 + k * 1024); } while (0)
; #define PG8_WAIT_V(n) asm volatile("s_waitcnt vmcnt(" #n ")" ::: "memory")
; template <class Epi, class Sched>
; DI void gemm_phase(LAS unsigned char* lds, const Gemm g, const Sched& S, const Epi& E) {
;     ...
;         const bool has_next = S.next(ui + 1, nxt);
;         E.pre(pre, cur, wr, fr);
;         const char* nA = has_next ? (const char*)(nxt.src ? g.A1 : g.A0) + (size_t)nxt.pm * tstepA : cA; const char* nB = has_next ? (const char*)(nxt.src ? g.B1 : g.B0) + (size_t)nxt.pn * tstepB : cB;
;         for (int t = 0; t < nt; t += 2) {
;             const bool last = (t == nt - 2);
;             const char* a1 = cA + (size_t)(t + 1) * kstep;
;             const char* a2 = last ? nA : cA + (size_t)(t + 2) * kstep; const char* b2 = last ? nB : cB + (size_t)(t + 2) * kstep;
;             const char* a3 = a2 + kstep; const char* b3 = b2 + kstep;
;             PG8_LDB(B0, 0, 0); PG8_LDB(B1, 0, 1); PG8_SCHED; PG8_LDA(At, 0, 0); PG8_STAGE(PG8_SA(1, 1), a1 + hstepA, voffA);
;             PG8_WAIT_V(8); PG8_WAIT_L(0); PG8_BAR; PG8_MMA(0, 0, At, B0); PG8_MMA(0, 1, At, B1); PG8_BAR; PG8_SCHED;
;             PG8_LDA(At, 0, 1); PG8_STAGE(PG8_SB(0, 0), b2, voffB); PG8_STAGE(PG8_SB(0, 1), b2 + hstepB, voffB); PG8_STAGE(PG8_SA(0, 0), a2, voffA);
; DI void load_rows(PreRows& pr, const float* ssq, const pg8::Unit& u, int wr, int fr) {
; #pragma unroll
;     for (int ai = 0; ai < 2; ++ai)
; #pragma unroll
;         for (int m = 0; m < 4; ++m) pr.v[ai * 4 + m] = ssq[u.pm * 256 + ai * 128 + wr * 64 + m * 16 + fr];
.LBB0_178:
	v_lshl_add_u32 v156, s44, 8, v147
	v_ashrrev_i32_e32 v157, 31, v156
	v_add_u32_e32 v154, 0x80, v156
	v_add_u32_e32 v152, 0x90, v156
	v_add_u32_e32 v150, 0xa0, v156
	v_add_u32_e32 v148, 0xb0, v156
	v_lshl_add_u64 v[2:3], v[156:157], 2, s[12:13]
	v_ashrrev_i32_e32 v155, 31, v154
	v_ashrrev_i32_e32 v153, 31, v152
	v_ashrrev_i32_e32 v151, 31, v150
	v_ashrrev_i32_e32 v149, 31, v148
	v_lshl_add_u64 v[4:5], v[154:155], 2, s[12:13]
	v_lshl_add_u64 v[6:7], v[152:153], 2, s[12:13]
	v_lshl_add_u64 v[8:9], v[150:151], 2, s[12:13]
	v_lshl_add_u64 v[10:11], v[148:149], 2, s[12:13]
	global_load_dword v166, v[2:3], off
	global_load_dword v165, v[2:3], off offset:64
	global_load_dword v164, v[2:3], off offset:128
	global_load_dword v157, v[2:3], off offset:192
	global_load_dword v155, v[4:5], off
	global_load_dword v153, v[6:7], off
	global_load_dword v151, v[8:9], off
	global_load_dword v149, v[10:11], off
	s_ashr_i32 s35, s34, 31
	s_lshl_b64 s[36:37], s[34:35], 19
	s_add_u32 s36, s30, s36
	s_addc_u32 s37, s31, s37
	s_and_b64 s[38:39], s[4:5], exec
	s_cselect_b32 s35, s37, s41
	s_cselect_b32 s61, s36, s40
	s_ashr_i32 s21, s20, 31
	s_lshl_b64 s[38:39], s[20:21], 19
	s_add_u32 s38, s28, s38
	s_addc_u32 s39, s29, s39
	s_and_b64 s[44:45], s[4:5], exec
	s_cselect_b32 s21, s39, s43
	s_cselect_b32 s62, s38, s42
	s_add_u32 s40, s40, 0x40080
	s_addc_u32 s41, s41, 0
	s_add_u32 s63, s42, 0x100
	s_addc_u32 s64, s43, 0
	s_mov_b32 s65, -2
	ds_read_b128 v[168:171], v162
	ds_read_b128 v[172:175], v162 offset:1024
	ds_read_b128 v[176:179], v162 offset:2048
	ds_read_b128 v[180:183], v162 offset:3072
	ds_read_b128 v[186:189], v163
	ds_read_b128 v[190:193], v163 offset:1024
	ds_read_b128 v[194:197], v163 offset:2048
	ds_read_b128 v[198:201], v163 offset:3072
	s_add_u32 s42, s40, 0xfffc0080
	s_addc_u32 s43, s41, -1
	s_cmp_eq_u32 s65, 12
	s_cselect_b32 s45, s35, s43
	s_cselect_b32 s44, s61, s42
	s_cselect_b32 s43, s21, s64
	s_cselect_b32 s42, s62, s63
	v_lshl_add_u64 v[234:235], s[40:41], 0, v[138:139]
	s_add_i32 m0, s49, 0xc000
	ds_read_b128 v[202:205], v160
	ds_read_b128 v[206:209], v160 offset:1024
	ds_read_b128 v[210:213], v160 offset:2048
	ds_read_b128 v[214:217], v160 offset:3072
	ds_read_b128 v[218:221], v160 offset:4096
	ds_read_b128 v[222:225], v160 offset:5120
	ds_read_b128 v[226:229], v160 offset:6144
	ds_read_b128 v[230:233], v160 offset:7168
	global_load_lds_dwordx4 v[234:235], off
	v_lshl_add_u64 v[234:235], s[40:41], 0, v[140:141]
	s_add_i32 m0, s49, 0xe000
	s_nop 0
	global_load_lds_dwordx4 v[234:235], off
	s_cmp_lg_u32 s99, 0
	s_cbranch_scc1 .Lpk0_w1
	s_waitcnt vmcnt(8)
.Lpk0_w1:
	s_waitcnt lgkmcnt(0)
	s_barrier
	s_setprio 1
	v_mfma_f32_16x16x32_bf16 v[126:129], v[168:171], v[202:205], 0
	v_mfma_f32_16x16x32_bf16 v[118:121], v[176:179], v[202:205], 0
	v_mfma_f32_16x16x32_bf16 v[110:113], v[168:171], v[210:213], 0
	v_mfma_f32_16x16x32_bf16 v[102:105], v[176:179], v[210:213], 0
	v_mfma_f32_16x16x32_bf16 v[94:97], v[168:171], v[218:221], 0
	v_mfma_f32_16x16x32_bf16 v[86:89], v[176:179], v[218:221], 0
	v_mfma_f32_16x16x32_bf16 v[78:81], v[168:171], v[226:229], 0
	v_mfma_f32_16x16x32_bf16 v[70:73], v[176:179], v[226:229], 0
	v_mfma_f32_16x16x32_bf16 v[126:129], v[172:175], v[206:209], v[126:129]
	v_mfma_f32_16x16x32_bf16 v[118:121], v[180:183], v[206:209], v[118:121]
	v_mfma_f32_16x16x32_bf16 v[110:113], v[172:175], v[214:217], v[110:113]
	v_mfma_f32_16x16x32_bf16 v[102:105], v[180:183], v[214:217], v[102:105]
	v_mfma_f32_16x16x32_bf16 v[94:97], v[172:175], v[222:225], v[94:97]
	v_mfma_f32_16x16x32_bf16 v[86:89], v[180:183], v[222:225], v[86:89]
	v_mfma_f32_16x16x32_bf16 v[78:81], v[172:175], v[230:233], v[78:81]
	v_mfma_f32_16x16x32_bf16 v[70:73], v[180:183], v[230:233], v[70:73]
	v_mfma_f32_16x16x32_bf16 v[122:125], v[186:189], v[202:205], 0
	v_mfma_f32_16x16x32_bf16 v[114:117], v[194:197], v[202:205], 0
	v_mfma_f32_16x16x32_bf16 v[106:109], v[186:189], v[210:213], 0
	v_mfma_f32_16x16x32_bf16 v[98:101], v[194:197], v[210:213], 0
	v_mfma_f32_16x16x32_bf16 v[90:93], v[186:189], v[218:221], 0
	v_mfma_f32_16x16x32_bf16 v[82:85], v[194:197], v[218:221], 0
	v_mfma_f32_16x16x32_bf16 v[74:77], v[186:189], v[226:229], 0
	v_mfma_f32_16x16x32_bf16 v[66:69], v[194:197], v[226:229], 0
	v_mfma_f32_16x16x32_bf16 v[122:125], v[190:193], v[206:209], v[122:125]
	v_mfma_f32_16x16x32_bf16 v[114:117], v[198:201], v[206:209], v[114:117]
	v_mfma_f32_16x16x32_bf16 v[106:109], v[190:193], v[214:217], v[106:109]
	v_mfma_f32_16x16x32_bf16 v[98:101], v[198:201], v[214:217], v[98:101]
	v_mfma_f32_16x16x32_bf16 v[90:93], v[190:193], v[222:225], v[90:93]
	v_mfma_f32_16x16x32_bf16 v[82:85], v[198:201], v[222:225], v[82:85]
	v_mfma_f32_16x16x32_bf16 v[74:77], v[190:193], v[230:233], v[74:77]
	v_mfma_f32_16x16x32_bf16 v[66:69], v[198:201], v[230:233], v[66:69]
	s_setprio 0
	s_barrier
	s_add_i32 s66, s57, s46
	v_lshl_add_u64 v[234:235], s[42:43], 0, v[134:135]
	s_mov_b32 m0, s66
	ds_read_b128 v[202:205], v160 offset:16384
	ds_read_b128 v[206:209], v160 offset:17408
	ds_read_b128 v[210:213], v160 offset:18432
	ds_read_b128 v[214:217], v160 offset:19456
	ds_read_b128 v[218:221], v160 offset:20480
	ds_read_b128 v[222:225], v160 offset:21504
	ds_read_b128 v[226:229], v160 offset:22528
	ds_read_b128 v[230:233], v160 offset:23552
	global_load_lds_dwordx4 v[234:235], off
	s_add_i32 m0, s66, 0x2000
	s_add_u32 s66, s42, 0x40000
	v_lshl_add_u64 v[236:237], s[42:43], 0, v[130:131]
	s_addc_u32 s67, s43, 0
	s_add_i32 s68, s58, s46
	global_load_lds_dwordx4 v[236:237], off
	v_lshl_add_u64 v[238:239], s[66:67], 0, v[134:135]
	s_mov_b32 m0, s68
	v_lshl_add_u64 v[240:241], s[44:45], 0, v[132:133]
	global_load_lds_dwordx4 v[238:239], off
	v_lshl_add_u64 v[238:239], s[66:67], 0, v[130:131]
	s_add_i32 m0, s68, 0x2000
	s_nop 0
	global_load_lds_dwordx4 v[238:239], off
	v_lshl_add_u64 v[238:239], s[44:45], 0, v[136:137]
	s_mov_b32 m0, s49
	s_nop 0
	global_load_lds_dwordx4 v[238:239], off
	s_mov_b32 m0, s50
	s_nop 0
	global_load_lds_dwordx4 v[240:241], off
	s_cmp_lg_u32 s99, 0
	s_cbranch_scc1 .Lpk0_w2
	s_waitcnt vmcnt(8)
; #define PG8_STAGE(bufoff, gbase, voff) do { _Pragma("unroll") for (int _i = 0; _i < 2; ++_i) \
;         __builtin_amdgcn_global_load_lds((const unsigned*)((const char*)(gbase) + (voff)[_i]), (LAS unsigned*)(lds + (bufoff) + ldsw + _i * 8192), 16, 0, 0); } while (0)
; #define PG8_LDA(dst, b, h) do { _Pragma("unroll") for (int m = 0; m < 4; ++m) _Pragma("unroll") for (int k = 0; k < 2; ++k) dst[m][k] = *(const LAS bf16x8*)(lds + PG8_SA(b, h) + aoff + m * 2048 + k * 1024); } while (0)
; #define PG8_LDB(dst, b, h) do { _Pragma("unroll") for (int n = 0; n < 2; ++n) _Pragma("unroll") for (int k = 0; k < 2; ++k) dst[n][k] = *(const LAS bf16x8*)(lds + PG8_SB(b, h) + boff + n * 2048 + k * 1024); } while (0)
; #define PG8_MMA(ai, bj, At, Bt) do { __builtin_amdgcn_s_setprio(1); _Pragma("unroll") for (int m = 0; m < 4; ++m) _Pragma("unroll") for (int n = 0; n < 2; ++n) _Pragma("unroll") for (int k = 0; k < 2; ++k) \
;         acc[ai][bj][m][n] = __builtin_amdgcn_mfma_f32_16x16x32_bf16(Bt[n][k], At[m][k], acc[ai][bj][m][n], 0, 0, 0); __builtin_amdgcn_s_setprio(0); } while (0)
; #define PG8_WAIT_V(n) asm volatile("s_waitcnt vmcnt(" #n ")" ::: "memory")
; #define PG8_WAIT_L(n) asm volatile("s_waitcnt lgkmcnt(" #n ")" ::: "memory")
; #define PG8_BAR __builtin_amdgcn_s_barrier()
; #define PG8_SCHED __builtin_amdgcn_sched_barrier(0)
; template <class Epi, class Sched>
; DI void gemm_phase(LAS unsigned char* lds, const Gemm g, const Sched& S, const Epi& E) {
;     ...
;             PG8_LDA(At, 0, 1); PG8_STAGE(PG8_SB(0, 0), b2, voffB); PG8_STAGE(PG8_SB(0, 1), b2 + hstepB, voffB); PG8_STAGE(PG8_SA(0, 0), a2, voffA);
;             PG8_WAIT_V(8); PG8_WAIT_L(0); PG8_BAR; PG8_MMA(1, 0, At, B0); PG8_MMA(1, 1, At, B1); PG8_BAR; PG8_SCHED;
;             PG8_LDB(B0, 1, 0); PG8_LDB(B1, 1, 1); PG8_SCHED; PG8_LDA(At, 1, 0); PG8_STAGE(PG8_SA(0, 1), a2 + hstepA, voffA);
;             PG8_WAIT_V(8); PG8_WAIT_L(0); PG8_BAR; PG8_MMA(0, 0, At, B0); PG8_MMA(0, 1, At, B1); PG8_BAR; PG8_SCHED;
.Lpk0_w2:
	s_mov_b32 s99, 0
	s_waitcnt lgkmcnt(0)
	s_barrier
	s_setprio 1
	v_mfma_f32_16x16x32_bf16 v[62:65], v[168:171], v[202:205], 0
	v_mfma_f32_16x16x32_bf16 v[54:57], v[176:179], v[202:205], 0
	v_mfma_f32_16x16x32_bf16 v[46:49], v[168:171], v[210:213], 0
	v_mfma_f32_16x16x32_bf16 v[38:41], v[176:179], v[210:213], 0
	v_mfma_f32_16x16x32_bf16 v[30:33], v[168:171], v[218:221], 0
	v_mfma_f32_16x16x32_bf16 v[22:25], v[176:179], v[218:221], 0
	v_mfma_f32_16x16x32_bf16 v[14:17], v[168:171], v[226:229], 0
	v_mfma_f32_16x16x32_bf16 v[6:9], v[176:179], v[226:229], 0
	v_mfma_f32_16x16x32_bf16 v[62:65], v[172:175], v[206:209], v[62:65]
	v_mfma_f32_16x16x32_bf16 v[54:57], v[180:183], v[206:209], v[54:57]
	v_mfma_f32_16x16x32_bf16 v[46:49], v[172:175], v[214:217], v[46:49]
	v_mfma_f32_16x16x32_bf16 v[38:41], v[180:183], v[214:217], v[38:41]
	v_mfma_f32_16x16x32_bf16 v[30:33], v[172:175], v[222:225], v[30:33]
	v_mfma_f32_16x16x32_bf16 v[22:25], v[180:183], v[222:225], v[22:25]
	v_mfma_f32_16x16x32_bf16 v[14:17], v[172:175], v[230:233], v[14:17]
	v_mfma_f32_16x16x32_bf16 v[6:9], v[180:183], v[230:233], v[6:9]
	v_mfma_f32_16x16x32_bf16 v[58:61], v[186:189], v[202:205], 0
	v_mfma_f32_16x16x32_bf16 v[50:53], v[194:197], v[202:205], 0
	v_mfma_f32_16x16x32_bf16 v[42:45], v[186:189], v[210:213], 0
	v_mfma_f32_16x16x32_bf16 v[34:37], v[194:197], v[210:213], 0
	v_mfma_f32_16x16x32_bf16 v[26:29], v[186:189], v[218:221], 0
	v_mfma_f32_16x16x32_bf16 v[18:21], v[194:197], v[218:221], 0
	v_mfma_f32_16x16x32_bf16 v[10:13], v[186:189], v[226:229], 0
	v_mfma_f32_16x16x32_bf16 v[2:5], v[194:197], v[226:229], 0
	v_mfma_f32_16x16x32_bf16 v[58:61], v[190:193], v[206:209], v[58:61]
	v_mfma_f32_16x16x32_bf16 v[50:53], v[198:201], v[206:209], v[50:53]
	v_mfma_f32_16x16x32_bf16 v[42:45], v[190:193], v[214:217], v[42:45]
	v_mfma_f32_16x16x32_bf16 v[34:37], v[198:201], v[214:217], v[34:37]
	v_mfma_f32_16x16x32_bf16 v[26:29], v[190:193], v[222:225], v[26:29]
	v_mfma_f32_16x16x32_bf16 v[18:21], v[198:201], v[222:225], v[18:21]
	v_mfma_f32_16x16x32_bf16 v[10:13], v[190:193], v[230:233], v[10:13]
	v_mfma_f32_16x16x32_bf16 v[2:5], v[198:201], v[230:233], v[2:5]
	s_setprio 0
	s_barrier
	s_add_i32 s66, 0, 0x18000
	v_add_u32_e32 v167, s66, v158
	s_add_i32 s67, 0, 0x1c000
	ds_read_b128 v[168:171], v167
	ds_read_b128 v[172:175], v167 offset:1024
	ds_read_b128 v[176:179], v167 offset:2048
	ds_read_b128 v[180:183], v167 offset:3072
	v_add_u32_e32 v167, s67, v158
	ds_read_b128 v[186:189], v167
	ds_read_b128 v[190:193], v167 offset:1024
	ds_read_b128 v[194:197], v167 offset:2048
	ds_read_b128 v[198:201], v167 offset:3072
	s_add_u32 s44, s44, 0x40000
	s_addc_u32 s45, s45, 0
	s_mov_b32 m0, s51
	v_lshl_add_u64 v[242:243], s[44:45], 0, v[136:137]
	ds_read_b128 v[202:205], v160 offset:32768
	ds_read_b128 v[206:209], v160 offset:33792
	ds_read_b128 v[210:213], v160 offset:34816
	ds_read_b128 v[214:217], v160 offset:35840
	ds_read_b128 v[218:221], v160 offset:36864
	ds_read_b128 v[222:225], v160 offset:37888
	ds_read_b128 v[226:229], v160 offset:38912
	ds_read_b128 v[230:233], v160 offset:39936
	global_load_lds_dwordx4 v[242:243], off
	v_lshl_add_u64 v[242:243], s[44:45], 0, v[132:133]
	s_mov_b32 m0, s52
	s_nop 0
	global_load_lds_dwordx4 v[242:243], off
	s_waitcnt vmcnt(8)
	s_waitcnt lgkmcnt(0)
	s_barrier
	s_setprio 1
	v_mfma_f32_16x16x32_bf16 v[126:129], v[168:171], v[202:205], v[126:129]
	v_mfma_f32_16x16x32_bf16 v[118:121], v[176:179], v[202:205], v[118:121]
	v_mfma_f32_16x16x32_bf16 v[110:113], v[168:171], v[210:213], v[110:113]
	v_mfma_f32_16x16x32_bf16 v[102:105], v[176:179], v[210:213], v[102:105]
	v_mfma_f32_16x16x32_bf16 v[94:97], v[168:171], v[218:221], v[94:97]
	v_mfma_f32_16x16x32_bf16 v[86:89], v[176:179], v[218:221], v[86:89]
	v_mfma_f32_16x16x32_bf16 v[78:81], v[168:171], v[226:229], v[78:81]
	v_mfma_f32_16x16x32_bf16 v[70:73], v[176:179], v[226:229], v[70:73]
	v_mfma_f32_16x16x32_bf16 v[126:129], v[172:175], v[206:209], v[126:129]
	v_mfma_f32_16x16x32_bf16 v[118:121], v[180:183], v[206:209], v[118:121]
	v_mfma_f32_16x16x32_bf16 v[110:113], v[172:175], v[214:217], v[110:113]
	v_mfma_f32_16x16x32_bf16 v[102:105], v[180:183], v[214:217], v[102:105]
	v_mfma_f32_16x16x32_bf16 v[94:97], v[172:175], v[222:225], v[94:97]
	v_mfma_f32_16x16x32_bf16 v[86:89], v[180:183], v[222:225], v[86:89]
	v_mfma_f32_16x16x32_bf16 v[78:81], v[172:175], v[230:233], v[78:81]
	v_mfma_f32_16x16x32_bf16 v[70:73], v[180:183], v[230:233], v[70:73]
	v_mfma_f32_16x16x32_bf16 v[122:125], v[186:189], v[202:205], v[122:125]
	v_mfma_f32_16x16x32_bf16 v[114:117], v[194:197], v[202:205], v[114:117]
	v_mfma_f32_16x16x32_bf16 v[106:109], v[186:189], v[210:213], v[106:109]
	v_mfma_f32_16x16x32_bf16 v[98:101], v[194:197], v[210:213], v[98:101]
	v_mfma_f32_16x16x32_bf16 v[90:93], v[186:189], v[218:221], v[90:93]
	v_mfma_f32_16x16x32_bf16 v[82:85], v[194:197], v[218:221], v[82:85]
	v_mfma_f32_16x16x32_bf16 v[74:77], v[186:189], v[226:229], v[74:77]
	v_mfma_f32_16x16x32_bf16 v[66:69], v[194:197], v[226:229], v[66:69]
	v_mfma_f32_16x16x32_bf16 v[122:125], v[190:193], v[206:209], v[122:125]
	v_mfma_f32_16x16x32_bf16 v[114:117], v[198:201], v[206:209], v[114:117]
	v_mfma_f32_16x16x32_bf16 v[106:109], v[190:193], v[214:217], v[106:109]
	v_mfma_f32_16x16x32_bf16 v[98:101], v[198:201], v[214:217], v[98:101]
	v_mfma_f32_16x16x32_bf16 v[90:93], v[190:193], v[222:225], v[90:93]
	v_mfma_f32_16x16x32_bf16 v[82:85], v[198:201], v[222:225], v[82:85]
	v_mfma_f32_16x16x32_bf16 v[74:77], v[190:193], v[230:233], v[74:77]
	v_mfma_f32_16x16x32_bf16 v[66:69], v[198:201], v[230:233], v[66:69]
	s_setprio 0
	s_barrier
; #define PG8_STAGE(bufoff, gbase, voff) do { _Pragma("unroll") for (int _i = 0; _i < 2; ++_i) \
;         __builtin_amdgcn_global_load_lds((const unsigned*)((const char*)(gbase) + (voff)[_i]), (LAS unsigned*)(lds + (bufoff) + ldsw + _i * 8192), 16, 0, 0); } while (0)
; #define PG8_LDA(dst, b, h) do { _Pragma("unroll") for (int m = 0; m < 4; ++m) _Pragma("unroll") for (int k = 0; k < 2; ++k) dst[m][k] = *(const LAS bf16x8*)(lds + PG8_SA(b, h) + aoff + m * 2048 + k * 1024); } while (0)
; #define PG8_LDB(dst, b, h) do { _Pragma("unroll") for (int n = 0; n < 2; ++n) _Pragma("unroll") for (int k = 0; k < 2; ++k) dst[n][k] = *(const LAS bf16x8*)(lds + PG8_SB(b, h) + boff + n * 2048 + k * 1024); } while (0)
; #define PG8_MMA(ai, bj, At, Bt) do { __builtin_amdgcn_s_setprio(1); _Pragma("unroll") for (int m = 0; m < 4; ++m) _Pragma("unroll") for (int n = 0; n < 2; ++n) _Pragma("unroll") for (int k = 0; k < 2; ++k) \
;         acc[ai][bj][m][n] = __builtin_amdgcn_mfma_f32_16x16x32_bf16(Bt[n][k], At[m][k], acc[ai][bj][m][n], 0, 0, 0); __builtin_amdgcn_s_setprio(0); } while (0)
; #define PG8_WAIT_V(n) asm volatile("s_waitcnt vmcnt(" #n ")" ::: "memory")
; #define PG8_WAIT_L(n) asm volatile("s_waitcnt lgkmcnt(" #n ")" ::: "memory")
; #define PG8_BAR __builtin_amdgcn_s_barrier()
; #define PG8_SCHED __builtin_amdgcn_sched_barrier(0)
; template <class Epi, class Sched>
; DI void gemm_phase(LAS unsigned char* lds, const Gemm g, const Sched& S, const Epi& E) {
;     ...
;             PG8_LDB(B0, 0, 0); PG8_LDB(B1, 0, 1); PG8_SCHED; PG8_LDA(At, 0, 0); PG8_STAGE(PG8_SA(1, 1), a1 + hstepA, voffA);
;             PG8_WAIT_V(8); PG8_WAIT_L(0); PG8_BAR; PG8_MMA(0, 0, At, B0); PG8_MMA(0, 1, At, B1); PG8_BAR; PG8_SCHED;
;     ...
;             PG8_LDA(At, 1, 1); PG8_STAGE(PG8_SB(1, 0), b3, voffB); PG8_STAGE(PG8_SB(1, 1), b3 + hstepB, voffB); PG8_STAGE(PG8_SA(1, 0), a3, voffA);
;             PG8_WAIT_V(8); PG8_WAIT_L(0); PG8_BAR; PG8_MMA(1, 0, At, B0); PG8_MMA(1, 1, At, B1); PG8_BAR; PG8_SCHED;
;         }
	s_add_i32 s44, s66, s46
	v_lshl_add_u64 v[234:235], v[234:235], 0, s[16:17]
	s_mov_b32 m0, s44
	ds_read_b128 v[202:205], v160 offset:49152
	ds_read_b128 v[206:209], v160 offset:50176
	ds_read_b128 v[210:213], v160 offset:51200
	ds_read_b128 v[214:217], v160 offset:52224
	ds_read_b128 v[218:221], v160 offset:53248
	ds_read_b128 v[222:225], v160 offset:54272
	ds_read_b128 v[226:229], v160 offset:55296
	ds_read_b128 v[230:233], v160 offset:56320
	global_load_lds_dwordx4 v[234:235], off
	s_add_i32 m0, s44, 0x2000
	s_add_u32 s42, s42, 0x40080
	v_lshl_add_u64 v[234:235], v[236:237], 0, s[16:17]
	s_addc_u32 s43, s43, 0
	s_add_i32 s44, s67, s46
	global_load_lds_dwordx4 v[234:235], off
	v_lshl_add_u64 v[234:235], s[42:43], 0, v[134:135]
	s_mov_b32 m0, s44
	s_nop 0
	global_load_lds_dwordx4 v[234:235], off
	v_lshl_add_u64 v[234:235], s[42:43], 0, v[130:131]
	s_add_i32 m0, s44, 0x2000
	s_nop 0
	global_load_lds_dwordx4 v[234:235], off
	v_lshl_add_u64 v[234:235], v[238:239], 0, s[16:17]
	s_mov_b32 m0, s54
	s_nop 0
	global_load_lds_dwordx4 v[234:235], off
	v_lshl_add_u64 v[234:235], v[240:241], 0, s[16:17]
	s_mov_b32 m0, s55
	s_nop 0
	global_load_lds_dwordx4 v[234:235], off
	s_waitcnt vmcnt(8)
	s_waitcnt lgkmcnt(0)
	s_barrier
	s_setprio 1
	v_mfma_f32_16x16x32_bf16 v[62:65], v[168:171], v[202:205], v[62:65]
	v_mfma_f32_16x16x32_bf16 v[54:57], v[176:179], v[202:205], v[54:57]
	v_mfma_f32_16x16x32_bf16 v[46:49], v[168:171], v[210:213], v[46:49]
	v_mfma_f32_16x16x32_bf16 v[38:41], v[176:179], v[210:213], v[38:41]
	v_mfma_f32_16x16x32_bf16 v[30:33], v[168:171], v[218:221], v[30:33]
	v_mfma_f32_16x16x32_bf16 v[22:25], v[176:179], v[218:221], v[22:25]
	v_mfma_f32_16x16x32_bf16 v[14:17], v[168:171], v[226:229], v[14:17]
	v_mfma_f32_16x16x32_bf16 v[6:9], v[176:179], v[226:229], v[6:9]
	v_mfma_f32_16x16x32_bf16 v[62:65], v[172:175], v[206:209], v[62:65]
	v_mfma_f32_16x16x32_bf16 v[54:57], v[180:183], v[206:209], v[54:57]
	v_mfma_f32_16x16x32_bf16 v[46:49], v[172:175], v[214:217], v[46:49]
	v_mfma_f32_16x16x32_bf16 v[38:41], v[180:183], v[214:217], v[38:41]
	v_mfma_f32_16x16x32_bf16 v[30:33], v[172:175], v[222:225], v[30:33]
	v_mfma_f32_16x16x32_bf16 v[22:25], v[180:183], v[222:225], v[22:25]
	v_mfma_f32_16x16x32_bf16 v[14:17], v[172:175], v[230:233], v[14:17]
	v_mfma_f32_16x16x32_bf16 v[6:9], v[180:183], v[230:233], v[6:9]
	v_mfma_f32_16x16x32_bf16 v[58:61], v[186:189], v[202:205], v[58:61]
	v_mfma_f32_16x16x32_bf16 v[50:53], v[194:197], v[202:205], v[50:53]
	v_mfma_f32_16x16x32_bf16 v[42:45], v[186:189], v[210:213], v[42:45]
	v_mfma_f32_16x16x32_bf16 v[34:37], v[194:197], v[210:213], v[34:37]
	v_mfma_f32_16x16x32_bf16 v[26:29], v[186:189], v[218:221], v[26:29]
	v_mfma_f32_16x16x32_bf16 v[18:21], v[194:197], v[218:221], v[18:21]
	v_mfma_f32_16x16x32_bf16 v[10:13], v[186:189], v[226:229], v[10:13]
	v_mfma_f32_16x16x32_bf16 v[2:5], v[194:197], v[226:229], v[2:5]
	v_mfma_f32_16x16x32_bf16 v[58:61], v[190:193], v[206:209], v[58:61]
	v_mfma_f32_16x16x32_bf16 v[50:53], v[198:201], v[206:209], v[50:53]
	v_mfma_f32_16x16x32_bf16 v[42:45], v[190:193], v[214:217], v[42:45]
	v_mfma_f32_16x16x32_bf16 v[34:37], v[198:201], v[214:217], v[34:37]
	v_mfma_f32_16x16x32_bf16 v[26:29], v[190:193], v[222:225], v[26:29]
	v_mfma_f32_16x16x32_bf16 v[18:21], v[198:201], v[222:225], v[18:21]
	v_mfma_f32_16x16x32_bf16 v[10:13], v[190:193], v[230:233], v[10:13]
	v_mfma_f32_16x16x32_bf16 v[2:5], v[198:201], v[230:233], v[2:5]
	s_setprio 0
	s_barrier
	s_add_i32 s65, s65, 2
	s_add_u32 s40, s40, 0x100
	s_addc_u32 s41, s41, 0
	s_add_u32 s63, s63, 0x100
	s_addc_u32 s64, s64, 0
	s_cmp_gt_u32 s65, 13
.LBB0_179:
	ds_read_b128 v[168:171], v162
	ds_read_b128 v[172:175], v162 offset:1024
	ds_read_b128 v[176:179], v162 offset:2048
	ds_read_b128 v[180:183], v162 offset:3072
	ds_read_b128 v[186:189], v163
	ds_read_b128 v[190:193], v163 offset:1024
	ds_read_b128 v[194:197], v163 offset:2048
	ds_read_b128 v[198:201], v163 offset:3072
	s_add_u32 s42, s40, 0xfffc0080
	s_addc_u32 s43, s41, -1
	s_cmp_eq_u32 s65, 12
	s_cselect_b32 s45, s35, s43
	s_cselect_b32 s44, s61, s42
	s_cselect_b32 s43, s21, s64
	s_cselect_b32 s42, s62, s63
	v_lshl_add_u64 v[234:235], s[40:41], 0, v[138:139]
	s_add_i32 m0, s49, 0xc000
	ds_read_b128 v[202:205], v160
	ds_read_b128 v[206:209], v160 offset:1024
	ds_read_b128 v[210:213], v160 offset:2048
	ds_read_b128 v[214:217], v160 offset:3072
	ds_read_b128 v[218:221], v160 offset:4096
	ds_read_b128 v[222:225], v160 offset:5120
	ds_read_b128 v[226:229], v160 offset:6144
	ds_read_b128 v[230:233], v160 offset:7168
	global_load_lds_dwordx4 v[234:235], off
	v_lshl_add_u64 v[234:235], s[40:41], 0, v[140:141]
	s_add_i32 m0, s49, 0xe000
	s_nop 0
	global_load_lds_dwordx4 v[234:235], off
	s_waitcnt vmcnt(8)
	s_waitcnt lgkmcnt(0)
	s_barrier
; #define PG8_STAGE(bufoff, gbase, voff) do { _Pragma("unroll") for (int _i = 0; _i < 2; ++_i) \
;         __builtin_amdgcn_global_load_lds((const unsigned*)((const char*)(gbase) + (voff)[_i]), (LAS unsigned*)(lds + (bufoff) + ldsw + _i * 8192), 16, 0, 0); } while (0)
; #define PG8_LDA(dst, b, h) do { _Pragma("unroll") for (int m = 0; m < 4; ++m) _Pragma("unroll") for (int k = 0; k < 2; ++k) dst[m][k] = *(const LAS bf16x8*)(lds + PG8_SA(b, h) + aoff + m * 2048 + k * 1024); } while (0)
; #define PG8_LDB(dst, b, h) do { _Pragma("unroll") for (int n = 0; n < 2; ++n) _Pragma("unroll") for (int k = 0; k < 2; ++k) dst[n][k] = *(const LAS bf16x8*)(lds + PG8_SB(b, h) + boff + n * 2048 + k * 1024); } while (0)
; #define PG8_MMA(ai, bj, At, Bt) do { __builtin_amdgcn_s_setprio(1); _Pragma("unroll") for (int m = 0; m < 4; ++m) _Pragma("unroll") for (int n = 0; n < 2; ++n) _Pragma("unroll") for (int k = 0; k < 2; ++k) \
;         acc[ai][bj][m][n] = __builtin_amdgcn_mfma_f32_16x16x32_bf16(Bt[n][k], At[m][k], acc[ai][bj][m][n], 0, 0, 0); __builtin_amdgcn_s_setprio(0); } while (0)
; #define PG8_WAIT_V(n) asm volatile("s_waitcnt vmcnt(" #n ")" ::: "memory")
; #define PG8_WAIT_L(n) asm volatile("s_waitcnt lgkmcnt(" #n ")" ::: "memory")
; #define PG8_BAR __builtin_amdgcn_s_barrier()
; #define PG8_SCHED __builtin_amdgcn_sched_barrier(0)
; template <class Epi, class Sched>
; DI void gemm_phase(LAS unsigned char* lds, const Gemm g, const Sched& S, const Epi& E) {
;     ...
;             PG8_WAIT_V(8); PG8_WAIT_L(0); PG8_BAR; PG8_MMA(0, 0, At, B0); PG8_MMA(0, 1, At, B1); PG8_BAR; PG8_SCHED;
;             PG8_LDA(At, 0, 1); PG8_STAGE(PG8_SB(0, 0), b2, voffB); PG8_STAGE(PG8_SB(0, 1), b2 + hstepB, voffB); PG8_STAGE(PG8_SA(0, 0), a2, voffA);
;             PG8_WAIT_V(8); PG8_WAIT_L(0); PG8_BAR; PG8_MMA(1, 0, At, B0); PG8_MMA(1, 1, At, B1); PG8_BAR; PG8_SCHED;
;             PG8_LDB(B0, 1, 0); PG8_LDB(B1, 1, 1); PG8_SCHED; PG8_LDA(At, 1, 0); PG8_STAGE(PG8_SA(0, 1), a2 + hstepA, voffA);
;             PG8_WAIT_V(8); PG8_WAIT_L(0); PG8_BAR; PG8_MMA(0, 0, At, B0); PG8_MMA(0, 1, At, B1); PG8_BAR; PG8_SCHED;
	s_setprio 1
	v_mfma_f32_16x16x32_bf16 v[126:129], v[168:171], v[202:205], v[126:129]
	v_mfma_f32_16x16x32_bf16 v[118:121], v[176:179], v[202:205], v[118:121]
	v_mfma_f32_16x16x32_bf16 v[110:113], v[168:171], v[210:213], v[110:113]
	v_mfma_f32_16x16x32_bf16 v[102:105], v[176:179], v[210:213], v[102:105]
	v_mfma_f32_16x16x32_bf16 v[94:97], v[168:171], v[218:221], v[94:97]
	v_mfma_f32_16x16x32_bf16 v[86:89], v[176:179], v[218:221], v[86:89]
	v_mfma_f32_16x16x32_bf16 v[78:81], v[168:171], v[226:229], v[78:81]
	v_mfma_f32_16x16x32_bf16 v[70:73], v[176:179], v[226:229], v[70:73]
	v_mfma_f32_16x16x32_bf16 v[126:129], v[172:175], v[206:209], v[126:129]
	v_mfma_f32_16x16x32_bf16 v[118:121], v[180:183], v[206:209], v[118:121]
	v_mfma_f32_16x16x32_bf16 v[110:113], v[172:175], v[214:217], v[110:113]
	v_mfma_f32_16x16x32_bf16 v[102:105], v[180:183], v[214:217], v[102:105]
	v_mfma_f32_16x16x32_bf16 v[94:97], v[172:175], v[222:225], v[94:97]
	v_mfma_f32_16x16x32_bf16 v[86:89], v[180:183], v[222:225], v[86:89]
	v_mfma_f32_16x16x32_bf16 v[78:81], v[172:175], v[230:233], v[78:81]
	v_mfma_f32_16x16x32_bf16 v[70:73], v[180:183], v[230:233], v[70:73]
	v_mfma_f32_16x16x32_bf16 v[122:125], v[186:189], v[202:205], v[122:125]
	v_mfma_f32_16x16x32_bf16 v[114:117], v[194:197], v[202:205], v[114:117]
	v_mfma_f32_16x16x32_bf16 v[106:109], v[186:189], v[210:213], v[106:109]
	v_mfma_f32_16x16x32_bf16 v[98:101], v[194:197], v[210:213], v[98:101]
	v_mfma_f32_16x16x32_bf16 v[90:93], v[186:189], v[218:221], v[90:93]
	v_mfma_f32_16x16x32_bf16 v[82:85], v[194:197], v[218:221], v[82:85]
	v_mfma_f32_16x16x32_bf16 v[74:77], v[186:189], v[226:229], v[74:77]
	v_mfma_f32_16x16x32_bf16 v[66:69], v[194:197], v[226:229], v[66:69]
	v_mfma_f32_16x16x32_bf16 v[122:125], v[190:193], v[206:209], v[122:125]
	v_mfma_f32_16x16x32_bf16 v[114:117], v[198:201], v[206:209], v[114:117]
	v_mfma_f32_16x16x32_bf16 v[106:109], v[190:193], v[214:217], v[106:109]
	v_mfma_f32_16x16x32_bf16 v[98:101], v[198:201], v[214:217], v[98:101]
	v_mfma_f32_16x16x32_bf16 v[90:93], v[190:193], v[222:225], v[90:93]
	v_mfma_f32_16x16x32_bf16 v[82:85], v[198:201], v[222:225], v[82:85]
	v_mfma_f32_16x16x32_bf16 v[74:77], v[190:193], v[230:233], v[74:77]
	v_mfma_f32_16x16x32_bf16 v[66:69], v[198:201], v[230:233], v[66:69]
	s_setprio 0
	s_barrier
	s_add_i32 s66, s57, s46
	v_lshl_add_u64 v[234:235], s[42:43], 0, v[134:135]
	s_mov_b32 m0, s66
	ds_read_b128 v[202:205], v160 offset:16384
	ds_read_b128 v[206:209], v160 offset:17408
	ds_read_b128 v[210:213], v160 offset:18432
	ds_read_b128 v[214:217], v160 offset:19456
	ds_read_b128 v[218:221], v160 offset:20480
	ds_read_b128 v[222:225], v160 offset:21504
	ds_read_b128 v[226:229], v160 offset:22528
	ds_read_b128 v[230:233], v160 offset:23552
	global_load_lds_dwordx4 v[234:235], off
	s_add_i32 m0, s66, 0x2000
	s_add_u32 s66, s42, 0x40000
	v_lshl_add_u64 v[236:237], s[42:43], 0, v[130:131]
	s_addc_u32 s67, s43, 0
	s_add_i32 s68, s58, s46
	global_load_lds_dwordx4 v[236:237], off
	v_lshl_add_u64 v[238:239], s[66:67], 0, v[134:135]
	s_mov_b32 m0, s68
	v_lshl_add_u64 v[240:241], s[44:45], 0, v[132:133]
	global_load_lds_dwordx4 v[238:239], off
	v_lshl_add_u64 v[238:239], s[66:67], 0, v[130:131]
	s_add_i32 m0, s68, 0x2000
	s_nop 0
	global_load_lds_dwordx4 v[238:239], off
	v_lshl_add_u64 v[238:239], s[44:45], 0, v[136:137]
	s_mov_b32 m0, s49
	s_nop 0
	global_load_lds_dwordx4 v[238:239], off
	s_mov_b32 m0, s50
	s_nop 0
	global_load_lds_dwordx4 v[240:241], off
	s_waitcnt vmcnt(8)
	s_waitcnt lgkmcnt(0)
	s_barrier
	s_setprio 1
	v_mfma_f32_16x16x32_bf16 v[62:65], v[168:171], v[202:205], v[62:65]
	v_mfma_f32_16x16x32_bf16 v[54:57], v[176:179], v[202:205], v[54:57]
	v_mfma_f32_16x16x32_bf16 v[46:49], v[168:171], v[210:213], v[46:49]
	v_mfma_f32_16x16x32_bf16 v[38:41], v[176:179], v[210:213], v[38:41]
	v_mfma_f32_16x16x32_bf16 v[30:33], v[168:171], v[218:221], v[30:33]
	v_mfma_f32_16x16x32_bf16 v[22:25], v[176:179], v[218:221], v[22:25]
	v_mfma_f32_16x16x32_bf16 v[14:17], v[168:171], v[226:229], v[14:17]
	v_mfma_f32_16x16x32_bf16 v[6:9], v[176:179], v[226:229], v[6:9]
	v_mfma_f32_16x16x32_bf16 v[62:65], v[172:175], v[206:209], v[62:65]
	v_mfma_f32_16x16x32_bf16 v[54:57], v[180:183], v[206:209], v[54:57]
	v_mfma_f32_16x16x32_bf16 v[46:49], v[172:175], v[214:217], v[46:49]
	v_mfma_f32_16x16x32_bf16 v[38:41], v[180:183], v[214:217], v[38:41]
	v_mfma_f32_16x16x32_bf16 v[30:33], v[172:175], v[222:225], v[30:33]
	v_mfma_f32_16x16x32_bf16 v[22:25], v[180:183], v[222:225], v[22:25]
	v_mfma_f32_16x16x32_bf16 v[14:17], v[172:175], v[230:233], v[14:17]
	v_mfma_f32_16x16x32_bf16 v[6:9], v[180:183], v[230:233], v[6:9]
	v_mfma_f32_16x16x32_bf16 v[58:61], v[186:189], v[202:205], v[58:61]
	v_mfma_f32_16x16x32_bf16 v[50:53], v[194:197], v[202:205], v[50:53]
	v_mfma_f32_16x16x32_bf16 v[42:45], v[186:189], v[210:213], v[42:45]
	v_mfma_f32_16x16x32_bf16 v[34:37], v[194:197], v[210:213], v[34:37]
	v_mfma_f32_16x16x32_bf16 v[26:29], v[186:189], v[218:221], v[26:29]
	v_mfma_f32_16x16x32_bf16 v[18:21], v[194:197], v[218:221], v[18:21]
	v_mfma_f32_16x16x32_bf16 v[10:13], v[186:189], v[226:229], v[10:13]
	v_mfma_f32_16x16x32_bf16 v[2:5], v[194:197], v[226:229], v[2:5]
	v_mfma_f32_16x16x32_bf16 v[58:61], v[190:193], v[206:209], v[58:61]
	v_mfma_f32_16x16x32_bf16 v[50:53], v[198:201], v[206:209], v[50:53]
	v_mfma_f32_16x16x32_bf16 v[42:45], v[190:193], v[214:217], v[42:45]
	v_mfma_f32_16x16x32_bf16 v[34:37], v[198:201], v[214:217], v[34:37]
	v_mfma_f32_16x16x32_bf16 v[26:29], v[190:193], v[222:225], v[26:29]
	v_mfma_f32_16x16x32_bf16 v[18:21], v[198:201], v[222:225], v[18:21]
	v_mfma_f32_16x16x32_bf16 v[10:13], v[190:193], v[230:233], v[10:13]
	v_mfma_f32_16x16x32_bf16 v[2:5], v[198:201], v[230:233], v[2:5]
	s_setprio 0
	s_barrier
; #define PG8_STAGE(bufoff, gbase, voff) do { _Pragma("unroll") for (int _i = 0; _i < 2; ++_i) \
;         __builtin_amdgcn_global_load_lds((const unsigned*)((const char*)(gbase) + (voff)[_i]), (LAS unsigned*)(lds + (bufoff) + ldsw + _i * 8192), 16, 0, 0); } while (0)
; #define PG8_LDA(dst, b, h) do { _Pragma("unroll") for (int m = 0; m < 4; ++m) _Pragma("unroll") for (int k = 0; k < 2; ++k) dst[m][k] = *(const LAS bf16x8*)(lds + PG8_SA(b, h) + aoff + m * 2048 + k * 1024); } while (0)
; #define PG8_LDB(dst, b, h) do { _Pragma("unroll") for (int n = 0; n < 2; ++n) _Pragma("unroll") for (int k = 0; k < 2; ++k) dst[n][k] = *(const LAS bf16x8*)(lds + PG8_SB(b, h) + boff + n * 2048 + k * 1024); } while (0)
; #define PG8_MMA(ai, bj, At, Bt) do { __builtin_amdgcn_s_setprio(1); _Pragma("unroll") for (int m = 0; m < 4; ++m) _Pragma("unroll") for (int n = 0; n < 2; ++n) _Pragma("unroll") for (int k = 0; k < 2; ++k) \
;         acc[ai][bj][m][n] = __builtin_amdgcn_mfma_f32_16x16x32_bf16(Bt[n][k], At[m][k], acc[ai][bj][m][n], 0, 0, 0); __builtin_amdgcn_s_setprio(0); } while (0)
; #define PG8_WAIT_V(n) asm volatile("s_waitcnt vmcnt(" #n ")" ::: "memory")
; #define PG8_WAIT_L(n) asm volatile("s_waitcnt lgkmcnt(" #n ")" ::: "memory")
; #define PG8_BAR __builtin_amdgcn_s_barrier()
; #define PG8_SCHED __builtin_amdgcn_sched_barrier(0)
; template <class Epi, class Sched>
; DI void gemm_phase(LAS unsigned char* lds, const Gemm g, const Sched& S, const Epi& E) {
;     ...
;             PG8_LDB(B0, 1, 0); PG8_LDB(B1, 1, 1); PG8_SCHED; PG8_LDA(At, 1, 0); PG8_STAGE(PG8_SA(0, 1), a2 + hstepA, voffA);
;             PG8_WAIT_V(8); PG8_WAIT_L(0); PG8_BAR; PG8_MMA(0, 0, At, B0); PG8_MMA(0, 1, At, B1); PG8_BAR; PG8_SCHED;
	s_add_i32 s66, 0, 0x18000
	v_add_u32_e32 v167, s66, v158
	s_add_i32 s67, 0, 0x1c000
	ds_read_b128 v[168:171], v167
	ds_read_b128 v[172:175], v167 offset:1024
	ds_read_b128 v[176:179], v167 offset:2048
	ds_read_b128 v[180:183], v167 offset:3072
	v_add_u32_e32 v167, s67, v158
	ds_read_b128 v[186:189], v167
	ds_read_b128 v[190:193], v167 offset:1024
	ds_read_b128 v[194:197], v167 offset:2048
	ds_read_b128 v[198:201], v167 offset:3072
	s_add_u32 s44, s44, 0x40000
	s_addc_u32 s45, s45, 0
	s_mov_b32 m0, s51
	v_lshl_add_u64 v[242:243], s[44:45], 0, v[136:137]
	ds_read_b128 v[202:205], v160 offset:32768
	ds_read_b128 v[206:209], v160 offset:33792
	ds_read_b128 v[210:213], v160 offset:34816
	ds_read_b128 v[214:217], v160 offset:35840
	ds_read_b128 v[218:221], v160 offset:36864
	ds_read_b128 v[222:225], v160 offset:37888
	ds_read_b128 v[226:229], v160 offset:38912
	ds_read_b128 v[230:233], v160 offset:39936
	global_load_lds_dwordx4 v[242:243], off
	v_lshl_add_u64 v[242:243], s[44:45], 0, v[132:133]
	s_mov_b32 m0, s52
	s_nop 0
	global_load_lds_dwordx4 v[242:243], off
	s_waitcnt vmcnt(8)
	s_waitcnt lgkmcnt(0)
	s_barrier
	s_setprio 1
	v_mfma_f32_16x16x32_bf16 v[126:129], v[168:171], v[202:205], v[126:129]
	v_mfma_f32_16x16x32_bf16 v[118:121], v[176:179], v[202:205], v[118:121]
	v_mfma_f32_16x16x32_bf16 v[110:113], v[168:171], v[210:213], v[110:113]
	v_mfma_f32_16x16x32_bf16 v[102:105], v[176:179], v[210:213], v[102:105]
	v_mfma_f32_16x16x32_bf16 v[94:97], v[168:171], v[218:221], v[94:97]
	v_mfma_f32_16x16x32_bf16 v[86:89], v[176:179], v[218:221], v[86:89]
	v_mfma_f32_16x16x32_bf16 v[78:81], v[168:171], v[226:229], v[78:81]
	v_mfma_f32_16x16x32_bf16 v[70:73], v[176:179], v[226:229], v[70:73]
	v_mfma_f32_16x16x32_bf16 v[126:129], v[172:175], v[206:209], v[126:129]
	v_mfma_f32_16x16x32_bf16 v[118:121], v[180:183], v[206:209], v[118:121]
	v_mfma_f32_16x16x32_bf16 v[110:113], v[172:175], v[214:217], v[110:113]
	v_mfma_f32_16x16x32_bf16 v[102:105], v[180:183], v[214:217], v[102:105]
	v_mfma_f32_16x16x32_bf16 v[94:97], v[172:175], v[222:225], v[94:97]
	v_mfma_f32_16x16x32_bf16 v[86:89], v[180:183], v[222:225], v[86:89]
	v_mfma_f32_16x16x32_bf16 v[78:81], v[172:175], v[230:233], v[78:81]
	v_mfma_f32_16x16x32_bf16 v[70:73], v[180:183], v[230:233], v[70:73]
	v_mfma_f32_16x16x32_bf16 v[122:125], v[186:189], v[202:205], v[122:125]
	v_mfma_f32_16x16x32_bf16 v[114:117], v[194:197], v[202:205], v[114:117]
	v_mfma_f32_16x16x32_bf16 v[106:109], v[186:189], v[210:213], v[106:109]
	v_mfma_f32_16x16x32_bf16 v[98:101], v[194:197], v[210:213], v[98:101]
	v_mfma_f32_16x16x32_bf16 v[90:93], v[186:189], v[218:221], v[90:93]
	v_mfma_f32_16x16x32_bf16 v[82:85], v[194:197], v[218:221], v[82:85]
	v_mfma_f32_16x16x32_bf16 v[74:77], v[186:189], v[226:229], v[74:77]
	v_mfma_f32_16x16x32_bf16 v[66:69], v[194:197], v[226:229], v[66:69]
	v_mfma_f32_16x16x32_bf16 v[122:125], v[190:193], v[206:209], v[122:125]
	v_mfma_f32_16x16x32_bf16 v[114:117], v[198:201], v[206:209], v[114:117]
	v_mfma_f32_16x16x32_bf16 v[106:109], v[190:193], v[214:217], v[106:109]
	v_mfma_f32_16x16x32_bf16 v[98:101], v[198:201], v[214:217], v[98:101]
	v_mfma_f32_16x16x32_bf16 v[90:93], v[190:193], v[222:225], v[90:93]
	v_mfma_f32_16x16x32_bf16 v[82:85], v[198:201], v[222:225], v[82:85]
	v_mfma_f32_16x16x32_bf16 v[74:77], v[190:193], v[230:233], v[74:77]
	v_mfma_f32_16x16x32_bf16 v[66:69], v[198:201], v[230:233], v[66:69]
	s_setprio 0
	s_barrier
; #define PG8_STAGE(bufoff, gbase, voff) do { _Pragma("unroll") for (int _i = 0; _i < 2; ++_i) \
;         __builtin_amdgcn_global_load_lds((const unsigned*)((const char*)(gbase) + (voff)[_i]), (LAS unsigned*)(lds + (bufoff) + ldsw + _i * 8192), 16, 0, 0); } while (0)
; #define PG8_LDA(dst, b, h) do { _Pragma("unroll") for (int m = 0; m < 4; ++m) _Pragma("unroll") for (int k = 0; k < 2; ++k) dst[m][k] = *(const LAS bf16x8*)(lds + PG8_SA(b, h) + aoff + m * 2048 + k * 1024); } while (0)
; #define PG8_MMA(ai, bj, At, Bt) do { __builtin_amdgcn_s_setprio(1); _Pragma("unroll") for (int m = 0; m < 4; ++m) _Pragma("unroll") for (int n = 0; n < 2; ++n) _Pragma("unroll") for (int k = 0; k < 2; ++k) \
;         acc[ai][bj][m][n] = __builtin_amdgcn_mfma_f32_16x16x32_bf16(Bt[n][k], At[m][k], acc[ai][bj][m][n], 0, 0, 0); __builtin_amdgcn_s_setprio(0); } while (0)
; #define PG8_WAIT_V(n) asm volatile("s_waitcnt vmcnt(" #n ")" ::: "memory")
; #define PG8_WAIT_L(n) asm volatile("s_waitcnt lgkmcnt(" #n ")" ::: "memory")
; #define PG8_BAR __builtin_amdgcn_s_barrier()
; #define PG8_SCHED __builtin_amdgcn_sched_barrier(0)
;     DI void pre(Pre& pr, const pg8::Unit& u, int wr, int fr) const { load_rows(pr, ssq, u, wr, fr); }
;     DI void pre(Pre& pr, const pg8::Unit& u, int wr, int fr) const { load_rows(pr, ssq, u, wr, fr); }
; template <class Epi, class Sched>
; DI void gemm_phase(LAS unsigned char* lds, const Gemm g, const Sched& S, const Epi& E) {
;     ...
;             PG8_LDA(At, 1, 1); PG8_STAGE(PG8_SB(1, 0), b3, voffB); PG8_STAGE(PG8_SB(1, 1), b3 + hstepB, voffB); PG8_STAGE(PG8_SA(1, 0), a3, voffA);
;             PG8_WAIT_V(8); PG8_WAIT_L(0); PG8_BAR; PG8_MMA(1, 0, At, B0); PG8_MMA(1, 1, At, B1); PG8_BAR; PG8_SCHED;
;         }
;         if (wr == 0) PG8_BAR;
;         E(acc, cur, wr, wc, fr, fq, pre);
;         if (!has_next) break;
	s_add_i32 s44, s66, s46
	v_lshl_add_u64 v[234:235], v[234:235], 0, s[16:17]
	s_mov_b32 m0, s44
	ds_read_b128 v[202:205], v160 offset:49152
	ds_read_b128 v[206:209], v160 offset:50176
	ds_read_b128 v[210:213], v160 offset:51200
	ds_read_b128 v[214:217], v160 offset:52224
	ds_read_b128 v[218:221], v160 offset:53248
	ds_read_b128 v[222:225], v160 offset:54272
	ds_read_b128 v[226:229], v160 offset:55296
	ds_read_b128 v[230:233], v160 offset:56320
	global_load_lds_dwordx4 v[234:235], off
	s_add_i32 m0, s44, 0x2000
	s_add_u32 s42, s42, 0x40080
	v_lshl_add_u64 v[234:235], v[236:237], 0, s[16:17]
	s_addc_u32 s43, s43, 0
	s_add_i32 s44, s67, s46
	global_load_lds_dwordx4 v[234:235], off
	v_lshl_add_u64 v[234:235], s[42:43], 0, v[134:135]
	s_mov_b32 m0, s44
	s_nop 0
	global_load_lds_dwordx4 v[234:235], off
	v_lshl_add_u64 v[234:235], s[42:43], 0, v[130:131]
	s_add_i32 m0, s44, 0x2000
	s_nop 0
	global_load_lds_dwordx4 v[234:235], off
	v_lshl_add_u64 v[234:235], v[238:239], 0, s[16:17]
	s_mov_b32 m0, s54
	s_nop 0
	global_load_lds_dwordx4 v[234:235], off
	v_lshl_add_u64 v[234:235], v[240:241], 0, s[16:17]
	s_mov_b32 m0, s55
	s_nop 0
	global_load_lds_dwordx4 v[234:235], off
	s_waitcnt vmcnt(8)
	s_waitcnt lgkmcnt(0)
	s_barrier
	s_setprio 1
	v_mfma_f32_16x16x32_bf16 v[62:65], v[168:171], v[202:205], v[62:65]
	v_mfma_f32_16x16x32_bf16 v[54:57], v[176:179], v[202:205], v[54:57]
	v_mfma_f32_16x16x32_bf16 v[46:49], v[168:171], v[210:213], v[46:49]
	v_mfma_f32_16x16x32_bf16 v[38:41], v[176:179], v[210:213], v[38:41]
	v_mfma_f32_16x16x32_bf16 v[30:33], v[168:171], v[218:221], v[30:33]
	v_mfma_f32_16x16x32_bf16 v[22:25], v[176:179], v[218:221], v[22:25]
	v_mfma_f32_16x16x32_bf16 v[14:17], v[168:171], v[226:229], v[14:17]
	v_mfma_f32_16x16x32_bf16 v[6:9], v[176:179], v[226:229], v[6:9]
	v_mfma_f32_16x16x32_bf16 v[62:65], v[172:175], v[206:209], v[62:65]
	v_mfma_f32_16x16x32_bf16 v[54:57], v[180:183], v[206:209], v[54:57]
	v_mfma_f32_16x16x32_bf16 v[46:49], v[172:175], v[214:217], v[46:49]
	v_mfma_f32_16x16x32_bf16 v[38:41], v[180:183], v[214:217], v[38:41]
	v_mfma_f32_16x16x32_bf16 v[30:33], v[172:175], v[222:225], v[30:33]
	v_mfma_f32_16x16x32_bf16 v[22:25], v[180:183], v[222:225], v[22:25]
	v_mfma_f32_16x16x32_bf16 v[14:17], v[172:175], v[230:233], v[14:17]
	v_mfma_f32_16x16x32_bf16 v[6:9], v[180:183], v[230:233], v[6:9]
	v_mfma_f32_16x16x32_bf16 v[58:61], v[186:189], v[202:205], v[58:61]
	v_mfma_f32_16x16x32_bf16 v[50:53], v[194:197], v[202:205], v[50:53]
	v_mfma_f32_16x16x32_bf16 v[42:45], v[186:189], v[210:213], v[42:45]
	v_mfma_f32_16x16x32_bf16 v[34:37], v[194:197], v[210:213], v[34:37]
	v_mfma_f32_16x16x32_bf16 v[26:29], v[186:189], v[218:221], v[26:29]
	v_mfma_f32_16x16x32_bf16 v[18:21], v[194:197], v[218:221], v[18:21]
	v_mfma_f32_16x16x32_bf16 v[10:13], v[186:189], v[226:229], v[10:13]
	v_mfma_f32_16x16x32_bf16 v[2:5], v[194:197], v[226:229], v[2:5]
	v_mfma_f32_16x16x32_bf16 v[58:61], v[190:193], v[206:209], v[58:61]
	v_mfma_f32_16x16x32_bf16 v[50:53], v[198:201], v[206:209], v[50:53]
	v_mfma_f32_16x16x32_bf16 v[42:45], v[190:193], v[214:217], v[42:45]
	v_mfma_f32_16x16x32_bf16 v[34:37], v[198:201], v[214:217], v[34:37]
	v_mfma_f32_16x16x32_bf16 v[26:29], v[190:193], v[222:225], v[26:29]
	v_mfma_f32_16x16x32_bf16 v[18:21], v[198:201], v[222:225], v[18:21]
	v_mfma_f32_16x16x32_bf16 v[10:13], v[190:193], v[230:233], v[10:13]
	v_mfma_f32_16x16x32_bf16 v[2:5], v[198:201], v[230:233], v[2:5]
	s_setprio 0
	s_barrier
	s_add_i32 s65, s65, 2
	s_add_u32 s40, s40, 0x100
	s_addc_u32 s41, s41, 0
	s_add_u32 s63, s63, 0x100
	s_addc_u32 s64, s64, 0
	s_cmp_gt_u32 s65, 13
	s_cbranch_scc0 .LBB0_179
	s_waitcnt vmcnt(0)
	s_mov_b32 s99, 1
	s_and_b64 vcc, exec, s[18:19]
	s_cbranch_vccz .LBB0_182
	s_barrier

; #define PG8_STAGE(bufoff, gbase, voff) do { _Pragma("unroll") for (int _i = 0; _i < 2; ++_i) \
;         __builtin_amdgcn_global_load_lds((const unsigned*)((const char*)(gbase) + (voff)[_i]), (LAS unsigned*)(lds + (bufoff) + ldsw + _i * 8192), 16, 0, 0); } while (0)
; #define PG8_WAIT_V(n) asm volatile("s_waitcnt vmcnt(" #n ")" ::: "memory")
; #define PG8_BAR __builtin_amdgcn_s_barrier()
; template <class Epi, class Sched>
; DI void gemm_phase(LAS unsigned char* lds, const Gemm g, const Sched& S, const Epi& E) {
;     const int tid = threadIdx.x, wid = __builtin_amdgcn_readfirstlane(tid >> 6), lane = tid & 63, wr = wid >> 2, wc = wid & 3, fr = lane & 15, fq = lane >> 4;
;     const int K = g.K, nt = K / BK;
;     unsigned voffA[2], voffB[2];
; #pragma unroll
;     for (int i = 0; i < 2; ++i) { int R, C; stage_rc(tid * 16 + i * 8192, R, C); const int Rb = Epi::PERM ? ((R & ~31) + perm32(R & 31)) : R;
;         voffA[i] = (unsigned)(R * g.lda + C) * 2u; voffB[i] = (unsigned)(Rb * g.ldb + C) * 2u; }
;     const size_t kstep = (size_t)(BK * 2);
;     const size_t hstepA = (size_t)HALF * g.lda * 2, hstepB = (size_t)HALF * g.ldb * 2;
;     const size_t tstepA = 2 * hstepA, tstepB = 2 * hstepB;
;     const unsigned ldsw = (unsigned)wid * 1024u;
;     const int aoff = lds_byte(wr * 64 + fr, fq * 8), boff = lds_byte(wc * 32 + fr, fq * 8);
;     ...
;     PG8_STAGE(PG8_SB(0, 0), cB, voffB); PG8_STAGE(PG8_SB(0, 1), cB + hstepB, voffB); PG8_STAGE(PG8_SA(0, 0), cA, voffA); PG8_STAGE(PG8_SA(0, 1), cA + hstepA, voffA);
;     if (wr == 1) PG8_BAR;
;     PG8_WAIT_V(2); PG8_BAR;
;     PG8_STAGE(PG8_SB(1, 0), cB + kstep, voffB); PG8_STAGE(PG8_SA(1, 0), cA + kstep, voffA); PG8_STAGE(PG8_SB(1, 1), cB + hstepB + kstep, voffB);
;     PG8_WAIT_V(6); PG8_BAR;
.LBB0_264:
	s_lshl_b32 s5, s5, 5
	s_waitcnt lgkmcnt(0)
	s_mov_b64 s[16:17], 0x80
	s_and_b32 s34, s5, 0x60
	s_add_i32 m0, s45, 0x18000
	v_lshl_add_u64 v[8:9], v[8:9], 0, s[16:17]
	s_lshl_b32 s9, s4, 13
	s_lshl_b32 s5, s34, 7
	s_waitcnt vmcnt(2)
	s_barrier
	global_load_lds_dwordx4 v[8:9], off
	v_lshl_add_u64 v[6:7], v[6:7], 0, s[16:17]
	s_add_i32 m0, s45, 0x1a000
	s_add_i32 s50, s45, 0x8000
	s_add_i32 s51, s45, 0xa000
	global_load_lds_dwordx4 v[6:7], off
	v_lshl_add_u64 v[2:3], v[2:3], 0, s[16:17]
	s_mov_b32 m0, s50
	s_add_u32 s6, s38, 0xb0080
	global_load_lds_dwordx4 v[2:3], off
	v_lshl_add_u64 v[2:3], v[4:5], 0, s[16:17]
	s_mov_b32 m0, s51
	s_addc_u32 s7, s39, 0
	global_load_lds_dwordx4 v[2:3], off
	s_add_i32 m0, s45, 0x1c000
	v_lshl_add_u64 v[2:3], s[6:7], 0, v[132:133]
	global_load_lds_dwordx4 v[2:3], off
	v_lshl_add_u64 v[2:3], s[6:7], 0, v[136:137]
	s_add_i32 m0, s45, 0x1e000
	v_lshlrev_b32_e32 v5, 2, v184
	global_load_lds_dwordx4 v[2:3], off
	v_bfe_u32 v2, v184, 4, 2
	v_and_b32_e32 v3, 15, v184
	v_lshl_or_b32 v147, s4, 6, v3
	v_lshlrev_b32_e32 v4, 4, v2
	v_lshlrev_b32_e32 v6, 6, v184
	s_movk_i32 s4, 0x3c0
	v_lshl_or_b32 v3, v3, 6, v4
	v_and_b32_e32 v5, 32, v5
	v_and_or_b32 v4, v6, s4, v4
	v_bitop3_b32 v152, s5, v4, v5 bitop3:0xf6
	v_cmp_eq_u32_e64 s[4:5], 0, v2
	v_lshl_or_b32 v153, v2, 3, s34
	v_add_u16_e32 v2, v10, v11
	s_waitcnt vmcnt(6)
	s_cmpk_lt_u32 s8, 0x100
	v_lshrrev_b16_e32 v2, 1, v2
	v_bitop3_b32 v3, v3, s9, v5 bitop3:0xde
	s_cselect_b64 s[18:19], -1, 0
	v_add_lshl_u32 v138, v12, v2, 1
	v_add_lshl_u32 v140, v13, v2, 1
	s_add_i32 s54, 0, 0x10000
	s_add_i32 s55, 0, 0x14000
	v_mbcnt_lo_u32_b32 v2, -1, 0
	s_ashr_i32 s52, s3, 31
	s_ashr_i32 s53, s2, 31
	v_mov_b32_e32 v139, v133
	v_mov_b32_e32 v141, v133
	v_mov_b64_e32 v[142:143], 0x400
	v_mov_b64_e32 v[144:145], 0x3ff
	v_add_u32_e32 v154, s54, v152
	v_add_u32_e32 v155, s55, v152
	v_add_u32_e32 v156, 0, v3
	v_mbcnt_hi_u32_b32 v157, -1, v2
	s_barrier
	s_mov_b32 s99, 0
	s_branch .LBB0_267

; #define PG8_STAGE(bufoff, gbase, voff) do { _Pragma("unroll") for (int _i = 0; _i < 2; ++_i) \
;         __builtin_amdgcn_global_load_lds((const unsigned*)((const char*)(gbase) + (voff)[_i]), (LAS unsigned*)(lds + (bufoff) + ldsw + _i * 8192), 16, 0, 0); } while (0)
; #define PG8_LDA(dst, b, h) do { _Pragma("unroll") for (int m = 0; m < 4; ++m) _Pragma("unroll") for (int k = 0; k < 2; ++k) dst[m][k] = *(const LAS bf16x8*)(lds + PG8_SA(b, h) + aoff + m * 2048 + k * 1024); } while (0)
; #define PG8_LDB(dst, b, h) do { _Pragma("unroll") for (int n = 0; n < 2; ++n) _Pragma("unroll") for (int k = 0; k < 2; ++k) dst[n][k] = *(const LAS bf16x8*)(lds + PG8_SB(b, h) + boff + n * 2048 + k * 1024); } while (0)
; #define PG8_WAIT_V(n) asm volatile("s_waitcnt vmcnt(" #n ")" ::: "memory")
; #define PG8_WAIT_L(n) asm volatile("s_waitcnt lgkmcnt(" #n ")" ::: "memory")
; #define PG8_BAR __builtin_amdgcn_s_barrier()
; template <class Epi, class Sched>
; DI void gemm_phase(LAS unsigned char* lds, const Gemm g, const Sched& S, const Epi& E) {
;     ...
;         const char* nA = has_next ? (const char*)(nxt.src ? g.A1 : g.A0) + (size_t)nxt.pm * tstepA : cA; const char* nB = has_next ? (const char*)(nxt.src ? g.B1 : g.B0) + (size_t)nxt.pn * tstepB : cB;
;         for (int t = 0; t < nt; t += 2) {
;             const bool last = (t == nt - 2);
;             const char* a1 = cA + (size_t)(t + 1) * kstep;
;             const char* a2 = last ? nA : cA + (size_t)(t + 2) * kstep; const char* b2 = last ? nB : cB + (size_t)(t + 2) * kstep;
;             const char* a3 = a2 + kstep; const char* b3 = b2 + kstep;
;             PG8_LDB(B0, 0, 0); PG8_LDB(B1, 0, 1); PG8_SCHED; PG8_LDA(At, 0, 0); PG8_STAGE(PG8_SA(1, 1), a1 + hstepA, voffA);
;             PG8_WAIT_V(8); PG8_WAIT_L(0); PG8_BAR; PG8_MMA(0, 0, At, B0); PG8_MMA(0, 1, At, B1); PG8_BAR; PG8_SCHED;
;             PG8_LDA(At, 0, 1); PG8_STAGE(PG8_SB(0, 0), b2, voffB); PG8_STAGE(PG8_SB(0, 1), b2 + hstepB, voffB); PG8_STAGE(PG8_SA(0, 0), a2, voffA);
;     ...
;         if (!(Epi::CHAIN && cur.src == 0)) {
; #pragma unroll
;             for (int a = 0; a < 2; ++a)
; #pragma unroll
;                 for (int b = 0; b < 2; ++b)
; #pragma unroll
;                     for (int m = 0; m < 4; ++m)
; #pragma unroll
;                         for (int n = 0; n < 2; ++n) acc[a][b][m][n] = (f32x4){0.f, 0.f, 0.f, 0.f};
;         }
.LBB0_277:
	s_add_u32 s36, s36, 0xb0080
	s_addc_u32 s37, s37, 0
	s_add_u32 s60, s38, 0x100
	s_addc_u32 s61, s39, 0
	s_mov_b32 s62, -2
	s_waitcnt lgkmcnt(0)
	ds_read_b128 v[148:151], v154
	ds_read_b128 v[158:161], v154 offset:1024
	ds_read_b128 v[162:165], v154 offset:2048
	ds_read_b128 v[166:169], v154 offset:3072
	ds_read_b128 v[170:173], v155
	ds_read_b128 v[174:177], v155 offset:1024
	ds_read_b128 v[178:181], v155 offset:2048
	ds_read_b128 v[186:189], v155 offset:3072
	s_add_u32 s38, s36, 0xfff50080
	s_addc_u32 s39, s37, -1
	s_cmp_eq_u32 s62, 40
	s_cselect_b32 s41, s9, s39
	s_cselect_b32 s40, s8, s38
	s_cselect_b32 s39, s35, s61
	s_cselect_b32 s38, s34, s60
	v_lshl_add_u64 v[182:183], s[36:37], 0, v[138:139]
	s_add_i32 m0, s45, 0xc000
	ds_read_b128 v[190:193], v156
	ds_read_b128 v[194:197], v156 offset:1024
	ds_read_b128 v[198:201], v156 offset:2048
	ds_read_b128 v[202:205], v156 offset:3072
	ds_read_b128 v[206:209], v156 offset:4096
	ds_read_b128 v[210:213], v156 offset:5120
	ds_read_b128 v[214:217], v156 offset:6144
	ds_read_b128 v[218:221], v156 offset:7168
	global_load_lds_dwordx4 v[182:183], off
	v_lshl_add_u64 v[182:183], s[36:37], 0, v[140:141]
	s_add_i32 m0, s45, 0xe000
	s_nop 0
	global_load_lds_dwordx4 v[182:183], off
	s_cmp_lg_u32 s99, 0
	s_cbranch_scc1 .Lpk1_w1
	s_waitcnt vmcnt(8)
.Lpk1_w1:
	s_waitcnt lgkmcnt(0)
	s_barrier
	s_setprio 1
	v_mfma_f32_16x16x32_bf16 v[126:129], v[148:151], v[190:193], 0
	v_mfma_f32_16x16x32_bf16 v[122:125], v[162:165], v[190:193], 0
	v_mfma_f32_16x16x32_bf16 v[110:113], v[148:151], v[198:201], 0
	v_mfma_f32_16x16x32_bf16 v[106:109], v[162:165], v[198:201], 0
	v_mfma_f32_16x16x32_bf16 v[94:97], v[148:151], v[206:209], 0
	v_mfma_f32_16x16x32_bf16 v[90:93], v[162:165], v[206:209], 0
	v_mfma_f32_16x16x32_bf16 v[78:81], v[148:151], v[214:217], 0
	v_mfma_f32_16x16x32_bf16 v[74:77], v[162:165], v[214:217], 0
	v_mfma_f32_16x16x32_bf16 v[126:129], v[158:161], v[194:197], v[126:129]
	v_mfma_f32_16x16x32_bf16 v[122:125], v[166:169], v[194:197], v[122:125]
	v_mfma_f32_16x16x32_bf16 v[110:113], v[158:161], v[202:205], v[110:113]
	v_mfma_f32_16x16x32_bf16 v[106:109], v[166:169], v[202:205], v[106:109]
	v_mfma_f32_16x16x32_bf16 v[94:97], v[158:161], v[210:213], v[94:97]
	v_mfma_f32_16x16x32_bf16 v[90:93], v[166:169], v[210:213], v[90:93]
	v_mfma_f32_16x16x32_bf16 v[78:81], v[158:161], v[218:221], v[78:81]
	v_mfma_f32_16x16x32_bf16 v[74:77], v[166:169], v[218:221], v[74:77]
	v_mfma_f32_16x16x32_bf16 v[118:121], v[170:173], v[190:193], 0
	v_mfma_f32_16x16x32_bf16 v[114:117], v[178:181], v[190:193], 0
	v_mfma_f32_16x16x32_bf16 v[102:105], v[170:173], v[198:201], 0
	v_mfma_f32_16x16x32_bf16 v[98:101], v[178:181], v[198:201], 0
	v_mfma_f32_16x16x32_bf16 v[86:89], v[170:173], v[206:209], 0
	v_mfma_f32_16x16x32_bf16 v[82:85], v[178:181], v[206:209], 0
	v_mfma_f32_16x16x32_bf16 v[70:73], v[170:173], v[214:217], 0
	v_mfma_f32_16x16x32_bf16 v[66:69], v[178:181], v[214:217], 0
	v_mfma_f32_16x16x32_bf16 v[118:121], v[174:177], v[194:197], v[118:121]
	v_mfma_f32_16x16x32_bf16 v[114:117], v[186:189], v[194:197], v[114:117]
	v_mfma_f32_16x16x32_bf16 v[102:105], v[174:177], v[202:205], v[102:105]
	v_mfma_f32_16x16x32_bf16 v[98:101], v[186:189], v[202:205], v[98:101]
	v_mfma_f32_16x16x32_bf16 v[86:89], v[174:177], v[210:213], v[86:89]
	v_mfma_f32_16x16x32_bf16 v[82:85], v[186:189], v[210:213], v[82:85]
	v_mfma_f32_16x16x32_bf16 v[70:73], v[174:177], v[218:221], v[70:73]
	v_mfma_f32_16x16x32_bf16 v[66:69], v[186:189], v[218:221], v[66:69]
	s_setprio 0
	s_barrier
	s_add_i32 s63, s54, s44
	v_lshl_add_u64 v[182:183], s[38:39], 0, v[132:133]
	s_mov_b32 m0, s63
	ds_read_b128 v[190:193], v156 offset:16384
	ds_read_b128 v[194:197], v156 offset:17408
	ds_read_b128 v[198:201], v156 offset:18432
	ds_read_b128 v[202:205], v156 offset:19456
	ds_read_b128 v[206:209], v156 offset:20480
	ds_read_b128 v[210:213], v156 offset:21504
	ds_read_b128 v[214:217], v156 offset:22528
	ds_read_b128 v[218:221], v156 offset:23552
	global_load_lds_dwordx4 v[182:183], off
	s_add_i32 m0, s63, 0x2000
	s_add_u32 s64, s38, 0xb0000
	v_lshl_add_u64 v[222:223], s[38:39], 0, v[136:137]
	s_addc_u32 s65, s39, 0
	s_add_i32 s63, s55, s44
	global_load_lds_dwordx4 v[222:223], off
	v_lshl_add_u64 v[224:225], s[64:65], 0, v[132:133]
	s_mov_b32 m0, s63
	v_lshl_add_u64 v[226:227], s[40:41], 0, v[134:135]
	global_load_lds_dwordx4 v[224:225], off
	v_lshl_add_u64 v[224:225], s[64:65], 0, v[136:137]
	s_add_i32 m0, s63, 0x2000
	s_nop 0
	global_load_lds_dwordx4 v[224:225], off
	v_lshl_add_u64 v[224:225], s[40:41], 0, v[130:131]
	s_mov_b32 m0, s45
	s_nop 0
	global_load_lds_dwordx4 v[224:225], off
	s_mov_b32 m0, s46
	s_nop 0
	global_load_lds_dwordx4 v[226:227], off
	s_cmp_lg_u32 s99, 0
	s_cbranch_scc1 .Lpk1_w2
	s_waitcnt vmcnt(8)
; #define PG8_STAGE(bufoff, gbase, voff) do { _Pragma("unroll") for (int _i = 0; _i < 2; ++_i) \
;         __builtin_amdgcn_global_load_lds((const unsigned*)((const char*)(gbase) + (voff)[_i]), (LAS unsigned*)(lds + (bufoff) + ldsw + _i * 8192), 16, 0, 0); } while (0)
; #define PG8_LDA(dst, b, h) do { _Pragma("unroll") for (int m = 0; m < 4; ++m) _Pragma("unroll") for (int k = 0; k < 2; ++k) dst[m][k] = *(const LAS bf16x8*)(lds + PG8_SA(b, h) + aoff + m * 2048 + k * 1024); } while (0)
; #define PG8_LDB(dst, b, h) do { _Pragma("unroll") for (int n = 0; n < 2; ++n) _Pragma("unroll") for (int k = 0; k < 2; ++k) dst[n][k] = *(const LAS bf16x8*)(lds + PG8_SB(b, h) + boff + n * 2048 + k * 1024); } while (0)
; #define PG8_MMA(ai, bj, At, Bt) do { __builtin_amdgcn_s_setprio(1); _Pragma("unroll") for (int m = 0; m < 4; ++m) _Pragma("unroll") for (int n = 0; n < 2; ++n) _Pragma("unroll") for (int k = 0; k < 2; ++k) \
;         acc[ai][bj][m][n] = __builtin_amdgcn_mfma_f32_16x16x32_bf16(Bt[n][k], At[m][k], acc[ai][bj][m][n], 0, 0, 0); __builtin_amdgcn_s_setprio(0); } while (0)
; #define PG8_WAIT_V(n) asm volatile("s_waitcnt vmcnt(" #n ")" ::: "memory")
; #define PG8_WAIT_L(n) asm volatile("s_waitcnt lgkmcnt(" #n ")" ::: "memory")
; #define PG8_BAR __builtin_amdgcn_s_barrier()
; #define PG8_SCHED __builtin_amdgcn_sched_barrier(0)
; template <class Epi, class Sched>
; DI void gemm_phase(LAS unsigned char* lds, const Gemm g, const Sched& S, const Epi& E) {
;     ...
;             PG8_WAIT_V(8); PG8_WAIT_L(0); PG8_BAR; PG8_MMA(0, 0, At, B0); PG8_MMA(0, 1, At, B1); PG8_BAR; PG8_SCHED;
;             PG8_LDA(At, 0, 1); PG8_STAGE(PG8_SB(0, 0), b2, voffB); PG8_STAGE(PG8_SB(0, 1), b2 + hstepB, voffB); PG8_STAGE(PG8_SA(0, 0), a2, voffA);
;             PG8_WAIT_V(8); PG8_WAIT_L(0); PG8_BAR; PG8_MMA(1, 0, At, B0); PG8_MMA(1, 1, At, B1); PG8_BAR; PG8_SCHED;
;             PG8_LDB(B0, 1, 0); PG8_LDB(B1, 1, 1); PG8_SCHED; PG8_LDA(At, 1, 0); PG8_STAGE(PG8_SA(0, 1), a2 + hstepA, voffA);
;             PG8_WAIT_V(8); PG8_WAIT_L(0); PG8_BAR; PG8_MMA(0, 0, At, B0); PG8_MMA(0, 1, At, B1); PG8_BAR; PG8_SCHED;
.Lpk1_w2:
	s_mov_b32 s99, 0
	s_waitcnt lgkmcnt(0)
	s_barrier
	s_setprio 1
	v_mfma_f32_16x16x32_bf16 v[62:65], v[148:151], v[190:193], 0
	v_mfma_f32_16x16x32_bf16 v[58:61], v[162:165], v[190:193], 0
	v_mfma_f32_16x16x32_bf16 v[46:49], v[148:151], v[198:201], 0
	v_mfma_f32_16x16x32_bf16 v[42:45], v[162:165], v[198:201], 0
	v_mfma_f32_16x16x32_bf16 v[30:33], v[148:151], v[206:209], 0
	v_mfma_f32_16x16x32_bf16 v[26:29], v[162:165], v[206:209], 0
	v_mfma_f32_16x16x32_bf16 v[14:17], v[148:151], v[214:217], 0
	v_mfma_f32_16x16x32_bf16 v[10:13], v[162:165], v[214:217], 0
	v_mfma_f32_16x16x32_bf16 v[62:65], v[158:161], v[194:197], v[62:65]
	v_mfma_f32_16x16x32_bf16 v[58:61], v[166:169], v[194:197], v[58:61]
	v_mfma_f32_16x16x32_bf16 v[46:49], v[158:161], v[202:205], v[46:49]
	v_mfma_f32_16x16x32_bf16 v[42:45], v[166:169], v[202:205], v[42:45]
	v_mfma_f32_16x16x32_bf16 v[30:33], v[158:161], v[210:213], v[30:33]
	v_mfma_f32_16x16x32_bf16 v[26:29], v[166:169], v[210:213], v[26:29]
	v_mfma_f32_16x16x32_bf16 v[14:17], v[158:161], v[218:221], v[14:17]
	v_mfma_f32_16x16x32_bf16 v[10:13], v[166:169], v[218:221], v[10:13]
	v_mfma_f32_16x16x32_bf16 v[54:57], v[170:173], v[190:193], 0
	v_mfma_f32_16x16x32_bf16 v[50:53], v[178:181], v[190:193], 0
	v_mfma_f32_16x16x32_bf16 v[38:41], v[170:173], v[198:201], 0
	v_mfma_f32_16x16x32_bf16 v[34:37], v[178:181], v[198:201], 0
	v_mfma_f32_16x16x32_bf16 v[22:25], v[170:173], v[206:209], 0
	v_mfma_f32_16x16x32_bf16 v[18:21], v[178:181], v[206:209], 0
	v_mfma_f32_16x16x32_bf16 v[6:9], v[170:173], v[214:217], 0
	v_mfma_f32_16x16x32_bf16 v[2:5], v[178:181], v[214:217], 0
	v_mfma_f32_16x16x32_bf16 v[54:57], v[174:177], v[194:197], v[54:57]
	v_mfma_f32_16x16x32_bf16 v[50:53], v[186:189], v[194:197], v[50:53]
	v_mfma_f32_16x16x32_bf16 v[38:41], v[174:177], v[202:205], v[38:41]
	v_mfma_f32_16x16x32_bf16 v[34:37], v[186:189], v[202:205], v[34:37]
	v_mfma_f32_16x16x32_bf16 v[22:25], v[174:177], v[210:213], v[22:25]
	v_mfma_f32_16x16x32_bf16 v[18:21], v[186:189], v[210:213], v[18:21]
	v_mfma_f32_16x16x32_bf16 v[6:9], v[174:177], v[218:221], v[6:9]
	v_mfma_f32_16x16x32_bf16 v[2:5], v[186:189], v[218:221], v[2:5]
	s_setprio 0
	s_barrier
	s_add_i32 s63, 0, 0x18000
	s_add_i32 s64, 0, 0x1c000
	v_add_u32_e32 v166, s63, v152
	v_add_u32_e32 v185, s64, v152
	ds_read_b128 v[148:151], v166
	ds_read_b128 v[158:161], v166 offset:1024
	ds_read_b128 v[162:165], v166 offset:2048
	ds_read_b128 v[166:169], v166 offset:3072
	ds_read_b128 v[170:173], v185
	ds_read_b128 v[174:177], v185 offset:1024
	ds_read_b128 v[178:181], v185 offset:2048
	ds_read_b128 v[186:189], v185 offset:3072
	s_add_u32 s40, s40, 0xb0000
	s_addc_u32 s41, s41, 0
	s_mov_b32 m0, s47
	v_lshl_add_u64 v[228:229], s[40:41], 0, v[130:131]
	ds_read_b128 v[190:193], v156 offset:32768
	ds_read_b128 v[194:197], v156 offset:33792
	ds_read_b128 v[198:201], v156 offset:34816
	ds_read_b128 v[202:205], v156 offset:35840
	ds_read_b128 v[206:209], v156 offset:36864
	ds_read_b128 v[210:213], v156 offset:37888
	ds_read_b128 v[214:217], v156 offset:38912
	ds_read_b128 v[218:221], v156 offset:39936
	global_load_lds_dwordx4 v[228:229], off
	v_lshl_add_u64 v[228:229], s[40:41], 0, v[134:135]
	s_mov_b32 m0, s48
	s_nop 0
	global_load_lds_dwordx4 v[228:229], off
	s_waitcnt vmcnt(8)
	s_waitcnt lgkmcnt(0)
	s_barrier
	s_setprio 1
	v_mfma_f32_16x16x32_bf16 v[126:129], v[148:151], v[190:193], v[126:129]
	v_mfma_f32_16x16x32_bf16 v[122:125], v[162:165], v[190:193], v[122:125]
	v_mfma_f32_16x16x32_bf16 v[110:113], v[148:151], v[198:201], v[110:113]
	v_mfma_f32_16x16x32_bf16 v[106:109], v[162:165], v[198:201], v[106:109]
	v_mfma_f32_16x16x32_bf16 v[94:97], v[148:151], v[206:209], v[94:97]
	v_mfma_f32_16x16x32_bf16 v[90:93], v[162:165], v[206:209], v[90:93]
	v_mfma_f32_16x16x32_bf16 v[78:81], v[148:151], v[214:217], v[78:81]
	v_mfma_f32_16x16x32_bf16 v[74:77], v[162:165], v[214:217], v[74:77]
	v_mfma_f32_16x16x32_bf16 v[126:129], v[158:161], v[194:197], v[126:129]
	v_mfma_f32_16x16x32_bf16 v[122:125], v[166:169], v[194:197], v[122:125]
	v_mfma_f32_16x16x32_bf16 v[110:113], v[158:161], v[202:205], v[110:113]
	v_mfma_f32_16x16x32_bf16 v[106:109], v[166:169], v[202:205], v[106:109]
	v_mfma_f32_16x16x32_bf16 v[94:97], v[158:161], v[210:213], v[94:97]
	v_mfma_f32_16x16x32_bf16 v[90:93], v[166:169], v[210:213], v[90:93]
	v_mfma_f32_16x16x32_bf16 v[78:81], v[158:161], v[218:221], v[78:81]
	v_mfma_f32_16x16x32_bf16 v[74:77], v[166:169], v[218:221], v[74:77]
	v_mfma_f32_16x16x32_bf16 v[118:121], v[170:173], v[190:193], v[118:121]
	v_mfma_f32_16x16x32_bf16 v[114:117], v[178:181], v[190:193], v[114:117]
	v_mfma_f32_16x16x32_bf16 v[102:105], v[170:173], v[198:201], v[102:105]
	v_mfma_f32_16x16x32_bf16 v[98:101], v[178:181], v[198:201], v[98:101]
	v_mfma_f32_16x16x32_bf16 v[86:89], v[170:173], v[206:209], v[86:89]
	v_mfma_f32_16x16x32_bf16 v[82:85], v[178:181], v[206:209], v[82:85]
	v_mfma_f32_16x16x32_bf16 v[70:73], v[170:173], v[214:217], v[70:73]
	v_mfma_f32_16x16x32_bf16 v[66:69], v[178:181], v[214:217], v[66:69]
	v_mfma_f32_16x16x32_bf16 v[118:121], v[174:177], v[194:197], v[118:121]
	v_mfma_f32_16x16x32_bf16 v[114:117], v[186:189], v[194:197], v[114:117]
	v_mfma_f32_16x16x32_bf16 v[102:105], v[174:177], v[202:205], v[102:105]
	v_mfma_f32_16x16x32_bf16 v[98:101], v[186:189], v[202:205], v[98:101]
	v_mfma_f32_16x16x32_bf16 v[86:89], v[174:177], v[210:213], v[86:89]
	v_mfma_f32_16x16x32_bf16 v[82:85], v[186:189], v[210:213], v[82:85]
	v_mfma_f32_16x16x32_bf16 v[70:73], v[174:177], v[218:221], v[70:73]
	v_mfma_f32_16x16x32_bf16 v[66:69], v[186:189], v[218:221], v[66:69]
	s_setprio 0
	s_barrier
; #define PG8_STAGE(bufoff, gbase, voff) do { _Pragma("unroll") for (int _i = 0; _i < 2; ++_i) \
;         __builtin_amdgcn_global_load_lds((const unsigned*)((const char*)(gbase) + (voff)[_i]), (LAS unsigned*)(lds + (bufoff) + ldsw + _i * 8192), 16, 0, 0); } while (0)
; #define PG8_LDA(dst, b, h) do { _Pragma("unroll") for (int m = 0; m < 4; ++m) _Pragma("unroll") for (int k = 0; k < 2; ++k) dst[m][k] = *(const LAS bf16x8*)(lds + PG8_SA(b, h) + aoff + m * 2048 + k * 1024); } while (0)
; #define PG8_LDB(dst, b, h) do { _Pragma("unroll") for (int n = 0; n < 2; ++n) _Pragma("unroll") for (int k = 0; k < 2; ++k) dst[n][k] = *(const LAS bf16x8*)(lds + PG8_SB(b, h) + boff + n * 2048 + k * 1024); } while (0)
; #define PG8_MMA(ai, bj, At, Bt) do { __builtin_amdgcn_s_setprio(1); _Pragma("unroll") for (int m = 0; m < 4; ++m) _Pragma("unroll") for (int n = 0; n < 2; ++n) _Pragma("unroll") for (int k = 0; k < 2; ++k) \
;         acc[ai][bj][m][n] = __builtin_amdgcn_mfma_f32_16x16x32_bf16(Bt[n][k], At[m][k], acc[ai][bj][m][n], 0, 0, 0); __builtin_amdgcn_s_setprio(0); } while (0)
; #define PG8_WAIT_V(n) asm volatile("s_waitcnt vmcnt(" #n ")" ::: "memory")
; #define PG8_WAIT_L(n) asm volatile("s_waitcnt lgkmcnt(" #n ")" ::: "memory")
; #define PG8_BAR __builtin_amdgcn_s_barrier()
; #define PG8_SCHED __builtin_amdgcn_sched_barrier(0)
; template <class Epi, class Sched>
; DI void gemm_phase(LAS unsigned char* lds, const Gemm g, const Sched& S, const Epi& E) {
;     ...
;         for (int t = 0; t < nt; t += 2) {
;             const bool last = (t == nt - 2);
;             const char* a1 = cA + (size_t)(t + 1) * kstep;
;             const char* a2 = last ? nA : cA + (size_t)(t + 2) * kstep; const char* b2 = last ? nB : cB + (size_t)(t + 2) * kstep;
;             const char* a3 = a2 + kstep; const char* b3 = b2 + kstep;
;             PG8_LDB(B0, 0, 0); PG8_LDB(B1, 0, 1); PG8_SCHED; PG8_LDA(At, 0, 0); PG8_STAGE(PG8_SA(1, 1), a1 + hstepA, voffA);
;             PG8_WAIT_V(8); PG8_WAIT_L(0); PG8_BAR; PG8_MMA(0, 0, At, B0); PG8_MMA(0, 1, At, B1); PG8_BAR; PG8_SCHED;
;     ...
;             PG8_LDA(At, 1, 1); PG8_STAGE(PG8_SB(1, 0), b3, voffB); PG8_STAGE(PG8_SB(1, 1), b3 + hstepB, voffB); PG8_STAGE(PG8_SA(1, 0), a3, voffA);
;             PG8_WAIT_V(8); PG8_WAIT_L(0); PG8_BAR; PG8_MMA(1, 0, At, B0); PG8_MMA(1, 1, At, B1); PG8_BAR; PG8_SCHED;
	s_add_i32 s40, s63, s44
	v_lshl_add_u64 v[182:183], v[182:183], 0, s[16:17]
	s_mov_b32 m0, s40
	ds_read_b128 v[190:193], v156 offset:49152
	ds_read_b128 v[194:197], v156 offset:50176
	ds_read_b128 v[198:201], v156 offset:51200
	ds_read_b128 v[202:205], v156 offset:52224
	ds_read_b128 v[206:209], v156 offset:53248
	ds_read_b128 v[210:213], v156 offset:54272
	ds_read_b128 v[214:217], v156 offset:55296
	ds_read_b128 v[218:221], v156 offset:56320
	global_load_lds_dwordx4 v[182:183], off
	s_add_i32 m0, s40, 0x2000
	s_add_u32 s38, s38, 0xb0080
	v_lshl_add_u64 v[182:183], v[222:223], 0, s[16:17]
	s_addc_u32 s39, s39, 0
	s_add_i32 s40, s64, s44
	global_load_lds_dwordx4 v[182:183], off
	v_lshl_add_u64 v[182:183], s[38:39], 0, v[132:133]
	s_mov_b32 m0, s40
	s_nop 0
	global_load_lds_dwordx4 v[182:183], off
	v_lshl_add_u64 v[182:183], s[38:39], 0, v[136:137]
	s_add_i32 m0, s40, 0x2000
	s_nop 0
	global_load_lds_dwordx4 v[182:183], off
	v_lshl_add_u64 v[182:183], v[224:225], 0, s[16:17]
	s_mov_b32 m0, s50
	s_nop 0
	global_load_lds_dwordx4 v[182:183], off
	v_lshl_add_u64 v[182:183], v[226:227], 0, s[16:17]
	s_mov_b32 m0, s51
	s_nop 0
	global_load_lds_dwordx4 v[182:183], off
	s_waitcnt vmcnt(8)
	s_waitcnt lgkmcnt(0)
	s_barrier
	s_setprio 1
	v_mfma_f32_16x16x32_bf16 v[62:65], v[148:151], v[190:193], v[62:65]
	v_mfma_f32_16x16x32_bf16 v[58:61], v[162:165], v[190:193], v[58:61]
	v_mfma_f32_16x16x32_bf16 v[46:49], v[148:151], v[198:201], v[46:49]
	v_mfma_f32_16x16x32_bf16 v[42:45], v[162:165], v[198:201], v[42:45]
	v_mfma_f32_16x16x32_bf16 v[30:33], v[148:151], v[206:209], v[30:33]
	v_mfma_f32_16x16x32_bf16 v[26:29], v[162:165], v[206:209], v[26:29]
	v_mfma_f32_16x16x32_bf16 v[14:17], v[148:151], v[214:217], v[14:17]
	v_mfma_f32_16x16x32_bf16 v[10:13], v[162:165], v[214:217], v[10:13]
	v_mfma_f32_16x16x32_bf16 v[62:65], v[158:161], v[194:197], v[62:65]
	v_mfma_f32_16x16x32_bf16 v[58:61], v[166:169], v[194:197], v[58:61]
	v_mfma_f32_16x16x32_bf16 v[46:49], v[158:161], v[202:205], v[46:49]
	v_mfma_f32_16x16x32_bf16 v[42:45], v[166:169], v[202:205], v[42:45]
	v_mfma_f32_16x16x32_bf16 v[30:33], v[158:161], v[210:213], v[30:33]
	v_mfma_f32_16x16x32_bf16 v[26:29], v[166:169], v[210:213], v[26:29]
	v_mfma_f32_16x16x32_bf16 v[14:17], v[158:161], v[218:221], v[14:17]
	v_mfma_f32_16x16x32_bf16 v[10:13], v[166:169], v[218:221], v[10:13]
	v_mfma_f32_16x16x32_bf16 v[54:57], v[170:173], v[190:193], v[54:57]
	v_mfma_f32_16x16x32_bf16 v[50:53], v[178:181], v[190:193], v[50:53]
	v_mfma_f32_16x16x32_bf16 v[38:41], v[170:173], v[198:201], v[38:41]
	v_mfma_f32_16x16x32_bf16 v[34:37], v[178:181], v[198:201], v[34:37]
	v_mfma_f32_16x16x32_bf16 v[22:25], v[170:173], v[206:209], v[22:25]
	v_mfma_f32_16x16x32_bf16 v[18:21], v[178:181], v[206:209], v[18:21]
	v_mfma_f32_16x16x32_bf16 v[6:9], v[170:173], v[214:217], v[6:9]
	v_mfma_f32_16x16x32_bf16 v[2:5], v[178:181], v[214:217], v[2:5]
	v_mfma_f32_16x16x32_bf16 v[54:57], v[174:177], v[194:197], v[54:57]
	v_mfma_f32_16x16x32_bf16 v[50:53], v[186:189], v[194:197], v[50:53]
	v_mfma_f32_16x16x32_bf16 v[38:41], v[174:177], v[202:205], v[38:41]
	v_mfma_f32_16x16x32_bf16 v[34:37], v[186:189], v[202:205], v[34:37]
	v_mfma_f32_16x16x32_bf16 v[22:25], v[174:177], v[210:213], v[22:25]
	v_mfma_f32_16x16x32_bf16 v[18:21], v[186:189], v[210:213], v[18:21]
	v_mfma_f32_16x16x32_bf16 v[6:9], v[174:177], v[218:221], v[6:9]
	v_mfma_f32_16x16x32_bf16 v[2:5], v[186:189], v[218:221], v[2:5]
	s_setprio 0
	s_barrier
	s_add_i32 s62, s62, 2
	s_add_u32 s36, s36, 0x100
	s_addc_u32 s37, s37, 0
	s_add_u32 s60, s60, 0x100
	s_addc_u32 s61, s61, 0
	s_cmp_gt_u32 s62, 41
.LBB0_278:
	ds_read_b128 v[148:151], v154
	ds_read_b128 v[158:161], v154 offset:1024
	ds_read_b128 v[162:165], v154 offset:2048
	ds_read_b128 v[166:169], v154 offset:3072
	ds_read_b128 v[170:173], v155
	ds_read_b128 v[174:177], v155 offset:1024
	ds_read_b128 v[178:181], v155 offset:2048
	ds_read_b128 v[186:189], v155 offset:3072
	s_add_u32 s38, s36, 0xfff50080
	s_addc_u32 s39, s37, -1
	s_cmp_eq_u32 s62, 40
	s_cselect_b32 s41, s9, s39
	s_cselect_b32 s40, s8, s38
	s_cselect_b32 s39, s35, s61
	s_cselect_b32 s38, s34, s60
	v_lshl_add_u64 v[182:183], s[36:37], 0, v[138:139]
	s_add_i32 m0, s45, 0xc000
	ds_read_b128 v[190:193], v156
	ds_read_b128 v[194:197], v156 offset:1024
	ds_read_b128 v[198:201], v156 offset:2048
	ds_read_b128 v[202:205], v156 offset:3072
	ds_read_b128 v[206:209], v156 offset:4096
	ds_read_b128 v[210:213], v156 offset:5120
	ds_read_b128 v[214:217], v156 offset:6144
	ds_read_b128 v[218:221], v156 offset:7168
	global_load_lds_dwordx4 v[182:183], off
	v_lshl_add_u64 v[182:183], s[36:37], 0, v[140:141]
	s_add_i32 m0, s45, 0xe000
	s_nop 0
	global_load_lds_dwordx4 v[182:183], off
	s_waitcnt vmcnt(8)
	s_waitcnt lgkmcnt(0)
	s_barrier
; #define PG8_STAGE(bufoff, gbase, voff) do { _Pragma("unroll") for (int _i = 0; _i < 2; ++_i) \
;         __builtin_amdgcn_global_load_lds((const unsigned*)((const char*)(gbase) + (voff)[_i]), (LAS unsigned*)(lds + (bufoff) + ldsw + _i * 8192), 16, 0, 0); } while (0)
; #define PG8_LDA(dst, b, h) do { _Pragma("unroll") for (int m = 0; m < 4; ++m) _Pragma("unroll") for (int k = 0; k < 2; ++k) dst[m][k] = *(const LAS bf16x8*)(lds + PG8_SA(b, h) + aoff + m * 2048 + k * 1024); } while (0)
; #define PG8_MMA(ai, bj, At, Bt) do { __builtin_amdgcn_s_setprio(1); _Pragma("unroll") for (int m = 0; m < 4; ++m) _Pragma("unroll") for (int n = 0; n < 2; ++n) _Pragma("unroll") for (int k = 0; k < 2; ++k) \
;         acc[ai][bj][m][n] = __builtin_amdgcn_mfma_f32_16x16x32_bf16(Bt[n][k], At[m][k], acc[ai][bj][m][n], 0, 0, 0); __builtin_amdgcn_s_setprio(0); } while (0)
; #define PG8_WAIT_V(n) asm volatile("s_waitcnt vmcnt(" #n ")" ::: "memory")
; #define PG8_WAIT_L(n) asm volatile("s_waitcnt lgkmcnt(" #n ")" ::: "memory")
; #define PG8_BAR __builtin_amdgcn_s_barrier()
; #define PG8_SCHED __builtin_amdgcn_sched_barrier(0)
; template <class Epi, class Sched>
; DI void gemm_phase(LAS unsigned char* lds, const Gemm g, const Sched& S, const Epi& E) {
;     ...
;             PG8_WAIT_V(8); PG8_WAIT_L(0); PG8_BAR; PG8_MMA(0, 0, At, B0); PG8_MMA(0, 1, At, B1); PG8_BAR; PG8_SCHED;
;             PG8_LDA(At, 0, 1); PG8_STAGE(PG8_SB(0, 0), b2, voffB); PG8_STAGE(PG8_SB(0, 1), b2 + hstepB, voffB); PG8_STAGE(PG8_SA(0, 0), a2, voffA);
;             PG8_WAIT_V(8); PG8_WAIT_L(0); PG8_BAR; PG8_MMA(1, 0, At, B0); PG8_MMA(1, 1, At, B1); PG8_BAR; PG8_SCHED;
	s_setprio 1
	v_mfma_f32_16x16x32_bf16 v[126:129], v[148:151], v[190:193], v[126:129]
	v_mfma_f32_16x16x32_bf16 v[122:125], v[162:165], v[190:193], v[122:125]
	v_mfma_f32_16x16x32_bf16 v[110:113], v[148:151], v[198:201], v[110:113]
	v_mfma_f32_16x16x32_bf16 v[106:109], v[162:165], v[198:201], v[106:109]
	v_mfma_f32_16x16x32_bf16 v[94:97], v[148:151], v[206:209], v[94:97]
	v_mfma_f32_16x16x32_bf16 v[90:93], v[162:165], v[206:209], v[90:93]
	v_mfma_f32_16x16x32_bf16 v[78:81], v[148:151], v[214:217], v[78:81]
	v_mfma_f32_16x16x32_bf16 v[74:77], v[162:165], v[214:217], v[74:77]
	v_mfma_f32_16x16x32_bf16 v[126:129], v[158:161], v[194:197], v[126:129]
	v_mfma_f32_16x16x32_bf16 v[122:125], v[166:169], v[194:197], v[122:125]
	v_mfma_f32_16x16x32_bf16 v[110:113], v[158:161], v[202:205], v[110:113]
	v_mfma_f32_16x16x32_bf16 v[106:109], v[166:169], v[202:205], v[106:109]
	v_mfma_f32_16x16x32_bf16 v[94:97], v[158:161], v[210:213], v[94:97]
	v_mfma_f32_16x16x32_bf16 v[90:93], v[166:169], v[210:213], v[90:93]
	v_mfma_f32_16x16x32_bf16 v[78:81], v[158:161], v[218:221], v[78:81]
	v_mfma_f32_16x16x32_bf16 v[74:77], v[166:169], v[218:221], v[74:77]
	v_mfma_f32_16x16x32_bf16 v[118:121], v[170:173], v[190:193], v[118:121]
	v_mfma_f32_16x16x32_bf16 v[114:117], v[178:181], v[190:193], v[114:117]
	v_mfma_f32_16x16x32_bf16 v[102:105], v[170:173], v[198:201], v[102:105]
	v_mfma_f32_16x16x32_bf16 v[98:101], v[178:181], v[198:201], v[98:101]
	v_mfma_f32_16x16x32_bf16 v[86:89], v[170:173], v[206:209], v[86:89]
	v_mfma_f32_16x16x32_bf16 v[82:85], v[178:181], v[206:209], v[82:85]
	v_mfma_f32_16x16x32_bf16 v[70:73], v[170:173], v[214:217], v[70:73]
	v_mfma_f32_16x16x32_bf16 v[66:69], v[178:181], v[214:217], v[66:69]
	v_mfma_f32_16x16x32_bf16 v[118:121], v[174:177], v[194:197], v[118:121]
	v_mfma_f32_16x16x32_bf16 v[114:117], v[186:189], v[194:197], v[114:117]
	v_mfma_f32_16x16x32_bf16 v[102:105], v[174:177], v[202:205], v[102:105]
	v_mfma_f32_16x16x32_bf16 v[98:101], v[186:189], v[202:205], v[98:101]
	v_mfma_f32_16x16x32_bf16 v[86:89], v[174:177], v[210:213], v[86:89]
	v_mfma_f32_16x16x32_bf16 v[82:85], v[186:189], v[210:213], v[82:85]
	v_mfma_f32_16x16x32_bf16 v[70:73], v[174:177], v[218:221], v[70:73]
	v_mfma_f32_16x16x32_bf16 v[66:69], v[186:189], v[218:221], v[66:69]
	s_setprio 0
	s_barrier
	s_add_i32 s63, s54, s44
	v_lshl_add_u64 v[182:183], s[38:39], 0, v[132:133]
	s_mov_b32 m0, s63
	ds_read_b128 v[190:193], v156 offset:16384
	ds_read_b128 v[194:197], v156 offset:17408
	ds_read_b128 v[198:201], v156 offset:18432
	ds_read_b128 v[202:205], v156 offset:19456
	ds_read_b128 v[206:209], v156 offset:20480
	ds_read_b128 v[210:213], v156 offset:21504
	ds_read_b128 v[214:217], v156 offset:22528
	ds_read_b128 v[218:221], v156 offset:23552
	global_load_lds_dwordx4 v[182:183], off
	s_add_i32 m0, s63, 0x2000
	s_add_u32 s64, s38, 0xb0000
	v_lshl_add_u64 v[222:223], s[38:39], 0, v[136:137]
	s_addc_u32 s65, s39, 0
	s_add_i32 s63, s55, s44
	global_load_lds_dwordx4 v[222:223], off
	v_lshl_add_u64 v[224:225], s[64:65], 0, v[132:133]
	s_mov_b32 m0, s63
	v_lshl_add_u64 v[226:227], s[40:41], 0, v[134:135]
	global_load_lds_dwordx4 v[224:225], off
	v_lshl_add_u64 v[224:225], s[64:65], 0, v[136:137]
	s_add_i32 m0, s63, 0x2000
	s_nop 0
	global_load_lds_dwordx4 v[224:225], off
	v_lshl_add_u64 v[224:225], s[40:41], 0, v[130:131]
	s_mov_b32 m0, s45
	s_nop 0
	global_load_lds_dwordx4 v[224:225], off
	s_mov_b32 m0, s46
	s_nop 0
	global_load_lds_dwordx4 v[226:227], off
	s_waitcnt vmcnt(8)
	s_waitcnt lgkmcnt(0)
	s_barrier
	s_setprio 1
	v_mfma_f32_16x16x32_bf16 v[62:65], v[148:151], v[190:193], v[62:65]
	v_mfma_f32_16x16x32_bf16 v[58:61], v[162:165], v[190:193], v[58:61]
	v_mfma_f32_16x16x32_bf16 v[46:49], v[148:151], v[198:201], v[46:49]
	v_mfma_f32_16x16x32_bf16 v[42:45], v[162:165], v[198:201], v[42:45]
	v_mfma_f32_16x16x32_bf16 v[30:33], v[148:151], v[206:209], v[30:33]
	v_mfma_f32_16x16x32_bf16 v[26:29], v[162:165], v[206:209], v[26:29]
	v_mfma_f32_16x16x32_bf16 v[14:17], v[148:151], v[214:217], v[14:17]
	v_mfma_f32_16x16x32_bf16 v[10:13], v[162:165], v[214:217], v[10:13]
	v_mfma_f32_16x16x32_bf16 v[62:65], v[158:161], v[194:197], v[62:65]
	v_mfma_f32_16x16x32_bf16 v[58:61], v[166:169], v[194:197], v[58:61]
	v_mfma_f32_16x16x32_bf16 v[46:49], v[158:161], v[202:205], v[46:49]
	v_mfma_f32_16x16x32_bf16 v[42:45], v[166:169], v[202:205], v[42:45]
	v_mfma_f32_16x16x32_bf16 v[30:33], v[158:161], v[210:213], v[30:33]
	v_mfma_f32_16x16x32_bf16 v[26:29], v[166:169], v[210:213], v[26:29]
	v_mfma_f32_16x16x32_bf16 v[14:17], v[158:161], v[218:221], v[14:17]
	v_mfma_f32_16x16x32_bf16 v[10:13], v[166:169], v[218:221], v[10:13]
	v_mfma_f32_16x16x32_bf16 v[54:57], v[170:173], v[190:193], v[54:57]
	v_mfma_f32_16x16x32_bf16 v[50:53], v[178:181], v[190:193], v[50:53]
	v_mfma_f32_16x16x32_bf16 v[38:41], v[170:173], v[198:201], v[38:41]
	v_mfma_f32_16x16x32_bf16 v[34:37], v[178:181], v[198:201], v[34:37]
	v_mfma_f32_16x16x32_bf16 v[22:25], v[170:173], v[206:209], v[22:25]
	v_mfma_f32_16x16x32_bf16 v[18:21], v[178:181], v[206:209], v[18:21]
	v_mfma_f32_16x16x32_bf16 v[6:9], v[170:173], v[214:217], v[6:9]
	v_mfma_f32_16x16x32_bf16 v[2:5], v[178:181], v[214:217], v[2:5]
	v_mfma_f32_16x16x32_bf16 v[54:57], v[174:177], v[194:197], v[54:57]
	v_mfma_f32_16x16x32_bf16 v[50:53], v[186:189], v[194:197], v[50:53]
	v_mfma_f32_16x16x32_bf16 v[38:41], v[174:177], v[202:205], v[38:41]
	v_mfma_f32_16x16x32_bf16 v[34:37], v[186:189], v[202:205], v[34:37]
	v_mfma_f32_16x16x32_bf16 v[22:25], v[174:177], v[210:213], v[22:25]
	v_mfma_f32_16x16x32_bf16 v[18:21], v[186:189], v[210:213], v[18:21]
	v_mfma_f32_16x16x32_bf16 v[6:9], v[174:177], v[218:221], v[6:9]
	v_mfma_f32_16x16x32_bf16 v[2:5], v[186:189], v[218:221], v[2:5]
	s_setprio 0
	s_barrier
; #define PG8_STAGE(bufoff, gbase, voff) do { _Pragma("unroll") for (int _i = 0; _i < 2; ++_i) \
;         __builtin_amdgcn_global_load_lds((const unsigned*)((const char*)(gbase) + (voff)[_i]), (LAS unsigned*)(lds + (bufoff) + ldsw + _i * 8192), 16, 0, 0); } while (0)
; #define PG8_LDA(dst, b, h) do { _Pragma("unroll") for (int m = 0; m < 4; ++m) _Pragma("unroll") for (int k = 0; k < 2; ++k) dst[m][k] = *(const LAS bf16x8*)(lds + PG8_SA(b, h) + aoff + m * 2048 + k * 1024); } while (0)
; #define PG8_LDB(dst, b, h) do { _Pragma("unroll") for (int n = 0; n < 2; ++n) _Pragma("unroll") for (int k = 0; k < 2; ++k) dst[n][k] = *(const LAS bf16x8*)(lds + PG8_SB(b, h) + boff + n * 2048 + k * 1024); } while (0)
; #define PG8_MMA(ai, bj, At, Bt) do { __builtin_amdgcn_s_setprio(1); _Pragma("unroll") for (int m = 0; m < 4; ++m) _Pragma("unroll") for (int n = 0; n < 2; ++n) _Pragma("unroll") for (int k = 0; k < 2; ++k) \
;         acc[ai][bj][m][n] = __builtin_amdgcn_mfma_f32_16x16x32_bf16(Bt[n][k], At[m][k], acc[ai][bj][m][n], 0, 0, 0); __builtin_amdgcn_s_setprio(0); } while (0)
; #define PG8_WAIT_V(n) asm volatile("s_waitcnt vmcnt(" #n ")" ::: "memory")
; #define PG8_WAIT_L(n) asm volatile("s_waitcnt lgkmcnt(" #n ")" ::: "memory")
; #define PG8_BAR __builtin_amdgcn_s_barrier()
; #define PG8_SCHED __builtin_amdgcn_sched_barrier(0)
; template <class Epi, class Sched>
; DI void gemm_phase(LAS unsigned char* lds, const Gemm g, const Sched& S, const Epi& E) {
;     ...
;             PG8_LDB(B0, 1, 0); PG8_LDB(B1, 1, 1); PG8_SCHED; PG8_LDA(At, 1, 0); PG8_STAGE(PG8_SA(0, 1), a2 + hstepA, voffA);
;             PG8_WAIT_V(8); PG8_WAIT_L(0); PG8_BAR; PG8_MMA(0, 0, At, B0); PG8_MMA(0, 1, At, B1); PG8_BAR; PG8_SCHED;
	s_add_i32 s63, 0, 0x18000
	s_add_i32 s64, 0, 0x1c000
	v_add_u32_e32 v166, s63, v152
	v_add_u32_e32 v185, s64, v152
	ds_read_b128 v[148:151], v166
	ds_read_b128 v[158:161], v166 offset:1024
	ds_read_b128 v[162:165], v166 offset:2048
	ds_read_b128 v[166:169], v166 offset:3072
	ds_read_b128 v[170:173], v185
	ds_read_b128 v[174:177], v185 offset:1024
	ds_read_b128 v[178:181], v185 offset:2048
	ds_read_b128 v[186:189], v185 offset:3072
	s_add_u32 s40, s40, 0xb0000
	s_addc_u32 s41, s41, 0
	s_mov_b32 m0, s47
	v_lshl_add_u64 v[228:229], s[40:41], 0, v[130:131]
	ds_read_b128 v[190:193], v156 offset:32768
	ds_read_b128 v[194:197], v156 offset:33792
	ds_read_b128 v[198:201], v156 offset:34816
	ds_read_b128 v[202:205], v156 offset:35840
	ds_read_b128 v[206:209], v156 offset:36864
	ds_read_b128 v[210:213], v156 offset:37888
	ds_read_b128 v[214:217], v156 offset:38912
	ds_read_b128 v[218:221], v156 offset:39936
	global_load_lds_dwordx4 v[228:229], off
	v_lshl_add_u64 v[228:229], s[40:41], 0, v[134:135]
	s_mov_b32 m0, s48
	s_nop 0
	global_load_lds_dwordx4 v[228:229], off
	s_waitcnt vmcnt(8)
	s_waitcnt lgkmcnt(0)
	s_barrier
	s_setprio 1
	v_mfma_f32_16x16x32_bf16 v[126:129], v[148:151], v[190:193], v[126:129]
	v_mfma_f32_16x16x32_bf16 v[122:125], v[162:165], v[190:193], v[122:125]
	v_mfma_f32_16x16x32_bf16 v[110:113], v[148:151], v[198:201], v[110:113]
	v_mfma_f32_16x16x32_bf16 v[106:109], v[162:165], v[198:201], v[106:109]
	v_mfma_f32_16x16x32_bf16 v[94:97], v[148:151], v[206:209], v[94:97]
	v_mfma_f32_16x16x32_bf16 v[90:93], v[162:165], v[206:209], v[90:93]
	v_mfma_f32_16x16x32_bf16 v[78:81], v[148:151], v[214:217], v[78:81]
	v_mfma_f32_16x16x32_bf16 v[74:77], v[162:165], v[214:217], v[74:77]
	v_mfma_f32_16x16x32_bf16 v[126:129], v[158:161], v[194:197], v[126:129]
	v_mfma_f32_16x16x32_bf16 v[122:125], v[166:169], v[194:197], v[122:125]
	v_mfma_f32_16x16x32_bf16 v[110:113], v[158:161], v[202:205], v[110:113]
	v_mfma_f32_16x16x32_bf16 v[106:109], v[166:169], v[202:205], v[106:109]
	v_mfma_f32_16x16x32_bf16 v[94:97], v[158:161], v[210:213], v[94:97]
	v_mfma_f32_16x16x32_bf16 v[90:93], v[166:169], v[210:213], v[90:93]
	v_mfma_f32_16x16x32_bf16 v[78:81], v[158:161], v[218:221], v[78:81]
	v_mfma_f32_16x16x32_bf16 v[74:77], v[166:169], v[218:221], v[74:77]
	v_mfma_f32_16x16x32_bf16 v[118:121], v[170:173], v[190:193], v[118:121]
	v_mfma_f32_16x16x32_bf16 v[114:117], v[178:181], v[190:193], v[114:117]
	v_mfma_f32_16x16x32_bf16 v[102:105], v[170:173], v[198:201], v[102:105]
	v_mfma_f32_16x16x32_bf16 v[98:101], v[178:181], v[198:201], v[98:101]
	v_mfma_f32_16x16x32_bf16 v[86:89], v[170:173], v[206:209], v[86:89]
	v_mfma_f32_16x16x32_bf16 v[82:85], v[178:181], v[206:209], v[82:85]
	v_mfma_f32_16x16x32_bf16 v[70:73], v[170:173], v[214:217], v[70:73]
	v_mfma_f32_16x16x32_bf16 v[66:69], v[178:181], v[214:217], v[66:69]
	v_mfma_f32_16x16x32_bf16 v[118:121], v[174:177], v[194:197], v[118:121]
	v_mfma_f32_16x16x32_bf16 v[114:117], v[186:189], v[194:197], v[114:117]
	v_mfma_f32_16x16x32_bf16 v[102:105], v[174:177], v[202:205], v[102:105]
	v_mfma_f32_16x16x32_bf16 v[98:101], v[186:189], v[202:205], v[98:101]
	v_mfma_f32_16x16x32_bf16 v[86:89], v[174:177], v[210:213], v[86:89]
	v_mfma_f32_16x16x32_bf16 v[82:85], v[186:189], v[210:213], v[82:85]
	v_mfma_f32_16x16x32_bf16 v[70:73], v[174:177], v[218:221], v[70:73]
	v_mfma_f32_16x16x32_bf16 v[66:69], v[186:189], v[218:221], v[66:69]
	s_setprio 0
	s_barrier
; #define PG8_STAGE(bufoff, gbase, voff) do { _Pragma("unroll") for (int _i = 0; _i < 2; ++_i) \
;         __builtin_amdgcn_global_load_lds((const unsigned*)((const char*)(gbase) + (voff)[_i]), (LAS unsigned*)(lds + (bufoff) + ldsw + _i * 8192), 16, 0, 0); } while (0)
; #define PG8_LDA(dst, b, h) do { _Pragma("unroll") for (int m = 0; m < 4; ++m) _Pragma("unroll") for (int k = 0; k < 2; ++k) dst[m][k] = *(const LAS bf16x8*)(lds + PG8_SA(b, h) + aoff + m * 2048 + k * 1024); } while (0)
; #define PG8_MMA(ai, bj, At, Bt) do { __builtin_amdgcn_s_setprio(1); _Pragma("unroll") for (int m = 0; m < 4; ++m) _Pragma("unroll") for (int n = 0; n < 2; ++n) _Pragma("unroll") for (int k = 0; k < 2; ++k) \
;         acc[ai][bj][m][n] = __builtin_amdgcn_mfma_f32_16x16x32_bf16(Bt[n][k], At[m][k], acc[ai][bj][m][n], 0, 0, 0); __builtin_amdgcn_s_setprio(0); } while (0)
; #define PG8_WAIT_V(n) asm volatile("s_waitcnt vmcnt(" #n ")" ::: "memory")
; #define PG8_WAIT_L(n) asm volatile("s_waitcnt lgkmcnt(" #n ")" ::: "memory")
; #define PG8_BAR __builtin_amdgcn_s_barrier()
; #define PG8_SCHED __builtin_amdgcn_sched_barrier(0)
; template <class Epi, class Sched>
; DI void gemm_phase(LAS unsigned char* lds, const Gemm g, const Sched& S, const Epi& E) {
;     ...
;             PG8_LDA(At, 1, 1); PG8_STAGE(PG8_SB(1, 0), b3, voffB); PG8_STAGE(PG8_SB(1, 1), b3 + hstepB, voffB); PG8_STAGE(PG8_SA(1, 0), a3, voffA);
;             PG8_WAIT_V(8); PG8_WAIT_L(0); PG8_BAR; PG8_MMA(1, 0, At, B0); PG8_MMA(1, 1, At, B1); PG8_BAR; PG8_SCHED;
;         }
;         if (wr == 0) PG8_BAR;
	s_add_i32 s40, s63, s44
	v_lshl_add_u64 v[182:183], v[182:183], 0, s[16:17]
	s_mov_b32 m0, s40
	ds_read_b128 v[190:193], v156 offset:49152
	ds_read_b128 v[194:197], v156 offset:50176
	ds_read_b128 v[198:201], v156 offset:51200
	ds_read_b128 v[202:205], v156 offset:52224
	ds_read_b128 v[206:209], v156 offset:53248
	ds_read_b128 v[210:213], v156 offset:54272
	ds_read_b128 v[214:217], v156 offset:55296
	ds_read_b128 v[218:221], v156 offset:56320
	global_load_lds_dwordx4 v[182:183], off
	s_add_i32 m0, s40, 0x2000
	s_add_u32 s38, s38, 0xb0080
	v_lshl_add_u64 v[182:183], v[222:223], 0, s[16:17]
	s_addc_u32 s39, s39, 0
	s_add_i32 s40, s64, s44
	global_load_lds_dwordx4 v[182:183], off
	v_lshl_add_u64 v[182:183], s[38:39], 0, v[132:133]
	s_mov_b32 m0, s40
	s_nop 0
	global_load_lds_dwordx4 v[182:183], off
	v_lshl_add_u64 v[182:183], s[38:39], 0, v[136:137]
	s_add_i32 m0, s40, 0x2000
	s_nop 0
	global_load_lds_dwordx4 v[182:183], off
	v_lshl_add_u64 v[182:183], v[224:225], 0, s[16:17]
	s_mov_b32 m0, s50
	s_nop 0
	global_load_lds_dwordx4 v[182:183], off
	v_lshl_add_u64 v[182:183], v[226:227], 0, s[16:17]
	s_mov_b32 m0, s51
	s_nop 0
	global_load_lds_dwordx4 v[182:183], off
	s_waitcnt vmcnt(8)
	s_waitcnt lgkmcnt(0)
	s_barrier
	s_setprio 1
	v_mfma_f32_16x16x32_bf16 v[62:65], v[148:151], v[190:193], v[62:65]
	v_mfma_f32_16x16x32_bf16 v[58:61], v[162:165], v[190:193], v[58:61]
	v_mfma_f32_16x16x32_bf16 v[46:49], v[148:151], v[198:201], v[46:49]
	v_mfma_f32_16x16x32_bf16 v[42:45], v[162:165], v[198:201], v[42:45]
	v_mfma_f32_16x16x32_bf16 v[30:33], v[148:151], v[206:209], v[30:33]
	v_mfma_f32_16x16x32_bf16 v[26:29], v[162:165], v[206:209], v[26:29]
	v_mfma_f32_16x16x32_bf16 v[14:17], v[148:151], v[214:217], v[14:17]
	v_mfma_f32_16x16x32_bf16 v[10:13], v[162:165], v[214:217], v[10:13]
	v_mfma_f32_16x16x32_bf16 v[62:65], v[158:161], v[194:197], v[62:65]
	v_mfma_f32_16x16x32_bf16 v[58:61], v[166:169], v[194:197], v[58:61]
	v_mfma_f32_16x16x32_bf16 v[46:49], v[158:161], v[202:205], v[46:49]
	v_mfma_f32_16x16x32_bf16 v[42:45], v[166:169], v[202:205], v[42:45]
	v_mfma_f32_16x16x32_bf16 v[30:33], v[158:161], v[210:213], v[30:33]
	v_mfma_f32_16x16x32_bf16 v[26:29], v[166:169], v[210:213], v[26:29]
	v_mfma_f32_16x16x32_bf16 v[14:17], v[158:161], v[218:221], v[14:17]
	v_mfma_f32_16x16x32_bf16 v[10:13], v[166:169], v[218:221], v[10:13]
	v_mfma_f32_16x16x32_bf16 v[54:57], v[170:173], v[190:193], v[54:57]
	v_mfma_f32_16x16x32_bf16 v[50:53], v[178:181], v[190:193], v[50:53]
	v_mfma_f32_16x16x32_bf16 v[38:41], v[170:173], v[198:201], v[38:41]
	v_mfma_f32_16x16x32_bf16 v[34:37], v[178:181], v[198:201], v[34:37]
	v_mfma_f32_16x16x32_bf16 v[22:25], v[170:173], v[206:209], v[22:25]
	v_mfma_f32_16x16x32_bf16 v[18:21], v[178:181], v[206:209], v[18:21]
	v_mfma_f32_16x16x32_bf16 v[6:9], v[170:173], v[214:217], v[6:9]
	v_mfma_f32_16x16x32_bf16 v[2:5], v[178:181], v[214:217], v[2:5]
	v_mfma_f32_16x16x32_bf16 v[54:57], v[174:177], v[194:197], v[54:57]
	v_mfma_f32_16x16x32_bf16 v[50:53], v[186:189], v[194:197], v[50:53]
	v_mfma_f32_16x16x32_bf16 v[38:41], v[174:177], v[202:205], v[38:41]
	v_mfma_f32_16x16x32_bf16 v[34:37], v[186:189], v[202:205], v[34:37]
	v_mfma_f32_16x16x32_bf16 v[22:25], v[174:177], v[210:213], v[22:25]
	v_mfma_f32_16x16x32_bf16 v[18:21], v[186:189], v[210:213], v[18:21]
	v_mfma_f32_16x16x32_bf16 v[6:9], v[174:177], v[218:221], v[6:9]
	v_mfma_f32_16x16x32_bf16 v[2:5], v[186:189], v[218:221], v[2:5]
	s_setprio 0
	s_barrier
	s_add_i32 s62, s62, 2
	s_add_u32 s36, s36, 0x100
	s_addc_u32 s37, s37, 0
	s_add_u32 s60, s60, 0x100
	s_addc_u32 s61, s61, 0
	s_cmp_gt_u32 s62, 41
	s_cbranch_scc0 .LBB0_278
	s_waitcnt vmcnt(0)
	s_mov_b32 s99, 1
	s_and_b64 vcc, exec, s[18:19]
	s_cbranch_vccz .LBB0_281
	s_barrier

; #define PG8_STAGE(bufoff, gbase, voff) do { _Pragma("unroll") for (int _i = 0; _i < 2; ++_i) \
;         __builtin_amdgcn_global_load_lds((const unsigned*)((const char*)(gbase) + (voff)[_i]), (LAS unsigned*)(lds + (bufoff) + ldsw + _i * 8192), 16, 0, 0); } while (0)
; #define PG8_WAIT_V(n) asm volatile("s_waitcnt vmcnt(" #n ")" ::: "memory")
; #define PG8_BAR __builtin_amdgcn_s_barrier()
; template <class Epi, class Sched>
; DI void gemm_phase(LAS unsigned char* lds, const Gemm g, const Sched& S, const Epi& E) {
;     ...
;     const char* cA = (const char*)(cur.src ? g.A1 : g.A0) + (size_t)cur.pm * tstepA; const char* cB = (const char*)(cur.src ? g.B1 : g.B0) + (size_t)cur.pn * tstepB;
;     PG8_STAGE(PG8_SB(0, 0), cB, voffB); PG8_STAGE(PG8_SB(0, 1), cB + hstepB, voffB); PG8_STAGE(PG8_SA(0, 0), cA, voffA); PG8_STAGE(PG8_SA(0, 1), cA + hstepA, voffA);
;     if (wr == 1) PG8_BAR;
;     PG8_WAIT_V(2); PG8_BAR;
;     PG8_STAGE(PG8_SB(1, 0), cB + kstep, voffB); PG8_STAGE(PG8_SA(1, 0), cA + kstep, voffA); PG8_STAGE(PG8_SB(1, 1), cB + hstepB + kstep, voffB);
;     PG8_WAIT_V(6); PG8_BAR;
;     for (;;) {
.LBB0_375:
	s_add_u32 s40, s24, 0x100000
	s_addc_u32 s41, s25, 0
	s_add_u32 s42, s24, 0xc000000
	s_addc_u32 s43, s25, 0
	s_add_u32 s83, s24, 0x10000000
	s_addc_u32 s84, s25, 0
	s_add_u32 s44, s24, 0x16200000
	s_addc_u32 s45, s25, 0
	s_add_u32 s46, s24, 0x1a200000
	s_addc_u32 s47, s25, 0
	s_add_u32 s48, s24, 0x1e200000
	s_mov_b64 s[50:51], 0x80
	s_addc_u32 s49, s25, 0
	s_and_b32 s8, s4, 3
	s_add_i32 m0, s79, 0x18000
	v_lshl_add_u64 v[8:9], v[8:9], 0, s[50:51]
	s_lshl_b32 s85, s5, 6
	s_lshl_b32 s7, s5, 13
	s_lshl_b32 s9, s8, 12
	s_waitcnt vmcnt(2)
	s_barrier
	global_load_lds_dwordx4 v[8:9], off
	v_lshl_add_u64 v[6:7], v[6:7], 0, s[50:51]
	s_add_i32 m0, s79, 0x1a000
	s_add_i32 s86, s79, 0x8000
	s_add_i32 s87, s79, 0xa000
	global_load_lds_dwordx4 v[6:7], off
	v_lshl_add_u64 v[2:3], v[2:3], 0, s[50:51]
	s_mov_b32 m0, s86
	s_add_u32 s4, s64, 0x40080
	global_load_lds_dwordx4 v[2:3], off
	v_lshl_add_u64 v[2:3], v[4:5], 0, s[50:51]
	s_mov_b32 m0, s87
	s_addc_u32 s5, s65, 0
	global_load_lds_dwordx4 v[2:3], off
	s_add_i32 m0, s79, 0x1c000
	v_lshl_add_u64 v[2:3], s[4:5], 0, v[150:151]
	global_load_lds_dwordx4 v[2:3], off
	v_lshl_add_u64 v[2:3], s[4:5], 0, v[154:155]
	s_add_i32 m0, s79, 0x1e000
	s_or_b32 s88, s8, -8
	global_load_lds_dwordx4 v[2:3], off
	v_bfe_u32 v2, v184, 4, 2
	v_and_b32_e32 v147, 15, v184
	v_lshlrev_b32_e32 v3, 4, v2
	v_lshlrev_b32_e32 v5, 2, v184
	v_lshlrev_b32_e32 v6, 6, v184
	s_movk_i32 s4, 0x3c0
	s_cmpk_lt_u32 s6, 0x100
	v_lshlrev_b32_e32 v158, 3, v2
	v_lshl_or_b32 v4, v147, 6, v3
	v_and_b32_e32 v5, 32, v5
	v_and_or_b32 v3, v6, s4, v3
	s_cselect_b64 s[52:53], -1, 0
	s_cmp_eq_u32 s8, 0
	v_bitop3_b32 v159, s9, v3, v5 bitop3:0xf6
	v_lshl_or_b32 v3, s8, 5, v158
	s_cselect_b64 s[4:5], -1, 0
	v_cmp_ne_u32_e32 vcc, 3, v2
	v_lshlrev_b32_e32 v156, 5, v2
	v_bitop3_b32 v4, v4, s7, v5 bitop3:0xde
	v_or_b32_e32 v182, 0xfffffa80, v3
	v_or_b32_e32 v183, 0xfffff700, v3
	v_or_b32_e32 v185, 0xfffffd80, v3
	s_and_b64 s[54:55], vcc, s[4:5]
	s_bfe_u32 s89, s6, 0x10006
	v_cmp_gt_u32_e64 s[4:5], 2, v2
	v_cmp_eq_u32_e64 s[6:7], 0, v2
	s_lshl_b32 s90, s8, 6
	v_lshl_add_u64 v[2:3], s[24:25], 0, v[156:157]
	s_mov_b64 s[8:9], 0x2e200000
	v_lshl_add_u64 v[160:161], v[2:3], 0, s[8:9]
	v_lshlrev_b32_e32 v2, 8, v184
	v_and_b32_e32 v2, 0x38000, v2
	v_lshlrev_b32_e32 v3, 11, v12
	v_or3_b32 v2, v10, v2, v3
	v_add_u32_e32 v162, v2, v11
	v_lshlrev_b32_e32 v2, 4, v13
	v_and_b32_e32 v2, 0x78000, v2
	s_waitcnt vmcnt(6)
	v_or3_b32 v2, v10, v2, v3
	v_add_u32_e32 v164, v2, v11
	s_add_i32 s94, 0, 0x10000
	s_add_i32 s95, 0, 0x14000
	v_mbcnt_lo_u32_b32 v2, -1, 0
	s_ashr_i32 s91, s3, 31
	s_ashr_i32 s92, s2, 31
	v_mov_b32_e32 v163, v157
	v_mov_b32_e32 v165, v157
	v_mov_b64_e32 v[166:167], 0x1400
	v_mov_b64_e32 v[168:169], 0x13ff
	s_movk_i32 s93, 0x281
	v_add_u32_e32 v186, 0, v4
	v_mov_b32_e32 v187, 0x358637bd
	s_movk_i32 s96, 0x200
	v_add_u32_e32 v188, s94, v159
	v_add_u32_e32 v189, s95, v159
	v_mbcnt_hi_u32_b32 v190, -1, v2
	s_mov_b32 s97, 0
	s_barrier
	s_mov_b32 s99, 0
	s_branch .LBB0_378

;     DI bool next(int i, Unit& u) const { if (i > 0 || c >= 64) return false; u.pm = c & 31; u.pn = 0; u.src = c >> 5; return true; }
; #define PG8_STAGE(bufoff, gbase, voff) do { _Pragma("unroll") for (int _i = 0; _i < 2; ++_i) \
;         __builtin_amdgcn_global_load_lds((const unsigned*)((const char*)(gbase) + (voff)[_i]), (LAS unsigned*)(lds + (bufoff) + ldsw + _i * 8192), 16, 0, 0); } while (0)
; #define PG8_LDA(dst, b, h) do { _Pragma("unroll") for (int m = 0; m < 4; ++m) _Pragma("unroll") for (int k = 0; k < 2; ++k) dst[m][k] = *(const LAS bf16x8*)(lds + PG8_SA(b, h) + aoff + m * 2048 + k * 1024); } while (0)
; #define PG8_LDB(dst, b, h) do { _Pragma("unroll") for (int n = 0; n < 2; ++n) _Pragma("unroll") for (int k = 0; k < 2; ++k) dst[n][k] = *(const LAS bf16x8*)(lds + PG8_SB(b, h) + boff + n * 2048 + k * 1024); } while (0)
; #define PG8_WAIT_V(n) asm volatile("s_waitcnt vmcnt(" #n ")" ::: "memory")
; template <class Epi, class Sched>
; DI void gemm_phase(LAS unsigned char* lds, const Gemm g, const Sched& S, const Epi& E) {
;     ...
;         const bool has_next = S.next(ui + 1, nxt);
;         E.pre(pre, cur, wr, fr);
;         const char* nA = has_next ? (const char*)(nxt.src ? g.A1 : g.A0) + (size_t)nxt.pm * tstepA : cA; const char* nB = has_next ? (const char*)(nxt.src ? g.B1 : g.B0) + (size_t)nxt.pn * tstepB : cB;
;         for (int t = 0; t < nt; t += 2) {
;             const bool last = (t == nt - 2);
;             const char* a1 = cA + (size_t)(t + 1) * kstep;
;             const char* a2 = last ? nA : cA + (size_t)(t + 2) * kstep; const char* b2 = last ? nB : cB + (size_t)(t + 2) * kstep;
;             const char* a3 = a2 + kstep; const char* b3 = b2 + kstep;
;             PG8_LDB(B0, 0, 0); PG8_LDB(B1, 0, 1); PG8_SCHED; PG8_LDA(At, 0, 0); PG8_STAGE(PG8_SA(1, 1), a1 + hstepA, voffA);
;             PG8_WAIT_V(8); PG8_WAIT_L(0); PG8_BAR; PG8_MMA(0, 0, At, B0); PG8_MMA(0, 1, At, B1); PG8_BAR; PG8_SCHED;
;             PG8_LDA(At, 0, 1); PG8_STAGE(PG8_SB(0, 0), b2, voffB); PG8_STAGE(PG8_SB(0, 1), b2 + hstepB, voffB); PG8_STAGE(PG8_SA(0, 0), a2, voffA);
; DI void load_rows(PreRows& pr, const float* ssq, const pg8::Unit& u, int wr, int fr) {
; #pragma unroll
;     for (int ai = 0; ai < 2; ++ai)
; #pragma unroll
;         for (int m = 0; m < 4; ++m) pr.v[ai * 4 + m] = ssq[u.pm * 256 + ai * 128 + wr * 64 + m * 16 + fr];
; }
.LBB0_380:
	s_lshl_b32 s28, s10, 8
	s_add_i32 s28, s28, s85
	v_or_b32_e32 v170, s28, v147
	v_ashrrev_i32_e32 v171, 31, v170
	v_add_u32_e32 v136, 0x80, v170
	v_add_u32_e32 v134, 0x90, v170
	v_add_u32_e32 v132, 0xa0, v170
	v_add_u32_e32 v130, 0xb0, v170
	v_lshl_add_u64 v[2:3], v[170:171], 2, s[20:21]
	v_ashrrev_i32_e32 v137, 31, v136
	v_ashrrev_i32_e32 v135, 31, v134
	v_ashrrev_i32_e32 v133, 31, v132
	v_ashrrev_i32_e32 v131, 31, v130
	v_lshl_add_u64 v[4:5], v[136:137], 2, s[20:21]
	v_lshl_add_u64 v[6:7], v[134:135], 2, s[20:21]
	v_lshl_add_u64 v[8:9], v[132:133], 2, s[20:21]
	v_lshl_add_u64 v[10:11], v[130:131], 2, s[20:21]
	global_load_dword v174, v[2:3], off
	global_load_dword v197, v[2:3], off offset:64
	global_load_dword v196, v[2:3], off offset:128
	global_load_dword v195, v[2:3], off offset:192
	global_load_dword v194, v[4:5], off
	global_load_dword v193, v[6:7], off
	global_load_dword v192, v[8:9], off
	global_load_dword v191, v[10:11], off
	s_ashr_i32 s59, s58, 31
	s_lshl_b64 s[10:11], s[58:59], 19
	s_add_u32 s60, s30, s10
	s_addc_u32 s61, s31, s11
	s_and_b64 s[10:11], s[8:9], exec
	s_cselect_b32 s13, s61, s67
	s_cselect_b32 s29, s60, s66
	s_ashr_i32 s57, s56, 31
	s_lshl_b64 s[10:11], s[56:57], 19
	s_add_u32 s62, s75, s10
	s_addc_u32 s63, s76, s11
	s_and_b64 s[10:11], s[8:9], exec
	s_cselect_b32 s36, s63, s65
	s_cselect_b32 s57, s62, s64
	s_add_u32 s10, s66, 0x40080
	s_addc_u32 s11, s67, 0
	s_add_u32 s59, s64, 0x100
	s_addc_u32 s68, s65, 0
	s_mov_b32 s69, -2
	s_waitcnt lgkmcnt(0)
	ds_read_b128 v[138:141], v188
	ds_read_b128 v[142:145], v188 offset:1024
	ds_read_b128 v[176:179], v188 offset:2048
	ds_read_b128 v[198:201], v188 offset:3072
	ds_read_b128 v[202:205], v189
	ds_read_b128 v[206:209], v189 offset:1024
	ds_read_b128 v[210:213], v189 offset:2048
	ds_read_b128 v[214:217], v189 offset:3072
	s_add_u32 s64, s10, 0xfffc0080
	s_addc_u32 s65, s11, -1
	s_cmp_eq_u32 s69, 12
	s_cselect_b32 s67, s13, s65
	s_cselect_b32 s66, s29, s64
	s_cselect_b32 s65, s36, s68
	s_cselect_b32 s64, s57, s59
	v_lshl_add_u64 v[172:173], s[10:11], 0, v[162:163]
	s_add_i32 m0, s79, 0xc000
	ds_read_b128 v[218:221], v186
	ds_read_b128 v[222:225], v186 offset:1024
	ds_read_b128 v[226:229], v186 offset:2048
	ds_read_b128 v[230:233], v186 offset:3072
	ds_read_b128 v[234:237], v186 offset:4096
	ds_read_b128 v[238:241], v186 offset:5120
	ds_read_b128 v[242:245], v186 offset:6144
	ds_read_b128 v[246:249], v186 offset:7168
	global_load_lds_dwordx4 v[172:173], off
	v_lshl_add_u64 v[172:173], s[10:11], 0, v[164:165]
	s_add_i32 m0, s79, 0xe000
	s_nop 0
	global_load_lds_dwordx4 v[172:173], off
	s_cmp_lg_u32 s99, 0
	s_cbranch_scc1 .Lpk2_w1
	s_waitcnt vmcnt(8)
.Lpk2_w1:
	s_waitcnt lgkmcnt(0)
	s_barrier
	s_setprio 1
	v_mfma_f32_16x16x32_bf16 v[126:129], v[138:141], v[218:221], 0
	v_mfma_f32_16x16x32_bf16 v[122:125], v[176:179], v[218:221], 0
	v_mfma_f32_16x16x32_bf16 v[110:113], v[138:141], v[226:229], 0
	v_mfma_f32_16x16x32_bf16 v[106:109], v[176:179], v[226:229], 0
	v_mfma_f32_16x16x32_bf16 v[94:97], v[138:141], v[234:237], 0
	v_mfma_f32_16x16x32_bf16 v[90:93], v[176:179], v[234:237], 0
	v_mfma_f32_16x16x32_bf16 v[78:81], v[138:141], v[242:245], 0
	v_mfma_f32_16x16x32_bf16 v[74:77], v[176:179], v[242:245], 0
	v_mfma_f32_16x16x32_bf16 v[126:129], v[142:145], v[222:225], v[126:129]
	v_mfma_f32_16x16x32_bf16 v[122:125], v[198:201], v[222:225], v[122:125]
	v_mfma_f32_16x16x32_bf16 v[110:113], v[142:145], v[230:233], v[110:113]
	v_mfma_f32_16x16x32_bf16 v[106:109], v[198:201], v[230:233], v[106:109]
	v_mfma_f32_16x16x32_bf16 v[94:97], v[142:145], v[238:241], v[94:97]
	v_mfma_f32_16x16x32_bf16 v[90:93], v[198:201], v[238:241], v[90:93]
	v_mfma_f32_16x16x32_bf16 v[78:81], v[142:145], v[246:249], v[78:81]
	v_mfma_f32_16x16x32_bf16 v[74:77], v[198:201], v[246:249], v[74:77]
	v_mfma_f32_16x16x32_bf16 v[118:121], v[202:205], v[218:221], 0
	v_mfma_f32_16x16x32_bf16 v[114:117], v[210:213], v[218:221], 0
	v_mfma_f32_16x16x32_bf16 v[102:105], v[202:205], v[226:229], 0
	v_mfma_f32_16x16x32_bf16 v[98:101], v[210:213], v[226:229], 0
	v_mfma_f32_16x16x32_bf16 v[86:89], v[202:205], v[234:237], 0
	v_mfma_f32_16x16x32_bf16 v[82:85], v[210:213], v[234:237], 0
	v_mfma_f32_16x16x32_bf16 v[70:73], v[202:205], v[242:245], 0
	v_mfma_f32_16x16x32_bf16 v[66:69], v[210:213], v[242:245], 0
	v_mfma_f32_16x16x32_bf16 v[118:121], v[206:209], v[222:225], v[118:121]
	v_mfma_f32_16x16x32_bf16 v[114:117], v[214:217], v[222:225], v[114:117]
	v_mfma_f32_16x16x32_bf16 v[102:105], v[206:209], v[230:233], v[102:105]
	v_mfma_f32_16x16x32_bf16 v[98:101], v[214:217], v[230:233], v[98:101]
	v_mfma_f32_16x16x32_bf16 v[86:89], v[206:209], v[238:241], v[86:89]
	v_mfma_f32_16x16x32_bf16 v[82:85], v[214:217], v[238:241], v[82:85]
	v_mfma_f32_16x16x32_bf16 v[70:73], v[206:209], v[246:249], v[70:73]
	v_mfma_f32_16x16x32_bf16 v[66:69], v[214:217], v[246:249], v[66:69]
	s_setprio 0
	s_barrier
	s_add_i32 s70, s94, s78
	v_lshl_add_u64 v[172:173], s[64:65], 0, v[150:151]
	s_mov_b32 m0, s70
	ds_read_b128 v[218:221], v186 offset:16384
	ds_read_b128 v[222:225], v186 offset:17408
	ds_read_b128 v[226:229], v186 offset:18432
	ds_read_b128 v[230:233], v186 offset:19456
	ds_read_b128 v[234:237], v186 offset:20480
	ds_read_b128 v[238:241], v186 offset:21504
	ds_read_b128 v[242:245], v186 offset:22528
	ds_read_b128 v[246:249], v186 offset:23552
	global_load_lds_dwordx4 v[172:173], off
	s_add_i32 m0, s70, 0x2000
	s_add_u32 s70, s64, 0x40000
	v_lshl_add_u64 v[180:181], s[64:65], 0, v[154:155]
	s_addc_u32 s71, s65, 0
	s_add_i32 s72, s95, s78
	global_load_lds_dwordx4 v[180:181], off
	v_lshl_add_u64 v[250:251], s[70:71], 0, v[150:151]
	s_mov_b32 m0, s72
	v_lshl_add_u64 v[252:253], s[66:67], 0, v[152:153]
	global_load_lds_dwordx4 v[250:251], off
	v_lshl_add_u64 v[250:251], s[70:71], 0, v[154:155]
	s_add_i32 m0, s72, 0x2000
	s_nop 0
	global_load_lds_dwordx4 v[250:251], off
	v_lshl_add_u64 v[250:251], s[66:67], 0, v[148:149]
	s_mov_b32 m0, s79
	s_nop 0
	global_load_lds_dwordx4 v[250:251], off
	s_mov_b32 m0, s80
	s_nop 0
	global_load_lds_dwordx4 v[252:253], off
	s_cmp_lg_u32 s99, 0
	s_cbranch_scc1 .Lpk2_w2
	s_waitcnt vmcnt(8)
; #define PG8_STAGE(bufoff, gbase, voff) do { _Pragma("unroll") for (int _i = 0; _i < 2; ++_i) \
;         __builtin_amdgcn_global_load_lds((const unsigned*)((const char*)(gbase) + (voff)[_i]), (LAS unsigned*)(lds + (bufoff) + ldsw + _i * 8192), 16, 0, 0); } while (0)
; #define PG8_LDA(dst, b, h) do { _Pragma("unroll") for (int m = 0; m < 4; ++m) _Pragma("unroll") for (int k = 0; k < 2; ++k) dst[m][k] = *(const LAS bf16x8*)(lds + PG8_SA(b, h) + aoff + m * 2048 + k * 1024); } while (0)
; #define PG8_LDB(dst, b, h) do { _Pragma("unroll") for (int n = 0; n < 2; ++n) _Pragma("unroll") for (int k = 0; k < 2; ++k) dst[n][k] = *(const LAS bf16x8*)(lds + PG8_SB(b, h) + boff + n * 2048 + k * 1024); } while (0)
; #define PG8_MMA(ai, bj, At, Bt) do { __builtin_amdgcn_s_setprio(1); _Pragma("unroll") for (int m = 0; m < 4; ++m) _Pragma("unroll") for (int n = 0; n < 2; ++n) _Pragma("unroll") for (int k = 0; k < 2; ++k) \
;         acc[ai][bj][m][n] = __builtin_amdgcn_mfma_f32_16x16x32_bf16(Bt[n][k], At[m][k], acc[ai][bj][m][n], 0, 0, 0); __builtin_amdgcn_s_setprio(0); } while (0)
; #define PG8_WAIT_V(n) asm volatile("s_waitcnt vmcnt(" #n ")" ::: "memory")
; #define PG8_WAIT_L(n) asm volatile("s_waitcnt lgkmcnt(" #n ")" ::: "memory")
; #define PG8_BAR __builtin_amdgcn_s_barrier()
; #define PG8_SCHED __builtin_amdgcn_sched_barrier(0)
; template <class Epi, class Sched>
; DI void gemm_phase(LAS unsigned char* lds, const Gemm g, const Sched& S, const Epi& E) {
;     ...
;             PG8_WAIT_V(8); PG8_WAIT_L(0); PG8_BAR; PG8_MMA(1, 0, At, B0); PG8_MMA(1, 1, At, B1); PG8_BAR; PG8_SCHED;
;             PG8_LDB(B0, 1, 0); PG8_LDB(B1, 1, 1); PG8_SCHED; PG8_LDA(At, 1, 0); PG8_STAGE(PG8_SA(0, 1), a2 + hstepA, voffA);
;             PG8_WAIT_V(8); PG8_WAIT_L(0); PG8_BAR; PG8_MMA(0, 0, At, B0); PG8_MMA(0, 1, At, B1); PG8_BAR; PG8_SCHED;
.Lpk2_w2:
	s_mov_b32 s99, 0
	s_waitcnt lgkmcnt(0)
	s_barrier
	s_setprio 1
	v_mfma_f32_16x16x32_bf16 v[62:65], v[138:141], v[218:221], 0
	v_mfma_f32_16x16x32_bf16 v[58:61], v[176:179], v[218:221], 0
	v_mfma_f32_16x16x32_bf16 v[46:49], v[138:141], v[226:229], 0
	v_mfma_f32_16x16x32_bf16 v[42:45], v[176:179], v[226:229], 0
	v_mfma_f32_16x16x32_bf16 v[30:33], v[138:141], v[234:237], 0
	v_mfma_f32_16x16x32_bf16 v[26:29], v[176:179], v[234:237], 0
	v_mfma_f32_16x16x32_bf16 v[14:17], v[138:141], v[242:245], 0
	v_mfma_f32_16x16x32_bf16 v[10:13], v[176:179], v[242:245], 0
	v_mfma_f32_16x16x32_bf16 v[62:65], v[142:145], v[222:225], v[62:65]
	v_mfma_f32_16x16x32_bf16 v[58:61], v[198:201], v[222:225], v[58:61]
	v_mfma_f32_16x16x32_bf16 v[46:49], v[142:145], v[230:233], v[46:49]
	v_mfma_f32_16x16x32_bf16 v[42:45], v[198:201], v[230:233], v[42:45]
	v_mfma_f32_16x16x32_bf16 v[30:33], v[142:145], v[238:241], v[30:33]
	v_mfma_f32_16x16x32_bf16 v[26:29], v[198:201], v[238:241], v[26:29]
	v_mfma_f32_16x16x32_bf16 v[14:17], v[142:145], v[246:249], v[14:17]
	v_mfma_f32_16x16x32_bf16 v[10:13], v[198:201], v[246:249], v[10:13]
	v_mfma_f32_16x16x32_bf16 v[54:57], v[202:205], v[218:221], 0
	v_mfma_f32_16x16x32_bf16 v[50:53], v[210:213], v[218:221], 0
	v_mfma_f32_16x16x32_bf16 v[38:41], v[202:205], v[226:229], 0
	v_mfma_f32_16x16x32_bf16 v[34:37], v[210:213], v[226:229], 0
	v_mfma_f32_16x16x32_bf16 v[22:25], v[202:205], v[234:237], 0
	v_mfma_f32_16x16x32_bf16 v[18:21], v[210:213], v[234:237], 0
	v_mfma_f32_16x16x32_bf16 v[6:9], v[202:205], v[242:245], 0
	v_mfma_f32_16x16x32_bf16 v[2:5], v[210:213], v[242:245], 0
	v_mfma_f32_16x16x32_bf16 v[54:57], v[206:209], v[222:225], v[54:57]
	v_mfma_f32_16x16x32_bf16 v[50:53], v[214:217], v[222:225], v[50:53]
	v_mfma_f32_16x16x32_bf16 v[38:41], v[206:209], v[230:233], v[38:41]
	v_mfma_f32_16x16x32_bf16 v[34:37], v[214:217], v[230:233], v[34:37]
	v_mfma_f32_16x16x32_bf16 v[22:25], v[206:209], v[238:241], v[22:25]
	v_mfma_f32_16x16x32_bf16 v[18:21], v[214:217], v[238:241], v[18:21]
	v_mfma_f32_16x16x32_bf16 v[6:9], v[206:209], v[246:249], v[6:9]
	v_mfma_f32_16x16x32_bf16 v[2:5], v[214:217], v[246:249], v[2:5]
	s_setprio 0
	s_barrier
	s_add_i32 s70, 0, 0x18000
	v_add_u32_e32 v156, s70, v159
	s_add_i32 s71, 0, 0x1c000
	ds_read_b128 v[138:141], v156
	ds_read_b128 v[142:145], v156 offset:1024
	ds_read_b128 v[176:179], v156 offset:2048
	ds_read_b128 v[198:201], v156 offset:3072
	v_add_u32_e32 v156, s71, v159
	ds_read_b128 v[202:205], v156
	ds_read_b128 v[206:209], v156 offset:1024
	ds_read_b128 v[210:213], v156 offset:2048
	ds_read_b128 v[214:217], v156 offset:3072
	s_add_u32 s66, s66, 0x40000
	s_addc_u32 s67, s67, 0
	s_mov_b32 m0, s81
	v_lshl_add_u64 v[254:255], s[66:67], 0, v[148:149]
	ds_read_b128 v[218:221], v186 offset:32768
	ds_read_b128 v[222:225], v186 offset:33792
	ds_read_b128 v[226:229], v186 offset:34816
	ds_read_b128 v[230:233], v186 offset:35840
	ds_read_b128 v[234:237], v186 offset:36864
	ds_read_b128 v[238:241], v186 offset:37888
	ds_read_b128 v[242:245], v186 offset:38912
	ds_read_b128 v[246:249], v186 offset:39936
	global_load_lds_dwordx4 v[254:255], off
	v_lshl_add_u64 v[254:255], s[66:67], 0, v[152:153]
	s_mov_b32 m0, s82
	s_nop 0
	global_load_lds_dwordx4 v[254:255], off
	s_waitcnt vmcnt(8)
	s_waitcnt lgkmcnt(0)
	s_barrier
	s_setprio 1
	v_mfma_f32_16x16x32_bf16 v[126:129], v[138:141], v[218:221], v[126:129]
	v_mfma_f32_16x16x32_bf16 v[122:125], v[176:179], v[218:221], v[122:125]
	v_mfma_f32_16x16x32_bf16 v[110:113], v[138:141], v[226:229], v[110:113]
	v_mfma_f32_16x16x32_bf16 v[106:109], v[176:179], v[226:229], v[106:109]
	v_mfma_f32_16x16x32_bf16 v[94:97], v[138:141], v[234:237], v[94:97]
	v_mfma_f32_16x16x32_bf16 v[90:93], v[176:179], v[234:237], v[90:93]
	v_mfma_f32_16x16x32_bf16 v[78:81], v[138:141], v[242:245], v[78:81]
	v_mfma_f32_16x16x32_bf16 v[74:77], v[176:179], v[242:245], v[74:77]
	v_mfma_f32_16x16x32_bf16 v[126:129], v[142:145], v[222:225], v[126:129]
	v_mfma_f32_16x16x32_bf16 v[122:125], v[198:201], v[222:225], v[122:125]
	v_mfma_f32_16x16x32_bf16 v[110:113], v[142:145], v[230:233], v[110:113]
	v_mfma_f32_16x16x32_bf16 v[106:109], v[198:201], v[230:233], v[106:109]
	v_mfma_f32_16x16x32_bf16 v[94:97], v[142:145], v[238:241], v[94:97]
	v_mfma_f32_16x16x32_bf16 v[90:93], v[198:201], v[238:241], v[90:93]
	v_mfma_f32_16x16x32_bf16 v[78:81], v[142:145], v[246:249], v[78:81]
	v_mfma_f32_16x16x32_bf16 v[74:77], v[198:201], v[246:249], v[74:77]
	v_mfma_f32_16x16x32_bf16 v[118:121], v[202:205], v[218:221], v[118:121]
	v_mfma_f32_16x16x32_bf16 v[114:117], v[210:213], v[218:221], v[114:117]
	v_mfma_f32_16x16x32_bf16 v[102:105], v[202:205], v[226:229], v[102:105]
	v_mfma_f32_16x16x32_bf16 v[98:101], v[210:213], v[226:229], v[98:101]
	v_mfma_f32_16x16x32_bf16 v[86:89], v[202:205], v[234:237], v[86:89]
	v_mfma_f32_16x16x32_bf16 v[82:85], v[210:213], v[234:237], v[82:85]
	v_mfma_f32_16x16x32_bf16 v[70:73], v[202:205], v[242:245], v[70:73]
	v_mfma_f32_16x16x32_bf16 v[66:69], v[210:213], v[242:245], v[66:69]
	v_mfma_f32_16x16x32_bf16 v[118:121], v[206:209], v[222:225], v[118:121]
	v_mfma_f32_16x16x32_bf16 v[114:117], v[214:217], v[222:225], v[114:117]
	v_mfma_f32_16x16x32_bf16 v[102:105], v[206:209], v[230:233], v[102:105]
	v_mfma_f32_16x16x32_bf16 v[98:101], v[214:217], v[230:233], v[98:101]
	v_mfma_f32_16x16x32_bf16 v[86:89], v[206:209], v[238:241], v[86:89]
	v_mfma_f32_16x16x32_bf16 v[82:85], v[214:217], v[238:241], v[82:85]
	v_mfma_f32_16x16x32_bf16 v[70:73], v[206:209], v[246:249], v[70:73]
	v_mfma_f32_16x16x32_bf16 v[66:69], v[214:217], v[246:249], v[66:69]
	s_setprio 0
	s_barrier
; #define PG8_STAGE(bufoff, gbase, voff) do { _Pragma("unroll") for (int _i = 0; _i < 2; ++_i) \
;         __builtin_amdgcn_global_load_lds((const unsigned*)((const char*)(gbase) + (voff)[_i]), (LAS unsigned*)(lds + (bufoff) + ldsw + _i * 8192), 16, 0, 0); } while (0)
; #define PG8_LDA(dst, b, h) do { _Pragma("unroll") for (int m = 0; m < 4; ++m) _Pragma("unroll") for (int k = 0; k < 2; ++k) dst[m][k] = *(const LAS bf16x8*)(lds + PG8_SA(b, h) + aoff + m * 2048 + k * 1024); } while (0)
; #define PG8_LDB(dst, b, h) do { _Pragma("unroll") for (int n = 0; n < 2; ++n) _Pragma("unroll") for (int k = 0; k < 2; ++k) dst[n][k] = *(const LAS bf16x8*)(lds + PG8_SB(b, h) + boff + n * 2048 + k * 1024); } while (0)
; #define PG8_MMA(ai, bj, At, Bt) do { __builtin_amdgcn_s_setprio(1); _Pragma("unroll") for (int m = 0; m < 4; ++m) _Pragma("unroll") for (int n = 0; n < 2; ++n) _Pragma("unroll") for (int k = 0; k < 2; ++k) \
;         acc[ai][bj][m][n] = __builtin_amdgcn_mfma_f32_16x16x32_bf16(Bt[n][k], At[m][k], acc[ai][bj][m][n], 0, 0, 0); __builtin_amdgcn_s_setprio(0); } while (0)
; #define PG8_WAIT_V(n) asm volatile("s_waitcnt vmcnt(" #n ")" ::: "memory")
; #define PG8_WAIT_L(n) asm volatile("s_waitcnt lgkmcnt(" #n ")" ::: "memory")
; #define PG8_BAR __builtin_amdgcn_s_barrier()
; #define PG8_SCHED __builtin_amdgcn_sched_barrier(0)
; template <class Epi, class Sched>
; DI void gemm_phase(LAS unsigned char* lds, const Gemm g, const Sched& S, const Epi& E) {
;     ...
;         for (int t = 0; t < nt; t += 2) {
;             const bool last = (t == nt - 2);
;             const char* a1 = cA + (size_t)(t + 1) * kstep;
;             const char* a2 = last ? nA : cA + (size_t)(t + 2) * kstep; const char* b2 = last ? nB : cB + (size_t)(t + 2) * kstep;
;             const char* a3 = a2 + kstep; const char* b3 = b2 + kstep;
;             PG8_LDB(B0, 0, 0); PG8_LDB(B1, 0, 1); PG8_SCHED; PG8_LDA(At, 0, 0); PG8_STAGE(PG8_SA(1, 1), a1 + hstepA, voffA);
;             PG8_WAIT_V(8); PG8_WAIT_L(0); PG8_BAR; PG8_MMA(0, 0, At, B0); PG8_MMA(0, 1, At, B1); PG8_BAR; PG8_SCHED;
;     ...
;             PG8_LDA(At, 1, 1); PG8_STAGE(PG8_SB(1, 0), b3, voffB); PG8_STAGE(PG8_SB(1, 1), b3 + hstepB, voffB); PG8_STAGE(PG8_SA(1, 0), a3, voffA);
;             PG8_WAIT_V(8); PG8_WAIT_L(0); PG8_BAR; PG8_MMA(1, 0, At, B0); PG8_MMA(1, 1, At, B1); PG8_BAR; PG8_SCHED;
	s_add_i32 s66, s70, s78
	v_lshl_add_u64 v[172:173], v[172:173], 0, s[50:51]
	s_mov_b32 m0, s66
	ds_read_b128 v[218:221], v186 offset:49152
	ds_read_b128 v[222:225], v186 offset:50176
	ds_read_b128 v[226:229], v186 offset:51200
	ds_read_b128 v[230:233], v186 offset:52224
	ds_read_b128 v[234:237], v186 offset:53248
	ds_read_b128 v[238:241], v186 offset:54272
	ds_read_b128 v[242:245], v186 offset:55296
	ds_read_b128 v[246:249], v186 offset:56320
	global_load_lds_dwordx4 v[172:173], off
	s_add_i32 m0, s66, 0x2000
	s_add_u32 s64, s64, 0x40080
	v_lshl_add_u64 v[172:173], v[180:181], 0, s[50:51]
	s_addc_u32 s65, s65, 0
	s_add_i32 s66, s71, s78
	global_load_lds_dwordx4 v[172:173], off
	v_lshl_add_u64 v[172:173], s[64:65], 0, v[150:151]
	s_mov_b32 m0, s66
	s_nop 0
	global_load_lds_dwordx4 v[172:173], off
	v_lshl_add_u64 v[172:173], s[64:65], 0, v[154:155]
	s_add_i32 m0, s66, 0x2000
	s_nop 0
	global_load_lds_dwordx4 v[172:173], off
	v_lshl_add_u64 v[172:173], v[250:251], 0, s[50:51]
	s_mov_b32 m0, s86
	s_nop 0
	global_load_lds_dwordx4 v[172:173], off
	v_lshl_add_u64 v[172:173], v[252:253], 0, s[50:51]
	s_mov_b32 m0, s87
	s_nop 0
	global_load_lds_dwordx4 v[172:173], off
	s_waitcnt vmcnt(8)
	s_waitcnt lgkmcnt(0)
	s_barrier
	s_setprio 1
	v_mfma_f32_16x16x32_bf16 v[62:65], v[138:141], v[218:221], v[62:65]
	v_mfma_f32_16x16x32_bf16 v[58:61], v[176:179], v[218:221], v[58:61]
	v_mfma_f32_16x16x32_bf16 v[46:49], v[138:141], v[226:229], v[46:49]
	v_mfma_f32_16x16x32_bf16 v[42:45], v[176:179], v[226:229], v[42:45]
	v_mfma_f32_16x16x32_bf16 v[30:33], v[138:141], v[234:237], v[30:33]
	v_mfma_f32_16x16x32_bf16 v[26:29], v[176:179], v[234:237], v[26:29]
	v_mfma_f32_16x16x32_bf16 v[14:17], v[138:141], v[242:245], v[14:17]
	v_mfma_f32_16x16x32_bf16 v[10:13], v[176:179], v[242:245], v[10:13]
	v_mfma_f32_16x16x32_bf16 v[62:65], v[142:145], v[222:225], v[62:65]
	v_mfma_f32_16x16x32_bf16 v[58:61], v[198:201], v[222:225], v[58:61]
	v_mfma_f32_16x16x32_bf16 v[46:49], v[142:145], v[230:233], v[46:49]
	v_mfma_f32_16x16x32_bf16 v[42:45], v[198:201], v[230:233], v[42:45]
	v_mfma_f32_16x16x32_bf16 v[30:33], v[142:145], v[238:241], v[30:33]
	v_mfma_f32_16x16x32_bf16 v[26:29], v[198:201], v[238:241], v[26:29]
	v_mfma_f32_16x16x32_bf16 v[14:17], v[142:145], v[246:249], v[14:17]
	v_mfma_f32_16x16x32_bf16 v[10:13], v[198:201], v[246:249], v[10:13]
	v_mfma_f32_16x16x32_bf16 v[54:57], v[202:205], v[218:221], v[54:57]
	v_mfma_f32_16x16x32_bf16 v[50:53], v[210:213], v[218:221], v[50:53]
	v_mfma_f32_16x16x32_bf16 v[38:41], v[202:205], v[226:229], v[38:41]
	v_mfma_f32_16x16x32_bf16 v[34:37], v[210:213], v[226:229], v[34:37]
	v_mfma_f32_16x16x32_bf16 v[22:25], v[202:205], v[234:237], v[22:25]
	v_mfma_f32_16x16x32_bf16 v[18:21], v[210:213], v[234:237], v[18:21]
	v_mfma_f32_16x16x32_bf16 v[6:9], v[202:205], v[242:245], v[6:9]
	v_mfma_f32_16x16x32_bf16 v[2:5], v[210:213], v[242:245], v[2:5]
	v_mfma_f32_16x16x32_bf16 v[54:57], v[206:209], v[222:225], v[54:57]
	v_mfma_f32_16x16x32_bf16 v[50:53], v[214:217], v[222:225], v[50:53]
	v_mfma_f32_16x16x32_bf16 v[38:41], v[206:209], v[230:233], v[38:41]
	v_mfma_f32_16x16x32_bf16 v[34:37], v[214:217], v[230:233], v[34:37]
	v_mfma_f32_16x16x32_bf16 v[22:25], v[206:209], v[238:241], v[22:25]
	v_mfma_f32_16x16x32_bf16 v[18:21], v[214:217], v[238:241], v[18:21]
	v_mfma_f32_16x16x32_bf16 v[6:9], v[206:209], v[246:249], v[6:9]
	v_mfma_f32_16x16x32_bf16 v[2:5], v[214:217], v[246:249], v[2:5]
	s_setprio 0
	s_barrier
	s_add_i32 s69, s69, 2
	s_add_u32 s10, s10, 0x100
	s_addc_u32 s11, s11, 0
	s_add_u32 s59, s59, 0x100
	s_addc_u32 s68, s68, 0
	s_cmp_gt_u32 s69, 13
.LBB0_381:
	ds_read_b128 v[138:141], v188
	ds_read_b128 v[142:145], v188 offset:1024
	ds_read_b128 v[176:179], v188 offset:2048
	ds_read_b128 v[198:201], v188 offset:3072
	ds_read_b128 v[202:205], v189
	ds_read_b128 v[206:209], v189 offset:1024
	ds_read_b128 v[210:213], v189 offset:2048
	ds_read_b128 v[214:217], v189 offset:3072
	s_add_u32 s64, s10, 0xfffc0080
	s_addc_u32 s65, s11, -1
	s_cmp_eq_u32 s69, 12
	s_cselect_b32 s67, s13, s65
	s_cselect_b32 s66, s29, s64
	s_cselect_b32 s65, s36, s68
	s_cselect_b32 s64, s57, s59
	v_lshl_add_u64 v[172:173], s[10:11], 0, v[162:163]
	s_add_i32 m0, s79, 0xc000
	ds_read_b128 v[218:221], v186
	ds_read_b128 v[222:225], v186 offset:1024
	ds_read_b128 v[226:229], v186 offset:2048
	ds_read_b128 v[230:233], v186 offset:3072
	ds_read_b128 v[234:237], v186 offset:4096
	ds_read_b128 v[238:241], v186 offset:5120
	ds_read_b128 v[242:245], v186 offset:6144
	ds_read_b128 v[246:249], v186 offset:7168
	global_load_lds_dwordx4 v[172:173], off
	v_lshl_add_u64 v[172:173], s[10:11], 0, v[164:165]
	s_add_i32 m0, s79, 0xe000
	s_nop 0
	global_load_lds_dwordx4 v[172:173], off
	s_waitcnt vmcnt(8)
	s_waitcnt lgkmcnt(0)
	s_barrier
; #define PG8_STAGE(bufoff, gbase, voff) do { _Pragma("unroll") for (int _i = 0; _i < 2; ++_i) \
;         __builtin_amdgcn_global_load_lds((const unsigned*)((const char*)(gbase) + (voff)[_i]), (LAS unsigned*)(lds + (bufoff) + ldsw + _i * 8192), 16, 0, 0); } while (0)
; #define PG8_LDA(dst, b, h) do { _Pragma("unroll") for (int m = 0; m < 4; ++m) _Pragma("unroll") for (int k = 0; k < 2; ++k) dst[m][k] = *(const LAS bf16x8*)(lds + PG8_SA(b, h) + aoff + m * 2048 + k * 1024); } while (0)
; #define PG8_MMA(ai, bj, At, Bt) do { __builtin_amdgcn_s_setprio(1); _Pragma("unroll") for (int m = 0; m < 4; ++m) _Pragma("unroll") for (int n = 0; n < 2; ++n) _Pragma("unroll") for (int k = 0; k < 2; ++k) \
;         acc[ai][bj][m][n] = __builtin_amdgcn_mfma_f32_16x16x32_bf16(Bt[n][k], At[m][k], acc[ai][bj][m][n], 0, 0, 0); __builtin_amdgcn_s_setprio(0); } while (0)
; #define PG8_WAIT_V(n) asm volatile("s_waitcnt vmcnt(" #n ")" ::: "memory")
; #define PG8_WAIT_L(n) asm volatile("s_waitcnt lgkmcnt(" #n ")" ::: "memory")
; #define PG8_BAR __builtin_amdgcn_s_barrier()
; #define PG8_SCHED __builtin_amdgcn_sched_barrier(0)
; template <class Epi, class Sched>
; DI void gemm_phase(LAS unsigned char* lds, const Gemm g, const Sched& S, const Epi& E) {
;     ...
;             PG8_WAIT_V(8); PG8_WAIT_L(0); PG8_BAR; PG8_MMA(0, 0, At, B0); PG8_MMA(0, 1, At, B1); PG8_BAR; PG8_SCHED;
;             PG8_LDA(At, 0, 1); PG8_STAGE(PG8_SB(0, 0), b2, voffB); PG8_STAGE(PG8_SB(0, 1), b2 + hstepB, voffB); PG8_STAGE(PG8_SA(0, 0), a2, voffA);
;             PG8_WAIT_V(8); PG8_WAIT_L(0); PG8_BAR; PG8_MMA(1, 0, At, B0); PG8_MMA(1, 1, At, B1); PG8_BAR; PG8_SCHED;
	s_setprio 1
	v_mfma_f32_16x16x32_bf16 v[126:129], v[138:141], v[218:221], v[126:129]
	v_mfma_f32_16x16x32_bf16 v[122:125], v[176:179], v[218:221], v[122:125]
	v_mfma_f32_16x16x32_bf16 v[110:113], v[138:141], v[226:229], v[110:113]
	v_mfma_f32_16x16x32_bf16 v[106:109], v[176:179], v[226:229], v[106:109]
	v_mfma_f32_16x16x32_bf16 v[94:97], v[138:141], v[234:237], v[94:97]
	v_mfma_f32_16x16x32_bf16 v[90:93], v[176:179], v[234:237], v[90:93]
	v_mfma_f32_16x16x32_bf16 v[78:81], v[138:141], v[242:245], v[78:81]
	v_mfma_f32_16x16x32_bf16 v[74:77], v[176:179], v[242:245], v[74:77]
	v_mfma_f32_16x16x32_bf16 v[126:129], v[142:145], v[222:225], v[126:129]
	v_mfma_f32_16x16x32_bf16 v[122:125], v[198:201], v[222:225], v[122:125]
	v_mfma_f32_16x16x32_bf16 v[110:113], v[142:145], v[230:233], v[110:113]
	v_mfma_f32_16x16x32_bf16 v[106:109], v[198:201], v[230:233], v[106:109]
	v_mfma_f32_16x16x32_bf16 v[94:97], v[142:145], v[238:241], v[94:97]
	v_mfma_f32_16x16x32_bf16 v[90:93], v[198:201], v[238:241], v[90:93]
	v_mfma_f32_16x16x32_bf16 v[78:81], v[142:145], v[246:249], v[78:81]
	v_mfma_f32_16x16x32_bf16 v[74:77], v[198:201], v[246:249], v[74:77]
	v_mfma_f32_16x16x32_bf16 v[118:121], v[202:205], v[218:221], v[118:121]
	v_mfma_f32_16x16x32_bf16 v[114:117], v[210:213], v[218:221], v[114:117]
	v_mfma_f32_16x16x32_bf16 v[102:105], v[202:205], v[226:229], v[102:105]
	v_mfma_f32_16x16x32_bf16 v[98:101], v[210:213], v[226:229], v[98:101]
	v_mfma_f32_16x16x32_bf16 v[86:89], v[202:205], v[234:237], v[86:89]
	v_mfma_f32_16x16x32_bf16 v[82:85], v[210:213], v[234:237], v[82:85]
	v_mfma_f32_16x16x32_bf16 v[70:73], v[202:205], v[242:245], v[70:73]
	v_mfma_f32_16x16x32_bf16 v[66:69], v[210:213], v[242:245], v[66:69]
	v_mfma_f32_16x16x32_bf16 v[118:121], v[206:209], v[222:225], v[118:121]
	v_mfma_f32_16x16x32_bf16 v[114:117], v[214:217], v[222:225], v[114:117]
	v_mfma_f32_16x16x32_bf16 v[102:105], v[206:209], v[230:233], v[102:105]
	v_mfma_f32_16x16x32_bf16 v[98:101], v[214:217], v[230:233], v[98:101]
	v_mfma_f32_16x16x32_bf16 v[86:89], v[206:209], v[238:241], v[86:89]
	v_mfma_f32_16x16x32_bf16 v[82:85], v[214:217], v[238:241], v[82:85]
	v_mfma_f32_16x16x32_bf16 v[70:73], v[206:209], v[246:249], v[70:73]
	v_mfma_f32_16x16x32_bf16 v[66:69], v[214:217], v[246:249], v[66:69]
	s_setprio 0
	s_barrier
	s_add_i32 s70, s94, s78
	v_lshl_add_u64 v[172:173], s[64:65], 0, v[150:151]
	s_mov_b32 m0, s70
	ds_read_b128 v[218:221], v186 offset:16384
	ds_read_b128 v[222:225], v186 offset:17408
	ds_read_b128 v[226:229], v186 offset:18432
	ds_read_b128 v[230:233], v186 offset:19456
	ds_read_b128 v[234:237], v186 offset:20480
	ds_read_b128 v[238:241], v186 offset:21504
	ds_read_b128 v[242:245], v186 offset:22528
	ds_read_b128 v[246:249], v186 offset:23552
	global_load_lds_dwordx4 v[172:173], off
	s_add_i32 m0, s70, 0x2000
	s_add_u32 s70, s64, 0x40000
	v_lshl_add_u64 v[180:181], s[64:65], 0, v[154:155]
	s_addc_u32 s71, s65, 0
	s_add_i32 s72, s95, s78
	global_load_lds_dwordx4 v[180:181], off
	v_lshl_add_u64 v[250:251], s[70:71], 0, v[150:151]
	s_mov_b32 m0, s72
	v_lshl_add_u64 v[252:253], s[66:67], 0, v[152:153]
	global_load_lds_dwordx4 v[250:251], off
	v_lshl_add_u64 v[250:251], s[70:71], 0, v[154:155]
	s_add_i32 m0, s72, 0x2000
	s_nop 0
	global_load_lds_dwordx4 v[250:251], off
	v_lshl_add_u64 v[250:251], s[66:67], 0, v[148:149]
	s_mov_b32 m0, s79
	s_nop 0
	global_load_lds_dwordx4 v[250:251], off
	s_mov_b32 m0, s80
	s_nop 0
	global_load_lds_dwordx4 v[252:253], off
	s_waitcnt vmcnt(8)
	s_waitcnt lgkmcnt(0)
	s_barrier
	s_setprio 1
	v_mfma_f32_16x16x32_bf16 v[62:65], v[138:141], v[218:221], v[62:65]
	v_mfma_f32_16x16x32_bf16 v[58:61], v[176:179], v[218:221], v[58:61]
	v_mfma_f32_16x16x32_bf16 v[46:49], v[138:141], v[226:229], v[46:49]
	v_mfma_f32_16x16x32_bf16 v[42:45], v[176:179], v[226:229], v[42:45]
	v_mfma_f32_16x16x32_bf16 v[30:33], v[138:141], v[234:237], v[30:33]
	v_mfma_f32_16x16x32_bf16 v[26:29], v[176:179], v[234:237], v[26:29]
	v_mfma_f32_16x16x32_bf16 v[14:17], v[138:141], v[242:245], v[14:17]
	v_mfma_f32_16x16x32_bf16 v[10:13], v[176:179], v[242:245], v[10:13]
	v_mfma_f32_16x16x32_bf16 v[62:65], v[142:145], v[222:225], v[62:65]
	v_mfma_f32_16x16x32_bf16 v[58:61], v[198:201], v[222:225], v[58:61]
	v_mfma_f32_16x16x32_bf16 v[46:49], v[142:145], v[230:233], v[46:49]
	v_mfma_f32_16x16x32_bf16 v[42:45], v[198:201], v[230:233], v[42:45]
	v_mfma_f32_16x16x32_bf16 v[30:33], v[142:145], v[238:241], v[30:33]
	v_mfma_f32_16x16x32_bf16 v[26:29], v[198:201], v[238:241], v[26:29]
	v_mfma_f32_16x16x32_bf16 v[14:17], v[142:145], v[246:249], v[14:17]
	v_mfma_f32_16x16x32_bf16 v[10:13], v[198:201], v[246:249], v[10:13]
	v_mfma_f32_16x16x32_bf16 v[54:57], v[202:205], v[218:221], v[54:57]
	v_mfma_f32_16x16x32_bf16 v[50:53], v[210:213], v[218:221], v[50:53]
	v_mfma_f32_16x16x32_bf16 v[38:41], v[202:205], v[226:229], v[38:41]
	v_mfma_f32_16x16x32_bf16 v[34:37], v[210:213], v[226:229], v[34:37]
	v_mfma_f32_16x16x32_bf16 v[22:25], v[202:205], v[234:237], v[22:25]
	v_mfma_f32_16x16x32_bf16 v[18:21], v[210:213], v[234:237], v[18:21]
	v_mfma_f32_16x16x32_bf16 v[6:9], v[202:205], v[242:245], v[6:9]
	v_mfma_f32_16x16x32_bf16 v[2:5], v[210:213], v[242:245], v[2:5]
	v_mfma_f32_16x16x32_bf16 v[54:57], v[206:209], v[222:225], v[54:57]
	v_mfma_f32_16x16x32_bf16 v[50:53], v[214:217], v[222:225], v[50:53]
	v_mfma_f32_16x16x32_bf16 v[38:41], v[206:209], v[230:233], v[38:41]
	v_mfma_f32_16x16x32_bf16 v[34:37], v[214:217], v[230:233], v[34:37]
	v_mfma_f32_16x16x32_bf16 v[22:25], v[206:209], v[238:241], v[22:25]
	v_mfma_f32_16x16x32_bf16 v[18:21], v[214:217], v[238:241], v[18:21]
	v_mfma_f32_16x16x32_bf16 v[6:9], v[206:209], v[246:249], v[6:9]
	v_mfma_f32_16x16x32_bf16 v[2:5], v[214:217], v[246:249], v[2:5]
	s_setprio 0
	s_barrier
; #define PG8_STAGE(bufoff, gbase, voff) do { _Pragma("unroll") for (int _i = 0; _i < 2; ++_i) \
;         __builtin_amdgcn_global_load_lds((const unsigned*)((const char*)(gbase) + (voff)[_i]), (LAS unsigned*)(lds + (bufoff) + ldsw + _i * 8192), 16, 0, 0); } while (0)
; #define PG8_LDA(dst, b, h) do { _Pragma("unroll") for (int m = 0; m < 4; ++m) _Pragma("unroll") for (int k = 0; k < 2; ++k) dst[m][k] = *(const LAS bf16x8*)(lds + PG8_SA(b, h) + aoff + m * 2048 + k * 1024); } while (0)
; #define PG8_LDB(dst, b, h) do { _Pragma("unroll") for (int n = 0; n < 2; ++n) _Pragma("unroll") for (int k = 0; k < 2; ++k) dst[n][k] = *(const LAS bf16x8*)(lds + PG8_SB(b, h) + boff + n * 2048 + k * 1024); } while (0)
; #define PG8_MMA(ai, bj, At, Bt) do { __builtin_amdgcn_s_setprio(1); _Pragma("unroll") for (int m = 0; m < 4; ++m) _Pragma("unroll") for (int n = 0; n < 2; ++n) _Pragma("unroll") for (int k = 0; k < 2; ++k) \
;         acc[ai][bj][m][n] = __builtin_amdgcn_mfma_f32_16x16x32_bf16(Bt[n][k], At[m][k], acc[ai][bj][m][n], 0, 0, 0); __builtin_amdgcn_s_setprio(0); } while (0)
; #define PG8_WAIT_V(n) asm volatile("s_waitcnt vmcnt(" #n ")" ::: "memory")
; #define PG8_WAIT_L(n) asm volatile("s_waitcnt lgkmcnt(" #n ")" ::: "memory")
; #define PG8_BAR __builtin_amdgcn_s_barrier()
; #define PG8_SCHED __builtin_amdgcn_sched_barrier(0)
; template <class Epi, class Sched>
; DI void gemm_phase(LAS unsigned char* lds, const Gemm g, const Sched& S, const Epi& E) {
;     ...
;             PG8_LDB(B0, 1, 0); PG8_LDB(B1, 1, 1); PG8_SCHED; PG8_LDA(At, 1, 0); PG8_STAGE(PG8_SA(0, 1), a2 + hstepA, voffA);
;             PG8_WAIT_V(8); PG8_WAIT_L(0); PG8_BAR; PG8_MMA(0, 0, At, B0); PG8_MMA(0, 1, At, B1); PG8_BAR; PG8_SCHED;
	s_add_i32 s70, 0, 0x18000
	v_add_u32_e32 v156, s70, v159
	s_add_i32 s71, 0, 0x1c000
	ds_read_b128 v[138:141], v156
	ds_read_b128 v[142:145], v156 offset:1024
	ds_read_b128 v[176:179], v156 offset:2048
	ds_read_b128 v[198:201], v156 offset:3072
	v_add_u32_e32 v156, s71, v159
	ds_read_b128 v[202:205], v156
	ds_read_b128 v[206:209], v156 offset:1024
	ds_read_b128 v[210:213], v156 offset:2048
	ds_read_b128 v[214:217], v156 offset:3072
	s_add_u32 s66, s66, 0x40000
	s_addc_u32 s67, s67, 0
	s_mov_b32 m0, s81
	v_lshl_add_u64 v[254:255], s[66:67], 0, v[148:149]
	ds_read_b128 v[218:221], v186 offset:32768
	ds_read_b128 v[222:225], v186 offset:33792
	ds_read_b128 v[226:229], v186 offset:34816
	ds_read_b128 v[230:233], v186 offset:35840
	ds_read_b128 v[234:237], v186 offset:36864
	ds_read_b128 v[238:241], v186 offset:37888
	ds_read_b128 v[242:245], v186 offset:38912
	ds_read_b128 v[246:249], v186 offset:39936
	global_load_lds_dwordx4 v[254:255], off
	v_lshl_add_u64 v[254:255], s[66:67], 0, v[152:153]
	s_mov_b32 m0, s82
	s_nop 0
	global_load_lds_dwordx4 v[254:255], off
	s_waitcnt vmcnt(8)
	s_waitcnt lgkmcnt(0)
	s_barrier
	s_setprio 1
	v_mfma_f32_16x16x32_bf16 v[126:129], v[138:141], v[218:221], v[126:129]
	v_mfma_f32_16x16x32_bf16 v[122:125], v[176:179], v[218:221], v[122:125]
	v_mfma_f32_16x16x32_bf16 v[110:113], v[138:141], v[226:229], v[110:113]
	v_mfma_f32_16x16x32_bf16 v[106:109], v[176:179], v[226:229], v[106:109]
	v_mfma_f32_16x16x32_bf16 v[94:97], v[138:141], v[234:237], v[94:97]
	v_mfma_f32_16x16x32_bf16 v[90:93], v[176:179], v[234:237], v[90:93]
	v_mfma_f32_16x16x32_bf16 v[78:81], v[138:141], v[242:245], v[78:81]
	v_mfma_f32_16x16x32_bf16 v[74:77], v[176:179], v[242:245], v[74:77]
	v_mfma_f32_16x16x32_bf16 v[126:129], v[142:145], v[222:225], v[126:129]
	v_mfma_f32_16x16x32_bf16 v[122:125], v[198:201], v[222:225], v[122:125]
	v_mfma_f32_16x16x32_bf16 v[110:113], v[142:145], v[230:233], v[110:113]
	v_mfma_f32_16x16x32_bf16 v[106:109], v[198:201], v[230:233], v[106:109]
	v_mfma_f32_16x16x32_bf16 v[94:97], v[142:145], v[238:241], v[94:97]
	v_mfma_f32_16x16x32_bf16 v[90:93], v[198:201], v[238:241], v[90:93]
	v_mfma_f32_16x16x32_bf16 v[78:81], v[142:145], v[246:249], v[78:81]
	v_mfma_f32_16x16x32_bf16 v[74:77], v[198:201], v[246:249], v[74:77]
	v_mfma_f32_16x16x32_bf16 v[118:121], v[202:205], v[218:221], v[118:121]
	v_mfma_f32_16x16x32_bf16 v[114:117], v[210:213], v[218:221], v[114:117]
	v_mfma_f32_16x16x32_bf16 v[102:105], v[202:205], v[226:229], v[102:105]
	v_mfma_f32_16x16x32_bf16 v[98:101], v[210:213], v[226:229], v[98:101]
	v_mfma_f32_16x16x32_bf16 v[86:89], v[202:205], v[234:237], v[86:89]
	v_mfma_f32_16x16x32_bf16 v[82:85], v[210:213], v[234:237], v[82:85]
	v_mfma_f32_16x16x32_bf16 v[70:73], v[202:205], v[242:245], v[70:73]
	v_mfma_f32_16x16x32_bf16 v[66:69], v[210:213], v[242:245], v[66:69]
	v_mfma_f32_16x16x32_bf16 v[118:121], v[206:209], v[222:225], v[118:121]
	v_mfma_f32_16x16x32_bf16 v[114:117], v[214:217], v[222:225], v[114:117]
	v_mfma_f32_16x16x32_bf16 v[102:105], v[206:209], v[230:233], v[102:105]
	v_mfma_f32_16x16x32_bf16 v[98:101], v[214:217], v[230:233], v[98:101]
	v_mfma_f32_16x16x32_bf16 v[86:89], v[206:209], v[238:241], v[86:89]
	v_mfma_f32_16x16x32_bf16 v[82:85], v[214:217], v[238:241], v[82:85]
	v_mfma_f32_16x16x32_bf16 v[70:73], v[206:209], v[246:249], v[70:73]
	v_mfma_f32_16x16x32_bf16 v[66:69], v[214:217], v[246:249], v[66:69]
	s_setprio 0
	s_barrier
; #define PG8_STAGE(bufoff, gbase, voff) do { _Pragma("unroll") for (int _i = 0; _i < 2; ++_i) \
;         __builtin_amdgcn_global_load_lds((const unsigned*)((const char*)(gbase) + (voff)[_i]), (LAS unsigned*)(lds + (bufoff) + ldsw + _i * 8192), 16, 0, 0); } while (0)
; #define PG8_LDA(dst, b, h) do { _Pragma("unroll") for (int m = 0; m < 4; ++m) _Pragma("unroll") for (int k = 0; k < 2; ++k) dst[m][k] = *(const LAS bf16x8*)(lds + PG8_SA(b, h) + aoff + m * 2048 + k * 1024); } while (0)
; #define PG8_MMA(ai, bj, At, Bt) do { __builtin_amdgcn_s_setprio(1); _Pragma("unroll") for (int m = 0; m < 4; ++m) _Pragma("unroll") for (int n = 0; n < 2; ++n) _Pragma("unroll") for (int k = 0; k < 2; ++k) \
;         acc[ai][bj][m][n] = __builtin_amdgcn_mfma_f32_16x16x32_bf16(Bt[n][k], At[m][k], acc[ai][bj][m][n], 0, 0, 0); __builtin_amdgcn_s_setprio(0); } while (0)
; #define PG8_WAIT_V(n) asm volatile("s_waitcnt vmcnt(" #n ")" ::: "memory")
; #define PG8_WAIT_L(n) asm volatile("s_waitcnt lgkmcnt(" #n ")" ::: "memory")
; #define PG8_BAR __builtin_amdgcn_s_barrier()
; #define PG8_SCHED __builtin_amdgcn_sched_barrier(0)
; template <class Epi, class Sched>
; DI void gemm_phase(LAS unsigned char* lds, const Gemm g, const Sched& S, const Epi& E) {
;     ...
;             PG8_LDA(At, 1, 1); PG8_STAGE(PG8_SB(1, 0), b3, voffB); PG8_STAGE(PG8_SB(1, 1), b3 + hstepB, voffB); PG8_STAGE(PG8_SA(1, 0), a3, voffA);
;             PG8_WAIT_V(8); PG8_WAIT_L(0); PG8_BAR; PG8_MMA(1, 0, At, B0); PG8_MMA(1, 1, At, B1); PG8_BAR; PG8_SCHED;
;         }
;         if (wr == 0) PG8_BAR;
	s_add_i32 s66, s70, s78
	v_lshl_add_u64 v[172:173], v[172:173], 0, s[50:51]
	s_mov_b32 m0, s66
	ds_read_b128 v[218:221], v186 offset:49152
	ds_read_b128 v[222:225], v186 offset:50176
	ds_read_b128 v[226:229], v186 offset:51200
	ds_read_b128 v[230:233], v186 offset:52224
	ds_read_b128 v[234:237], v186 offset:53248
	ds_read_b128 v[238:241], v186 offset:54272
	ds_read_b128 v[242:245], v186 offset:55296
	ds_read_b128 v[246:249], v186 offset:56320
	global_load_lds_dwordx4 v[172:173], off
	s_add_i32 m0, s66, 0x2000
	s_add_u32 s64, s64, 0x40080
	v_lshl_add_u64 v[172:173], v[180:181], 0, s[50:51]
	s_addc_u32 s65, s65, 0
	s_add_i32 s66, s71, s78
	global_load_lds_dwordx4 v[172:173], off
	v_lshl_add_u64 v[172:173], s[64:65], 0, v[150:151]
	s_mov_b32 m0, s66
	s_nop 0
	global_load_lds_dwordx4 v[172:173], off
	v_lshl_add_u64 v[172:173], s[64:65], 0, v[154:155]
	s_add_i32 m0, s66, 0x2000
	s_nop 0
	global_load_lds_dwordx4 v[172:173], off
	v_lshl_add_u64 v[172:173], v[250:251], 0, s[50:51]
	s_mov_b32 m0, s86
	s_nop 0
	global_load_lds_dwordx4 v[172:173], off
	v_lshl_add_u64 v[172:173], v[252:253], 0, s[50:51]
	s_mov_b32 m0, s87
	s_nop 0
	global_load_lds_dwordx4 v[172:173], off
	s_waitcnt vmcnt(8)
	s_waitcnt lgkmcnt(0)
	s_barrier
	s_setprio 1
	v_mfma_f32_16x16x32_bf16 v[62:65], v[138:141], v[218:221], v[62:65]
	v_mfma_f32_16x16x32_bf16 v[58:61], v[176:179], v[218:221], v[58:61]
	v_mfma_f32_16x16x32_bf16 v[46:49], v[138:141], v[226:229], v[46:49]
	v_mfma_f32_16x16x32_bf16 v[42:45], v[176:179], v[226:229], v[42:45]
	v_mfma_f32_16x16x32_bf16 v[30:33], v[138:141], v[234:237], v[30:33]
	v_mfma_f32_16x16x32_bf16 v[26:29], v[176:179], v[234:237], v[26:29]
	v_mfma_f32_16x16x32_bf16 v[14:17], v[138:141], v[242:245], v[14:17]
	v_mfma_f32_16x16x32_bf16 v[10:13], v[176:179], v[242:245], v[10:13]
	v_mfma_f32_16x16x32_bf16 v[62:65], v[142:145], v[222:225], v[62:65]
	v_mfma_f32_16x16x32_bf16 v[58:61], v[198:201], v[222:225], v[58:61]
	v_mfma_f32_16x16x32_bf16 v[46:49], v[142:145], v[230:233], v[46:49]
	v_mfma_f32_16x16x32_bf16 v[42:45], v[198:201], v[230:233], v[42:45]
	v_mfma_f32_16x16x32_bf16 v[30:33], v[142:145], v[238:241], v[30:33]
	v_mfma_f32_16x16x32_bf16 v[26:29], v[198:201], v[238:241], v[26:29]
	v_mfma_f32_16x16x32_bf16 v[14:17], v[142:145], v[246:249], v[14:17]
	v_mfma_f32_16x16x32_bf16 v[10:13], v[198:201], v[246:249], v[10:13]
	v_mfma_f32_16x16x32_bf16 v[54:57], v[202:205], v[218:221], v[54:57]
	v_mfma_f32_16x16x32_bf16 v[50:53], v[210:213], v[218:221], v[50:53]
	v_mfma_f32_16x16x32_bf16 v[38:41], v[202:205], v[226:229], v[38:41]
	v_mfma_f32_16x16x32_bf16 v[34:37], v[210:213], v[226:229], v[34:37]
	v_mfma_f32_16x16x32_bf16 v[22:25], v[202:205], v[234:237], v[22:25]
	v_mfma_f32_16x16x32_bf16 v[18:21], v[210:213], v[234:237], v[18:21]
	v_mfma_f32_16x16x32_bf16 v[6:9], v[202:205], v[242:245], v[6:9]
	v_mfma_f32_16x16x32_bf16 v[2:5], v[210:213], v[242:245], v[2:5]
	v_mfma_f32_16x16x32_bf16 v[54:57], v[206:209], v[222:225], v[54:57]
	v_mfma_f32_16x16x32_bf16 v[50:53], v[214:217], v[222:225], v[50:53]
	v_mfma_f32_16x16x32_bf16 v[38:41], v[206:209], v[230:233], v[38:41]
	v_mfma_f32_16x16x32_bf16 v[34:37], v[214:217], v[230:233], v[34:37]
	v_mfma_f32_16x16x32_bf16 v[22:25], v[206:209], v[238:241], v[22:25]
	v_mfma_f32_16x16x32_bf16 v[18:21], v[214:217], v[238:241], v[18:21]
	v_mfma_f32_16x16x32_bf16 v[6:9], v[206:209], v[246:249], v[6:9]
	v_mfma_f32_16x16x32_bf16 v[2:5], v[214:217], v[246:249], v[2:5]
	s_setprio 0
	s_barrier
	s_add_i32 s69, s69, 2
	s_add_u32 s10, s10, 0x100
	s_addc_u32 s11, s11, 0
	s_add_u32 s59, s59, 0x100
	s_addc_u32 s68, s68, 0
	s_cmp_gt_u32 s69, 13
	s_cbranch_scc0 .LBB0_381
	s_waitcnt vmcnt(0)
	s_mov_b32 s99, 1
	s_and_b64 vcc, exec, s[52:53]
	s_cbranch_vccnz .LBB0_386
	s_cmp_gt_i32 s12, 4
	s_mov_b64 s[10:11], -1
	s_cbranch_scc1 .LBB0_387

; #define PG8_STAGE(bufoff, gbase, voff) do { _Pragma("unroll") for (int _i = 0; _i < 2; ++_i) \
;         __builtin_amdgcn_global_load_lds((const unsigned*)((const char*)(gbase) + (voff)[_i]), (LAS unsigned*)(lds + (bufoff) + ldsw + _i * 8192), 16, 0, 0); } while (0)
; #define PG8_WAIT_V(n) asm volatile("s_waitcnt vmcnt(" #n ")" ::: "memory")
; #define PG8_BAR __builtin_amdgcn_s_barrier()
; template <class Epi, class Sched>
; DI void gemm_phase(LAS unsigned char* lds, const Gemm g, const Sched& S, const Epi& E) {
;     ...
;                 for (int n = 0; n < 2; ++n) acc[a][b][m][n] = (f32x4){0.f, 0.f, 0.f, 0.f};
;     bf16x8 At[4][2], B0[2][2], B1[2][2];
;     const char* cA = (const char*)(cur.src ? g.A1 : g.A0) + (size_t)cur.pm * tstepA; const char* cB = (const char*)(cur.src ? g.B1 : g.B0) + (size_t)cur.pn * tstepB;
;     PG8_STAGE(PG8_SB(0, 0), cB, voffB); PG8_STAGE(PG8_SB(0, 1), cB + hstepB, voffB); PG8_STAGE(PG8_SA(0, 0), cA, voffA); PG8_STAGE(PG8_SA(0, 1), cA + hstepA, voffA);
;     if (wr == 1) PG8_BAR;
;     PG8_WAIT_V(2); PG8_BAR;
;     PG8_STAGE(PG8_SB(1, 0), cB + kstep, voffB); PG8_STAGE(PG8_SA(1, 0), cA + kstep, voffA); PG8_STAGE(PG8_SB(1, 1), cB + hstepB + kstep, voffB);
;     PG8_WAIT_V(6); PG8_BAR;
;     for (;;) {
.LBB0_962:
	s_add_u32 s57, s24, 0x1a200000
	s_addc_u32 s58, s25, 0
	s_add_u32 s59, s24, 0x1e00000
	s_addc_u32 s60, s25, 0
	s_add_u32 s16, s24, 0x1e200000
	s_addc_u32 s17, s25, 0
	s_add_u32 s18, s24, 0xc000000
	v_and_b32_e32 v15, 15, v184
	v_lshlrev_b32_e32 v16, 1, v13
	v_lshlrev_b32_e32 v17, 2, v184
	s_addc_u32 s19, s25, 0
	v_lshl_or_b32 v1, s4, 6, v15
	v_lshl_or_b32 v15, v15, 6, v16
	s_lshl_b32 s4, s4, 13
	v_and_b32_e32 v17, 32, v17
	v_bitop3_b32 v15, v15, s4, v17 bitop3:0xde
	s_lshl_b32 s4, s5, 5
	s_mov_b64 s[20:21], 0x80
	s_and_b32 s7, s4, 0x60
	v_lshlrev_b32_e32 v18, 6, v184
	s_movk_i32 s4, 0x3c0
	s_add_i32 m0, s53, 0x18000
	v_lshl_add_u64 v[8:9], v[8:9], 0, s[20:21]
	v_and_or_b32 v16, v18, s4, v16
	s_lshl_b32 s4, s7, 7
	s_waitcnt vmcnt(2)
	s_barrier
	global_load_lds_dwordx4 v[8:9], off
	v_lshl_add_u64 v[6:7], v[6:7], 0, s[20:21]
	s_add_i32 m0, s53, 0x1a000
	s_add_i32 s61, s53, 0x8000
	s_add_i32 s62, s53, 0xa000
	v_bitop3_b32 v162, s4, v16, v17 bitop3:0xf6
	global_load_lds_dwordx4 v[6:7], off
	v_lshl_add_u64 v[2:3], v[2:3], 0, s[20:21]
	s_mov_b32 m0, s61
	s_add_u32 s4, s46, 0x20080
	global_load_lds_dwordx4 v[2:3], off
	v_lshl_add_u64 v[2:3], v[4:5], 0, s[20:21]
	s_mov_b32 m0, s62
	s_addc_u32 s5, s47, 0
	global_load_lds_dwordx4 v[2:3], off
	s_add_i32 m0, s53, 0x1c000
	v_lshl_add_u64 v[2:3], s[4:5], 0, v[132:133]
	global_load_lds_dwordx4 v[2:3], off
	v_lshl_add_u64 v[2:3], s[4:5], 0, v[136:137]
	s_add_i32 m0, s53, 0x1e000
	s_cmpk_lt_u32 s34, 0x100
	global_load_lds_dwordx4 v[2:3], off
	v_lshlrev_b32_e32 v2, 7, v184
	v_and_b32_e32 v2, 0x1c000, v2
	v_lshlrev_b32_e32 v3, 10, v12
	v_or3_b32 v2, v10, v2, v3
	v_add_u32_e32 v138, v2, v11
	v_lshlrev_b32_e32 v2, 3, v14
	s_waitcnt vmcnt(6)
	v_and_b32_e32 v2, 0x3c000, v2
	v_or3_b32 v2, v10, v2, v3
	s_cselect_b64 s[34:35], -1, 0
	v_or_b32_e32 v163, 16, v1
	v_or_b32_e32 v164, 32, v1
	v_or_b32_e32 v165, 48, v1
	s_ashr_i32 s63, s2, 31
	v_or_b32_e32 v166, s7, v13
	v_mov_b32_e32 v139, v133
	v_add_u32_e32 v140, v2, v11
	v_mov_b32_e32 v141, v133
	v_mov_b64_e32 v[142:143], 0x400
	v_mov_b64_e32 v[144:145], 0x3ff
	s_add_i32 s64, 0, 0x10000
	s_add_i32 s65, 0, 0x14000
	v_add_u32_e32 v167, 0, v15
	s_mov_b32 s7, 0
	s_mov_b32 s66, 0
	v_mov_b32_e32 v2, v133
	v_mov_b32_e32 v3, v133
	v_mov_b32_e32 v4, v133
	v_mov_b32_e32 v5, v133
	v_mov_b32_e32 v6, v133
	v_mov_b32_e32 v7, v133
	v_mov_b32_e32 v8, v133
	v_mov_b32_e32 v9, v133
	v_mov_b32_e32 v10, v133
	v_mov_b32_e32 v11, v133
	v_mov_b32_e32 v12, v133
	v_mov_b32_e32 v13, v133
	v_mov_b32_e32 v14, v133
	v_mov_b32_e32 v15, v133
	v_mov_b32_e32 v16, v133
	v_mov_b32_e32 v17, v133
	v_mov_b32_e32 v18, v133
	v_mov_b32_e32 v19, v133
	v_mov_b32_e32 v20, v133
	v_mov_b32_e32 v21, v133
	v_mov_b32_e32 v22, v133
	v_mov_b32_e32 v23, v133
	v_mov_b32_e32 v24, v133
	v_mov_b32_e32 v25, v133
	v_mov_b32_e32 v26, v133
	v_mov_b32_e32 v27, v133
	v_mov_b32_e32 v28, v133
	v_mov_b32_e32 v29, v133
	v_mov_b32_e32 v30, v133
	v_mov_b32_e32 v31, v133
	v_mov_b32_e32 v32, v133
	v_mov_b32_e32 v33, v133
	v_mov_b32_e32 v34, v133
	v_mov_b32_e32 v35, v133
	v_mov_b32_e32 v36, v133
	v_mov_b32_e32 v37, v133
	v_mov_b32_e32 v38, v133
	v_mov_b32_e32 v39, v133
	v_mov_b32_e32 v40, v133
	v_mov_b32_e32 v41, v133
	v_mov_b32_e32 v42, v133
	v_mov_b32_e32 v43, v133
	v_mov_b32_e32 v44, v133
	v_mov_b32_e32 v45, v133
	v_mov_b32_e32 v46, v133
	v_mov_b32_e32 v47, v133
	v_mov_b32_e32 v48, v133
	v_mov_b32_e32 v49, v133
	v_mov_b32_e32 v50, v133
	v_mov_b32_e32 v51, v133
	v_mov_b32_e32 v52, v133
	v_mov_b32_e32 v53, v133
	v_mov_b32_e32 v54, v133
	v_mov_b32_e32 v55, v133
	v_mov_b32_e32 v56, v133
	v_mov_b32_e32 v57, v133
	v_mov_b32_e32 v58, v133
	v_mov_b32_e32 v59, v133
	v_mov_b32_e32 v60, v133
	v_mov_b32_e32 v61, v133
	v_mov_b32_e32 v62, v133
	v_mov_b32_e32 v63, v133
	v_mov_b32_e32 v64, v133
	v_mov_b32_e32 v65, v133
	v_mov_b32_e32 v66, v133
	v_mov_b32_e32 v67, v133
	v_mov_b32_e32 v68, v133
	v_mov_b32_e32 v69, v133
	v_mov_b32_e32 v70, v133
	v_mov_b32_e32 v71, v133
	v_mov_b32_e32 v72, v133
	v_mov_b32_e32 v73, v133
	v_mov_b32_e32 v74, v133
	v_mov_b32_e32 v75, v133
	v_mov_b32_e32 v76, v133
	v_mov_b32_e32 v77, v133
	v_mov_b32_e32 v78, v133
	v_mov_b32_e32 v79, v133
	v_mov_b32_e32 v80, v133
	v_mov_b32_e32 v81, v133
	v_mov_b32_e32 v82, v133
	v_mov_b32_e32 v83, v133
	v_mov_b32_e32 v84, v133
	v_mov_b32_e32 v85, v133
	v_mov_b32_e32 v86, v133
	v_mov_b32_e32 v87, v133
	v_mov_b32_e32 v88, v133
	v_mov_b32_e32 v89, v133
	v_mov_b32_e32 v90, v133
	v_mov_b32_e32 v91, v133
	v_mov_b32_e32 v92, v133
	v_mov_b32_e32 v93, v133
	v_mov_b32_e32 v94, v133
	v_mov_b32_e32 v95, v133
	v_mov_b32_e32 v96, v133
	v_mov_b32_e32 v97, v133
	v_mov_b32_e32 v98, v133
	v_mov_b32_e32 v99, v133
	v_mov_b32_e32 v100, v133
	v_mov_b32_e32 v101, v133
	v_mov_b32_e32 v102, v133
	v_mov_b32_e32 v103, v133
	v_mov_b32_e32 v104, v133
	v_mov_b32_e32 v105, v133
	v_mov_b32_e32 v106, v133
	v_mov_b32_e32 v107, v133
	v_mov_b32_e32 v108, v133
	v_mov_b32_e32 v109, v133
	v_mov_b32_e32 v110, v133
	v_mov_b32_e32 v111, v133
	v_mov_b32_e32 v112, v133
	v_mov_b32_e32 v113, v133
	v_mov_b32_e32 v114, v133
	v_mov_b32_e32 v115, v133
	v_mov_b32_e32 v116, v133
	v_mov_b32_e32 v117, v133
	v_mov_b32_e32 v118, v133
	v_mov_b32_e32 v119, v133
	v_mov_b32_e32 v120, v133
	v_mov_b32_e32 v121, v133
	v_mov_b32_e32 v122, v133
	v_mov_b32_e32 v123, v133
	v_mov_b32_e32 v124, v133
	v_mov_b32_e32 v125, v133
	v_mov_b32_e32 v126, v133
	v_mov_b32_e32 v127, v133
	v_mov_b32_e32 v128, v133
	v_mov_b32_e32 v129, v133
	s_barrier
	s_mov_b32 s99, 0
	s_branch .LBB0_965

;     DI bool next(int i, Unit& u) const { if (i > 0 || c >= 64) return false; u.pm = c & 31; u.pn = 0; u.src = c >> 5; return true; }
; #define PG8_STAGE(bufoff, gbase, voff) do { _Pragma("unroll") for (int _i = 0; _i < 2; ++_i) \
;         __builtin_amdgcn_global_load_lds((const unsigned*)((const char*)(gbase) + (voff)[_i]), (LAS unsigned*)(lds + (bufoff) + ldsw + _i * 8192), 16, 0, 0); } while (0)
; #define PG8_LDA(dst, b, h) do { _Pragma("unroll") for (int m = 0; m < 4; ++m) _Pragma("unroll") for (int k = 0; k < 2; ++k) dst[m][k] = *(const LAS bf16x8*)(lds + PG8_SA(b, h) + aoff + m * 2048 + k * 1024); } while (0)
; #define PG8_LDB(dst, b, h) do { _Pragma("unroll") for (int n = 0; n < 2; ++n) _Pragma("unroll") for (int k = 0; k < 2; ++k) dst[n][k] = *(const LAS bf16x8*)(lds + PG8_SB(b, h) + boff + n * 2048 + k * 1024); } while (0)
; #define PG8_MMA(ai, bj, At, Bt) do { __builtin_amdgcn_s_setprio(1); _Pragma("unroll") for (int m = 0; m < 4; ++m) _Pragma("unroll") for (int n = 0; n < 2; ++n) _Pragma("unroll") for (int k = 0; k < 2; ++k) \
;         acc[ai][bj][m][n] = __builtin_amdgcn_mfma_f32_16x16x32_bf16(Bt[n][k], At[m][k], acc[ai][bj][m][n], 0, 0, 0); __builtin_amdgcn_s_setprio(0); } while (0)
; template <class Epi, class Sched>
; DI void gemm_phase(LAS unsigned char* lds, const Gemm g, const Sched& S, const Epi& E) {
;     ...
;         const bool has_next = S.next(ui + 1, nxt);
;         E.pre(pre, cur, wr, fr);
;         const char* nA = has_next ? (const char*)(nxt.src ? g.A1 : g.A0) + (size_t)nxt.pm * tstepA : cA; const char* nB = has_next ? (const char*)(nxt.src ? g.B1 : g.B0) + (size_t)nxt.pn * tstepB : cB;
;         for (int t = 0; t < nt; t += 2) {
;             const bool last = (t == nt - 2);
;             const char* a1 = cA + (size_t)(t + 1) * kstep;
;             const char* a2 = last ? nA : cA + (size_t)(t + 2) * kstep; const char* b2 = last ? nB : cB + (size_t)(t + 2) * kstep;
;             const char* a3 = a2 + kstep; const char* b3 = b2 + kstep;
;             PG8_LDB(B0, 0, 0); PG8_LDB(B1, 0, 1); PG8_SCHED; PG8_LDA(At, 0, 0); PG8_STAGE(PG8_SA(1, 1), a1 + hstepA, voffA);
;             PG8_WAIT_V(8); PG8_WAIT_L(0); PG8_BAR; PG8_MMA(0, 0, At, B0); PG8_MMA(0, 1, At, B1); PG8_BAR; PG8_SCHED;
;             PG8_LDA(At, 0, 1); PG8_STAGE(PG8_SB(0, 0), b2, voffB); PG8_STAGE(PG8_SB(0, 1), b2 + hstepB, voffB); PG8_STAGE(PG8_SA(0, 0), a2, voffA);
.LBB0_971:
	s_ashr_i32 s39, s38, 31
	s_and_b32 s67, s66, 1
	s_lshl_b64 s[40:41], s[38:39], 18
	s_cmp_eq_u32 s67, 0
	s_cselect_b32 s39, s28, s57
	s_cselect_b32 s37, s29, s58
	s_cselect_b32 s48, s50, s59
	s_cselect_b32 s49, s51, s60
	s_add_u32 s40, s39, s40
	s_addc_u32 s41, s37, s41
	s_and_b64 s[42:43], s[4:5], exec
	s_cselect_b32 s39, s41, s45
	s_cselect_b32 s68, s40, s44
	s_ashr_i32 s37, s36, 31
	s_lshl_b64 s[42:43], s[36:37], 18
	s_add_u32 s42, s48, s42
	s_addc_u32 s43, s49, s43
	s_and_b64 s[48:49], s[4:5], exec
	s_cselect_b32 s37, s43, s47
	s_cselect_b32 s69, s42, s46
	s_add_u32 s44, s44, 0x20080
	s_addc_u32 s45, s45, 0
	s_add_u32 s70, s46, 0x100
	s_addc_u32 s71, s47, 0
	s_mov_b32 s72, -2
	v_add_u32_e32 v158, s64, v162
	v_add_u32_e32 v180, s65, v162
	ds_read_b128 v[146:149], v158
	ds_read_b128 v[150:153], v158 offset:1024
	ds_read_b128 v[154:157], v158 offset:2048
	ds_read_b128 v[158:161], v158 offset:3072
	ds_read_b128 v[168:171], v180
	ds_read_b128 v[172:175], v180 offset:1024
	ds_read_b128 v[176:179], v180 offset:2048
	ds_read_b128 v[180:183], v180 offset:3072
	s_add_u32 s46, s44, 0xfffe0080
	s_addc_u32 s47, s45, -1
	s_cmp_eq_u32 s72, 4
	s_cselect_b32 s49, s39, s47
	s_cselect_b32 s48, s68, s46
	s_cselect_b32 s47, s37, s71
	s_cselect_b32 s46, s69, s70
	v_lshl_add_u64 v[218:219], s[44:45], 0, v[138:139]
	s_add_i32 m0, s53, 0xc000
	ds_read_b128 v[186:189], v167
	ds_read_b128 v[190:193], v167 offset:1024
	ds_read_b128 v[194:197], v167 offset:2048
	ds_read_b128 v[198:201], v167 offset:3072
	ds_read_b128 v[202:205], v167 offset:4096
	ds_read_b128 v[206:209], v167 offset:5120
	ds_read_b128 v[210:213], v167 offset:6144
	ds_read_b128 v[214:217], v167 offset:7168
	global_load_lds_dwordx4 v[218:219], off
	v_lshl_add_u64 v[218:219], s[44:45], 0, v[140:141]
	s_add_i32 m0, s53, 0xe000
	s_nop 0
	global_load_lds_dwordx4 v[218:219], off
	s_cmp_lg_u32 s99, 0
	s_cbranch_scc1 .Lpk3_w1
	s_waitcnt vmcnt(8)
.Lpk3_w1:
	s_waitcnt lgkmcnt(0)
	s_barrier
	s_setprio 1
	v_mfma_f32_16x16x32_bf16 v[126:129], v[146:149], v[186:189], v[126:129]
	v_mfma_f32_16x16x32_bf16 v[122:125], v[154:157], v[186:189], v[122:125]
	v_mfma_f32_16x16x32_bf16 v[118:121], v[146:149], v[194:197], v[118:121]
	v_mfma_f32_16x16x32_bf16 v[114:117], v[154:157], v[194:197], v[114:117]
	v_mfma_f32_16x16x32_bf16 v[110:113], v[146:149], v[202:205], v[110:113]
	v_mfma_f32_16x16x32_bf16 v[106:109], v[154:157], v[202:205], v[106:109]
	v_mfma_f32_16x16x32_bf16 v[102:105], v[146:149], v[210:213], v[102:105]
	v_mfma_f32_16x16x32_bf16 v[98:101], v[154:157], v[210:213], v[98:101]
	v_mfma_f32_16x16x32_bf16 v[126:129], v[150:153], v[190:193], v[126:129]
	v_mfma_f32_16x16x32_bf16 v[122:125], v[158:161], v[190:193], v[122:125]
	v_mfma_f32_16x16x32_bf16 v[118:121], v[150:153], v[198:201], v[118:121]
	v_mfma_f32_16x16x32_bf16 v[114:117], v[158:161], v[198:201], v[114:117]
	v_mfma_f32_16x16x32_bf16 v[110:113], v[150:153], v[206:209], v[110:113]
	v_mfma_f32_16x16x32_bf16 v[106:109], v[158:161], v[206:209], v[106:109]
	v_mfma_f32_16x16x32_bf16 v[102:105], v[150:153], v[214:217], v[102:105]
	v_mfma_f32_16x16x32_bf16 v[98:101], v[158:161], v[214:217], v[98:101]
	v_mfma_f32_16x16x32_bf16 v[94:97], v[168:171], v[186:189], v[94:97]
	v_mfma_f32_16x16x32_bf16 v[90:93], v[176:179], v[186:189], v[90:93]
	v_mfma_f32_16x16x32_bf16 v[86:89], v[168:171], v[194:197], v[86:89]
	v_mfma_f32_16x16x32_bf16 v[82:85], v[176:179], v[194:197], v[82:85]
	v_mfma_f32_16x16x32_bf16 v[78:81], v[168:171], v[202:205], v[78:81]
	v_mfma_f32_16x16x32_bf16 v[74:77], v[176:179], v[202:205], v[74:77]
	v_mfma_f32_16x16x32_bf16 v[70:73], v[168:171], v[210:213], v[70:73]
	v_mfma_f32_16x16x32_bf16 v[66:69], v[176:179], v[210:213], v[66:69]
	v_mfma_f32_16x16x32_bf16 v[94:97], v[172:175], v[190:193], v[94:97]
	v_mfma_f32_16x16x32_bf16 v[90:93], v[180:183], v[190:193], v[90:93]
	v_mfma_f32_16x16x32_bf16 v[86:89], v[172:175], v[198:201], v[86:89]
	v_mfma_f32_16x16x32_bf16 v[82:85], v[180:183], v[198:201], v[82:85]
	v_mfma_f32_16x16x32_bf16 v[78:81], v[172:175], v[206:209], v[78:81]
	v_mfma_f32_16x16x32_bf16 v[74:77], v[180:183], v[206:209], v[74:77]
	v_mfma_f32_16x16x32_bf16 v[70:73], v[172:175], v[214:217], v[70:73]
	v_mfma_f32_16x16x32_bf16 v[66:69], v[180:183], v[214:217], v[66:69]
	s_setprio 0
	s_barrier
	s_add_i32 s73, s64, s52
	v_lshl_add_u64 v[218:219], s[46:47], 0, v[132:133]
	s_mov_b32 m0, s73
	ds_read_b128 v[186:189], v167 offset:16384
	ds_read_b128 v[190:193], v167 offset:17408
	ds_read_b128 v[194:197], v167 offset:18432
	ds_read_b128 v[198:201], v167 offset:19456
	ds_read_b128 v[202:205], v167 offset:20480
	ds_read_b128 v[206:209], v167 offset:21504
	ds_read_b128 v[210:213], v167 offset:22528
	ds_read_b128 v[214:217], v167 offset:23552
	global_load_lds_dwordx4 v[218:219], off
	s_add_i32 m0, s73, 0x2000
	s_add_u32 s74, s46, 0x20000
	v_lshl_add_u64 v[220:221], s[46:47], 0, v[136:137]
	s_addc_u32 s75, s47, 0
	s_add_i32 s73, s65, s52
	global_load_lds_dwordx4 v[220:221], off
	v_lshl_add_u64 v[222:223], s[74:75], 0, v[132:133]
	s_mov_b32 m0, s73
	v_lshl_add_u64 v[224:225], s[48:49], 0, v[134:135]
	global_load_lds_dwordx4 v[222:223], off
	v_lshl_add_u64 v[222:223], s[74:75], 0, v[136:137]
	s_add_i32 m0, s73, 0x2000
	s_nop 0
	global_load_lds_dwordx4 v[222:223], off
	v_lshl_add_u64 v[222:223], s[48:49], 0, v[130:131]
	s_mov_b32 m0, s53
	s_nop 0
	global_load_lds_dwordx4 v[222:223], off
	s_mov_b32 m0, s54
	s_nop 0
	global_load_lds_dwordx4 v[224:225], off
	s_cmp_lg_u32 s99, 0
	s_cbranch_scc1 .Lpk3_w2
	s_waitcnt vmcnt(8)
; #define PG8_STAGE(bufoff, gbase, voff) do { _Pragma("unroll") for (int _i = 0; _i < 2; ++_i) \
;         __builtin_amdgcn_global_load_lds((const unsigned*)((const char*)(gbase) + (voff)[_i]), (LAS unsigned*)(lds + (bufoff) + ldsw + _i * 8192), 16, 0, 0); } while (0)
; #define PG8_LDA(dst, b, h) do { _Pragma("unroll") for (int m = 0; m < 4; ++m) _Pragma("unroll") for (int k = 0; k < 2; ++k) dst[m][k] = *(const LAS bf16x8*)(lds + PG8_SA(b, h) + aoff + m * 2048 + k * 1024); } while (0)
; #define PG8_LDB(dst, b, h) do { _Pragma("unroll") for (int n = 0; n < 2; ++n) _Pragma("unroll") for (int k = 0; k < 2; ++k) dst[n][k] = *(const LAS bf16x8*)(lds + PG8_SB(b, h) + boff + n * 2048 + k * 1024); } while (0)
; #define PG8_MMA(ai, bj, At, Bt) do { __builtin_amdgcn_s_setprio(1); _Pragma("unroll") for (int m = 0; m < 4; ++m) _Pragma("unroll") for (int n = 0; n < 2; ++n) _Pragma("unroll") for (int k = 0; k < 2; ++k) \
;         acc[ai][bj][m][n] = __builtin_amdgcn_mfma_f32_16x16x32_bf16(Bt[n][k], At[m][k], acc[ai][bj][m][n], 0, 0, 0); __builtin_amdgcn_s_setprio(0); } while (0)
; #define PG8_WAIT_V(n) asm volatile("s_waitcnt vmcnt(" #n ")" ::: "memory")
; #define PG8_WAIT_L(n) asm volatile("s_waitcnt lgkmcnt(" #n ")" ::: "memory")
; #define PG8_BAR __builtin_amdgcn_s_barrier()
; #define PG8_SCHED __builtin_amdgcn_sched_barrier(0)
; template <class Epi, class Sched>
; DI void gemm_phase(LAS unsigned char* lds, const Gemm g, const Sched& S, const Epi& E) {
;     ...
;             PG8_WAIT_V(8); PG8_WAIT_L(0); PG8_BAR; PG8_MMA(1, 0, At, B0); PG8_MMA(1, 1, At, B1); PG8_BAR; PG8_SCHED;
;             PG8_LDB(B0, 1, 0); PG8_LDB(B1, 1, 1); PG8_SCHED; PG8_LDA(At, 1, 0); PG8_STAGE(PG8_SA(0, 1), a2 + hstepA, voffA);
;             PG8_WAIT_V(8); PG8_WAIT_L(0); PG8_BAR; PG8_MMA(0, 0, At, B0); PG8_MMA(0, 1, At, B1); PG8_BAR; PG8_SCHED;
.Lpk3_w2:
	s_mov_b32 s99, 0
	s_waitcnt lgkmcnt(0)
	s_barrier
	s_setprio 1
	v_mfma_f32_16x16x32_bf16 v[62:65], v[146:149], v[186:189], v[62:65]
	v_mfma_f32_16x16x32_bf16 v[58:61], v[154:157], v[186:189], v[58:61]
	v_mfma_f32_16x16x32_bf16 v[54:57], v[146:149], v[194:197], v[54:57]
	v_mfma_f32_16x16x32_bf16 v[50:53], v[154:157], v[194:197], v[50:53]
	v_mfma_f32_16x16x32_bf16 v[46:49], v[146:149], v[202:205], v[46:49]
	v_mfma_f32_16x16x32_bf16 v[42:45], v[154:157], v[202:205], v[42:45]
	v_mfma_f32_16x16x32_bf16 v[38:41], v[146:149], v[210:213], v[38:41]
	v_mfma_f32_16x16x32_bf16 v[34:37], v[154:157], v[210:213], v[34:37]
	v_mfma_f32_16x16x32_bf16 v[62:65], v[150:153], v[190:193], v[62:65]
	v_mfma_f32_16x16x32_bf16 v[58:61], v[158:161], v[190:193], v[58:61]
	v_mfma_f32_16x16x32_bf16 v[54:57], v[150:153], v[198:201], v[54:57]
	v_mfma_f32_16x16x32_bf16 v[50:53], v[158:161], v[198:201], v[50:53]
	v_mfma_f32_16x16x32_bf16 v[46:49], v[150:153], v[206:209], v[46:49]
	v_mfma_f32_16x16x32_bf16 v[42:45], v[158:161], v[206:209], v[42:45]
	v_mfma_f32_16x16x32_bf16 v[38:41], v[150:153], v[214:217], v[38:41]
	v_mfma_f32_16x16x32_bf16 v[34:37], v[158:161], v[214:217], v[34:37]
	v_mfma_f32_16x16x32_bf16 v[30:33], v[168:171], v[186:189], v[30:33]
	v_mfma_f32_16x16x32_bf16 v[26:29], v[176:179], v[186:189], v[26:29]
	v_mfma_f32_16x16x32_bf16 v[22:25], v[168:171], v[194:197], v[22:25]
	v_mfma_f32_16x16x32_bf16 v[18:21], v[176:179], v[194:197], v[18:21]
	v_mfma_f32_16x16x32_bf16 v[14:17], v[168:171], v[202:205], v[14:17]
	v_mfma_f32_16x16x32_bf16 v[10:13], v[176:179], v[202:205], v[10:13]
	v_mfma_f32_16x16x32_bf16 v[6:9], v[168:171], v[210:213], v[6:9]
	v_mfma_f32_16x16x32_bf16 v[2:5], v[176:179], v[210:213], v[2:5]
	v_mfma_f32_16x16x32_bf16 v[30:33], v[172:175], v[190:193], v[30:33]
	v_mfma_f32_16x16x32_bf16 v[26:29], v[180:183], v[190:193], v[26:29]
	v_mfma_f32_16x16x32_bf16 v[22:25], v[172:175], v[198:201], v[22:25]
	v_mfma_f32_16x16x32_bf16 v[18:21], v[180:183], v[198:201], v[18:21]
	v_mfma_f32_16x16x32_bf16 v[14:17], v[172:175], v[206:209], v[14:17]
	v_mfma_f32_16x16x32_bf16 v[10:13], v[180:183], v[206:209], v[10:13]
	v_mfma_f32_16x16x32_bf16 v[6:9], v[172:175], v[214:217], v[6:9]
	v_mfma_f32_16x16x32_bf16 v[2:5], v[180:183], v[214:217], v[2:5]
	s_setprio 0
	s_barrier
	s_add_i32 s73, 0, 0x18000
	s_add_i32 s74, 0, 0x1c000
	v_add_u32_e32 v158, s73, v162
	v_add_u32_e32 v180, s74, v162
	ds_read_b128 v[146:149], v158
	ds_read_b128 v[150:153], v158 offset:1024
	ds_read_b128 v[154:157], v158 offset:2048
	ds_read_b128 v[158:161], v158 offset:3072
	ds_read_b128 v[168:171], v180
	ds_read_b128 v[172:175], v180 offset:1024
	ds_read_b128 v[176:179], v180 offset:2048
	ds_read_b128 v[180:183], v180 offset:3072
	s_add_u32 s48, s48, 0x20000
	s_addc_u32 s49, s49, 0
	s_mov_b32 m0, s55
	v_lshl_add_u64 v[226:227], s[48:49], 0, v[130:131]
	ds_read_b128 v[186:189], v167 offset:32768
	ds_read_b128 v[190:193], v167 offset:33792
	ds_read_b128 v[194:197], v167 offset:34816
	ds_read_b128 v[198:201], v167 offset:35840
	ds_read_b128 v[202:205], v167 offset:36864
	ds_read_b128 v[206:209], v167 offset:37888
	ds_read_b128 v[210:213], v167 offset:38912
	ds_read_b128 v[214:217], v167 offset:39936
	global_load_lds_dwordx4 v[226:227], off
	v_lshl_add_u64 v[226:227], s[48:49], 0, v[134:135]
	s_mov_b32 m0, s56
	s_nop 0
	global_load_lds_dwordx4 v[226:227], off
	s_waitcnt vmcnt(8)
	s_waitcnt lgkmcnt(0)
	s_barrier
	s_setprio 1
	v_mfma_f32_16x16x32_bf16 v[126:129], v[146:149], v[186:189], v[126:129]
	v_mfma_f32_16x16x32_bf16 v[122:125], v[154:157], v[186:189], v[122:125]
	v_mfma_f32_16x16x32_bf16 v[118:121], v[146:149], v[194:197], v[118:121]
	v_mfma_f32_16x16x32_bf16 v[114:117], v[154:157], v[194:197], v[114:117]
	v_mfma_f32_16x16x32_bf16 v[110:113], v[146:149], v[202:205], v[110:113]
	v_mfma_f32_16x16x32_bf16 v[106:109], v[154:157], v[202:205], v[106:109]
	v_mfma_f32_16x16x32_bf16 v[102:105], v[146:149], v[210:213], v[102:105]
	v_mfma_f32_16x16x32_bf16 v[98:101], v[154:157], v[210:213], v[98:101]
	v_mfma_f32_16x16x32_bf16 v[126:129], v[150:153], v[190:193], v[126:129]
	v_mfma_f32_16x16x32_bf16 v[122:125], v[158:161], v[190:193], v[122:125]
	v_mfma_f32_16x16x32_bf16 v[118:121], v[150:153], v[198:201], v[118:121]
	v_mfma_f32_16x16x32_bf16 v[114:117], v[158:161], v[198:201], v[114:117]
	v_mfma_f32_16x16x32_bf16 v[110:113], v[150:153], v[206:209], v[110:113]
	v_mfma_f32_16x16x32_bf16 v[106:109], v[158:161], v[206:209], v[106:109]
	v_mfma_f32_16x16x32_bf16 v[102:105], v[150:153], v[214:217], v[102:105]
	v_mfma_f32_16x16x32_bf16 v[98:101], v[158:161], v[214:217], v[98:101]
	v_mfma_f32_16x16x32_bf16 v[94:97], v[168:171], v[186:189], v[94:97]
	v_mfma_f32_16x16x32_bf16 v[90:93], v[176:179], v[186:189], v[90:93]
	v_mfma_f32_16x16x32_bf16 v[86:89], v[168:171], v[194:197], v[86:89]
	v_mfma_f32_16x16x32_bf16 v[82:85], v[176:179], v[194:197], v[82:85]
	v_mfma_f32_16x16x32_bf16 v[78:81], v[168:171], v[202:205], v[78:81]
	v_mfma_f32_16x16x32_bf16 v[74:77], v[176:179], v[202:205], v[74:77]
	v_mfma_f32_16x16x32_bf16 v[70:73], v[168:171], v[210:213], v[70:73]
	v_mfma_f32_16x16x32_bf16 v[66:69], v[176:179], v[210:213], v[66:69]
	v_mfma_f32_16x16x32_bf16 v[94:97], v[172:175], v[190:193], v[94:97]
	v_mfma_f32_16x16x32_bf16 v[90:93], v[180:183], v[190:193], v[90:93]
	v_mfma_f32_16x16x32_bf16 v[86:89], v[172:175], v[198:201], v[86:89]
	v_mfma_f32_16x16x32_bf16 v[82:85], v[180:183], v[198:201], v[82:85]
	v_mfma_f32_16x16x32_bf16 v[78:81], v[172:175], v[206:209], v[78:81]
	v_mfma_f32_16x16x32_bf16 v[74:77], v[180:183], v[206:209], v[74:77]
	v_mfma_f32_16x16x32_bf16 v[70:73], v[172:175], v[214:217], v[70:73]
	v_mfma_f32_16x16x32_bf16 v[66:69], v[180:183], v[214:217], v[66:69]
	s_setprio 0
	s_barrier
; #define PG8_STAGE(bufoff, gbase, voff) do { _Pragma("unroll") for (int _i = 0; _i < 2; ++_i) \
;         __builtin_amdgcn_global_load_lds((const unsigned*)((const char*)(gbase) + (voff)[_i]), (LAS unsigned*)(lds + (bufoff) + ldsw + _i * 8192), 16, 0, 0); } while (0)
; #define PG8_LDA(dst, b, h) do { _Pragma("unroll") for (int m = 0; m < 4; ++m) _Pragma("unroll") for (int k = 0; k < 2; ++k) dst[m][k] = *(const LAS bf16x8*)(lds + PG8_SA(b, h) + aoff + m * 2048 + k * 1024); } while (0)
; #define PG8_LDB(dst, b, h) do { _Pragma("unroll") for (int n = 0; n < 2; ++n) _Pragma("unroll") for (int k = 0; k < 2; ++k) dst[n][k] = *(const LAS bf16x8*)(lds + PG8_SB(b, h) + boff + n * 2048 + k * 1024); } while (0)
; #define PG8_MMA(ai, bj, At, Bt) do { __builtin_amdgcn_s_setprio(1); _Pragma("unroll") for (int m = 0; m < 4; ++m) _Pragma("unroll") for (int n = 0; n < 2; ++n) _Pragma("unroll") for (int k = 0; k < 2; ++k) \
;         acc[ai][bj][m][n] = __builtin_amdgcn_mfma_f32_16x16x32_bf16(Bt[n][k], At[m][k], acc[ai][bj][m][n], 0, 0, 0); __builtin_amdgcn_s_setprio(0); } while (0)
; #define PG8_WAIT_V(n) asm volatile("s_waitcnt vmcnt(" #n ")" ::: "memory")
; #define PG8_WAIT_L(n) asm volatile("s_waitcnt lgkmcnt(" #n ")" ::: "memory")
; #define PG8_BAR __builtin_amdgcn_s_barrier()
; #define PG8_SCHED __builtin_amdgcn_sched_barrier(0)
; template <class Epi, class Sched>
; DI void gemm_phase(LAS unsigned char* lds, const Gemm g, const Sched& S, const Epi& E) {
;     ...
;         for (int t = 0; t < nt; t += 2) {
;             const bool last = (t == nt - 2);
;             const char* a1 = cA + (size_t)(t + 1) * kstep;
;             const char* a2 = last ? nA : cA + (size_t)(t + 2) * kstep; const char* b2 = last ? nB : cB + (size_t)(t + 2) * kstep;
;             const char* a3 = a2 + kstep; const char* b3 = b2 + kstep;
;             PG8_LDB(B0, 0, 0); PG8_LDB(B1, 0, 1); PG8_SCHED; PG8_LDA(At, 0, 0); PG8_STAGE(PG8_SA(1, 1), a1 + hstepA, voffA);
;             PG8_WAIT_V(8); PG8_WAIT_L(0); PG8_BAR; PG8_MMA(0, 0, At, B0); PG8_MMA(0, 1, At, B1); PG8_BAR; PG8_SCHED;
;     ...
;             PG8_LDA(At, 1, 1); PG8_STAGE(PG8_SB(1, 0), b3, voffB); PG8_STAGE(PG8_SB(1, 1), b3 + hstepB, voffB); PG8_STAGE(PG8_SA(1, 0), a3, voffA);
;             PG8_WAIT_V(8); PG8_WAIT_L(0); PG8_BAR; PG8_MMA(1, 0, At, B0); PG8_MMA(1, 1, At, B1); PG8_BAR; PG8_SCHED;
	s_add_i32 s48, s73, s52
	v_lshl_add_u64 v[218:219], v[218:219], 0, s[20:21]
	s_mov_b32 m0, s48
	ds_read_b128 v[186:189], v167 offset:49152
	ds_read_b128 v[190:193], v167 offset:50176
	ds_read_b128 v[194:197], v167 offset:51200
	ds_read_b128 v[198:201], v167 offset:52224
	ds_read_b128 v[202:205], v167 offset:53248
	ds_read_b128 v[206:209], v167 offset:54272
	ds_read_b128 v[210:213], v167 offset:55296
	ds_read_b128 v[214:217], v167 offset:56320
	global_load_lds_dwordx4 v[218:219], off
	s_add_i32 m0, s48, 0x2000
	s_add_u32 s46, s46, 0x20080
	v_lshl_add_u64 v[218:219], v[220:221], 0, s[20:21]
	s_addc_u32 s47, s47, 0
	s_add_i32 s48, s74, s52
	global_load_lds_dwordx4 v[218:219], off
	v_lshl_add_u64 v[218:219], s[46:47], 0, v[132:133]
	s_mov_b32 m0, s48
	s_nop 0
	global_load_lds_dwordx4 v[218:219], off
	v_lshl_add_u64 v[218:219], s[46:47], 0, v[136:137]
	s_add_i32 m0, s48, 0x2000
	s_nop 0
	global_load_lds_dwordx4 v[218:219], off
	v_lshl_add_u64 v[218:219], v[222:223], 0, s[20:21]
	s_mov_b32 m0, s61
	s_nop 0
	global_load_lds_dwordx4 v[218:219], off
	v_lshl_add_u64 v[218:219], v[224:225], 0, s[20:21]
	s_mov_b32 m0, s62
	s_nop 0
	global_load_lds_dwordx4 v[218:219], off
	s_waitcnt vmcnt(8)
	s_waitcnt lgkmcnt(0)
	s_barrier
	s_setprio 1
	v_mfma_f32_16x16x32_bf16 v[62:65], v[146:149], v[186:189], v[62:65]
	v_mfma_f32_16x16x32_bf16 v[58:61], v[154:157], v[186:189], v[58:61]
	v_mfma_f32_16x16x32_bf16 v[54:57], v[146:149], v[194:197], v[54:57]
	v_mfma_f32_16x16x32_bf16 v[50:53], v[154:157], v[194:197], v[50:53]
	v_mfma_f32_16x16x32_bf16 v[46:49], v[146:149], v[202:205], v[46:49]
	v_mfma_f32_16x16x32_bf16 v[42:45], v[154:157], v[202:205], v[42:45]
	v_mfma_f32_16x16x32_bf16 v[38:41], v[146:149], v[210:213], v[38:41]
	v_mfma_f32_16x16x32_bf16 v[34:37], v[154:157], v[210:213], v[34:37]
	v_mfma_f32_16x16x32_bf16 v[62:65], v[150:153], v[190:193], v[62:65]
	v_mfma_f32_16x16x32_bf16 v[58:61], v[158:161], v[190:193], v[58:61]
	v_mfma_f32_16x16x32_bf16 v[54:57], v[150:153], v[198:201], v[54:57]
	v_mfma_f32_16x16x32_bf16 v[50:53], v[158:161], v[198:201], v[50:53]
	v_mfma_f32_16x16x32_bf16 v[46:49], v[150:153], v[206:209], v[46:49]
	v_mfma_f32_16x16x32_bf16 v[42:45], v[158:161], v[206:209], v[42:45]
	v_mfma_f32_16x16x32_bf16 v[38:41], v[150:153], v[214:217], v[38:41]
	v_mfma_f32_16x16x32_bf16 v[34:37], v[158:161], v[214:217], v[34:37]
	v_mfma_f32_16x16x32_bf16 v[30:33], v[168:171], v[186:189], v[30:33]
	v_mfma_f32_16x16x32_bf16 v[26:29], v[176:179], v[186:189], v[26:29]
	v_mfma_f32_16x16x32_bf16 v[22:25], v[168:171], v[194:197], v[22:25]
	v_mfma_f32_16x16x32_bf16 v[18:21], v[176:179], v[194:197], v[18:21]
	v_mfma_f32_16x16x32_bf16 v[14:17], v[168:171], v[202:205], v[14:17]
	v_mfma_f32_16x16x32_bf16 v[10:13], v[176:179], v[202:205], v[10:13]
	v_mfma_f32_16x16x32_bf16 v[6:9], v[168:171], v[210:213], v[6:9]
	v_mfma_f32_16x16x32_bf16 v[2:5], v[176:179], v[210:213], v[2:5]
	v_mfma_f32_16x16x32_bf16 v[30:33], v[172:175], v[190:193], v[30:33]
	v_mfma_f32_16x16x32_bf16 v[26:29], v[180:183], v[190:193], v[26:29]
	v_mfma_f32_16x16x32_bf16 v[22:25], v[172:175], v[198:201], v[22:25]
	v_mfma_f32_16x16x32_bf16 v[18:21], v[180:183], v[198:201], v[18:21]
	v_mfma_f32_16x16x32_bf16 v[14:17], v[172:175], v[206:209], v[14:17]
	v_mfma_f32_16x16x32_bf16 v[10:13], v[180:183], v[206:209], v[10:13]
	v_mfma_f32_16x16x32_bf16 v[6:9], v[172:175], v[214:217], v[6:9]
	v_mfma_f32_16x16x32_bf16 v[2:5], v[180:183], v[214:217], v[2:5]
	s_setprio 0
	s_barrier
	s_add_i32 s72, s72, 2
	s_add_u32 s44, s44, 0x100
	s_addc_u32 s45, s45, 0
	s_add_u32 s70, s70, 0x100
	s_addc_u32 s71, s71, 0
	s_cmp_gt_u32 s72, 5
.LBB0_972:
	v_add_u32_e32 v158, s64, v162
	v_add_u32_e32 v180, s65, v162
	ds_read_b128 v[146:149], v158
	ds_read_b128 v[150:153], v158 offset:1024
	ds_read_b128 v[154:157], v158 offset:2048
	ds_read_b128 v[158:161], v158 offset:3072
	ds_read_b128 v[168:171], v180
	ds_read_b128 v[172:175], v180 offset:1024
	ds_read_b128 v[176:179], v180 offset:2048
	ds_read_b128 v[180:183], v180 offset:3072
	s_add_u32 s46, s44, 0xfffe0080
	s_addc_u32 s47, s45, -1
	s_cmp_eq_u32 s72, 4
	s_cselect_b32 s49, s39, s47
	s_cselect_b32 s48, s68, s46
	s_cselect_b32 s47, s37, s71
	s_cselect_b32 s46, s69, s70
	v_lshl_add_u64 v[218:219], s[44:45], 0, v[138:139]
	s_add_i32 m0, s53, 0xc000
	ds_read_b128 v[186:189], v167
	ds_read_b128 v[190:193], v167 offset:1024
	ds_read_b128 v[194:197], v167 offset:2048
	ds_read_b128 v[198:201], v167 offset:3072
	ds_read_b128 v[202:205], v167 offset:4096
	ds_read_b128 v[206:209], v167 offset:5120
	ds_read_b128 v[210:213], v167 offset:6144
	ds_read_b128 v[214:217], v167 offset:7168
	global_load_lds_dwordx4 v[218:219], off
	v_lshl_add_u64 v[218:219], s[44:45], 0, v[140:141]
	s_add_i32 m0, s53, 0xe000
	s_nop 0
	global_load_lds_dwordx4 v[218:219], off
	s_waitcnt vmcnt(8)
	s_waitcnt lgkmcnt(0)
	s_barrier
; #define PG8_STAGE(bufoff, gbase, voff) do { _Pragma("unroll") for (int _i = 0; _i < 2; ++_i) \
;         __builtin_amdgcn_global_load_lds((const unsigned*)((const char*)(gbase) + (voff)[_i]), (LAS unsigned*)(lds + (bufoff) + ldsw + _i * 8192), 16, 0, 0); } while (0)
; #define PG8_LDA(dst, b, h) do { _Pragma("unroll") for (int m = 0; m < 4; ++m) _Pragma("unroll") for (int k = 0; k < 2; ++k) dst[m][k] = *(const LAS bf16x8*)(lds + PG8_SA(b, h) + aoff + m * 2048 + k * 1024); } while (0)
; #define PG8_MMA(ai, bj, At, Bt) do { __builtin_amdgcn_s_setprio(1); _Pragma("unroll") for (int m = 0; m < 4; ++m) _Pragma("unroll") for (int n = 0; n < 2; ++n) _Pragma("unroll") for (int k = 0; k < 2; ++k) \
;         acc[ai][bj][m][n] = __builtin_amdgcn_mfma_f32_16x16x32_bf16(Bt[n][k], At[m][k], acc[ai][bj][m][n], 0, 0, 0); __builtin_amdgcn_s_setprio(0); } while (0)
; #define PG8_WAIT_V(n) asm volatile("s_waitcnt vmcnt(" #n ")" ::: "memory")
; #define PG8_WAIT_L(n) asm volatile("s_waitcnt lgkmcnt(" #n ")" ::: "memory")
; #define PG8_BAR __builtin_amdgcn_s_barrier()
; #define PG8_SCHED __builtin_amdgcn_sched_barrier(0)
; template <class Epi, class Sched>
; DI void gemm_phase(LAS unsigned char* lds, const Gemm g, const Sched& S, const Epi& E) {
;     ...
;             PG8_WAIT_V(8); PG8_WAIT_L(0); PG8_BAR; PG8_MMA(0, 0, At, B0); PG8_MMA(0, 1, At, B1); PG8_BAR; PG8_SCHED;
;             PG8_LDA(At, 0, 1); PG8_STAGE(PG8_SB(0, 0), b2, voffB); PG8_STAGE(PG8_SB(0, 1), b2 + hstepB, voffB); PG8_STAGE(PG8_SA(0, 0), a2, voffA);
;             PG8_WAIT_V(8); PG8_WAIT_L(0); PG8_BAR; PG8_MMA(1, 0, At, B0); PG8_MMA(1, 1, At, B1); PG8_BAR; PG8_SCHED;
	s_setprio 1
	v_mfma_f32_16x16x32_bf16 v[126:129], v[146:149], v[186:189], v[126:129]
	v_mfma_f32_16x16x32_bf16 v[122:125], v[154:157], v[186:189], v[122:125]
	v_mfma_f32_16x16x32_bf16 v[118:121], v[146:149], v[194:197], v[118:121]
	v_mfma_f32_16x16x32_bf16 v[114:117], v[154:157], v[194:197], v[114:117]
	v_mfma_f32_16x16x32_bf16 v[110:113], v[146:149], v[202:205], v[110:113]
	v_mfma_f32_16x16x32_bf16 v[106:109], v[154:157], v[202:205], v[106:109]
	v_mfma_f32_16x16x32_bf16 v[102:105], v[146:149], v[210:213], v[102:105]
	v_mfma_f32_16x16x32_bf16 v[98:101], v[154:157], v[210:213], v[98:101]
	v_mfma_f32_16x16x32_bf16 v[126:129], v[150:153], v[190:193], v[126:129]
	v_mfma_f32_16x16x32_bf16 v[122:125], v[158:161], v[190:193], v[122:125]
	v_mfma_f32_16x16x32_bf16 v[118:121], v[150:153], v[198:201], v[118:121]
	v_mfma_f32_16x16x32_bf16 v[114:117], v[158:161], v[198:201], v[114:117]
	v_mfma_f32_16x16x32_bf16 v[110:113], v[150:153], v[206:209], v[110:113]
	v_mfma_f32_16x16x32_bf16 v[106:109], v[158:161], v[206:209], v[106:109]
	v_mfma_f32_16x16x32_bf16 v[102:105], v[150:153], v[214:217], v[102:105]
	v_mfma_f32_16x16x32_bf16 v[98:101], v[158:161], v[214:217], v[98:101]
	v_mfma_f32_16x16x32_bf16 v[94:97], v[168:171], v[186:189], v[94:97]
	v_mfma_f32_16x16x32_bf16 v[90:93], v[176:179], v[186:189], v[90:93]
	v_mfma_f32_16x16x32_bf16 v[86:89], v[168:171], v[194:197], v[86:89]
	v_mfma_f32_16x16x32_bf16 v[82:85], v[176:179], v[194:197], v[82:85]
	v_mfma_f32_16x16x32_bf16 v[78:81], v[168:171], v[202:205], v[78:81]
	v_mfma_f32_16x16x32_bf16 v[74:77], v[176:179], v[202:205], v[74:77]
	v_mfma_f32_16x16x32_bf16 v[70:73], v[168:171], v[210:213], v[70:73]
	v_mfma_f32_16x16x32_bf16 v[66:69], v[176:179], v[210:213], v[66:69]
	v_mfma_f32_16x16x32_bf16 v[94:97], v[172:175], v[190:193], v[94:97]
	v_mfma_f32_16x16x32_bf16 v[90:93], v[180:183], v[190:193], v[90:93]
	v_mfma_f32_16x16x32_bf16 v[86:89], v[172:175], v[198:201], v[86:89]
	v_mfma_f32_16x16x32_bf16 v[82:85], v[180:183], v[198:201], v[82:85]
	v_mfma_f32_16x16x32_bf16 v[78:81], v[172:175], v[206:209], v[78:81]
	v_mfma_f32_16x16x32_bf16 v[74:77], v[180:183], v[206:209], v[74:77]
	v_mfma_f32_16x16x32_bf16 v[70:73], v[172:175], v[214:217], v[70:73]
	v_mfma_f32_16x16x32_bf16 v[66:69], v[180:183], v[214:217], v[66:69]
	s_setprio 0
	s_barrier
	s_add_i32 s73, s64, s52
	v_lshl_add_u64 v[218:219], s[46:47], 0, v[132:133]
	s_mov_b32 m0, s73
	ds_read_b128 v[186:189], v167 offset:16384
	ds_read_b128 v[190:193], v167 offset:17408
	ds_read_b128 v[194:197], v167 offset:18432
	ds_read_b128 v[198:201], v167 offset:19456
	ds_read_b128 v[202:205], v167 offset:20480
	ds_read_b128 v[206:209], v167 offset:21504
	ds_read_b128 v[210:213], v167 offset:22528
	ds_read_b128 v[214:217], v167 offset:23552
	global_load_lds_dwordx4 v[218:219], off
	s_add_i32 m0, s73, 0x2000
	s_add_u32 s74, s46, 0x20000
	v_lshl_add_u64 v[220:221], s[46:47], 0, v[136:137]
	s_addc_u32 s75, s47, 0
	s_add_i32 s73, s65, s52
	global_load_lds_dwordx4 v[220:221], off
	v_lshl_add_u64 v[222:223], s[74:75], 0, v[132:133]
	s_mov_b32 m0, s73
	v_lshl_add_u64 v[224:225], s[48:49], 0, v[134:135]
	global_load_lds_dwordx4 v[222:223], off
	v_lshl_add_u64 v[222:223], s[74:75], 0, v[136:137]
	s_add_i32 m0, s73, 0x2000
	s_nop 0
	global_load_lds_dwordx4 v[222:223], off
	v_lshl_add_u64 v[222:223], s[48:49], 0, v[130:131]
	s_mov_b32 m0, s53
	s_nop 0
	global_load_lds_dwordx4 v[222:223], off
	s_mov_b32 m0, s54
	s_nop 0
	global_load_lds_dwordx4 v[224:225], off
	s_waitcnt vmcnt(8)
	s_waitcnt lgkmcnt(0)
	s_barrier
	s_setprio 1
	v_mfma_f32_16x16x32_bf16 v[62:65], v[146:149], v[186:189], v[62:65]
	v_mfma_f32_16x16x32_bf16 v[58:61], v[154:157], v[186:189], v[58:61]
	v_mfma_f32_16x16x32_bf16 v[54:57], v[146:149], v[194:197], v[54:57]
	v_mfma_f32_16x16x32_bf16 v[50:53], v[154:157], v[194:197], v[50:53]
	v_mfma_f32_16x16x32_bf16 v[46:49], v[146:149], v[202:205], v[46:49]
	v_mfma_f32_16x16x32_bf16 v[42:45], v[154:157], v[202:205], v[42:45]
	v_mfma_f32_16x16x32_bf16 v[38:41], v[146:149], v[210:213], v[38:41]
	v_mfma_f32_16x16x32_bf16 v[34:37], v[154:157], v[210:213], v[34:37]
	v_mfma_f32_16x16x32_bf16 v[62:65], v[150:153], v[190:193], v[62:65]
	v_mfma_f32_16x16x32_bf16 v[58:61], v[158:161], v[190:193], v[58:61]
	v_mfma_f32_16x16x32_bf16 v[54:57], v[150:153], v[198:201], v[54:57]
	v_mfma_f32_16x16x32_bf16 v[50:53], v[158:161], v[198:201], v[50:53]
	v_mfma_f32_16x16x32_bf16 v[46:49], v[150:153], v[206:209], v[46:49]
	v_mfma_f32_16x16x32_bf16 v[42:45], v[158:161], v[206:209], v[42:45]
	v_mfma_f32_16x16x32_bf16 v[38:41], v[150:153], v[214:217], v[38:41]
	v_mfma_f32_16x16x32_bf16 v[34:37], v[158:161], v[214:217], v[34:37]
	v_mfma_f32_16x16x32_bf16 v[30:33], v[168:171], v[186:189], v[30:33]
	v_mfma_f32_16x16x32_bf16 v[26:29], v[176:179], v[186:189], v[26:29]
	v_mfma_f32_16x16x32_bf16 v[22:25], v[168:171], v[194:197], v[22:25]
	v_mfma_f32_16x16x32_bf16 v[18:21], v[176:179], v[194:197], v[18:21]
	v_mfma_f32_16x16x32_bf16 v[14:17], v[168:171], v[202:205], v[14:17]
	v_mfma_f32_16x16x32_bf16 v[10:13], v[176:179], v[202:205], v[10:13]
	v_mfma_f32_16x16x32_bf16 v[6:9], v[168:171], v[210:213], v[6:9]
	v_mfma_f32_16x16x32_bf16 v[2:5], v[176:179], v[210:213], v[2:5]
	v_mfma_f32_16x16x32_bf16 v[30:33], v[172:175], v[190:193], v[30:33]
	v_mfma_f32_16x16x32_bf16 v[26:29], v[180:183], v[190:193], v[26:29]
	v_mfma_f32_16x16x32_bf16 v[22:25], v[172:175], v[198:201], v[22:25]
	v_mfma_f32_16x16x32_bf16 v[18:21], v[180:183], v[198:201], v[18:21]
	v_mfma_f32_16x16x32_bf16 v[14:17], v[172:175], v[206:209], v[14:17]
	v_mfma_f32_16x16x32_bf16 v[10:13], v[180:183], v[206:209], v[10:13]
	v_mfma_f32_16x16x32_bf16 v[6:9], v[172:175], v[214:217], v[6:9]
	v_mfma_f32_16x16x32_bf16 v[2:5], v[180:183], v[214:217], v[2:5]
	s_setprio 0
	s_barrier
; #define PG8_STAGE(bufoff, gbase, voff) do { _Pragma("unroll") for (int _i = 0; _i < 2; ++_i) \
;         __builtin_amdgcn_global_load_lds((const unsigned*)((const char*)(gbase) + (voff)[_i]), (LAS unsigned*)(lds + (bufoff) + ldsw + _i * 8192), 16, 0, 0); } while (0)
; #define PG8_LDA(dst, b, h) do { _Pragma("unroll") for (int m = 0; m < 4; ++m) _Pragma("unroll") for (int k = 0; k < 2; ++k) dst[m][k] = *(const LAS bf16x8*)(lds + PG8_SA(b, h) + aoff + m * 2048 + k * 1024); } while (0)
; #define PG8_LDB(dst, b, h) do { _Pragma("unroll") for (int n = 0; n < 2; ++n) _Pragma("unroll") for (int k = 0; k < 2; ++k) dst[n][k] = *(const LAS bf16x8*)(lds + PG8_SB(b, h) + boff + n * 2048 + k * 1024); } while (0)
; #define PG8_MMA(ai, bj, At, Bt) do { __builtin_amdgcn_s_setprio(1); _Pragma("unroll") for (int m = 0; m < 4; ++m) _Pragma("unroll") for (int n = 0; n < 2; ++n) _Pragma("unroll") for (int k = 0; k < 2; ++k) \
;         acc[ai][bj][m][n] = __builtin_amdgcn_mfma_f32_16x16x32_bf16(Bt[n][k], At[m][k], acc[ai][bj][m][n], 0, 0, 0); __builtin_amdgcn_s_setprio(0); } while (0)
; #define PG8_WAIT_V(n) asm volatile("s_waitcnt vmcnt(" #n ")" ::: "memory")
; #define PG8_WAIT_L(n) asm volatile("s_waitcnt lgkmcnt(" #n ")" ::: "memory")
; #define PG8_BAR __builtin_amdgcn_s_barrier()
; #define PG8_SCHED __builtin_amdgcn_sched_barrier(0)
; template <class Epi, class Sched>
; DI void gemm_phase(LAS unsigned char* lds, const Gemm g, const Sched& S, const Epi& E) {
;     ...
;             PG8_LDB(B0, 1, 0); PG8_LDB(B1, 1, 1); PG8_SCHED; PG8_LDA(At, 1, 0); PG8_STAGE(PG8_SA(0, 1), a2 + hstepA, voffA);
;             PG8_WAIT_V(8); PG8_WAIT_L(0); PG8_BAR; PG8_MMA(0, 0, At, B0); PG8_MMA(0, 1, At, B1); PG8_BAR; PG8_SCHED;
	s_add_i32 s73, 0, 0x18000
	s_add_i32 s74, 0, 0x1c000
	v_add_u32_e32 v158, s73, v162
	v_add_u32_e32 v180, s74, v162
	ds_read_b128 v[146:149], v158
	ds_read_b128 v[150:153], v158 offset:1024
	ds_read_b128 v[154:157], v158 offset:2048
	ds_read_b128 v[158:161], v158 offset:3072
	ds_read_b128 v[168:171], v180
	ds_read_b128 v[172:175], v180 offset:1024
	ds_read_b128 v[176:179], v180 offset:2048
	ds_read_b128 v[180:183], v180 offset:3072
	s_add_u32 s48, s48, 0x20000
	s_addc_u32 s49, s49, 0
	s_mov_b32 m0, s55
	v_lshl_add_u64 v[226:227], s[48:49], 0, v[130:131]
	ds_read_b128 v[186:189], v167 offset:32768
	ds_read_b128 v[190:193], v167 offset:33792
	ds_read_b128 v[194:197], v167 offset:34816
	ds_read_b128 v[198:201], v167 offset:35840
	ds_read_b128 v[202:205], v167 offset:36864
	ds_read_b128 v[206:209], v167 offset:37888
	ds_read_b128 v[210:213], v167 offset:38912
	ds_read_b128 v[214:217], v167 offset:39936
	global_load_lds_dwordx4 v[226:227], off
	v_lshl_add_u64 v[226:227], s[48:49], 0, v[134:135]
	s_mov_b32 m0, s56
	s_nop 0
	global_load_lds_dwordx4 v[226:227], off
	s_waitcnt vmcnt(8)
	s_waitcnt lgkmcnt(0)
	s_barrier
	s_setprio 1
	v_mfma_f32_16x16x32_bf16 v[126:129], v[146:149], v[186:189], v[126:129]
	v_mfma_f32_16x16x32_bf16 v[122:125], v[154:157], v[186:189], v[122:125]
	v_mfma_f32_16x16x32_bf16 v[118:121], v[146:149], v[194:197], v[118:121]
	v_mfma_f32_16x16x32_bf16 v[114:117], v[154:157], v[194:197], v[114:117]
	v_mfma_f32_16x16x32_bf16 v[110:113], v[146:149], v[202:205], v[110:113]
	v_mfma_f32_16x16x32_bf16 v[106:109], v[154:157], v[202:205], v[106:109]
	v_mfma_f32_16x16x32_bf16 v[102:105], v[146:149], v[210:213], v[102:105]
	v_mfma_f32_16x16x32_bf16 v[98:101], v[154:157], v[210:213], v[98:101]
	v_mfma_f32_16x16x32_bf16 v[126:129], v[150:153], v[190:193], v[126:129]
	v_mfma_f32_16x16x32_bf16 v[122:125], v[158:161], v[190:193], v[122:125]
	v_mfma_f32_16x16x32_bf16 v[118:121], v[150:153], v[198:201], v[118:121]
	v_mfma_f32_16x16x32_bf16 v[114:117], v[158:161], v[198:201], v[114:117]
	v_mfma_f32_16x16x32_bf16 v[110:113], v[150:153], v[206:209], v[110:113]
	v_mfma_f32_16x16x32_bf16 v[106:109], v[158:161], v[206:209], v[106:109]
	v_mfma_f32_16x16x32_bf16 v[102:105], v[150:153], v[214:217], v[102:105]
	v_mfma_f32_16x16x32_bf16 v[98:101], v[158:161], v[214:217], v[98:101]
	v_mfma_f32_16x16x32_bf16 v[94:97], v[168:171], v[186:189], v[94:97]
	v_mfma_f32_16x16x32_bf16 v[90:93], v[176:179], v[186:189], v[90:93]
	v_mfma_f32_16x16x32_bf16 v[86:89], v[168:171], v[194:197], v[86:89]
	v_mfma_f32_16x16x32_bf16 v[82:85], v[176:179], v[194:197], v[82:85]
	v_mfma_f32_16x16x32_bf16 v[78:81], v[168:171], v[202:205], v[78:81]
	v_mfma_f32_16x16x32_bf16 v[74:77], v[176:179], v[202:205], v[74:77]
	v_mfma_f32_16x16x32_bf16 v[70:73], v[168:171], v[210:213], v[70:73]
	v_mfma_f32_16x16x32_bf16 v[66:69], v[176:179], v[210:213], v[66:69]
	v_mfma_f32_16x16x32_bf16 v[94:97], v[172:175], v[190:193], v[94:97]
	v_mfma_f32_16x16x32_bf16 v[90:93], v[180:183], v[190:193], v[90:93]
	v_mfma_f32_16x16x32_bf16 v[86:89], v[172:175], v[198:201], v[86:89]
	v_mfma_f32_16x16x32_bf16 v[82:85], v[180:183], v[198:201], v[82:85]
	v_mfma_f32_16x16x32_bf16 v[78:81], v[172:175], v[206:209], v[78:81]
	v_mfma_f32_16x16x32_bf16 v[74:77], v[180:183], v[206:209], v[74:77]
	v_mfma_f32_16x16x32_bf16 v[70:73], v[172:175], v[214:217], v[70:73]
	v_mfma_f32_16x16x32_bf16 v[66:69], v[180:183], v[214:217], v[66:69]
	s_setprio 0
	s_barrier
; #define PG8_STAGE(bufoff, gbase, voff) do { _Pragma("unroll") for (int _i = 0; _i < 2; ++_i) \
;         __builtin_amdgcn_global_load_lds((const unsigned*)((const char*)(gbase) + (voff)[_i]), (LAS unsigned*)(lds + (bufoff) + ldsw + _i * 8192), 16, 0, 0); } while (0)
; #define PG8_LDA(dst, b, h) do { _Pragma("unroll") for (int m = 0; m < 4; ++m) _Pragma("unroll") for (int k = 0; k < 2; ++k) dst[m][k] = *(const LAS bf16x8*)(lds + PG8_SA(b, h) + aoff + m * 2048 + k * 1024); } while (0)
; #define PG8_MMA(ai, bj, At, Bt) do { __builtin_amdgcn_s_setprio(1); _Pragma("unroll") for (int m = 0; m < 4; ++m) _Pragma("unroll") for (int n = 0; n < 2; ++n) _Pragma("unroll") for (int k = 0; k < 2; ++k) \
;         acc[ai][bj][m][n] = __builtin_amdgcn_mfma_f32_16x16x32_bf16(Bt[n][k], At[m][k], acc[ai][bj][m][n], 0, 0, 0); __builtin_amdgcn_s_setprio(0); } while (0)
; #define PG8_WAIT_V(n) asm volatile("s_waitcnt vmcnt(" #n ")" ::: "memory")
; #define PG8_WAIT_L(n) asm volatile("s_waitcnt lgkmcnt(" #n ")" ::: "memory")
; #define PG8_BAR __builtin_amdgcn_s_barrier()
; #define PG8_SCHED __builtin_amdgcn_sched_barrier(0)
; template <class Epi, class Sched>
; DI void gemm_phase(LAS unsigned char* lds, const Gemm g, const Sched& S, const Epi& E) {
;     ...
;             PG8_LDA(At, 1, 1); PG8_STAGE(PG8_SB(1, 0), b3, voffB); PG8_STAGE(PG8_SB(1, 1), b3 + hstepB, voffB); PG8_STAGE(PG8_SA(1, 0), a3, voffA);
;             PG8_WAIT_V(8); PG8_WAIT_L(0); PG8_BAR; PG8_MMA(1, 0, At, B0); PG8_MMA(1, 1, At, B1); PG8_BAR; PG8_SCHED;
;         }
;         if (wr == 0) PG8_BAR;
	s_add_i32 s48, s73, s52
	v_lshl_add_u64 v[218:219], v[218:219], 0, s[20:21]
	s_mov_b32 m0, s48
	ds_read_b128 v[186:189], v167 offset:49152
	ds_read_b128 v[190:193], v167 offset:50176
	ds_read_b128 v[194:197], v167 offset:51200
	ds_read_b128 v[198:201], v167 offset:52224
	ds_read_b128 v[202:205], v167 offset:53248
	ds_read_b128 v[206:209], v167 offset:54272
	ds_read_b128 v[210:213], v167 offset:55296
	ds_read_b128 v[214:217], v167 offset:56320
	global_load_lds_dwordx4 v[218:219], off
	s_add_i32 m0, s48, 0x2000
	s_add_u32 s46, s46, 0x20080
	v_lshl_add_u64 v[218:219], v[220:221], 0, s[20:21]
	s_addc_u32 s47, s47, 0
	s_add_i32 s48, s74, s52
	global_load_lds_dwordx4 v[218:219], off
	v_lshl_add_u64 v[218:219], s[46:47], 0, v[132:133]
	s_mov_b32 m0, s48
	s_nop 0
	global_load_lds_dwordx4 v[218:219], off
	v_lshl_add_u64 v[218:219], s[46:47], 0, v[136:137]
	s_add_i32 m0, s48, 0x2000
	s_nop 0
	global_load_lds_dwordx4 v[218:219], off
	v_lshl_add_u64 v[218:219], v[222:223], 0, s[20:21]
	s_mov_b32 m0, s61
	s_nop 0
	global_load_lds_dwordx4 v[218:219], off
	v_lshl_add_u64 v[218:219], v[224:225], 0, s[20:21]
	s_mov_b32 m0, s62
	s_nop 0
	global_load_lds_dwordx4 v[218:219], off
	s_waitcnt vmcnt(8)
	s_waitcnt lgkmcnt(0)
	s_barrier
	s_setprio 1
	v_mfma_f32_16x16x32_bf16 v[62:65], v[146:149], v[186:189], v[62:65]
	v_mfma_f32_16x16x32_bf16 v[58:61], v[154:157], v[186:189], v[58:61]
	v_mfma_f32_16x16x32_bf16 v[54:57], v[146:149], v[194:197], v[54:57]
	v_mfma_f32_16x16x32_bf16 v[50:53], v[154:157], v[194:197], v[50:53]
	v_mfma_f32_16x16x32_bf16 v[46:49], v[146:149], v[202:205], v[46:49]
	v_mfma_f32_16x16x32_bf16 v[42:45], v[154:157], v[202:205], v[42:45]
	v_mfma_f32_16x16x32_bf16 v[38:41], v[146:149], v[210:213], v[38:41]
	v_mfma_f32_16x16x32_bf16 v[34:37], v[154:157], v[210:213], v[34:37]
	v_mfma_f32_16x16x32_bf16 v[62:65], v[150:153], v[190:193], v[62:65]
	v_mfma_f32_16x16x32_bf16 v[58:61], v[158:161], v[190:193], v[58:61]
	v_mfma_f32_16x16x32_bf16 v[54:57], v[150:153], v[198:201], v[54:57]
	v_mfma_f32_16x16x32_bf16 v[50:53], v[158:161], v[198:201], v[50:53]
	v_mfma_f32_16x16x32_bf16 v[46:49], v[150:153], v[206:209], v[46:49]
	v_mfma_f32_16x16x32_bf16 v[42:45], v[158:161], v[206:209], v[42:45]
	v_mfma_f32_16x16x32_bf16 v[38:41], v[150:153], v[214:217], v[38:41]
	v_mfma_f32_16x16x32_bf16 v[34:37], v[158:161], v[214:217], v[34:37]
	v_mfma_f32_16x16x32_bf16 v[30:33], v[168:171], v[186:189], v[30:33]
	v_mfma_f32_16x16x32_bf16 v[26:29], v[176:179], v[186:189], v[26:29]
	v_mfma_f32_16x16x32_bf16 v[22:25], v[168:171], v[194:197], v[22:25]
	v_mfma_f32_16x16x32_bf16 v[18:21], v[176:179], v[194:197], v[18:21]
	v_mfma_f32_16x16x32_bf16 v[14:17], v[168:171], v[202:205], v[14:17]
	v_mfma_f32_16x16x32_bf16 v[10:13], v[176:179], v[202:205], v[10:13]
	v_mfma_f32_16x16x32_bf16 v[6:9], v[168:171], v[210:213], v[6:9]
	v_mfma_f32_16x16x32_bf16 v[2:5], v[176:179], v[210:213], v[2:5]
	v_mfma_f32_16x16x32_bf16 v[30:33], v[172:175], v[190:193], v[30:33]
	v_mfma_f32_16x16x32_bf16 v[26:29], v[180:183], v[190:193], v[26:29]
	v_mfma_f32_16x16x32_bf16 v[22:25], v[172:175], v[198:201], v[22:25]
	v_mfma_f32_16x16x32_bf16 v[18:21], v[180:183], v[198:201], v[18:21]
	v_mfma_f32_16x16x32_bf16 v[14:17], v[172:175], v[206:209], v[14:17]
	v_mfma_f32_16x16x32_bf16 v[10:13], v[180:183], v[206:209], v[10:13]
	v_mfma_f32_16x16x32_bf16 v[6:9], v[172:175], v[214:217], v[6:9]
	v_mfma_f32_16x16x32_bf16 v[2:5], v[180:183], v[214:217], v[2:5]
	s_setprio 0
	s_barrier
	s_add_i32 s72, s72, 2
	s_add_u32 s44, s44, 0x100
	s_addc_u32 s45, s45, 0
	s_add_u32 s70, s70, 0x100
	s_addc_u32 s71, s71, 0
	s_cmp_gt_u32 s72, 5
	s_cbranch_scc0 .LBB0_972
	s_waitcnt vmcnt(0)
	s_mov_b32 s99, 1
	s_and_b64 vcc, exec, s[34:35]
	s_cbranch_vccz .LBB0_975
	s_barrier

; #define PG8_STAGE(bufoff, gbase, voff) do { _Pragma("unroll") for (int _i = 0; _i < 2; ++_i) \
;         __builtin_amdgcn_global_load_lds((const unsigned*)((const char*)(gbase) + (voff)[_i]), (LAS unsigned*)(lds + (bufoff) + ldsw + _i * 8192), 16, 0, 0); } while (0)
; #define PG8_WAIT_V(n) asm volatile("s_waitcnt vmcnt(" #n ")" ::: "memory")
; #define PG8_BAR __builtin_amdgcn_s_barrier()
; template <class Epi, class Sched>
; DI void gemm_phase(LAS unsigned char* lds, const Gemm g, const Sched& S, const Epi& E) {
;     ...
;     const char* cA = (const char*)(cur.src ? g.A1 : g.A0) + (size_t)cur.pm * tstepA; const char* cB = (const char*)(cur.src ? g.B1 : g.B0) + (size_t)cur.pn * tstepB;
;     PG8_STAGE(PG8_SB(0, 0), cB, voffB); PG8_STAGE(PG8_SB(0, 1), cB + hstepB, voffB); PG8_STAGE(PG8_SA(0, 0), cA, voffA); PG8_STAGE(PG8_SA(0, 1), cA + hstepA, voffA);
;     if (wr == 1) PG8_BAR;
;     PG8_WAIT_V(2); PG8_BAR;
;     PG8_STAGE(PG8_SB(1, 0), cB + kstep, voffB); PG8_STAGE(PG8_SA(1, 0), cA + kstep, voffA); PG8_STAGE(PG8_SB(1, 1), cB + hstepB + kstep, voffB);
;     PG8_WAIT_V(6); PG8_BAR;
;     for (;;) {
.LBB0_1123:
	s_lshl_b32 s5, s5, 5
	s_mov_b64 s[16:17], 0x80
	s_and_b32 s20, s5, 0x60
	s_add_i32 m0, s43, 0x18000
	v_lshl_add_u64 v[8:9], v[8:9], 0, s[16:17]
	s_lshl_b32 s19, s4, 13
	s_lshl_b32 s5, s20, 7
	s_waitcnt vmcnt(2)
	s_barrier
	global_load_lds_dwordx4 v[8:9], off
	v_lshl_add_u64 v[6:7], v[6:7], 0, s[16:17]
	s_add_i32 m0, s43, 0x1a000
	s_add_i32 s57, s43, 0x8000
	s_add_i32 s58, s43, 0xa000
	global_load_lds_dwordx4 v[6:7], off
	v_lshl_add_u64 v[2:3], v[2:3], 0, s[16:17]
	s_mov_b32 m0, s57
	s_add_u32 s6, s46, 0x40080
	global_load_lds_dwordx4 v[2:3], off
	v_lshl_add_u64 v[2:3], v[4:5], 0, s[16:17]
	s_mov_b32 m0, s58
	s_addc_u32 s7, s47, 0
	global_load_lds_dwordx4 v[2:3], off
	s_add_i32 m0, s43, 0x1c000
	v_lshl_add_u64 v[2:3], s[6:7], 0, v[132:133]
	global_load_lds_dwordx4 v[2:3], off
	v_lshl_add_u64 v[2:3], s[6:7], 0, v[136:137]
	s_add_i32 m0, s43, 0x1e000
	v_lshlrev_b32_e32 v5, 2, v184
	global_load_lds_dwordx4 v[2:3], off
	v_bfe_u32 v2, v184, 4, 2
	v_and_b32_e32 v3, 15, v184
	v_lshl_or_b32 v1, s4, 6, v3
	v_lshlrev_b32_e32 v4, 4, v2
	v_lshlrev_b32_e32 v6, 6, v184
	s_movk_i32 s4, 0x3c0
	v_lshl_or_b32 v3, v3, 6, v4
	v_and_b32_e32 v5, 32, v5
	v_and_or_b32 v4, v6, s4, v4
	v_bitop3_b32 v150, s5, v4, v5 bitop3:0xf6
	v_cmp_eq_u32_e64 s[4:5], 0, v2
	v_lshl_or_b32 v151, v2, 3, s20
	v_lshlrev_b32_e32 v2, 8, v184
	v_and_b32_e32 v2, 0x38000, v2
	v_lshlrev_b32_e32 v4, 11, v12
	v_or3_b32 v2, v10, v2, v4
	v_add_u32_e32 v138, v2, v11
	v_lshlrev_b32_e32 v2, 4, v13
	v_and_b32_e32 v2, 0x78000, v2
	s_waitcnt vmcnt(6)
	s_cmpk_lt_u32 s18, 0x100
	v_or3_b32 v2, v10, v2, v4
	v_bitop3_b32 v3, v3, s19, v5 bitop3:0xde
	s_cselect_b64 s[18:19], -1, 0
	v_add_u32_e32 v140, v2, v11
	s_add_i32 s61, 0, 0x10000
	s_add_i32 s62, 0, 0x14000
	v_mbcnt_lo_u32_b32 v2, -1, 0
	s_ashr_i32 s59, s3, 31
	s_ashr_i32 s60, s2, 31
	v_mov_b32_e32 v139, v133
	v_mov_b32_e32 v141, v133
	v_mov_b64_e32 v[142:143], 0x400
	v_mov_b64_e32 v[144:145], 0x3ff
	v_add_u32_e32 v152, s61, v150
	v_add_u32_e32 v153, s62, v150
	v_add_u32_e32 v154, 0, v3
	v_mbcnt_hi_u32_b32 v155, -1, v2
	s_barrier
	s_mov_b32 s99, 0
	s_branch .LBB0_1126

;     DI bool next(int i, Unit& u) const { if (i > 0 || c >= 64) return false; u.pm = c & 31; u.pn = 0; u.src = c >> 5; return true; }
; #define PG8_STAGE(bufoff, gbase, voff) do { _Pragma("unroll") for (int _i = 0; _i < 2; ++_i) \
;         __builtin_amdgcn_global_load_lds((const unsigned*)((const char*)(gbase) + (voff)[_i]), (LAS unsigned*)(lds + (bufoff) + ldsw + _i * 8192), 16, 0, 0); } while (0)
; #define PG8_LDA(dst, b, h) do { _Pragma("unroll") for (int m = 0; m < 4; ++m) _Pragma("unroll") for (int k = 0; k < 2; ++k) dst[m][k] = *(const LAS bf16x8*)(lds + PG8_SA(b, h) + aoff + m * 2048 + k * 1024); } while (0)
; #define PG8_LDB(dst, b, h) do { _Pragma("unroll") for (int n = 0; n < 2; ++n) _Pragma("unroll") for (int k = 0; k < 2; ++k) dst[n][k] = *(const LAS bf16x8*)(lds + PG8_SB(b, h) + boff + n * 2048 + k * 1024); } while (0)
; #define PG8_MMA(ai, bj, At, Bt) do { __builtin_amdgcn_s_setprio(1); _Pragma("unroll") for (int m = 0; m < 4; ++m) _Pragma("unroll") for (int n = 0; n < 2; ++n) _Pragma("unroll") for (int k = 0; k < 2; ++k) \
;         acc[ai][bj][m][n] = __builtin_amdgcn_mfma_f32_16x16x32_bf16(Bt[n][k], At[m][k], acc[ai][bj][m][n], 0, 0, 0); __builtin_amdgcn_s_setprio(0); } while (0)
; template <class Epi, class Sched>
; DI void gemm_phase(LAS unsigned char* lds, const Gemm g, const Sched& S, const Epi& E) {
;     ...
;         const bool has_next = S.next(ui + 1, nxt);
;         E.pre(pre, cur, wr, fr);
;         const char* nA = has_next ? (const char*)(nxt.src ? g.A1 : g.A0) + (size_t)nxt.pm * tstepA : cA; const char* nB = has_next ? (const char*)(nxt.src ? g.B1 : g.B0) + (size_t)nxt.pn * tstepB : cB;
;         for (int t = 0; t < nt; t += 2) {
;             const bool last = (t == nt - 2);
;             const char* a1 = cA + (size_t)(t + 1) * kstep;
;             const char* a2 = last ? nA : cA + (size_t)(t + 2) * kstep; const char* b2 = last ? nB : cB + (size_t)(t + 2) * kstep;
;             const char* a3 = a2 + kstep; const char* b3 = b2 + kstep;
;             PG8_LDB(B0, 0, 0); PG8_LDB(B1, 0, 1); PG8_SCHED; PG8_LDA(At, 0, 0); PG8_STAGE(PG8_SA(1, 1), a1 + hstepA, voffA);
;             PG8_WAIT_V(8); PG8_WAIT_L(0); PG8_BAR; PG8_MMA(0, 0, At, B0); PG8_MMA(0, 1, At, B1); PG8_BAR; PG8_SCHED;
;             PG8_LDA(At, 0, 1); PG8_STAGE(PG8_SB(0, 0), b2, voffB); PG8_STAGE(PG8_SB(0, 1), b2 + hstepB, voffB); PG8_STAGE(PG8_SA(0, 0), a2, voffA);
.LBB0_1132:
	s_ashr_i32 s35, s34, 31
	s_lshl_b64 s[36:37], s[34:35], 19
	s_add_u32 s36, s28, s36
	s_addc_u32 s37, s29, s37
	s_and_b64 s[38:39], s[6:7], exec
	s_cselect_b32 s35, s37, s45
	s_cselect_b32 s41, s36, s44
	s_ashr_i32 s21, s20, 31
	s_lshl_b64 s[38:39], s[20:21], 19
	s_add_u32 s38, s50, s38
	s_addc_u32 s39, s51, s39
	s_and_b64 s[48:49], s[6:7], exec
	s_cselect_b32 s21, s39, s47
	s_cselect_b32 s63, s38, s46
	s_add_u32 s44, s44, 0x40080
	s_addc_u32 s45, s45, 0
	s_add_u32 s64, s46, 0x100
	s_addc_u32 s65, s47, 0
	s_mov_b32 s66, -2
	s_waitcnt lgkmcnt(0)
	ds_read_b128 v[146:149], v152
	ds_read_b128 v[156:159], v152 offset:1024
	ds_read_b128 v[160:163], v152 offset:2048
	ds_read_b128 v[164:167], v152 offset:3072
	ds_read_b128 v[168:171], v153
	ds_read_b128 v[172:175], v153 offset:1024
	ds_read_b128 v[176:179], v153 offset:2048
	ds_read_b128 v[180:183], v153 offset:3072
	s_add_u32 s46, s44, 0xfffc0080
	s_addc_u32 s47, s45, -1
	s_cmp_eq_u32 s66, 12
	s_cselect_b32 s49, s35, s47
	s_cselect_b32 s48, s41, s46
	s_cselect_b32 s47, s21, s65
	s_cselect_b32 s46, s63, s64
	v_lshl_add_u64 v[218:219], s[44:45], 0, v[138:139]
	s_add_i32 m0, s43, 0xc000
	ds_read_b128 v[186:189], v154
	ds_read_b128 v[190:193], v154 offset:1024
	ds_read_b128 v[194:197], v154 offset:2048
	ds_read_b128 v[198:201], v154 offset:3072
	ds_read_b128 v[202:205], v154 offset:4096
	ds_read_b128 v[206:209], v154 offset:5120
	ds_read_b128 v[210:213], v154 offset:6144
	ds_read_b128 v[214:217], v154 offset:7168
	global_load_lds_dwordx4 v[218:219], off
	v_lshl_add_u64 v[218:219], s[44:45], 0, v[140:141]
	s_add_i32 m0, s43, 0xe000
	s_nop 0
	global_load_lds_dwordx4 v[218:219], off
	s_cmp_lg_u32 s99, 0
	s_cbranch_scc1 .Lpk4_w1
	s_waitcnt vmcnt(8)
.Lpk4_w1:
	s_waitcnt lgkmcnt(0)
	s_barrier
	s_setprio 1
	v_mfma_f32_16x16x32_bf16 v[126:129], v[146:149], v[186:189], 0
	v_mfma_f32_16x16x32_bf16 v[122:125], v[160:163], v[186:189], 0
	v_mfma_f32_16x16x32_bf16 v[110:113], v[146:149], v[194:197], 0
	v_mfma_f32_16x16x32_bf16 v[106:109], v[160:163], v[194:197], 0
	v_mfma_f32_16x16x32_bf16 v[94:97], v[146:149], v[202:205], 0
	v_mfma_f32_16x16x32_bf16 v[90:93], v[160:163], v[202:205], 0
	v_mfma_f32_16x16x32_bf16 v[78:81], v[146:149], v[210:213], 0
	v_mfma_f32_16x16x32_bf16 v[74:77], v[160:163], v[210:213], 0
	v_mfma_f32_16x16x32_bf16 v[126:129], v[156:159], v[190:193], v[126:129]
	v_mfma_f32_16x16x32_bf16 v[122:125], v[164:167], v[190:193], v[122:125]
	v_mfma_f32_16x16x32_bf16 v[110:113], v[156:159], v[198:201], v[110:113]
	v_mfma_f32_16x16x32_bf16 v[106:109], v[164:167], v[198:201], v[106:109]
	v_mfma_f32_16x16x32_bf16 v[94:97], v[156:159], v[206:209], v[94:97]
	v_mfma_f32_16x16x32_bf16 v[90:93], v[164:167], v[206:209], v[90:93]
	v_mfma_f32_16x16x32_bf16 v[78:81], v[156:159], v[214:217], v[78:81]
	v_mfma_f32_16x16x32_bf16 v[74:77], v[164:167], v[214:217], v[74:77]
	v_mfma_f32_16x16x32_bf16 v[118:121], v[168:171], v[186:189], 0
	v_mfma_f32_16x16x32_bf16 v[114:117], v[176:179], v[186:189], 0
	v_mfma_f32_16x16x32_bf16 v[102:105], v[168:171], v[194:197], 0
	v_mfma_f32_16x16x32_bf16 v[98:101], v[176:179], v[194:197], 0
	v_mfma_f32_16x16x32_bf16 v[86:89], v[168:171], v[202:205], 0
	v_mfma_f32_16x16x32_bf16 v[82:85], v[176:179], v[202:205], 0
	v_mfma_f32_16x16x32_bf16 v[70:73], v[168:171], v[210:213], 0
	v_mfma_f32_16x16x32_bf16 v[66:69], v[176:179], v[210:213], 0
	v_mfma_f32_16x16x32_bf16 v[118:121], v[172:175], v[190:193], v[118:121]
	v_mfma_f32_16x16x32_bf16 v[114:117], v[180:183], v[190:193], v[114:117]
	v_mfma_f32_16x16x32_bf16 v[102:105], v[172:175], v[198:201], v[102:105]
	v_mfma_f32_16x16x32_bf16 v[98:101], v[180:183], v[198:201], v[98:101]
	v_mfma_f32_16x16x32_bf16 v[86:89], v[172:175], v[206:209], v[86:89]
	v_mfma_f32_16x16x32_bf16 v[82:85], v[180:183], v[206:209], v[82:85]
	v_mfma_f32_16x16x32_bf16 v[70:73], v[172:175], v[214:217], v[70:73]
	v_mfma_f32_16x16x32_bf16 v[66:69], v[180:183], v[214:217], v[66:69]
	s_setprio 0
	s_barrier
	s_add_i32 s67, s61, s52
	v_lshl_add_u64 v[218:219], s[46:47], 0, v[132:133]
	s_mov_b32 m0, s67
	ds_read_b128 v[186:189], v154 offset:16384
	ds_read_b128 v[190:193], v154 offset:17408
	ds_read_b128 v[194:197], v154 offset:18432
	ds_read_b128 v[198:201], v154 offset:19456
	ds_read_b128 v[202:205], v154 offset:20480
	ds_read_b128 v[206:209], v154 offset:21504
	ds_read_b128 v[210:213], v154 offset:22528
	ds_read_b128 v[214:217], v154 offset:23552
	global_load_lds_dwordx4 v[218:219], off
	s_add_i32 m0, s67, 0x2000
	s_add_u32 s68, s46, 0x40000
	v_lshl_add_u64 v[220:221], s[46:47], 0, v[136:137]
	s_addc_u32 s69, s47, 0
	s_add_i32 s67, s62, s52
	global_load_lds_dwordx4 v[220:221], off
	v_lshl_add_u64 v[222:223], s[68:69], 0, v[132:133]
	s_mov_b32 m0, s67
	v_lshl_add_u64 v[224:225], s[48:49], 0, v[134:135]
	global_load_lds_dwordx4 v[222:223], off
	v_lshl_add_u64 v[222:223], s[68:69], 0, v[136:137]
	s_add_i32 m0, s67, 0x2000
	s_nop 0
	global_load_lds_dwordx4 v[222:223], off
	v_lshl_add_u64 v[222:223], s[48:49], 0, v[130:131]
	s_mov_b32 m0, s43
	s_nop 0
	global_load_lds_dwordx4 v[222:223], off
	s_mov_b32 m0, s53
	s_nop 0
	global_load_lds_dwordx4 v[224:225], off
	s_cmp_lg_u32 s99, 0
	s_cbranch_scc1 .Lpk4_w2
	s_waitcnt vmcnt(8)
; #define PG8_STAGE(bufoff, gbase, voff) do { _Pragma("unroll") for (int _i = 0; _i < 2; ++_i) \
;         __builtin_amdgcn_global_load_lds((const unsigned*)((const char*)(gbase) + (voff)[_i]), (LAS unsigned*)(lds + (bufoff) + ldsw + _i * 8192), 16, 0, 0); } while (0)
; #define PG8_LDA(dst, b, h) do { _Pragma("unroll") for (int m = 0; m < 4; ++m) _Pragma("unroll") for (int k = 0; k < 2; ++k) dst[m][k] = *(const LAS bf16x8*)(lds + PG8_SA(b, h) + aoff + m * 2048 + k * 1024); } while (0)
; #define PG8_LDB(dst, b, h) do { _Pragma("unroll") for (int n = 0; n < 2; ++n) _Pragma("unroll") for (int k = 0; k < 2; ++k) dst[n][k] = *(const LAS bf16x8*)(lds + PG8_SB(b, h) + boff + n * 2048 + k * 1024); } while (0)
; #define PG8_MMA(ai, bj, At, Bt) do { __builtin_amdgcn_s_setprio(1); _Pragma("unroll") for (int m = 0; m < 4; ++m) _Pragma("unroll") for (int n = 0; n < 2; ++n) _Pragma("unroll") for (int k = 0; k < 2; ++k) \
;         acc[ai][bj][m][n] = __builtin_amdgcn_mfma_f32_16x16x32_bf16(Bt[n][k], At[m][k], acc[ai][bj][m][n], 0, 0, 0); __builtin_amdgcn_s_setprio(0); } while (0)
; #define PG8_WAIT_V(n) asm volatile("s_waitcnt vmcnt(" #n ")" ::: "memory")
; #define PG8_WAIT_L(n) asm volatile("s_waitcnt lgkmcnt(" #n ")" ::: "memory")
; #define PG8_BAR __builtin_amdgcn_s_barrier()
; #define PG8_SCHED __builtin_amdgcn_sched_barrier(0)
; template <class Epi, class Sched>
; DI void gemm_phase(LAS unsigned char* lds, const Gemm g, const Sched& S, const Epi& E) {
;     ...
;             PG8_WAIT_V(8); PG8_WAIT_L(0); PG8_BAR; PG8_MMA(1, 0, At, B0); PG8_MMA(1, 1, At, B1); PG8_BAR; PG8_SCHED;
;             PG8_LDB(B0, 1, 0); PG8_LDB(B1, 1, 1); PG8_SCHED; PG8_LDA(At, 1, 0); PG8_STAGE(PG8_SA(0, 1), a2 + hstepA, voffA);
;             PG8_WAIT_V(8); PG8_WAIT_L(0); PG8_BAR; PG8_MMA(0, 0, At, B0); PG8_MMA(0, 1, At, B1); PG8_BAR; PG8_SCHED;
.Lpk4_w2:
	s_mov_b32 s99, 0
	s_waitcnt lgkmcnt(0)
	s_barrier
	s_setprio 1
	v_mfma_f32_16x16x32_bf16 v[62:65], v[146:149], v[186:189], 0
	v_mfma_f32_16x16x32_bf16 v[58:61], v[160:163], v[186:189], 0
	v_mfma_f32_16x16x32_bf16 v[46:49], v[146:149], v[194:197], 0
	v_mfma_f32_16x16x32_bf16 v[42:45], v[160:163], v[194:197], 0
	v_mfma_f32_16x16x32_bf16 v[30:33], v[146:149], v[202:205], 0
	v_mfma_f32_16x16x32_bf16 v[26:29], v[160:163], v[202:205], 0
	v_mfma_f32_16x16x32_bf16 v[14:17], v[146:149], v[210:213], 0
	v_mfma_f32_16x16x32_bf16 v[10:13], v[160:163], v[210:213], 0
	v_mfma_f32_16x16x32_bf16 v[62:65], v[156:159], v[190:193], v[62:65]
	v_mfma_f32_16x16x32_bf16 v[58:61], v[164:167], v[190:193], v[58:61]
	v_mfma_f32_16x16x32_bf16 v[46:49], v[156:159], v[198:201], v[46:49]
	v_mfma_f32_16x16x32_bf16 v[42:45], v[164:167], v[198:201], v[42:45]
	v_mfma_f32_16x16x32_bf16 v[30:33], v[156:159], v[206:209], v[30:33]
	v_mfma_f32_16x16x32_bf16 v[26:29], v[164:167], v[206:209], v[26:29]
	v_mfma_f32_16x16x32_bf16 v[14:17], v[156:159], v[214:217], v[14:17]
	v_mfma_f32_16x16x32_bf16 v[10:13], v[164:167], v[214:217], v[10:13]
	v_mfma_f32_16x16x32_bf16 v[54:57], v[168:171], v[186:189], 0
	v_mfma_f32_16x16x32_bf16 v[50:53], v[176:179], v[186:189], 0
	v_mfma_f32_16x16x32_bf16 v[38:41], v[168:171], v[194:197], 0
	v_mfma_f32_16x16x32_bf16 v[34:37], v[176:179], v[194:197], 0
	v_mfma_f32_16x16x32_bf16 v[22:25], v[168:171], v[202:205], 0
	v_mfma_f32_16x16x32_bf16 v[18:21], v[176:179], v[202:205], 0
	v_mfma_f32_16x16x32_bf16 v[6:9], v[168:171], v[210:213], 0
	v_mfma_f32_16x16x32_bf16 v[2:5], v[176:179], v[210:213], 0
	v_mfma_f32_16x16x32_bf16 v[54:57], v[172:175], v[190:193], v[54:57]
	v_mfma_f32_16x16x32_bf16 v[50:53], v[180:183], v[190:193], v[50:53]
	v_mfma_f32_16x16x32_bf16 v[38:41], v[172:175], v[198:201], v[38:41]
	v_mfma_f32_16x16x32_bf16 v[34:37], v[180:183], v[198:201], v[34:37]
	v_mfma_f32_16x16x32_bf16 v[22:25], v[172:175], v[206:209], v[22:25]
	v_mfma_f32_16x16x32_bf16 v[18:21], v[180:183], v[206:209], v[18:21]
	v_mfma_f32_16x16x32_bf16 v[6:9], v[172:175], v[214:217], v[6:9]
	v_mfma_f32_16x16x32_bf16 v[2:5], v[180:183], v[214:217], v[2:5]
	s_setprio 0
	s_barrier
	s_add_i32 s67, 0, 0x18000
	s_add_i32 s68, 0, 0x1c000
	v_add_u32_e32 v164, s67, v150
	v_add_u32_e32 v180, s68, v150
	ds_read_b128 v[146:149], v164
	ds_read_b128 v[156:159], v164 offset:1024
	ds_read_b128 v[160:163], v164 offset:2048
	ds_read_b128 v[164:167], v164 offset:3072
	ds_read_b128 v[168:171], v180
	ds_read_b128 v[172:175], v180 offset:1024
	ds_read_b128 v[176:179], v180 offset:2048
	ds_read_b128 v[180:183], v180 offset:3072
	s_add_u32 s48, s48, 0x40000
	s_addc_u32 s49, s49, 0
	s_mov_b32 m0, s54
	v_lshl_add_u64 v[226:227], s[48:49], 0, v[130:131]
	ds_read_b128 v[186:189], v154 offset:32768
	ds_read_b128 v[190:193], v154 offset:33792
	ds_read_b128 v[194:197], v154 offset:34816
	ds_read_b128 v[198:201], v154 offset:35840
	ds_read_b128 v[202:205], v154 offset:36864
	ds_read_b128 v[206:209], v154 offset:37888
	ds_read_b128 v[210:213], v154 offset:38912
	ds_read_b128 v[214:217], v154 offset:39936
	global_load_lds_dwordx4 v[226:227], off
	v_lshl_add_u64 v[226:227], s[48:49], 0, v[134:135]
	s_mov_b32 m0, s55
	s_nop 0
	global_load_lds_dwordx4 v[226:227], off
	s_waitcnt vmcnt(8)
	s_waitcnt lgkmcnt(0)
	s_barrier
	s_setprio 1
	v_mfma_f32_16x16x32_bf16 v[126:129], v[146:149], v[186:189], v[126:129]
	v_mfma_f32_16x16x32_bf16 v[122:125], v[160:163], v[186:189], v[122:125]
	v_mfma_f32_16x16x32_bf16 v[110:113], v[146:149], v[194:197], v[110:113]
	v_mfma_f32_16x16x32_bf16 v[106:109], v[160:163], v[194:197], v[106:109]
	v_mfma_f32_16x16x32_bf16 v[94:97], v[146:149], v[202:205], v[94:97]
	v_mfma_f32_16x16x32_bf16 v[90:93], v[160:163], v[202:205], v[90:93]
	v_mfma_f32_16x16x32_bf16 v[78:81], v[146:149], v[210:213], v[78:81]
	v_mfma_f32_16x16x32_bf16 v[74:77], v[160:163], v[210:213], v[74:77]
	v_mfma_f32_16x16x32_bf16 v[126:129], v[156:159], v[190:193], v[126:129]
	v_mfma_f32_16x16x32_bf16 v[122:125], v[164:167], v[190:193], v[122:125]
	v_mfma_f32_16x16x32_bf16 v[110:113], v[156:159], v[198:201], v[110:113]
	v_mfma_f32_16x16x32_bf16 v[106:109], v[164:167], v[198:201], v[106:109]
	v_mfma_f32_16x16x32_bf16 v[94:97], v[156:159], v[206:209], v[94:97]
	v_mfma_f32_16x16x32_bf16 v[90:93], v[164:167], v[206:209], v[90:93]
	v_mfma_f32_16x16x32_bf16 v[78:81], v[156:159], v[214:217], v[78:81]
	v_mfma_f32_16x16x32_bf16 v[74:77], v[164:167], v[214:217], v[74:77]
	v_mfma_f32_16x16x32_bf16 v[118:121], v[168:171], v[186:189], v[118:121]
	v_mfma_f32_16x16x32_bf16 v[114:117], v[176:179], v[186:189], v[114:117]
	v_mfma_f32_16x16x32_bf16 v[102:105], v[168:171], v[194:197], v[102:105]
	v_mfma_f32_16x16x32_bf16 v[98:101], v[176:179], v[194:197], v[98:101]
	v_mfma_f32_16x16x32_bf16 v[86:89], v[168:171], v[202:205], v[86:89]
	v_mfma_f32_16x16x32_bf16 v[82:85], v[176:179], v[202:205], v[82:85]
	v_mfma_f32_16x16x32_bf16 v[70:73], v[168:171], v[210:213], v[70:73]
	v_mfma_f32_16x16x32_bf16 v[66:69], v[176:179], v[210:213], v[66:69]
	v_mfma_f32_16x16x32_bf16 v[118:121], v[172:175], v[190:193], v[118:121]
	v_mfma_f32_16x16x32_bf16 v[114:117], v[180:183], v[190:193], v[114:117]
	v_mfma_f32_16x16x32_bf16 v[102:105], v[172:175], v[198:201], v[102:105]
	v_mfma_f32_16x16x32_bf16 v[98:101], v[180:183], v[198:201], v[98:101]
	v_mfma_f32_16x16x32_bf16 v[86:89], v[172:175], v[206:209], v[86:89]
	v_mfma_f32_16x16x32_bf16 v[82:85], v[180:183], v[206:209], v[82:85]
	v_mfma_f32_16x16x32_bf16 v[70:73], v[172:175], v[214:217], v[70:73]
	v_mfma_f32_16x16x32_bf16 v[66:69], v[180:183], v[214:217], v[66:69]
	s_setprio 0
	s_barrier
; #define PG8_STAGE(bufoff, gbase, voff) do { _Pragma("unroll") for (int _i = 0; _i < 2; ++_i) \
;         __builtin_amdgcn_global_load_lds((const unsigned*)((const char*)(gbase) + (voff)[_i]), (LAS unsigned*)(lds + (bufoff) + ldsw + _i * 8192), 16, 0, 0); } while (0)
; #define PG8_LDA(dst, b, h) do { _Pragma("unroll") for (int m = 0; m < 4; ++m) _Pragma("unroll") for (int k = 0; k < 2; ++k) dst[m][k] = *(const LAS bf16x8*)(lds + PG8_SA(b, h) + aoff + m * 2048 + k * 1024); } while (0)
; #define PG8_LDB(dst, b, h) do { _Pragma("unroll") for (int n = 0; n < 2; ++n) _Pragma("unroll") for (int k = 0; k < 2; ++k) dst[n][k] = *(const LAS bf16x8*)(lds + PG8_SB(b, h) + boff + n * 2048 + k * 1024); } while (0)
; #define PG8_MMA(ai, bj, At, Bt) do { __builtin_amdgcn_s_setprio(1); _Pragma("unroll") for (int m = 0; m < 4; ++m) _Pragma("unroll") for (int n = 0; n < 2; ++n) _Pragma("unroll") for (int k = 0; k < 2; ++k) \
;         acc[ai][bj][m][n] = __builtin_amdgcn_mfma_f32_16x16x32_bf16(Bt[n][k], At[m][k], acc[ai][bj][m][n], 0, 0, 0); __builtin_amdgcn_s_setprio(0); } while (0)
; #define PG8_WAIT_V(n) asm volatile("s_waitcnt vmcnt(" #n ")" ::: "memory")
; #define PG8_WAIT_L(n) asm volatile("s_waitcnt lgkmcnt(" #n ")" ::: "memory")
; #define PG8_BAR __builtin_amdgcn_s_barrier()
; #define PG8_SCHED __builtin_amdgcn_sched_barrier(0)
; template <class Epi, class Sched>
; DI void gemm_phase(LAS unsigned char* lds, const Gemm g, const Sched& S, const Epi& E) {
;     ...
;         for (int t = 0; t < nt; t += 2) {
;             const bool last = (t == nt - 2);
;             const char* a1 = cA + (size_t)(t + 1) * kstep;
;             const char* a2 = last ? nA : cA + (size_t)(t + 2) * kstep; const char* b2 = last ? nB : cB + (size_t)(t + 2) * kstep;
;             const char* a3 = a2 + kstep; const char* b3 = b2 + kstep;
;             PG8_LDB(B0, 0, 0); PG8_LDB(B1, 0, 1); PG8_SCHED; PG8_LDA(At, 0, 0); PG8_STAGE(PG8_SA(1, 1), a1 + hstepA, voffA);
;             PG8_WAIT_V(8); PG8_WAIT_L(0); PG8_BAR; PG8_MMA(0, 0, At, B0); PG8_MMA(0, 1, At, B1); PG8_BAR; PG8_SCHED;
;     ...
;             PG8_LDA(At, 1, 1); PG8_STAGE(PG8_SB(1, 0), b3, voffB); PG8_STAGE(PG8_SB(1, 1), b3 + hstepB, voffB); PG8_STAGE(PG8_SA(1, 0), a3, voffA);
;             PG8_WAIT_V(8); PG8_WAIT_L(0); PG8_BAR; PG8_MMA(1, 0, At, B0); PG8_MMA(1, 1, At, B1); PG8_BAR; PG8_SCHED;
	s_add_i32 s48, s67, s52
	v_lshl_add_u64 v[218:219], v[218:219], 0, s[16:17]
	s_mov_b32 m0, s48
	ds_read_b128 v[186:189], v154 offset:49152
	ds_read_b128 v[190:193], v154 offset:50176
	ds_read_b128 v[194:197], v154 offset:51200
	ds_read_b128 v[198:201], v154 offset:52224
	ds_read_b128 v[202:205], v154 offset:53248
	ds_read_b128 v[206:209], v154 offset:54272
	ds_read_b128 v[210:213], v154 offset:55296
	ds_read_b128 v[214:217], v154 offset:56320
	global_load_lds_dwordx4 v[218:219], off
	s_add_i32 m0, s48, 0x2000
	s_add_u32 s46, s46, 0x40080
	v_lshl_add_u64 v[218:219], v[220:221], 0, s[16:17]
	s_addc_u32 s47, s47, 0
	s_add_i32 s48, s68, s52
	global_load_lds_dwordx4 v[218:219], off
	v_lshl_add_u64 v[218:219], s[46:47], 0, v[132:133]
	s_mov_b32 m0, s48
	s_nop 0
	global_load_lds_dwordx4 v[218:219], off
	v_lshl_add_u64 v[218:219], s[46:47], 0, v[136:137]
	s_add_i32 m0, s48, 0x2000
	s_nop 0
	global_load_lds_dwordx4 v[218:219], off
	v_lshl_add_u64 v[218:219], v[222:223], 0, s[16:17]
	s_mov_b32 m0, s57
	s_nop 0
	global_load_lds_dwordx4 v[218:219], off
	v_lshl_add_u64 v[218:219], v[224:225], 0, s[16:17]
	s_mov_b32 m0, s58
	s_nop 0
	global_load_lds_dwordx4 v[218:219], off
	s_waitcnt vmcnt(8)
	s_waitcnt lgkmcnt(0)
	s_barrier
	s_setprio 1
	v_mfma_f32_16x16x32_bf16 v[62:65], v[146:149], v[186:189], v[62:65]
	v_mfma_f32_16x16x32_bf16 v[58:61], v[160:163], v[186:189], v[58:61]
	v_mfma_f32_16x16x32_bf16 v[46:49], v[146:149], v[194:197], v[46:49]
	v_mfma_f32_16x16x32_bf16 v[42:45], v[160:163], v[194:197], v[42:45]
	v_mfma_f32_16x16x32_bf16 v[30:33], v[146:149], v[202:205], v[30:33]
	v_mfma_f32_16x16x32_bf16 v[26:29], v[160:163], v[202:205], v[26:29]
	v_mfma_f32_16x16x32_bf16 v[14:17], v[146:149], v[210:213], v[14:17]
	v_mfma_f32_16x16x32_bf16 v[10:13], v[160:163], v[210:213], v[10:13]
	v_mfma_f32_16x16x32_bf16 v[62:65], v[156:159], v[190:193], v[62:65]
	v_mfma_f32_16x16x32_bf16 v[58:61], v[164:167], v[190:193], v[58:61]
	v_mfma_f32_16x16x32_bf16 v[46:49], v[156:159], v[198:201], v[46:49]
	v_mfma_f32_16x16x32_bf16 v[42:45], v[164:167], v[198:201], v[42:45]
	v_mfma_f32_16x16x32_bf16 v[30:33], v[156:159], v[206:209], v[30:33]
	v_mfma_f32_16x16x32_bf16 v[26:29], v[164:167], v[206:209], v[26:29]
	v_mfma_f32_16x16x32_bf16 v[14:17], v[156:159], v[214:217], v[14:17]
	v_mfma_f32_16x16x32_bf16 v[10:13], v[164:167], v[214:217], v[10:13]
	v_mfma_f32_16x16x32_bf16 v[54:57], v[168:171], v[186:189], v[54:57]
	v_mfma_f32_16x16x32_bf16 v[50:53], v[176:179], v[186:189], v[50:53]
	v_mfma_f32_16x16x32_bf16 v[38:41], v[168:171], v[194:197], v[38:41]
	v_mfma_f32_16x16x32_bf16 v[34:37], v[176:179], v[194:197], v[34:37]
	v_mfma_f32_16x16x32_bf16 v[22:25], v[168:171], v[202:205], v[22:25]
	v_mfma_f32_16x16x32_bf16 v[18:21], v[176:179], v[202:205], v[18:21]
	v_mfma_f32_16x16x32_bf16 v[6:9], v[168:171], v[210:213], v[6:9]
	v_mfma_f32_16x16x32_bf16 v[2:5], v[176:179], v[210:213], v[2:5]
	v_mfma_f32_16x16x32_bf16 v[54:57], v[172:175], v[190:193], v[54:57]
	v_mfma_f32_16x16x32_bf16 v[50:53], v[180:183], v[190:193], v[50:53]
	v_mfma_f32_16x16x32_bf16 v[38:41], v[172:175], v[198:201], v[38:41]
	v_mfma_f32_16x16x32_bf16 v[34:37], v[180:183], v[198:201], v[34:37]
	v_mfma_f32_16x16x32_bf16 v[22:25], v[172:175], v[206:209], v[22:25]
	v_mfma_f32_16x16x32_bf16 v[18:21], v[180:183], v[206:209], v[18:21]
	v_mfma_f32_16x16x32_bf16 v[6:9], v[172:175], v[214:217], v[6:9]
	v_mfma_f32_16x16x32_bf16 v[2:5], v[180:183], v[214:217], v[2:5]
	s_setprio 0
	s_barrier
	s_add_i32 s66, s66, 2
	s_add_u32 s44, s44, 0x100
	s_addc_u32 s45, s45, 0
	s_add_u32 s64, s64, 0x100
	s_addc_u32 s65, s65, 0
	s_cmp_gt_u32 s66, 13
.LBB0_1133:
	ds_read_b128 v[146:149], v152
	ds_read_b128 v[156:159], v152 offset:1024
	ds_read_b128 v[160:163], v152 offset:2048
	ds_read_b128 v[164:167], v152 offset:3072
	ds_read_b128 v[168:171], v153
	ds_read_b128 v[172:175], v153 offset:1024
	ds_read_b128 v[176:179], v153 offset:2048
	ds_read_b128 v[180:183], v153 offset:3072
	s_add_u32 s46, s44, 0xfffc0080
	s_addc_u32 s47, s45, -1
	s_cmp_eq_u32 s66, 12
	s_cselect_b32 s49, s35, s47
	s_cselect_b32 s48, s41, s46
	s_cselect_b32 s47, s21, s65
	s_cselect_b32 s46, s63, s64
	v_lshl_add_u64 v[218:219], s[44:45], 0, v[138:139]
	s_add_i32 m0, s43, 0xc000
	ds_read_b128 v[186:189], v154
	ds_read_b128 v[190:193], v154 offset:1024
	ds_read_b128 v[194:197], v154 offset:2048
	ds_read_b128 v[198:201], v154 offset:3072
	ds_read_b128 v[202:205], v154 offset:4096
	ds_read_b128 v[206:209], v154 offset:5120
	ds_read_b128 v[210:213], v154 offset:6144
	ds_read_b128 v[214:217], v154 offset:7168
	global_load_lds_dwordx4 v[218:219], off
	v_lshl_add_u64 v[218:219], s[44:45], 0, v[140:141]
	s_add_i32 m0, s43, 0xe000
	s_nop 0
	global_load_lds_dwordx4 v[218:219], off
	s_waitcnt vmcnt(8)
	s_waitcnt lgkmcnt(0)
	s_barrier
; #define PG8_STAGE(bufoff, gbase, voff) do { _Pragma("unroll") for (int _i = 0; _i < 2; ++_i) \
;         __builtin_amdgcn_global_load_lds((const unsigned*)((const char*)(gbase) + (voff)[_i]), (LAS unsigned*)(lds + (bufoff) + ldsw + _i * 8192), 16, 0, 0); } while (0)
; #define PG8_LDA(dst, b, h) do { _Pragma("unroll") for (int m = 0; m < 4; ++m) _Pragma("unroll") for (int k = 0; k < 2; ++k) dst[m][k] = *(const LAS bf16x8*)(lds + PG8_SA(b, h) + aoff + m * 2048 + k * 1024); } while (0)
; #define PG8_MMA(ai, bj, At, Bt) do { __builtin_amdgcn_s_setprio(1); _Pragma("unroll") for (int m = 0; m < 4; ++m) _Pragma("unroll") for (int n = 0; n < 2; ++n) _Pragma("unroll") for (int k = 0; k < 2; ++k) \
;         acc[ai][bj][m][n] = __builtin_amdgcn_mfma_f32_16x16x32_bf16(Bt[n][k], At[m][k], acc[ai][bj][m][n], 0, 0, 0); __builtin_amdgcn_s_setprio(0); } while (0)
; #define PG8_WAIT_V(n) asm volatile("s_waitcnt vmcnt(" #n ")" ::: "memory")
; #define PG8_WAIT_L(n) asm volatile("s_waitcnt lgkmcnt(" #n ")" ::: "memory")
; #define PG8_BAR __builtin_amdgcn_s_barrier()
; #define PG8_SCHED __builtin_amdgcn_sched_barrier(0)
; template <class Epi, class Sched>
; DI void gemm_phase(LAS unsigned char* lds, const Gemm g, const Sched& S, const Epi& E) {
;     ...
;             PG8_WAIT_V(8); PG8_WAIT_L(0); PG8_BAR; PG8_MMA(0, 0, At, B0); PG8_MMA(0, 1, At, B1); PG8_BAR; PG8_SCHED;
;             PG8_LDA(At, 0, 1); PG8_STAGE(PG8_SB(0, 0), b2, voffB); PG8_STAGE(PG8_SB(0, 1), b2 + hstepB, voffB); PG8_STAGE(PG8_SA(0, 0), a2, voffA);
;             PG8_WAIT_V(8); PG8_WAIT_L(0); PG8_BAR; PG8_MMA(1, 0, At, B0); PG8_MMA(1, 1, At, B1); PG8_BAR; PG8_SCHED;
	s_setprio 1
	v_mfma_f32_16x16x32_bf16 v[126:129], v[146:149], v[186:189], v[126:129]
	v_mfma_f32_16x16x32_bf16 v[122:125], v[160:163], v[186:189], v[122:125]
	v_mfma_f32_16x16x32_bf16 v[110:113], v[146:149], v[194:197], v[110:113]
	v_mfma_f32_16x16x32_bf16 v[106:109], v[160:163], v[194:197], v[106:109]
	v_mfma_f32_16x16x32_bf16 v[94:97], v[146:149], v[202:205], v[94:97]
	v_mfma_f32_16x16x32_bf16 v[90:93], v[160:163], v[202:205], v[90:93]
	v_mfma_f32_16x16x32_bf16 v[78:81], v[146:149], v[210:213], v[78:81]
	v_mfma_f32_16x16x32_bf16 v[74:77], v[160:163], v[210:213], v[74:77]
	v_mfma_f32_16x16x32_bf16 v[126:129], v[156:159], v[190:193], v[126:129]
	v_mfma_f32_16x16x32_bf16 v[122:125], v[164:167], v[190:193], v[122:125]
	v_mfma_f32_16x16x32_bf16 v[110:113], v[156:159], v[198:201], v[110:113]
	v_mfma_f32_16x16x32_bf16 v[106:109], v[164:167], v[198:201], v[106:109]
	v_mfma_f32_16x16x32_bf16 v[94:97], v[156:159], v[206:209], v[94:97]
	v_mfma_f32_16x16x32_bf16 v[90:93], v[164:167], v[206:209], v[90:93]
	v_mfma_f32_16x16x32_bf16 v[78:81], v[156:159], v[214:217], v[78:81]
	v_mfma_f32_16x16x32_bf16 v[74:77], v[164:167], v[214:217], v[74:77]
	v_mfma_f32_16x16x32_bf16 v[118:121], v[168:171], v[186:189], v[118:121]
	v_mfma_f32_16x16x32_bf16 v[114:117], v[176:179], v[186:189], v[114:117]
	v_mfma_f32_16x16x32_bf16 v[102:105], v[168:171], v[194:197], v[102:105]
	v_mfma_f32_16x16x32_bf16 v[98:101], v[176:179], v[194:197], v[98:101]
	v_mfma_f32_16x16x32_bf16 v[86:89], v[168:171], v[202:205], v[86:89]
	v_mfma_f32_16x16x32_bf16 v[82:85], v[176:179], v[202:205], v[82:85]
	v_mfma_f32_16x16x32_bf16 v[70:73], v[168:171], v[210:213], v[70:73]
	v_mfma_f32_16x16x32_bf16 v[66:69], v[176:179], v[210:213], v[66:69]
	v_mfma_f32_16x16x32_bf16 v[118:121], v[172:175], v[190:193], v[118:121]
	v_mfma_f32_16x16x32_bf16 v[114:117], v[180:183], v[190:193], v[114:117]
	v_mfma_f32_16x16x32_bf16 v[102:105], v[172:175], v[198:201], v[102:105]
	v_mfma_f32_16x16x32_bf16 v[98:101], v[180:183], v[198:201], v[98:101]
	v_mfma_f32_16x16x32_bf16 v[86:89], v[172:175], v[206:209], v[86:89]
	v_mfma_f32_16x16x32_bf16 v[82:85], v[180:183], v[206:209], v[82:85]
	v_mfma_f32_16x16x32_bf16 v[70:73], v[172:175], v[214:217], v[70:73]
	v_mfma_f32_16x16x32_bf16 v[66:69], v[180:183], v[214:217], v[66:69]
	s_setprio 0
	s_barrier
	s_add_i32 s67, s61, s52
	v_lshl_add_u64 v[218:219], s[46:47], 0, v[132:133]
	s_mov_b32 m0, s67
	ds_read_b128 v[186:189], v154 offset:16384
	ds_read_b128 v[190:193], v154 offset:17408
	ds_read_b128 v[194:197], v154 offset:18432
	ds_read_b128 v[198:201], v154 offset:19456
	ds_read_b128 v[202:205], v154 offset:20480
	ds_read_b128 v[206:209], v154 offset:21504
	ds_read_b128 v[210:213], v154 offset:22528
	ds_read_b128 v[214:217], v154 offset:23552
	global_load_lds_dwordx4 v[218:219], off
	s_add_i32 m0, s67, 0x2000
	s_add_u32 s68, s46, 0x40000
	v_lshl_add_u64 v[220:221], s[46:47], 0, v[136:137]
	s_addc_u32 s69, s47, 0
	s_add_i32 s67, s62, s52
	global_load_lds_dwordx4 v[220:221], off
	v_lshl_add_u64 v[222:223], s[68:69], 0, v[132:133]
	s_mov_b32 m0, s67
	v_lshl_add_u64 v[224:225], s[48:49], 0, v[134:135]
	global_load_lds_dwordx4 v[222:223], off
	v_lshl_add_u64 v[222:223], s[68:69], 0, v[136:137]
	s_add_i32 m0, s67, 0x2000
	s_nop 0
	global_load_lds_dwordx4 v[222:223], off
	v_lshl_add_u64 v[222:223], s[48:49], 0, v[130:131]
	s_mov_b32 m0, s43
	s_nop 0
	global_load_lds_dwordx4 v[222:223], off
	s_mov_b32 m0, s53
	s_nop 0
	global_load_lds_dwordx4 v[224:225], off
	s_waitcnt vmcnt(8)
	s_waitcnt lgkmcnt(0)
	s_barrier
	s_setprio 1
	v_mfma_f32_16x16x32_bf16 v[62:65], v[146:149], v[186:189], v[62:65]
	v_mfma_f32_16x16x32_bf16 v[58:61], v[160:163], v[186:189], v[58:61]
	v_mfma_f32_16x16x32_bf16 v[46:49], v[146:149], v[194:197], v[46:49]
	v_mfma_f32_16x16x32_bf16 v[42:45], v[160:163], v[194:197], v[42:45]
	v_mfma_f32_16x16x32_bf16 v[30:33], v[146:149], v[202:205], v[30:33]
	v_mfma_f32_16x16x32_bf16 v[26:29], v[160:163], v[202:205], v[26:29]
	v_mfma_f32_16x16x32_bf16 v[14:17], v[146:149], v[210:213], v[14:17]
	v_mfma_f32_16x16x32_bf16 v[10:13], v[160:163], v[210:213], v[10:13]
	v_mfma_f32_16x16x32_bf16 v[62:65], v[156:159], v[190:193], v[62:65]
	v_mfma_f32_16x16x32_bf16 v[58:61], v[164:167], v[190:193], v[58:61]
	v_mfma_f32_16x16x32_bf16 v[46:49], v[156:159], v[198:201], v[46:49]
	v_mfma_f32_16x16x32_bf16 v[42:45], v[164:167], v[198:201], v[42:45]
	v_mfma_f32_16x16x32_bf16 v[30:33], v[156:159], v[206:209], v[30:33]
	v_mfma_f32_16x16x32_bf16 v[26:29], v[164:167], v[206:209], v[26:29]
	v_mfma_f32_16x16x32_bf16 v[14:17], v[156:159], v[214:217], v[14:17]
	v_mfma_f32_16x16x32_bf16 v[10:13], v[164:167], v[214:217], v[10:13]
	v_mfma_f32_16x16x32_bf16 v[54:57], v[168:171], v[186:189], v[54:57]
	v_mfma_f32_16x16x32_bf16 v[50:53], v[176:179], v[186:189], v[50:53]
	v_mfma_f32_16x16x32_bf16 v[38:41], v[168:171], v[194:197], v[38:41]
	v_mfma_f32_16x16x32_bf16 v[34:37], v[176:179], v[194:197], v[34:37]
	v_mfma_f32_16x16x32_bf16 v[22:25], v[168:171], v[202:205], v[22:25]
	v_mfma_f32_16x16x32_bf16 v[18:21], v[176:179], v[202:205], v[18:21]
	v_mfma_f32_16x16x32_bf16 v[6:9], v[168:171], v[210:213], v[6:9]
	v_mfma_f32_16x16x32_bf16 v[2:5], v[176:179], v[210:213], v[2:5]
	v_mfma_f32_16x16x32_bf16 v[54:57], v[172:175], v[190:193], v[54:57]
	v_mfma_f32_16x16x32_bf16 v[50:53], v[180:183], v[190:193], v[50:53]
	v_mfma_f32_16x16x32_bf16 v[38:41], v[172:175], v[198:201], v[38:41]
	v_mfma_f32_16x16x32_bf16 v[34:37], v[180:183], v[198:201], v[34:37]
	v_mfma_f32_16x16x32_bf16 v[22:25], v[172:175], v[206:209], v[22:25]
	v_mfma_f32_16x16x32_bf16 v[18:21], v[180:183], v[206:209], v[18:21]
	v_mfma_f32_16x16x32_bf16 v[6:9], v[172:175], v[214:217], v[6:9]
	v_mfma_f32_16x16x32_bf16 v[2:5], v[180:183], v[214:217], v[2:5]
	s_setprio 0
	s_barrier
; #define PG8_STAGE(bufoff, gbase, voff) do { _Pragma("unroll") for (int _i = 0; _i < 2; ++_i) \
;         __builtin_amdgcn_global_load_lds((const unsigned*)((const char*)(gbase) + (voff)[_i]), (LAS unsigned*)(lds + (bufoff) + ldsw + _i * 8192), 16, 0, 0); } while (0)
; #define PG8_LDA(dst, b, h) do { _Pragma("unroll") for (int m = 0; m < 4; ++m) _Pragma("unroll") for (int k = 0; k < 2; ++k) dst[m][k] = *(const LAS bf16x8*)(lds + PG8_SA(b, h) + aoff + m * 2048 + k * 1024); } while (0)
; #define PG8_LDB(dst, b, h) do { _Pragma("unroll") for (int n = 0; n < 2; ++n) _Pragma("unroll") for (int k = 0; k < 2; ++k) dst[n][k] = *(const LAS bf16x8*)(lds + PG8_SB(b, h) + boff + n * 2048 + k * 1024); } while (0)
; #define PG8_MMA(ai, bj, At, Bt) do { __builtin_amdgcn_s_setprio(1); _Pragma("unroll") for (int m = 0; m < 4; ++m) _Pragma("unroll") for (int n = 0; n < 2; ++n) _Pragma("unroll") for (int k = 0; k < 2; ++k) \
;         acc[ai][bj][m][n] = __builtin_amdgcn_mfma_f32_16x16x32_bf16(Bt[n][k], At[m][k], acc[ai][bj][m][n], 0, 0, 0); __builtin_amdgcn_s_setprio(0); } while (0)
; #define PG8_WAIT_V(n) asm volatile("s_waitcnt vmcnt(" #n ")" ::: "memory")
; #define PG8_WAIT_L(n) asm volatile("s_waitcnt lgkmcnt(" #n ")" ::: "memory")
; #define PG8_BAR __builtin_amdgcn_s_barrier()
; #define PG8_SCHED __builtin_amdgcn_sched_barrier(0)
; template <class Epi, class Sched>
; DI void gemm_phase(LAS unsigned char* lds, const Gemm g, const Sched& S, const Epi& E) {
;     ...
;             PG8_LDB(B0, 1, 0); PG8_LDB(B1, 1, 1); PG8_SCHED; PG8_LDA(At, 1, 0); PG8_STAGE(PG8_SA(0, 1), a2 + hstepA, voffA);
;             PG8_WAIT_V(8); PG8_WAIT_L(0); PG8_BAR; PG8_MMA(0, 0, At, B0); PG8_MMA(0, 1, At, B1); PG8_BAR; PG8_SCHED;
	s_add_i32 s67, 0, 0x18000
	s_add_i32 s68, 0, 0x1c000
	v_add_u32_e32 v164, s67, v150
	v_add_u32_e32 v180, s68, v150
	ds_read_b128 v[146:149], v164
	ds_read_b128 v[156:159], v164 offset:1024
	ds_read_b128 v[160:163], v164 offset:2048
	ds_read_b128 v[164:167], v164 offset:3072
	ds_read_b128 v[168:171], v180
	ds_read_b128 v[172:175], v180 offset:1024
	ds_read_b128 v[176:179], v180 offset:2048
	ds_read_b128 v[180:183], v180 offset:3072
	s_add_u32 s48, s48, 0x40000
	s_addc_u32 s49, s49, 0
	s_mov_b32 m0, s54
	v_lshl_add_u64 v[226:227], s[48:49], 0, v[130:131]
	ds_read_b128 v[186:189], v154 offset:32768
	ds_read_b128 v[190:193], v154 offset:33792
	ds_read_b128 v[194:197], v154 offset:34816
	ds_read_b128 v[198:201], v154 offset:35840
	ds_read_b128 v[202:205], v154 offset:36864
	ds_read_b128 v[206:209], v154 offset:37888
	ds_read_b128 v[210:213], v154 offset:38912
	ds_read_b128 v[214:217], v154 offset:39936
	global_load_lds_dwordx4 v[226:227], off
	v_lshl_add_u64 v[226:227], s[48:49], 0, v[134:135]
	s_mov_b32 m0, s55
	s_nop 0
	global_load_lds_dwordx4 v[226:227], off
	s_waitcnt vmcnt(8)
	s_waitcnt lgkmcnt(0)
	s_barrier
	s_setprio 1
	v_mfma_f32_16x16x32_bf16 v[126:129], v[146:149], v[186:189], v[126:129]
	v_mfma_f32_16x16x32_bf16 v[122:125], v[160:163], v[186:189], v[122:125]
	v_mfma_f32_16x16x32_bf16 v[110:113], v[146:149], v[194:197], v[110:113]
	v_mfma_f32_16x16x32_bf16 v[106:109], v[160:163], v[194:197], v[106:109]
	v_mfma_f32_16x16x32_bf16 v[94:97], v[146:149], v[202:205], v[94:97]
	v_mfma_f32_16x16x32_bf16 v[90:93], v[160:163], v[202:205], v[90:93]
	v_mfma_f32_16x16x32_bf16 v[78:81], v[146:149], v[210:213], v[78:81]
	v_mfma_f32_16x16x32_bf16 v[74:77], v[160:163], v[210:213], v[74:77]
	v_mfma_f32_16x16x32_bf16 v[126:129], v[156:159], v[190:193], v[126:129]
	v_mfma_f32_16x16x32_bf16 v[122:125], v[164:167], v[190:193], v[122:125]
	v_mfma_f32_16x16x32_bf16 v[110:113], v[156:159], v[198:201], v[110:113]
	v_mfma_f32_16x16x32_bf16 v[106:109], v[164:167], v[198:201], v[106:109]
	v_mfma_f32_16x16x32_bf16 v[94:97], v[156:159], v[206:209], v[94:97]
	v_mfma_f32_16x16x32_bf16 v[90:93], v[164:167], v[206:209], v[90:93]
	v_mfma_f32_16x16x32_bf16 v[78:81], v[156:159], v[214:217], v[78:81]
	v_mfma_f32_16x16x32_bf16 v[74:77], v[164:167], v[214:217], v[74:77]
	v_mfma_f32_16x16x32_bf16 v[118:121], v[168:171], v[186:189], v[118:121]
	v_mfma_f32_16x16x32_bf16 v[114:117], v[176:179], v[186:189], v[114:117]
	v_mfma_f32_16x16x32_bf16 v[102:105], v[168:171], v[194:197], v[102:105]
	v_mfma_f32_16x16x32_bf16 v[98:101], v[176:179], v[194:197], v[98:101]
	v_mfma_f32_16x16x32_bf16 v[86:89], v[168:171], v[202:205], v[86:89]
	v_mfma_f32_16x16x32_bf16 v[82:85], v[176:179], v[202:205], v[82:85]
	v_mfma_f32_16x16x32_bf16 v[70:73], v[168:171], v[210:213], v[70:73]
	v_mfma_f32_16x16x32_bf16 v[66:69], v[176:179], v[210:213], v[66:69]
	v_mfma_f32_16x16x32_bf16 v[118:121], v[172:175], v[190:193], v[118:121]
	v_mfma_f32_16x16x32_bf16 v[114:117], v[180:183], v[190:193], v[114:117]
	v_mfma_f32_16x16x32_bf16 v[102:105], v[172:175], v[198:201], v[102:105]
	v_mfma_f32_16x16x32_bf16 v[98:101], v[180:183], v[198:201], v[98:101]
	v_mfma_f32_16x16x32_bf16 v[86:89], v[172:175], v[206:209], v[86:89]
	v_mfma_f32_16x16x32_bf16 v[82:85], v[180:183], v[206:209], v[82:85]
	v_mfma_f32_16x16x32_bf16 v[70:73], v[172:175], v[214:217], v[70:73]
	v_mfma_f32_16x16x32_bf16 v[66:69], v[180:183], v[214:217], v[66:69]
	s_setprio 0
	s_barrier
; #define PG8_STAGE(bufoff, gbase, voff) do { _Pragma("unroll") for (int _i = 0; _i < 2; ++_i) \
;         __builtin_amdgcn_global_load_lds((const unsigned*)((const char*)(gbase) + (voff)[_i]), (LAS unsigned*)(lds + (bufoff) + ldsw + _i * 8192), 16, 0, 0); } while (0)
; #define PG8_LDA(dst, b, h) do { _Pragma("unroll") for (int m = 0; m < 4; ++m) _Pragma("unroll") for (int k = 0; k < 2; ++k) dst[m][k] = *(const LAS bf16x8*)(lds + PG8_SA(b, h) + aoff + m * 2048 + k * 1024); } while (0)
; #define PG8_MMA(ai, bj, At, Bt) do { __builtin_amdgcn_s_setprio(1); _Pragma("unroll") for (int m = 0; m < 4; ++m) _Pragma("unroll") for (int n = 0; n < 2; ++n) _Pragma("unroll") for (int k = 0; k < 2; ++k) \
;         acc[ai][bj][m][n] = __builtin_amdgcn_mfma_f32_16x16x32_bf16(Bt[n][k], At[m][k], acc[ai][bj][m][n], 0, 0, 0); __builtin_amdgcn_s_setprio(0); } while (0)
; #define PG8_WAIT_V(n) asm volatile("s_waitcnt vmcnt(" #n ")" ::: "memory")
; #define PG8_WAIT_L(n) asm volatile("s_waitcnt lgkmcnt(" #n ")" ::: "memory")
; #define PG8_BAR __builtin_amdgcn_s_barrier()
; #define PG8_SCHED __builtin_amdgcn_sched_barrier(0)
;     DI void pre(Pre& pr, const pg8::Unit& u, int wr, int fr) const { load_rows(pr, ssq, u, wr, fr); }
;     DI void pre(Pre& pr, const pg8::Unit& u, int wr, int fr) const { load_rows(pr, ssq, u, wr, fr); }
; template <class Epi, class Sched>
; DI void gemm_phase(LAS unsigned char* lds, const Gemm g, const Sched& S, const Epi& E) {
;     ...
;             PG8_LDA(At, 1, 1); PG8_STAGE(PG8_SB(1, 0), b3, voffB); PG8_STAGE(PG8_SB(1, 1), b3 + hstepB, voffB); PG8_STAGE(PG8_SA(1, 0), a3, voffA);
;             PG8_WAIT_V(8); PG8_WAIT_L(0); PG8_BAR; PG8_MMA(1, 0, At, B0); PG8_MMA(1, 1, At, B1); PG8_BAR; PG8_SCHED;
;         }
;         if (wr == 0) PG8_BAR;
;         E(acc, cur, wr, wc, fr, fq, pre);
;         if (!has_next) break;
	s_add_i32 s48, s67, s52
	v_lshl_add_u64 v[218:219], v[218:219], 0, s[16:17]
	s_mov_b32 m0, s48
	ds_read_b128 v[186:189], v154 offset:49152
	ds_read_b128 v[190:193], v154 offset:50176
	ds_read_b128 v[194:197], v154 offset:51200
	ds_read_b128 v[198:201], v154 offset:52224
	ds_read_b128 v[202:205], v154 offset:53248
	ds_read_b128 v[206:209], v154 offset:54272
	ds_read_b128 v[210:213], v154 offset:55296
	ds_read_b128 v[214:217], v154 offset:56320
	global_load_lds_dwordx4 v[218:219], off
	s_add_i32 m0, s48, 0x2000
	s_add_u32 s46, s46, 0x40080
	v_lshl_add_u64 v[218:219], v[220:221], 0, s[16:17]
	s_addc_u32 s47, s47, 0
	s_add_i32 s48, s68, s52
	global_load_lds_dwordx4 v[218:219], off
	v_lshl_add_u64 v[218:219], s[46:47], 0, v[132:133]
	s_mov_b32 m0, s48
	s_nop 0
	global_load_lds_dwordx4 v[218:219], off
	v_lshl_add_u64 v[218:219], s[46:47], 0, v[136:137]
	s_add_i32 m0, s48, 0x2000
	s_nop 0
	global_load_lds_dwordx4 v[218:219], off
	v_lshl_add_u64 v[218:219], v[222:223], 0, s[16:17]
	s_mov_b32 m0, s57
	s_nop 0
	global_load_lds_dwordx4 v[218:219], off
	v_lshl_add_u64 v[218:219], v[224:225], 0, s[16:17]
	s_mov_b32 m0, s58
	s_nop 0
	global_load_lds_dwordx4 v[218:219], off
	s_waitcnt vmcnt(8)
	s_waitcnt lgkmcnt(0)
	s_barrier
	s_setprio 1
	v_mfma_f32_16x16x32_bf16 v[62:65], v[146:149], v[186:189], v[62:65]
	v_mfma_f32_16x16x32_bf16 v[58:61], v[160:163], v[186:189], v[58:61]
	v_mfma_f32_16x16x32_bf16 v[46:49], v[146:149], v[194:197], v[46:49]
	v_mfma_f32_16x16x32_bf16 v[42:45], v[160:163], v[194:197], v[42:45]
	v_mfma_f32_16x16x32_bf16 v[30:33], v[146:149], v[202:205], v[30:33]
	v_mfma_f32_16x16x32_bf16 v[26:29], v[160:163], v[202:205], v[26:29]
	v_mfma_f32_16x16x32_bf16 v[14:17], v[146:149], v[210:213], v[14:17]
	v_mfma_f32_16x16x32_bf16 v[10:13], v[160:163], v[210:213], v[10:13]
	v_mfma_f32_16x16x32_bf16 v[62:65], v[156:159], v[190:193], v[62:65]
	v_mfma_f32_16x16x32_bf16 v[58:61], v[164:167], v[190:193], v[58:61]
	v_mfma_f32_16x16x32_bf16 v[46:49], v[156:159], v[198:201], v[46:49]
	v_mfma_f32_16x16x32_bf16 v[42:45], v[164:167], v[198:201], v[42:45]
	v_mfma_f32_16x16x32_bf16 v[30:33], v[156:159], v[206:209], v[30:33]
	v_mfma_f32_16x16x32_bf16 v[26:29], v[164:167], v[206:209], v[26:29]
	v_mfma_f32_16x16x32_bf16 v[14:17], v[156:159], v[214:217], v[14:17]
	v_mfma_f32_16x16x32_bf16 v[10:13], v[164:167], v[214:217], v[10:13]
	v_mfma_f32_16x16x32_bf16 v[54:57], v[168:171], v[186:189], v[54:57]
	v_mfma_f32_16x16x32_bf16 v[50:53], v[176:179], v[186:189], v[50:53]
	v_mfma_f32_16x16x32_bf16 v[38:41], v[168:171], v[194:197], v[38:41]
	v_mfma_f32_16x16x32_bf16 v[34:37], v[176:179], v[194:197], v[34:37]
	v_mfma_f32_16x16x32_bf16 v[22:25], v[168:171], v[202:205], v[22:25]
	v_mfma_f32_16x16x32_bf16 v[18:21], v[176:179], v[202:205], v[18:21]
	v_mfma_f32_16x16x32_bf16 v[6:9], v[168:171], v[210:213], v[6:9]
	v_mfma_f32_16x16x32_bf16 v[2:5], v[176:179], v[210:213], v[2:5]
	v_mfma_f32_16x16x32_bf16 v[54:57], v[172:175], v[190:193], v[54:57]
	v_mfma_f32_16x16x32_bf16 v[50:53], v[180:183], v[190:193], v[50:53]
	v_mfma_f32_16x16x32_bf16 v[38:41], v[172:175], v[198:201], v[38:41]
	v_mfma_f32_16x16x32_bf16 v[34:37], v[180:183], v[198:201], v[34:37]
	v_mfma_f32_16x16x32_bf16 v[22:25], v[172:175], v[206:209], v[22:25]
	v_mfma_f32_16x16x32_bf16 v[18:21], v[180:183], v[206:209], v[18:21]
	v_mfma_f32_16x16x32_bf16 v[6:9], v[172:175], v[214:217], v[6:9]
	v_mfma_f32_16x16x32_bf16 v[2:5], v[180:183], v[214:217], v[2:5]
	s_setprio 0
	s_barrier
	s_add_i32 s66, s66, 2
	s_add_u32 s44, s44, 0x100
	s_addc_u32 s45, s45, 0
	s_add_u32 s64, s64, 0x100
	s_addc_u32 s65, s65, 0
	s_cmp_gt_u32 s66, 13
	s_cbranch_scc0 .LBB0_1133
	s_waitcnt vmcnt(0)
	s_mov_b32 s99, 1
	s_and_b64 vcc, exec, s[18:19]
	s_cbranch_vccz .LBB0_1136
	s_barrier

;     DI bool next(int i, Unit& u) const { if (i > 0 || c >= 64) return false; u.pm = c & 31; u.pn = 0; u.src = c >> 5; return true; }
; #define PG8_STAGE(bufoff, gbase, voff) do { _Pragma("unroll") for (int _i = 0; _i < 2; ++_i) \
;         __builtin_amdgcn_global_load_lds((const unsigned*)((const char*)(gbase) + (voff)[_i]), (LAS unsigned*)(lds + (bufoff) + ldsw + _i * 8192), 16, 0, 0); } while (0)
; template <class Epi, class Sched>
; DI void gemm_phase(LAS unsigned char* lds, const Gemm g, const Sched& S, const Epi& E) {
;     const int tid = threadIdx.x, wid = __builtin_amdgcn_readfirstlane(tid >> 6), lane = tid & 63, wr = wid >> 2, wc = wid & 3, fr = lane & 15, fq = lane >> 4;
;     const int K = g.K, nt = K / BK;
;     unsigned voffA[2], voffB[2];
; #pragma unroll
;     for (int i = 0; i < 2; ++i) { int R, C; stage_rc(tid * 16 + i * 8192, R, C); const int Rb = Epi::PERM ? ((R & ~31) + perm32(R & 31)) : R;
;         voffA[i] = (unsigned)(R * g.lda + C) * 2u; voffB[i] = (unsigned)(Rb * g.ldb + C) * 2u; }
;     const size_t kstep = (size_t)(BK * 2);
;     const size_t hstepA = (size_t)HALF * g.lda * 2, hstepB = (size_t)HALF * g.ldb * 2;
;     const size_t tstepA = 2 * hstepA, tstepB = 2 * hstepB;
;     const unsigned ldsw = (unsigned)wid * 1024u;
;     const int aoff = lds_byte(wr * 64 + fr, fq * 8), boff = lds_byte(wc * 32 + fr, fq * 8);
;     ...
;     Unit cur, nxt; int ui = 0;
;     if (!S.next(0, cur)) return;
;     typename Epi::Pre pre;
;     f32x4 acc[2][2][4][2];
; #pragma unroll
;     for (int a = 0; a < 2; ++a)
; #pragma unroll
;         for (int b = 0; b < 2; ++b)
; #pragma unroll
;             for (int m = 0; m < 4; ++m)
; #pragma unroll
;                 for (int n = 0; n < 2; ++n) acc[a][b][m][n] = (f32x4){0.f, 0.f, 0.f, 0.f};
;     bf16x8 At[4][2], B0[2][2], B1[2][2];
;     const char* cA = (const char*)(cur.src ? g.A1 : g.A0) + (size_t)cur.pm * tstepA; const char* cB = (const char*)(cur.src ? g.B1 : g.B0) + (size_t)cur.pn * tstepB;
;     PG8_STAGE(PG8_SB(0, 0), cB, voffB); PG8_STAGE(PG8_SB(0, 1), cB + hstepB, voffB); PG8_STAGE(PG8_SA(0, 0), cA, voffA); PG8_STAGE(PG8_SA(0, 1), cA + hstepA, voffA);
;     if (wr == 1) PG8_BAR;
;     PG8_WAIT_V(2); PG8_BAR;
;     PG8_STAGE(PG8_SB(1, 0), cB + kstep, voffB); PG8_STAGE(PG8_SA(1, 0), cA + kstep, voffA); PG8_STAGE(PG8_SB(1, 1), cB + hstepB + kstep, voffB);
;     PG8_WAIT_V(6); PG8_BAR;
.LBB0_1228:
	s_add_u32 s12, s24, 0xc000000
	s_addc_u32 s13, s25, 0
	s_lshl_b32 s16, s16, 5
	s_and_b32 s34, s16, 0x60
	s_mov_b64 s[16:17], 0x80
	s_add_i32 m0, s49, 0x18000
	v_lshl_add_u64 v[8:9], v[8:9], 0, s[16:17]
	s_lshl_b32 s19, s18, 13
	s_lshl_b32 s35, s34, 7
	s_waitcnt vmcnt(2)
	s_barrier
	global_load_lds_dwordx4 v[8:9], off
	v_lshl_add_u64 v[6:7], v[6:7], 0, s[16:17]
	s_add_i32 m0, s49, 0x1a000
	s_add_i32 s54, s49, 0x8000
	s_add_i32 s55, s49, 0xa000
	global_load_lds_dwordx4 v[6:7], off
	v_lshl_add_u64 v[2:3], v[2:3], 0, s[16:17]
	s_mov_b32 m0, s54
	s_add_u32 s20, s42, 0x40080
	global_load_lds_dwordx4 v[2:3], off
	v_lshl_add_u64 v[2:3], v[4:5], 0, s[16:17]
	s_mov_b32 m0, s55
	s_addc_u32 s21, s43, 0
	global_load_lds_dwordx4 v[2:3], off
	s_add_i32 m0, s49, 0x1c000
	v_lshl_add_u64 v[2:3], s[20:21], 0, v[134:135]
	global_load_lds_dwordx4 v[2:3], off
	v_lshl_add_u64 v[2:3], s[20:21], 0, v[130:131]
	s_add_i32 m0, s49, 0x1e000
	s_sext_i32_i16 s60, s4
	global_load_lds_dwordx4 v[2:3], off
	v_and_b32_e32 v2, 15, v184
	v_lshlrev_b32_e32 v3, 1, v13
	v_lshlrev_b32_e32 v4, 2, v184
	v_lshlrev_b32_e32 v5, 6, v184
	s_movk_i32 s4, 0x3c0
	v_lshl_or_b32 v1, s18, 6, v2
	v_lshl_or_b32 v2, v2, 6, v3
	v_and_b32_e32 v4, 32, v4
	v_and_or_b32 v3, v5, s4, v3
	v_bitop3_b32 v156, s35, v3, v4 bitop3:0xf6
	v_lshlrev_b32_e32 v3, 8, v184
	v_bitop3_b32 v2, v2, s19, v4 bitop3:0xde
	v_and_b32_e32 v3, 0x38000, v3
	v_lshlrev_b32_e32 v4, 11, v14
	v_or3_b32 v3, v11, v3, v4
	v_add_u32_e32 v138, v3, v12
	v_lshlrev_b32_e32 v3, 4, v10
	s_waitcnt vmcnt(6)
	s_cmpk_lt_u32 s5, 0x100
	v_and_b32_e32 v3, 0x78000, v3
	s_cselect_b64 s[18:19], -1, 0
	v_or3_b32 v3, v11, v3, v4
	s_add_i32 s57, 0, 0x10000
	s_add_i32 s58, 0, 0x14000
	s_ashr_i32 s56, s3, 31
	v_or_b32_e32 v157, s34, v13
	v_mov_b32_e32 v139, v135
	v_add_u32_e32 v140, v3, v12
	v_mov_b32_e32 v141, v135
	v_mov_b64_e32 v[142:143], 0x1600
	v_mov_b64_e32 v[144:145], 0x15ff
	v_add_u32_e32 v158, 0, v2
	v_mov_b32_e32 v159, 0x358637bd
	s_movk_i32 s59, 0x1600
	v_add_u32_e32 v160, s57, v156
	v_add_u32_e32 v161, s58, v156
	s_barrier
	s_mov_b32 s99, 0
	s_branch .LBB0_1231

; #define PG8_STAGE(bufoff, gbase, voff) do { _Pragma("unroll") for (int _i = 0; _i < 2; ++_i) \
;         __builtin_amdgcn_global_load_lds((const unsigned*)((const char*)(gbase) + (voff)[_i]), (LAS unsigned*)(lds + (bufoff) + ldsw + _i * 8192), 16, 0, 0); } while (0)
; #define PG8_LDA(dst, b, h) do { _Pragma("unroll") for (int m = 0; m < 4; ++m) _Pragma("unroll") for (int k = 0; k < 2; ++k) dst[m][k] = *(const LAS bf16x8*)(lds + PG8_SA(b, h) + aoff + m * 2048 + k * 1024); } while (0)
; #define PG8_LDB(dst, b, h) do { _Pragma("unroll") for (int n = 0; n < 2; ++n) _Pragma("unroll") for (int k = 0; k < 2; ++k) dst[n][k] = *(const LAS bf16x8*)(lds + PG8_SB(b, h) + boff + n * 2048 + k * 1024); } while (0)
; #define PG8_WAIT_V(n) asm volatile("s_waitcnt vmcnt(" #n ")" ::: "memory")
; #define PG8_WAIT_L(n) asm volatile("s_waitcnt lgkmcnt(" #n ")" ::: "memory")
; template <class Epi, class Sched>
; DI void gemm_phase(LAS unsigned char* lds, const Gemm g, const Sched& S, const Epi& E) {
;     ...
;         E.pre(pre, cur, wr, fr);
;         const char* nA = has_next ? (const char*)(nxt.src ? g.A1 : g.A0) + (size_t)nxt.pm * tstepA : cA; const char* nB = has_next ? (const char*)(nxt.src ? g.B1 : g.B0) + (size_t)nxt.pn * tstepB : cB;
;         for (int t = 0; t < nt; t += 2) {
;             const bool last = (t == nt - 2);
;             const char* a1 = cA + (size_t)(t + 1) * kstep;
;             const char* a2 = last ? nA : cA + (size_t)(t + 2) * kstep; const char* b2 = last ? nB : cB + (size_t)(t + 2) * kstep;
;             const char* a3 = a2 + kstep; const char* b3 = b2 + kstep;
;             PG8_LDB(B0, 0, 0); PG8_LDB(B1, 0, 1); PG8_SCHED; PG8_LDA(At, 0, 0); PG8_STAGE(PG8_SA(1, 1), a1 + hstepA, voffA);
;             PG8_WAIT_V(8); PG8_WAIT_L(0); PG8_BAR; PG8_MMA(0, 0, At, B0); PG8_MMA(0, 1, At, B1); PG8_BAR; PG8_SCHED;
;             PG8_LDA(At, 0, 1); PG8_STAGE(PG8_SB(0, 0), b2, voffB); PG8_STAGE(PG8_SB(0, 1), b2 + hstepB, voffB); PG8_STAGE(PG8_SA(0, 0), a2, voffA);
;             PG8_WAIT_V(8); PG8_WAIT_L(0); PG8_BAR; PG8_MMA(1, 0, At, B0); PG8_MMA(1, 1, At, B1); PG8_BAR; PG8_SCHED;
; DI void load_rows(PreRows& pr, const float* ssq, const pg8::Unit& u, int wr, int fr) {
; #pragma unroll
;     for (int ai = 0; ai < 2; ++ai)
; #pragma unroll
;         for (int m = 0; m < 4; ++m) pr.v[ai * 4 + m] = ssq[u.pm * 256 + ai * 128 + wr * 64 + m * 16 + fr];
; }
.LBB0_1233:
	v_lshl_add_u32 v154, s44, 8, v1
	v_ashrrev_i32_e32 v155, 31, v154
	v_add_u32_e32 v152, 0x80, v154
	v_add_u32_e32 v150, 0x90, v154
	v_add_u32_e32 v148, 0xa0, v154
	v_add_u32_e32 v146, 0xb0, v154
	v_lshl_add_u64 v[2:3], v[154:155], 2, s[8:9]
	v_ashrrev_i32_e32 v153, 31, v152
	v_ashrrev_i32_e32 v151, 31, v150
	v_ashrrev_i32_e32 v149, 31, v148
	v_ashrrev_i32_e32 v147, 31, v146
	v_lshl_add_u64 v[4:5], v[152:153], 2, s[8:9]
	v_lshl_add_u64 v[6:7], v[150:151], 2, s[8:9]
	v_lshl_add_u64 v[8:9], v[148:149], 2, s[8:9]
	v_lshl_add_u64 v[10:11], v[146:147], 2, s[8:9]
	global_load_dword v164, v[2:3], off
	global_load_dword v163, v[2:3], off offset:64
	global_load_dword v162, v[2:3], off offset:128
	global_load_dword v155, v[2:3], off offset:192
	global_load_dword v153, v[4:5], off
	global_load_dword v151, v[6:7], off
	global_load_dword v149, v[8:9], off
	global_load_dword v147, v[10:11], off
	s_ashr_i32 s35, s34, 31
	s_lshl_b64 s[36:37], s[34:35], 19
	s_add_u32 s36, s30, s36
	s_addc_u32 s37, s31, s37
	s_and_b64 s[38:39], s[4:5], exec
	s_cselect_b32 s35, s37, s41
	s_cselect_b32 s61, s36, s40
	s_ashr_i32 s21, s20, 31
	s_lshl_b64 s[38:39], s[20:21], 19
	s_add_u32 s38, s28, s38
	s_addc_u32 s39, s29, s39
	s_and_b64 s[44:45], s[4:5], exec
	s_cselect_b32 s21, s39, s43
	s_cselect_b32 s62, s38, s42
	s_add_u32 s40, s40, 0x40080
	s_addc_u32 s41, s41, 0
	s_add_u32 s63, s42, 0x100
	s_addc_u32 s64, s43, 0
	s_mov_b32 s65, -2
	ds_read_b128 v[166:169], v160
	ds_read_b128 v[170:173], v160 offset:1024
	ds_read_b128 v[174:177], v160 offset:2048
	ds_read_b128 v[178:181], v160 offset:3072
	ds_read_b128 v[186:189], v161
	ds_read_b128 v[190:193], v161 offset:1024
	ds_read_b128 v[194:197], v161 offset:2048
	ds_read_b128 v[198:201], v161 offset:3072
	s_add_u32 s42, s40, 0xfffc0080
	s_addc_u32 s43, s41, -1
	s_cmp_eq_u32 s65, 12
	s_cselect_b32 s45, s35, s43
	s_cselect_b32 s44, s61, s42
	s_cselect_b32 s43, s21, s64
	s_cselect_b32 s42, s62, s63
	v_lshl_add_u64 v[182:183], s[40:41], 0, v[138:139]
	s_add_i32 m0, s49, 0xc000
	ds_read_b128 v[202:205], v158
	ds_read_b128 v[206:209], v158 offset:1024
	ds_read_b128 v[210:213], v158 offset:2048
	ds_read_b128 v[214:217], v158 offset:3072
	ds_read_b128 v[218:221], v158 offset:4096
	ds_read_b128 v[222:225], v158 offset:5120
	ds_read_b128 v[226:229], v158 offset:6144
	ds_read_b128 v[230:233], v158 offset:7168
	global_load_lds_dwordx4 v[182:183], off
	v_lshl_add_u64 v[182:183], s[40:41], 0, v[140:141]
	s_add_i32 m0, s49, 0xe000
	s_nop 0
	global_load_lds_dwordx4 v[182:183], off
	s_cmp_lg_u32 s99, 0
	s_cbranch_scc1 .Lpk5_w1
	s_waitcnt vmcnt(8)
.Lpk5_w1:
	s_waitcnt lgkmcnt(0)
	s_barrier
	s_setprio 1
	v_mfma_f32_16x16x32_bf16 v[126:129], v[166:169], v[202:205], 0
	v_mfma_f32_16x16x32_bf16 v[118:121], v[174:177], v[202:205], 0
	v_mfma_f32_16x16x32_bf16 v[110:113], v[166:169], v[210:213], 0
	v_mfma_f32_16x16x32_bf16 v[102:105], v[174:177], v[210:213], 0
	v_mfma_f32_16x16x32_bf16 v[94:97], v[166:169], v[218:221], 0
	v_mfma_f32_16x16x32_bf16 v[86:89], v[174:177], v[218:221], 0
	v_mfma_f32_16x16x32_bf16 v[78:81], v[166:169], v[226:229], 0
	v_mfma_f32_16x16x32_bf16 v[70:73], v[174:177], v[226:229], 0
	v_mfma_f32_16x16x32_bf16 v[126:129], v[170:173], v[206:209], v[126:129]
	v_mfma_f32_16x16x32_bf16 v[118:121], v[178:181], v[206:209], v[118:121]
	v_mfma_f32_16x16x32_bf16 v[110:113], v[170:173], v[214:217], v[110:113]
	v_mfma_f32_16x16x32_bf16 v[102:105], v[178:181], v[214:217], v[102:105]
	v_mfma_f32_16x16x32_bf16 v[94:97], v[170:173], v[222:225], v[94:97]
	v_mfma_f32_16x16x32_bf16 v[86:89], v[178:181], v[222:225], v[86:89]
	v_mfma_f32_16x16x32_bf16 v[78:81], v[170:173], v[230:233], v[78:81]
	v_mfma_f32_16x16x32_bf16 v[70:73], v[178:181], v[230:233], v[70:73]
	v_mfma_f32_16x16x32_bf16 v[122:125], v[186:189], v[202:205], 0
	v_mfma_f32_16x16x32_bf16 v[114:117], v[194:197], v[202:205], 0
	v_mfma_f32_16x16x32_bf16 v[106:109], v[186:189], v[210:213], 0
	v_mfma_f32_16x16x32_bf16 v[98:101], v[194:197], v[210:213], 0
	v_mfma_f32_16x16x32_bf16 v[90:93], v[186:189], v[218:221], 0
	v_mfma_f32_16x16x32_bf16 v[82:85], v[194:197], v[218:221], 0
	v_mfma_f32_16x16x32_bf16 v[74:77], v[186:189], v[226:229], 0
	v_mfma_f32_16x16x32_bf16 v[66:69], v[194:197], v[226:229], 0
	v_mfma_f32_16x16x32_bf16 v[122:125], v[190:193], v[206:209], v[122:125]
	v_mfma_f32_16x16x32_bf16 v[114:117], v[198:201], v[206:209], v[114:117]
	v_mfma_f32_16x16x32_bf16 v[106:109], v[190:193], v[214:217], v[106:109]
	v_mfma_f32_16x16x32_bf16 v[98:101], v[198:201], v[214:217], v[98:101]
	v_mfma_f32_16x16x32_bf16 v[90:93], v[190:193], v[222:225], v[90:93]
	v_mfma_f32_16x16x32_bf16 v[82:85], v[198:201], v[222:225], v[82:85]
	v_mfma_f32_16x16x32_bf16 v[74:77], v[190:193], v[230:233], v[74:77]
	v_mfma_f32_16x16x32_bf16 v[66:69], v[198:201], v[230:233], v[66:69]
	s_setprio 0
	s_barrier
	s_add_i32 s66, s57, s46
	v_lshl_add_u64 v[182:183], s[42:43], 0, v[134:135]
	s_mov_b32 m0, s66
	ds_read_b128 v[202:205], v158 offset:16384
	ds_read_b128 v[206:209], v158 offset:17408
	ds_read_b128 v[210:213], v158 offset:18432
	ds_read_b128 v[214:217], v158 offset:19456
	ds_read_b128 v[218:221], v158 offset:20480
	ds_read_b128 v[222:225], v158 offset:21504
	ds_read_b128 v[226:229], v158 offset:22528
	ds_read_b128 v[230:233], v158 offset:23552
	global_load_lds_dwordx4 v[182:183], off
	s_add_i32 m0, s66, 0x2000
	s_add_u32 s66, s42, 0x40000
	v_lshl_add_u64 v[234:235], s[42:43], 0, v[130:131]
	s_addc_u32 s67, s43, 0
	s_add_i32 s68, s58, s46
	global_load_lds_dwordx4 v[234:235], off
	v_lshl_add_u64 v[236:237], s[66:67], 0, v[134:135]
	s_mov_b32 m0, s68
	v_lshl_add_u64 v[238:239], s[44:45], 0, v[132:133]
	global_load_lds_dwordx4 v[236:237], off
	v_lshl_add_u64 v[236:237], s[66:67], 0, v[130:131]
	s_add_i32 m0, s68, 0x2000
	s_nop 0
	global_load_lds_dwordx4 v[236:237], off
	v_lshl_add_u64 v[236:237], s[44:45], 0, v[136:137]
	s_mov_b32 m0, s49
	s_nop 0
	global_load_lds_dwordx4 v[236:237], off
	s_mov_b32 m0, s50
	s_nop 0
	global_load_lds_dwordx4 v[238:239], off
	s_cmp_lg_u32 s99, 0
	s_cbranch_scc1 .Lpk5_w2
	s_waitcnt vmcnt(8)
; #define PG8_STAGE(bufoff, gbase, voff) do { _Pragma("unroll") for (int _i = 0; _i < 2; ++_i) \
;         __builtin_amdgcn_global_load_lds((const unsigned*)((const char*)(gbase) + (voff)[_i]), (LAS unsigned*)(lds + (bufoff) + ldsw + _i * 8192), 16, 0, 0); } while (0)
; #define PG8_LDA(dst, b, h) do { _Pragma("unroll") for (int m = 0; m < 4; ++m) _Pragma("unroll") for (int k = 0; k < 2; ++k) dst[m][k] = *(const LAS bf16x8*)(lds + PG8_SA(b, h) + aoff + m * 2048 + k * 1024); } while (0)
; #define PG8_LDB(dst, b, h) do { _Pragma("unroll") for (int n = 0; n < 2; ++n) _Pragma("unroll") for (int k = 0; k < 2; ++k) dst[n][k] = *(const LAS bf16x8*)(lds + PG8_SB(b, h) + boff + n * 2048 + k * 1024); } while (0)
; #define PG8_MMA(ai, bj, At, Bt) do { __builtin_amdgcn_s_setprio(1); _Pragma("unroll") for (int m = 0; m < 4; ++m) _Pragma("unroll") for (int n = 0; n < 2; ++n) _Pragma("unroll") for (int k = 0; k < 2; ++k) \
;         acc[ai][bj][m][n] = __builtin_amdgcn_mfma_f32_16x16x32_bf16(Bt[n][k], At[m][k], acc[ai][bj][m][n], 0, 0, 0); __builtin_amdgcn_s_setprio(0); } while (0)
; #define PG8_WAIT_V(n) asm volatile("s_waitcnt vmcnt(" #n ")" ::: "memory")
; #define PG8_WAIT_L(n) asm volatile("s_waitcnt lgkmcnt(" #n ")" ::: "memory")
; #define PG8_BAR __builtin_amdgcn_s_barrier()
; #define PG8_SCHED __builtin_amdgcn_sched_barrier(0)
; template <class Epi, class Sched>
; DI void gemm_phase(LAS unsigned char* lds, const Gemm g, const Sched& S, const Epi& E) {
;     ...
;             PG8_WAIT_V(8); PG8_WAIT_L(0); PG8_BAR; PG8_MMA(1, 0, At, B0); PG8_MMA(1, 1, At, B1); PG8_BAR; PG8_SCHED;
;             PG8_LDB(B0, 1, 0); PG8_LDB(B1, 1, 1); PG8_SCHED; PG8_LDA(At, 1, 0); PG8_STAGE(PG8_SA(0, 1), a2 + hstepA, voffA);
;             PG8_WAIT_V(8); PG8_WAIT_L(0); PG8_BAR; PG8_MMA(0, 0, At, B0); PG8_MMA(0, 1, At, B1); PG8_BAR; PG8_SCHED;
.Lpk5_w2:
	s_mov_b32 s99, 0
	s_waitcnt lgkmcnt(0)
	s_barrier
	s_setprio 1
	v_mfma_f32_16x16x32_bf16 v[62:65], v[166:169], v[202:205], 0
	v_mfma_f32_16x16x32_bf16 v[54:57], v[174:177], v[202:205], 0
	v_mfma_f32_16x16x32_bf16 v[46:49], v[166:169], v[210:213], 0
	v_mfma_f32_16x16x32_bf16 v[38:41], v[174:177], v[210:213], 0
	v_mfma_f32_16x16x32_bf16 v[30:33], v[166:169], v[218:221], 0
	v_mfma_f32_16x16x32_bf16 v[22:25], v[174:177], v[218:221], 0
	v_mfma_f32_16x16x32_bf16 v[14:17], v[166:169], v[226:229], 0
	v_mfma_f32_16x16x32_bf16 v[6:9], v[174:177], v[226:229], 0
	v_mfma_f32_16x16x32_bf16 v[62:65], v[170:173], v[206:209], v[62:65]
	v_mfma_f32_16x16x32_bf16 v[54:57], v[178:181], v[206:209], v[54:57]
	v_mfma_f32_16x16x32_bf16 v[46:49], v[170:173], v[214:217], v[46:49]
	v_mfma_f32_16x16x32_bf16 v[38:41], v[178:181], v[214:217], v[38:41]
	v_mfma_f32_16x16x32_bf16 v[30:33], v[170:173], v[222:225], v[30:33]
	v_mfma_f32_16x16x32_bf16 v[22:25], v[178:181], v[222:225], v[22:25]
	v_mfma_f32_16x16x32_bf16 v[14:17], v[170:173], v[230:233], v[14:17]
	v_mfma_f32_16x16x32_bf16 v[6:9], v[178:181], v[230:233], v[6:9]
	v_mfma_f32_16x16x32_bf16 v[58:61], v[186:189], v[202:205], 0
	v_mfma_f32_16x16x32_bf16 v[50:53], v[194:197], v[202:205], 0
	v_mfma_f32_16x16x32_bf16 v[42:45], v[186:189], v[210:213], 0
	v_mfma_f32_16x16x32_bf16 v[34:37], v[194:197], v[210:213], 0
	v_mfma_f32_16x16x32_bf16 v[26:29], v[186:189], v[218:221], 0
	v_mfma_f32_16x16x32_bf16 v[18:21], v[194:197], v[218:221], 0
	v_mfma_f32_16x16x32_bf16 v[10:13], v[186:189], v[226:229], 0
	v_mfma_f32_16x16x32_bf16 v[2:5], v[194:197], v[226:229], 0
	v_mfma_f32_16x16x32_bf16 v[58:61], v[190:193], v[206:209], v[58:61]
	v_mfma_f32_16x16x32_bf16 v[50:53], v[198:201], v[206:209], v[50:53]
	v_mfma_f32_16x16x32_bf16 v[42:45], v[190:193], v[214:217], v[42:45]
	v_mfma_f32_16x16x32_bf16 v[34:37], v[198:201], v[214:217], v[34:37]
	v_mfma_f32_16x16x32_bf16 v[26:29], v[190:193], v[222:225], v[26:29]
	v_mfma_f32_16x16x32_bf16 v[18:21], v[198:201], v[222:225], v[18:21]
	v_mfma_f32_16x16x32_bf16 v[10:13], v[190:193], v[230:233], v[10:13]
	v_mfma_f32_16x16x32_bf16 v[2:5], v[198:201], v[230:233], v[2:5]
	s_setprio 0
	s_barrier
	s_add_i32 s66, 0, 0x18000
	v_add_u32_e32 v165, s66, v156
	s_add_i32 s67, 0, 0x1c000
	ds_read_b128 v[166:169], v165
	ds_read_b128 v[170:173], v165 offset:1024
	ds_read_b128 v[174:177], v165 offset:2048
	ds_read_b128 v[178:181], v165 offset:3072
	v_add_u32_e32 v165, s67, v156
	ds_read_b128 v[186:189], v165
	ds_read_b128 v[190:193], v165 offset:1024
	ds_read_b128 v[194:197], v165 offset:2048
	ds_read_b128 v[198:201], v165 offset:3072
	s_add_u32 s44, s44, 0x40000
	s_addc_u32 s45, s45, 0
	s_mov_b32 m0, s51
	v_lshl_add_u64 v[240:241], s[44:45], 0, v[136:137]
	ds_read_b128 v[202:205], v158 offset:32768
	ds_read_b128 v[206:209], v158 offset:33792
	ds_read_b128 v[210:213], v158 offset:34816
	ds_read_b128 v[214:217], v158 offset:35840
	ds_read_b128 v[218:221], v158 offset:36864
	ds_read_b128 v[222:225], v158 offset:37888
	ds_read_b128 v[226:229], v158 offset:38912
	ds_read_b128 v[230:233], v158 offset:39936
	global_load_lds_dwordx4 v[240:241], off
	v_lshl_add_u64 v[240:241], s[44:45], 0, v[132:133]
	s_mov_b32 m0, s52
	s_nop 0
	global_load_lds_dwordx4 v[240:241], off
	s_waitcnt vmcnt(8)
	s_waitcnt lgkmcnt(0)
	s_barrier
	s_setprio 1
	v_mfma_f32_16x16x32_bf16 v[126:129], v[166:169], v[202:205], v[126:129]
	v_mfma_f32_16x16x32_bf16 v[118:121], v[174:177], v[202:205], v[118:121]
	v_mfma_f32_16x16x32_bf16 v[110:113], v[166:169], v[210:213], v[110:113]
	v_mfma_f32_16x16x32_bf16 v[102:105], v[174:177], v[210:213], v[102:105]
	v_mfma_f32_16x16x32_bf16 v[94:97], v[166:169], v[218:221], v[94:97]
	v_mfma_f32_16x16x32_bf16 v[86:89], v[174:177], v[218:221], v[86:89]
	v_mfma_f32_16x16x32_bf16 v[78:81], v[166:169], v[226:229], v[78:81]
	v_mfma_f32_16x16x32_bf16 v[70:73], v[174:177], v[226:229], v[70:73]
	v_mfma_f32_16x16x32_bf16 v[126:129], v[170:173], v[206:209], v[126:129]
	v_mfma_f32_16x16x32_bf16 v[118:121], v[178:181], v[206:209], v[118:121]
	v_mfma_f32_16x16x32_bf16 v[110:113], v[170:173], v[214:217], v[110:113]
	v_mfma_f32_16x16x32_bf16 v[102:105], v[178:181], v[214:217], v[102:105]
	v_mfma_f32_16x16x32_bf16 v[94:97], v[170:173], v[222:225], v[94:97]
	v_mfma_f32_16x16x32_bf16 v[86:89], v[178:181], v[222:225], v[86:89]
	v_mfma_f32_16x16x32_bf16 v[78:81], v[170:173], v[230:233], v[78:81]
	v_mfma_f32_16x16x32_bf16 v[70:73], v[178:181], v[230:233], v[70:73]
	v_mfma_f32_16x16x32_bf16 v[122:125], v[186:189], v[202:205], v[122:125]
	v_mfma_f32_16x16x32_bf16 v[114:117], v[194:197], v[202:205], v[114:117]
	v_mfma_f32_16x16x32_bf16 v[106:109], v[186:189], v[210:213], v[106:109]
	v_mfma_f32_16x16x32_bf16 v[98:101], v[194:197], v[210:213], v[98:101]
	v_mfma_f32_16x16x32_bf16 v[90:93], v[186:189], v[218:221], v[90:93]
	v_mfma_f32_16x16x32_bf16 v[82:85], v[194:197], v[218:221], v[82:85]
	v_mfma_f32_16x16x32_bf16 v[74:77], v[186:189], v[226:229], v[74:77]
	v_mfma_f32_16x16x32_bf16 v[66:69], v[194:197], v[226:229], v[66:69]
	v_mfma_f32_16x16x32_bf16 v[122:125], v[190:193], v[206:209], v[122:125]
	v_mfma_f32_16x16x32_bf16 v[114:117], v[198:201], v[206:209], v[114:117]
	v_mfma_f32_16x16x32_bf16 v[106:109], v[190:193], v[214:217], v[106:109]
	v_mfma_f32_16x16x32_bf16 v[98:101], v[198:201], v[214:217], v[98:101]
	v_mfma_f32_16x16x32_bf16 v[90:93], v[190:193], v[222:225], v[90:93]
	v_mfma_f32_16x16x32_bf16 v[82:85], v[198:201], v[222:225], v[82:85]
	v_mfma_f32_16x16x32_bf16 v[74:77], v[190:193], v[230:233], v[74:77]
	v_mfma_f32_16x16x32_bf16 v[66:69], v[198:201], v[230:233], v[66:69]
	s_setprio 0
	s_barrier
; #define PG8_STAGE(bufoff, gbase, voff) do { _Pragma("unroll") for (int _i = 0; _i < 2; ++_i) \
;         __builtin_amdgcn_global_load_lds((const unsigned*)((const char*)(gbase) + (voff)[_i]), (LAS unsigned*)(lds + (bufoff) + ldsw + _i * 8192), 16, 0, 0); } while (0)
; #define PG8_LDA(dst, b, h) do { _Pragma("unroll") for (int m = 0; m < 4; ++m) _Pragma("unroll") for (int k = 0; k < 2; ++k) dst[m][k] = *(const LAS bf16x8*)(lds + PG8_SA(b, h) + aoff + m * 2048 + k * 1024); } while (0)
; #define PG8_LDB(dst, b, h) do { _Pragma("unroll") for (int n = 0; n < 2; ++n) _Pragma("unroll") for (int k = 0; k < 2; ++k) dst[n][k] = *(const LAS bf16x8*)(lds + PG8_SB(b, h) + boff + n * 2048 + k * 1024); } while (0)
; #define PG8_MMA(ai, bj, At, Bt) do { __builtin_amdgcn_s_setprio(1); _Pragma("unroll") for (int m = 0; m < 4; ++m) _Pragma("unroll") for (int n = 0; n < 2; ++n) _Pragma("unroll") for (int k = 0; k < 2; ++k) \
;         acc[ai][bj][m][n] = __builtin_amdgcn_mfma_f32_16x16x32_bf16(Bt[n][k], At[m][k], acc[ai][bj][m][n], 0, 0, 0); __builtin_amdgcn_s_setprio(0); } while (0)
; #define PG8_WAIT_V(n) asm volatile("s_waitcnt vmcnt(" #n ")" ::: "memory")
; #define PG8_BAR __builtin_amdgcn_s_barrier()
; template <class Epi, class Sched>
; DI void gemm_phase(LAS unsigned char* lds, const Gemm g, const Sched& S, const Epi& E) {
;     ...
;             PG8_LDB(B0, 0, 0); PG8_LDB(B1, 0, 1); PG8_SCHED; PG8_LDA(At, 0, 0); PG8_STAGE(PG8_SA(1, 1), a1 + hstepA, voffA);
;             PG8_WAIT_V(8); PG8_WAIT_L(0); PG8_BAR; PG8_MMA(0, 0, At, B0); PG8_MMA(0, 1, At, B1); PG8_BAR; PG8_SCHED;
;             PG8_LDA(At, 0, 1); PG8_STAGE(PG8_SB(0, 0), b2, voffB); PG8_STAGE(PG8_SB(0, 1), b2 + hstepB, voffB); PG8_STAGE(PG8_SA(0, 0), a2, voffA);
;             PG8_WAIT_V(8); PG8_WAIT_L(0); PG8_BAR; PG8_MMA(1, 0, At, B0); PG8_MMA(1, 1, At, B1); PG8_BAR; PG8_SCHED;
;             PG8_LDB(B0, 1, 0); PG8_LDB(B1, 1, 1); PG8_SCHED; PG8_LDA(At, 1, 0); PG8_STAGE(PG8_SA(0, 1), a2 + hstepA, voffA);
;             PG8_WAIT_V(8); PG8_WAIT_L(0); PG8_BAR; PG8_MMA(0, 0, At, B0); PG8_MMA(0, 1, At, B1); PG8_BAR; PG8_SCHED;
;             PG8_LDA(At, 1, 1); PG8_STAGE(PG8_SB(1, 0), b3, voffB); PG8_STAGE(PG8_SB(1, 1), b3 + hstepB, voffB); PG8_STAGE(PG8_SA(1, 0), a3, voffA);
;             PG8_WAIT_V(8); PG8_WAIT_L(0); PG8_BAR; PG8_MMA(1, 0, At, B0); PG8_MMA(1, 1, At, B1); PG8_BAR; PG8_SCHED;
;         }
	s_add_i32 s44, s66, s46
	v_lshl_add_u64 v[182:183], v[182:183], 0, s[16:17]
	s_mov_b32 m0, s44
	ds_read_b128 v[202:205], v158 offset:49152
	ds_read_b128 v[206:209], v158 offset:50176
	ds_read_b128 v[210:213], v158 offset:51200
	ds_read_b128 v[214:217], v158 offset:52224
	ds_read_b128 v[218:221], v158 offset:53248
	ds_read_b128 v[222:225], v158 offset:54272
	ds_read_b128 v[226:229], v158 offset:55296
	ds_read_b128 v[230:233], v158 offset:56320
	global_load_lds_dwordx4 v[182:183], off
	s_add_i32 m0, s44, 0x2000
	s_add_u32 s42, s42, 0x40080
	v_lshl_add_u64 v[182:183], v[234:235], 0, s[16:17]
	s_addc_u32 s43, s43, 0
	s_add_i32 s44, s67, s46
	global_load_lds_dwordx4 v[182:183], off
	v_lshl_add_u64 v[182:183], s[42:43], 0, v[134:135]
	s_mov_b32 m0, s44
	s_nop 0
	global_load_lds_dwordx4 v[182:183], off
	v_lshl_add_u64 v[182:183], s[42:43], 0, v[130:131]
	s_add_i32 m0, s44, 0x2000
	s_nop 0
	global_load_lds_dwordx4 v[182:183], off
	v_lshl_add_u64 v[182:183], v[236:237], 0, s[16:17]
	s_mov_b32 m0, s54
	s_nop 0
	global_load_lds_dwordx4 v[182:183], off
	v_lshl_add_u64 v[182:183], v[238:239], 0, s[16:17]
	s_mov_b32 m0, s55
	s_nop 0
	global_load_lds_dwordx4 v[182:183], off
	s_waitcnt vmcnt(8)
	s_waitcnt lgkmcnt(0)
	s_barrier
	s_setprio 1
	v_mfma_f32_16x16x32_bf16 v[62:65], v[166:169], v[202:205], v[62:65]
	v_mfma_f32_16x16x32_bf16 v[54:57], v[174:177], v[202:205], v[54:57]
	v_mfma_f32_16x16x32_bf16 v[46:49], v[166:169], v[210:213], v[46:49]
	v_mfma_f32_16x16x32_bf16 v[38:41], v[174:177], v[210:213], v[38:41]
	v_mfma_f32_16x16x32_bf16 v[30:33], v[166:169], v[218:221], v[30:33]
	v_mfma_f32_16x16x32_bf16 v[22:25], v[174:177], v[218:221], v[22:25]
	v_mfma_f32_16x16x32_bf16 v[14:17], v[166:169], v[226:229], v[14:17]
	v_mfma_f32_16x16x32_bf16 v[6:9], v[174:177], v[226:229], v[6:9]
	v_mfma_f32_16x16x32_bf16 v[62:65], v[170:173], v[206:209], v[62:65]
	v_mfma_f32_16x16x32_bf16 v[54:57], v[178:181], v[206:209], v[54:57]
	v_mfma_f32_16x16x32_bf16 v[46:49], v[170:173], v[214:217], v[46:49]
	v_mfma_f32_16x16x32_bf16 v[38:41], v[178:181], v[214:217], v[38:41]
	v_mfma_f32_16x16x32_bf16 v[30:33], v[170:173], v[222:225], v[30:33]
	v_mfma_f32_16x16x32_bf16 v[22:25], v[178:181], v[222:225], v[22:25]
	v_mfma_f32_16x16x32_bf16 v[14:17], v[170:173], v[230:233], v[14:17]
	v_mfma_f32_16x16x32_bf16 v[6:9], v[178:181], v[230:233], v[6:9]
	v_mfma_f32_16x16x32_bf16 v[58:61], v[186:189], v[202:205], v[58:61]
	v_mfma_f32_16x16x32_bf16 v[50:53], v[194:197], v[202:205], v[50:53]
	v_mfma_f32_16x16x32_bf16 v[42:45], v[186:189], v[210:213], v[42:45]
	v_mfma_f32_16x16x32_bf16 v[34:37], v[194:197], v[210:213], v[34:37]
	v_mfma_f32_16x16x32_bf16 v[26:29], v[186:189], v[218:221], v[26:29]
	v_mfma_f32_16x16x32_bf16 v[18:21], v[194:197], v[218:221], v[18:21]
	v_mfma_f32_16x16x32_bf16 v[10:13], v[186:189], v[226:229], v[10:13]
	v_mfma_f32_16x16x32_bf16 v[2:5], v[194:197], v[226:229], v[2:5]
	v_mfma_f32_16x16x32_bf16 v[58:61], v[190:193], v[206:209], v[58:61]
	v_mfma_f32_16x16x32_bf16 v[50:53], v[198:201], v[206:209], v[50:53]
	v_mfma_f32_16x16x32_bf16 v[42:45], v[190:193], v[214:217], v[42:45]
	v_mfma_f32_16x16x32_bf16 v[34:37], v[198:201], v[214:217], v[34:37]
	v_mfma_f32_16x16x32_bf16 v[26:29], v[190:193], v[222:225], v[26:29]
	v_mfma_f32_16x16x32_bf16 v[18:21], v[198:201], v[222:225], v[18:21]
	v_mfma_f32_16x16x32_bf16 v[10:13], v[190:193], v[230:233], v[10:13]
	v_mfma_f32_16x16x32_bf16 v[2:5], v[198:201], v[230:233], v[2:5]
	s_setprio 0
	s_barrier
	s_add_i32 s65, s65, 2
	s_add_u32 s40, s40, 0x100
	s_addc_u32 s41, s41, 0
	s_add_u32 s63, s63, 0x100
	s_addc_u32 s64, s64, 0
	s_cmp_gt_u32 s65, 13
.LBB0_1234:
	ds_read_b128 v[166:169], v160
	ds_read_b128 v[170:173], v160 offset:1024
	ds_read_b128 v[174:177], v160 offset:2048
	ds_read_b128 v[178:181], v160 offset:3072
	ds_read_b128 v[186:189], v161
	ds_read_b128 v[190:193], v161 offset:1024
	ds_read_b128 v[194:197], v161 offset:2048
	ds_read_b128 v[198:201], v161 offset:3072
	s_add_u32 s42, s40, 0xfffc0080
	s_addc_u32 s43, s41, -1
	s_cmp_eq_u32 s65, 12
	s_cselect_b32 s45, s35, s43
	s_cselect_b32 s44, s61, s42
	s_cselect_b32 s43, s21, s64
	s_cselect_b32 s42, s62, s63
	v_lshl_add_u64 v[182:183], s[40:41], 0, v[138:139]
	s_add_i32 m0, s49, 0xc000
	ds_read_b128 v[202:205], v158
	ds_read_b128 v[206:209], v158 offset:1024
	ds_read_b128 v[210:213], v158 offset:2048
	ds_read_b128 v[214:217], v158 offset:3072
	ds_read_b128 v[218:221], v158 offset:4096
	ds_read_b128 v[222:225], v158 offset:5120
	ds_read_b128 v[226:229], v158 offset:6144
	ds_read_b128 v[230:233], v158 offset:7168
	global_load_lds_dwordx4 v[182:183], off
	v_lshl_add_u64 v[182:183], s[40:41], 0, v[140:141]
	s_add_i32 m0, s49, 0xe000
	s_nop 0
	global_load_lds_dwordx4 v[182:183], off
	s_waitcnt vmcnt(8)
	s_waitcnt lgkmcnt(0)
	s_barrier
; #define PG8_STAGE(bufoff, gbase, voff) do { _Pragma("unroll") for (int _i = 0; _i < 2; ++_i) \
;         __builtin_amdgcn_global_load_lds((const unsigned*)((const char*)(gbase) + (voff)[_i]), (LAS unsigned*)(lds + (bufoff) + ldsw + _i * 8192), 16, 0, 0); } while (0)
; #define PG8_LDA(dst, b, h) do { _Pragma("unroll") for (int m = 0; m < 4; ++m) _Pragma("unroll") for (int k = 0; k < 2; ++k) dst[m][k] = *(const LAS bf16x8*)(lds + PG8_SA(b, h) + aoff + m * 2048 + k * 1024); } while (0)
; #define PG8_MMA(ai, bj, At, Bt) do { __builtin_amdgcn_s_setprio(1); _Pragma("unroll") for (int m = 0; m < 4; ++m) _Pragma("unroll") for (int n = 0; n < 2; ++n) _Pragma("unroll") for (int k = 0; k < 2; ++k) \
;         acc[ai][bj][m][n] = __builtin_amdgcn_mfma_f32_16x16x32_bf16(Bt[n][k], At[m][k], acc[ai][bj][m][n], 0, 0, 0); __builtin_amdgcn_s_setprio(0); } while (0)
; #define PG8_WAIT_V(n) asm volatile("s_waitcnt vmcnt(" #n ")" ::: "memory")
; #define PG8_WAIT_L(n) asm volatile("s_waitcnt lgkmcnt(" #n ")" ::: "memory")
; #define PG8_BAR __builtin_amdgcn_s_barrier()
; #define PG8_SCHED __builtin_amdgcn_sched_barrier(0)
; template <class Epi, class Sched>
; DI void gemm_phase(LAS unsigned char* lds, const Gemm g, const Sched& S, const Epi& E) {
;     ...
;             PG8_WAIT_V(8); PG8_WAIT_L(0); PG8_BAR; PG8_MMA(0, 0, At, B0); PG8_MMA(0, 1, At, B1); PG8_BAR; PG8_SCHED;
;             PG8_LDA(At, 0, 1); PG8_STAGE(PG8_SB(0, 0), b2, voffB); PG8_STAGE(PG8_SB(0, 1), b2 + hstepB, voffB); PG8_STAGE(PG8_SA(0, 0), a2, voffA);
;             PG8_WAIT_V(8); PG8_WAIT_L(0); PG8_BAR; PG8_MMA(1, 0, At, B0); PG8_MMA(1, 1, At, B1); PG8_BAR; PG8_SCHED;
	s_setprio 1
	v_mfma_f32_16x16x32_bf16 v[126:129], v[166:169], v[202:205], v[126:129]
	v_mfma_f32_16x16x32_bf16 v[118:121], v[174:177], v[202:205], v[118:121]
	v_mfma_f32_16x16x32_bf16 v[110:113], v[166:169], v[210:213], v[110:113]
	v_mfma_f32_16x16x32_bf16 v[102:105], v[174:177], v[210:213], v[102:105]
	v_mfma_f32_16x16x32_bf16 v[94:97], v[166:169], v[218:221], v[94:97]
	v_mfma_f32_16x16x32_bf16 v[86:89], v[174:177], v[218:221], v[86:89]
	v_mfma_f32_16x16x32_bf16 v[78:81], v[166:169], v[226:229], v[78:81]
	v_mfma_f32_16x16x32_bf16 v[70:73], v[174:177], v[226:229], v[70:73]
	v_mfma_f32_16x16x32_bf16 v[126:129], v[170:173], v[206:209], v[126:129]
	v_mfma_f32_16x16x32_bf16 v[118:121], v[178:181], v[206:209], v[118:121]
	v_mfma_f32_16x16x32_bf16 v[110:113], v[170:173], v[214:217], v[110:113]
	v_mfma_f32_16x16x32_bf16 v[102:105], v[178:181], v[214:217], v[102:105]
	v_mfma_f32_16x16x32_bf16 v[94:97], v[170:173], v[222:225], v[94:97]
	v_mfma_f32_16x16x32_bf16 v[86:89], v[178:181], v[222:225], v[86:89]
	v_mfma_f32_16x16x32_bf16 v[78:81], v[170:173], v[230:233], v[78:81]
	v_mfma_f32_16x16x32_bf16 v[70:73], v[178:181], v[230:233], v[70:73]
	v_mfma_f32_16x16x32_bf16 v[122:125], v[186:189], v[202:205], v[122:125]
	v_mfma_f32_16x16x32_bf16 v[114:117], v[194:197], v[202:205], v[114:117]
	v_mfma_f32_16x16x32_bf16 v[106:109], v[186:189], v[210:213], v[106:109]
	v_mfma_f32_16x16x32_bf16 v[98:101], v[194:197], v[210:213], v[98:101]
	v_mfma_f32_16x16x32_bf16 v[90:93], v[186:189], v[218:221], v[90:93]
	v_mfma_f32_16x16x32_bf16 v[82:85], v[194:197], v[218:221], v[82:85]
	v_mfma_f32_16x16x32_bf16 v[74:77], v[186:189], v[226:229], v[74:77]
	v_mfma_f32_16x16x32_bf16 v[66:69], v[194:197], v[226:229], v[66:69]
	v_mfma_f32_16x16x32_bf16 v[122:125], v[190:193], v[206:209], v[122:125]
	v_mfma_f32_16x16x32_bf16 v[114:117], v[198:201], v[206:209], v[114:117]
	v_mfma_f32_16x16x32_bf16 v[106:109], v[190:193], v[214:217], v[106:109]
	v_mfma_f32_16x16x32_bf16 v[98:101], v[198:201], v[214:217], v[98:101]
	v_mfma_f32_16x16x32_bf16 v[90:93], v[190:193], v[222:225], v[90:93]
	v_mfma_f32_16x16x32_bf16 v[82:85], v[198:201], v[222:225], v[82:85]
	v_mfma_f32_16x16x32_bf16 v[74:77], v[190:193], v[230:233], v[74:77]
	v_mfma_f32_16x16x32_bf16 v[66:69], v[198:201], v[230:233], v[66:69]
	s_setprio 0
	s_barrier
	s_add_i32 s66, s57, s46
	v_lshl_add_u64 v[182:183], s[42:43], 0, v[134:135]
	s_mov_b32 m0, s66
	ds_read_b128 v[202:205], v158 offset:16384
	ds_read_b128 v[206:209], v158 offset:17408
	ds_read_b128 v[210:213], v158 offset:18432
	ds_read_b128 v[214:217], v158 offset:19456
	ds_read_b128 v[218:221], v158 offset:20480
	ds_read_b128 v[222:225], v158 offset:21504
	ds_read_b128 v[226:229], v158 offset:22528
	ds_read_b128 v[230:233], v158 offset:23552
	global_load_lds_dwordx4 v[182:183], off
	s_add_i32 m0, s66, 0x2000
	s_add_u32 s66, s42, 0x40000
	v_lshl_add_u64 v[234:235], s[42:43], 0, v[130:131]
	s_addc_u32 s67, s43, 0
	s_add_i32 s68, s58, s46
	global_load_lds_dwordx4 v[234:235], off
	v_lshl_add_u64 v[236:237], s[66:67], 0, v[134:135]
	s_mov_b32 m0, s68
	v_lshl_add_u64 v[238:239], s[44:45], 0, v[132:133]
	global_load_lds_dwordx4 v[236:237], off
	v_lshl_add_u64 v[236:237], s[66:67], 0, v[130:131]
	s_add_i32 m0, s68, 0x2000
	s_nop 0
	global_load_lds_dwordx4 v[236:237], off
	v_lshl_add_u64 v[236:237], s[44:45], 0, v[136:137]
	s_mov_b32 m0, s49
	s_nop 0
	global_load_lds_dwordx4 v[236:237], off
	s_mov_b32 m0, s50
	s_nop 0
	global_load_lds_dwordx4 v[238:239], off
	s_waitcnt vmcnt(8)
	s_waitcnt lgkmcnt(0)
	s_barrier
	s_setprio 1
	v_mfma_f32_16x16x32_bf16 v[62:65], v[166:169], v[202:205], v[62:65]
	v_mfma_f32_16x16x32_bf16 v[54:57], v[174:177], v[202:205], v[54:57]
	v_mfma_f32_16x16x32_bf16 v[46:49], v[166:169], v[210:213], v[46:49]
	v_mfma_f32_16x16x32_bf16 v[38:41], v[174:177], v[210:213], v[38:41]
	v_mfma_f32_16x16x32_bf16 v[30:33], v[166:169], v[218:221], v[30:33]
	v_mfma_f32_16x16x32_bf16 v[22:25], v[174:177], v[218:221], v[22:25]
	v_mfma_f32_16x16x32_bf16 v[14:17], v[166:169], v[226:229], v[14:17]
	v_mfma_f32_16x16x32_bf16 v[6:9], v[174:177], v[226:229], v[6:9]
	v_mfma_f32_16x16x32_bf16 v[62:65], v[170:173], v[206:209], v[62:65]
	v_mfma_f32_16x16x32_bf16 v[54:57], v[178:181], v[206:209], v[54:57]
	v_mfma_f32_16x16x32_bf16 v[46:49], v[170:173], v[214:217], v[46:49]
	v_mfma_f32_16x16x32_bf16 v[38:41], v[178:181], v[214:217], v[38:41]
	v_mfma_f32_16x16x32_bf16 v[30:33], v[170:173], v[222:225], v[30:33]
	v_mfma_f32_16x16x32_bf16 v[22:25], v[178:181], v[222:225], v[22:25]
	v_mfma_f32_16x16x32_bf16 v[14:17], v[170:173], v[230:233], v[14:17]
	v_mfma_f32_16x16x32_bf16 v[6:9], v[178:181], v[230:233], v[6:9]
	v_mfma_f32_16x16x32_bf16 v[58:61], v[186:189], v[202:205], v[58:61]
	v_mfma_f32_16x16x32_bf16 v[50:53], v[194:197], v[202:205], v[50:53]
	v_mfma_f32_16x16x32_bf16 v[42:45], v[186:189], v[210:213], v[42:45]
	v_mfma_f32_16x16x32_bf16 v[34:37], v[194:197], v[210:213], v[34:37]
	v_mfma_f32_16x16x32_bf16 v[26:29], v[186:189], v[218:221], v[26:29]
	v_mfma_f32_16x16x32_bf16 v[18:21], v[194:197], v[218:221], v[18:21]
	v_mfma_f32_16x16x32_bf16 v[10:13], v[186:189], v[226:229], v[10:13]
	v_mfma_f32_16x16x32_bf16 v[2:5], v[194:197], v[226:229], v[2:5]
	v_mfma_f32_16x16x32_bf16 v[58:61], v[190:193], v[206:209], v[58:61]
	v_mfma_f32_16x16x32_bf16 v[50:53], v[198:201], v[206:209], v[50:53]
	v_mfma_f32_16x16x32_bf16 v[42:45], v[190:193], v[214:217], v[42:45]
	v_mfma_f32_16x16x32_bf16 v[34:37], v[198:201], v[214:217], v[34:37]
	v_mfma_f32_16x16x32_bf16 v[26:29], v[190:193], v[222:225], v[26:29]
	v_mfma_f32_16x16x32_bf16 v[18:21], v[198:201], v[222:225], v[18:21]
	v_mfma_f32_16x16x32_bf16 v[10:13], v[190:193], v[230:233], v[10:13]
	v_mfma_f32_16x16x32_bf16 v[2:5], v[198:201], v[230:233], v[2:5]
	s_setprio 0
	s_barrier
; #define PG8_STAGE(bufoff, gbase, voff) do { _Pragma("unroll") for (int _i = 0; _i < 2; ++_i) \
;         __builtin_amdgcn_global_load_lds((const unsigned*)((const char*)(gbase) + (voff)[_i]), (LAS unsigned*)(lds + (bufoff) + ldsw + _i * 8192), 16, 0, 0); } while (0)
; #define PG8_LDA(dst, b, h) do { _Pragma("unroll") for (int m = 0; m < 4; ++m) _Pragma("unroll") for (int k = 0; k < 2; ++k) dst[m][k] = *(const LAS bf16x8*)(lds + PG8_SA(b, h) + aoff + m * 2048 + k * 1024); } while (0)
; #define PG8_LDB(dst, b, h) do { _Pragma("unroll") for (int n = 0; n < 2; ++n) _Pragma("unroll") for (int k = 0; k < 2; ++k) dst[n][k] = *(const LAS bf16x8*)(lds + PG8_SB(b, h) + boff + n * 2048 + k * 1024); } while (0)
; #define PG8_MMA(ai, bj, At, Bt) do { __builtin_amdgcn_s_setprio(1); _Pragma("unroll") for (int m = 0; m < 4; ++m) _Pragma("unroll") for (int n = 0; n < 2; ++n) _Pragma("unroll") for (int k = 0; k < 2; ++k) \
;         acc[ai][bj][m][n] = __builtin_amdgcn_mfma_f32_16x16x32_bf16(Bt[n][k], At[m][k], acc[ai][bj][m][n], 0, 0, 0); __builtin_amdgcn_s_setprio(0); } while (0)
; #define PG8_WAIT_V(n) asm volatile("s_waitcnt vmcnt(" #n ")" ::: "memory")
; #define PG8_WAIT_L(n) asm volatile("s_waitcnt lgkmcnt(" #n ")" ::: "memory")
; #define PG8_BAR __builtin_amdgcn_s_barrier()
; #define PG8_SCHED __builtin_amdgcn_sched_barrier(0)
; template <class Epi, class Sched>
; DI void gemm_phase(LAS unsigned char* lds, const Gemm g, const Sched& S, const Epi& E) {
;     ...
;             PG8_LDB(B0, 1, 0); PG8_LDB(B1, 1, 1); PG8_SCHED; PG8_LDA(At, 1, 0); PG8_STAGE(PG8_SA(0, 1), a2 + hstepA, voffA);
;             PG8_WAIT_V(8); PG8_WAIT_L(0); PG8_BAR; PG8_MMA(0, 0, At, B0); PG8_MMA(0, 1, At, B1); PG8_BAR; PG8_SCHED;
	s_add_i32 s66, 0, 0x18000
	v_add_u32_e32 v165, s66, v156
	s_add_i32 s67, 0, 0x1c000
	ds_read_b128 v[166:169], v165
	ds_read_b128 v[170:173], v165 offset:1024
	ds_read_b128 v[174:177], v165 offset:2048
	ds_read_b128 v[178:181], v165 offset:3072
	v_add_u32_e32 v165, s67, v156
	ds_read_b128 v[186:189], v165
	ds_read_b128 v[190:193], v165 offset:1024
	ds_read_b128 v[194:197], v165 offset:2048
	ds_read_b128 v[198:201], v165 offset:3072
	s_add_u32 s44, s44, 0x40000
	s_addc_u32 s45, s45, 0
	s_mov_b32 m0, s51
	v_lshl_add_u64 v[240:241], s[44:45], 0, v[136:137]
	ds_read_b128 v[202:205], v158 offset:32768
	ds_read_b128 v[206:209], v158 offset:33792
	ds_read_b128 v[210:213], v158 offset:34816
	ds_read_b128 v[214:217], v158 offset:35840
	ds_read_b128 v[218:221], v158 offset:36864
	ds_read_b128 v[222:225], v158 offset:37888
	ds_read_b128 v[226:229], v158 offset:38912
	ds_read_b128 v[230:233], v158 offset:39936
	global_load_lds_dwordx4 v[240:241], off
	v_lshl_add_u64 v[240:241], s[44:45], 0, v[132:133]
	s_mov_b32 m0, s52
	s_nop 0
	global_load_lds_dwordx4 v[240:241], off
	s_waitcnt vmcnt(8)
	s_waitcnt lgkmcnt(0)
	s_barrier
	s_setprio 1
	v_mfma_f32_16x16x32_bf16 v[126:129], v[166:169], v[202:205], v[126:129]
	v_mfma_f32_16x16x32_bf16 v[118:121], v[174:177], v[202:205], v[118:121]
	v_mfma_f32_16x16x32_bf16 v[110:113], v[166:169], v[210:213], v[110:113]
	v_mfma_f32_16x16x32_bf16 v[102:105], v[174:177], v[210:213], v[102:105]
	v_mfma_f32_16x16x32_bf16 v[94:97], v[166:169], v[218:221], v[94:97]
	v_mfma_f32_16x16x32_bf16 v[86:89], v[174:177], v[218:221], v[86:89]
	v_mfma_f32_16x16x32_bf16 v[78:81], v[166:169], v[226:229], v[78:81]
	v_mfma_f32_16x16x32_bf16 v[70:73], v[174:177], v[226:229], v[70:73]
	v_mfma_f32_16x16x32_bf16 v[126:129], v[170:173], v[206:209], v[126:129]
	v_mfma_f32_16x16x32_bf16 v[118:121], v[178:181], v[206:209], v[118:121]
	v_mfma_f32_16x16x32_bf16 v[110:113], v[170:173], v[214:217], v[110:113]
	v_mfma_f32_16x16x32_bf16 v[102:105], v[178:181], v[214:217], v[102:105]
	v_mfma_f32_16x16x32_bf16 v[94:97], v[170:173], v[222:225], v[94:97]
	v_mfma_f32_16x16x32_bf16 v[86:89], v[178:181], v[222:225], v[86:89]
	v_mfma_f32_16x16x32_bf16 v[78:81], v[170:173], v[230:233], v[78:81]
	v_mfma_f32_16x16x32_bf16 v[70:73], v[178:181], v[230:233], v[70:73]
	v_mfma_f32_16x16x32_bf16 v[122:125], v[186:189], v[202:205], v[122:125]
	v_mfma_f32_16x16x32_bf16 v[114:117], v[194:197], v[202:205], v[114:117]
	v_mfma_f32_16x16x32_bf16 v[106:109], v[186:189], v[210:213], v[106:109]
	v_mfma_f32_16x16x32_bf16 v[98:101], v[194:197], v[210:213], v[98:101]
	v_mfma_f32_16x16x32_bf16 v[90:93], v[186:189], v[218:221], v[90:93]
	v_mfma_f32_16x16x32_bf16 v[82:85], v[194:197], v[218:221], v[82:85]
	v_mfma_f32_16x16x32_bf16 v[74:77], v[186:189], v[226:229], v[74:77]
	v_mfma_f32_16x16x32_bf16 v[66:69], v[194:197], v[226:229], v[66:69]
	v_mfma_f32_16x16x32_bf16 v[122:125], v[190:193], v[206:209], v[122:125]
	v_mfma_f32_16x16x32_bf16 v[114:117], v[198:201], v[206:209], v[114:117]
	v_mfma_f32_16x16x32_bf16 v[106:109], v[190:193], v[214:217], v[106:109]
	v_mfma_f32_16x16x32_bf16 v[98:101], v[198:201], v[214:217], v[98:101]
	v_mfma_f32_16x16x32_bf16 v[90:93], v[190:193], v[222:225], v[90:93]
	v_mfma_f32_16x16x32_bf16 v[82:85], v[198:201], v[222:225], v[82:85]
	v_mfma_f32_16x16x32_bf16 v[74:77], v[190:193], v[230:233], v[74:77]
	v_mfma_f32_16x16x32_bf16 v[66:69], v[198:201], v[230:233], v[66:69]
	s_setprio 0
	s_barrier
; #define PG8_STAGE(bufoff, gbase, voff) do { _Pragma("unroll") for (int _i = 0; _i < 2; ++_i) \
;         __builtin_amdgcn_global_load_lds((const unsigned*)((const char*)(gbase) + (voff)[_i]), (LAS unsigned*)(lds + (bufoff) + ldsw + _i * 8192), 16, 0, 0); } while (0)
; #define PG8_LDA(dst, b, h) do { _Pragma("unroll") for (int m = 0; m < 4; ++m) _Pragma("unroll") for (int k = 0; k < 2; ++k) dst[m][k] = *(const LAS bf16x8*)(lds + PG8_SA(b, h) + aoff + m * 2048 + k * 1024); } while (0)
; #define PG8_MMA(ai, bj, At, Bt) do { __builtin_amdgcn_s_setprio(1); _Pragma("unroll") for (int m = 0; m < 4; ++m) _Pragma("unroll") for (int n = 0; n < 2; ++n) _Pragma("unroll") for (int k = 0; k < 2; ++k) \
;         acc[ai][bj][m][n] = __builtin_amdgcn_mfma_f32_16x16x32_bf16(Bt[n][k], At[m][k], acc[ai][bj][m][n], 0, 0, 0); __builtin_amdgcn_s_setprio(0); } while (0)
; #define PG8_WAIT_V(n) asm volatile("s_waitcnt vmcnt(" #n ")" ::: "memory")
; #define PG8_WAIT_L(n) asm volatile("s_waitcnt lgkmcnt(" #n ")" ::: "memory")
; #define PG8_BAR __builtin_amdgcn_s_barrier()
; #define PG8_SCHED __builtin_amdgcn_sched_barrier(0)
;     DI void pre(Pre& pr, const pg8::Unit& u, int wr, int fr) const { load_rows(pr, ssq, u, wr, fr); }
;     DI void pre(Pre& pr, const pg8::Unit& u, int wr, int fr) const { load_rows(pr, ssq, u, wr, fr); }
; template <class Epi, class Sched>
; DI void gemm_phase(LAS unsigned char* lds, const Gemm g, const Sched& S, const Epi& E) {
;     ...
;             PG8_LDA(At, 1, 1); PG8_STAGE(PG8_SB(1, 0), b3, voffB); PG8_STAGE(PG8_SB(1, 1), b3 + hstepB, voffB); PG8_STAGE(PG8_SA(1, 0), a3, voffA);
;             PG8_WAIT_V(8); PG8_WAIT_L(0); PG8_BAR; PG8_MMA(1, 0, At, B0); PG8_MMA(1, 1, At, B1); PG8_BAR; PG8_SCHED;
;         }
;         if (wr == 0) PG8_BAR;
;         E(acc, cur, wr, wc, fr, fq, pre);
;         if (!has_next) break;
	s_add_i32 s44, s66, s46
	v_lshl_add_u64 v[182:183], v[182:183], 0, s[16:17]
	s_mov_b32 m0, s44
	ds_read_b128 v[202:205], v158 offset:49152
	ds_read_b128 v[206:209], v158 offset:50176
	ds_read_b128 v[210:213], v158 offset:51200
	ds_read_b128 v[214:217], v158 offset:52224
	ds_read_b128 v[218:221], v158 offset:53248
	ds_read_b128 v[222:225], v158 offset:54272
	ds_read_b128 v[226:229], v158 offset:55296
	ds_read_b128 v[230:233], v158 offset:56320
	global_load_lds_dwordx4 v[182:183], off
	s_add_i32 m0, s44, 0x2000
	s_add_u32 s42, s42, 0x40080
	v_lshl_add_u64 v[182:183], v[234:235], 0, s[16:17]
	s_addc_u32 s43, s43, 0
	s_add_i32 s44, s67, s46
	global_load_lds_dwordx4 v[182:183], off
	v_lshl_add_u64 v[182:183], s[42:43], 0, v[134:135]
	s_mov_b32 m0, s44
	s_nop 0
	global_load_lds_dwordx4 v[182:183], off
	v_lshl_add_u64 v[182:183], s[42:43], 0, v[130:131]
	s_add_i32 m0, s44, 0x2000
	s_nop 0
	global_load_lds_dwordx4 v[182:183], off
	v_lshl_add_u64 v[182:183], v[236:237], 0, s[16:17]
	s_mov_b32 m0, s54
	s_nop 0
	global_load_lds_dwordx4 v[182:183], off
	v_lshl_add_u64 v[182:183], v[238:239], 0, s[16:17]
	s_mov_b32 m0, s55
	s_nop 0
	global_load_lds_dwordx4 v[182:183], off
	s_waitcnt vmcnt(8)
	s_waitcnt lgkmcnt(0)
	s_barrier
	s_setprio 1
	v_mfma_f32_16x16x32_bf16 v[62:65], v[166:169], v[202:205], v[62:65]
	v_mfma_f32_16x16x32_bf16 v[54:57], v[174:177], v[202:205], v[54:57]
	v_mfma_f32_16x16x32_bf16 v[46:49], v[166:169], v[210:213], v[46:49]
	v_mfma_f32_16x16x32_bf16 v[38:41], v[174:177], v[210:213], v[38:41]
	v_mfma_f32_16x16x32_bf16 v[30:33], v[166:169], v[218:221], v[30:33]
	v_mfma_f32_16x16x32_bf16 v[22:25], v[174:177], v[218:221], v[22:25]
	v_mfma_f32_16x16x32_bf16 v[14:17], v[166:169], v[226:229], v[14:17]
	v_mfma_f32_16x16x32_bf16 v[6:9], v[174:177], v[226:229], v[6:9]
	v_mfma_f32_16x16x32_bf16 v[62:65], v[170:173], v[206:209], v[62:65]
	v_mfma_f32_16x16x32_bf16 v[54:57], v[178:181], v[206:209], v[54:57]
	v_mfma_f32_16x16x32_bf16 v[46:49], v[170:173], v[214:217], v[46:49]
	v_mfma_f32_16x16x32_bf16 v[38:41], v[178:181], v[214:217], v[38:41]
	v_mfma_f32_16x16x32_bf16 v[30:33], v[170:173], v[222:225], v[30:33]
	v_mfma_f32_16x16x32_bf16 v[22:25], v[178:181], v[222:225], v[22:25]
	v_mfma_f32_16x16x32_bf16 v[14:17], v[170:173], v[230:233], v[14:17]
	v_mfma_f32_16x16x32_bf16 v[6:9], v[178:181], v[230:233], v[6:9]
	v_mfma_f32_16x16x32_bf16 v[58:61], v[186:189], v[202:205], v[58:61]
	v_mfma_f32_16x16x32_bf16 v[50:53], v[194:197], v[202:205], v[50:53]
	v_mfma_f32_16x16x32_bf16 v[42:45], v[186:189], v[210:213], v[42:45]
	v_mfma_f32_16x16x32_bf16 v[34:37], v[194:197], v[210:213], v[34:37]
	v_mfma_f32_16x16x32_bf16 v[26:29], v[186:189], v[218:221], v[26:29]
	v_mfma_f32_16x16x32_bf16 v[18:21], v[194:197], v[218:221], v[18:21]
	v_mfma_f32_16x16x32_bf16 v[10:13], v[186:189], v[226:229], v[10:13]
	v_mfma_f32_16x16x32_bf16 v[2:5], v[194:197], v[226:229], v[2:5]
	v_mfma_f32_16x16x32_bf16 v[58:61], v[190:193], v[206:209], v[58:61]
	v_mfma_f32_16x16x32_bf16 v[50:53], v[198:201], v[206:209], v[50:53]
	v_mfma_f32_16x16x32_bf16 v[42:45], v[190:193], v[214:217], v[42:45]
	v_mfma_f32_16x16x32_bf16 v[34:37], v[198:201], v[214:217], v[34:37]
	v_mfma_f32_16x16x32_bf16 v[26:29], v[190:193], v[222:225], v[26:29]
	v_mfma_f32_16x16x32_bf16 v[18:21], v[198:201], v[222:225], v[18:21]
	v_mfma_f32_16x16x32_bf16 v[10:13], v[190:193], v[230:233], v[10:13]
	v_mfma_f32_16x16x32_bf16 v[2:5], v[198:201], v[230:233], v[2:5]
	s_setprio 0
	s_barrier
	s_add_i32 s65, s65, 2
	s_add_u32 s40, s40, 0x100
	s_addc_u32 s41, s41, 0
	s_add_u32 s63, s63, 0x100
	s_addc_u32 s64, s64, 0
	s_cmp_gt_u32 s65, 13
	s_cbranch_scc0 .LBB0_1234
	s_waitcnt vmcnt(0)
	s_mov_b32 s99, 1
	s_and_b64 vcc, exec, s[18:19]
	s_cbranch_vccz .LBB0_1237
	s_barrier

;     DI bool next(int i, Unit& u) const { if (i > 0 || c >= 64) return false; u.pm = c & 31; u.pn = 0; u.src = c >> 5; return true; }
; #define PG8_STAGE(bufoff, gbase, voff) do { _Pragma("unroll") for (int _i = 0; _i < 2; ++_i) \
;         __builtin_amdgcn_global_load_lds((const unsigned*)((const char*)(gbase) + (voff)[_i]), (LAS unsigned*)(lds + (bufoff) + ldsw + _i * 8192), 16, 0, 0); } while (0)
; template <class Epi, class Sched>
; DI void gemm_phase(LAS unsigned char* lds, const Gemm g, const Sched& S, const Epi& E) {
;     const int tid = threadIdx.x, wid = __builtin_amdgcn_readfirstlane(tid >> 6), lane = tid & 63, wr = wid >> 2, wc = wid & 3, fr = lane & 15, fq = lane >> 4;
;     const int K = g.K, nt = K / BK;
;     unsigned voffA[2], voffB[2];
; #pragma unroll
;     for (int i = 0; i < 2; ++i) { int R, C; stage_rc(tid * 16 + i * 8192, R, C); const int Rb = Epi::PERM ? ((R & ~31) + perm32(R & 31)) : R;
;         voffA[i] = (unsigned)(R * g.lda + C) * 2u; voffB[i] = (unsigned)(Rb * g.ldb + C) * 2u; }
;     const size_t kstep = (size_t)(BK * 2);
;     const size_t hstepA = (size_t)HALF * g.lda * 2, hstepB = (size_t)HALF * g.ldb * 2;
;     const size_t tstepA = 2 * hstepA, tstepB = 2 * hstepB;
;     const unsigned ldsw = (unsigned)wid * 1024u;
;     const int aoff = lds_byte(wr * 64 + fr, fq * 8), boff = lds_byte(wc * 32 + fr, fq * 8);
;     ...
;     Unit cur, nxt; int ui = 0;
;     if (!S.next(0, cur)) return;
;     typename Epi::Pre pre;
;     f32x4 acc[2][2][4][2];
; #pragma unroll
;     for (int a = 0; a < 2; ++a)
; #pragma unroll
;         for (int b = 0; b < 2; ++b)
; #pragma unroll
;             for (int m = 0; m < 4; ++m)
; #pragma unroll
;                 for (int n = 0; n < 2; ++n) acc[a][b][m][n] = (f32x4){0.f, 0.f, 0.f, 0.f};
;     bf16x8 At[4][2], B0[2][2], B1[2][2];
;     const char* cA = (const char*)(cur.src ? g.A1 : g.A0) + (size_t)cur.pm * tstepA; const char* cB = (const char*)(cur.src ? g.B1 : g.B0) + (size_t)cur.pn * tstepB;
;     PG8_STAGE(PG8_SB(0, 0), cB, voffB); PG8_STAGE(PG8_SB(0, 1), cB + hstepB, voffB); PG8_STAGE(PG8_SA(0, 0), cA, voffA); PG8_STAGE(PG8_SA(0, 1), cA + hstepA, voffA);
;     if (wr == 1) PG8_BAR;
;     PG8_WAIT_V(2); PG8_BAR;
;     PG8_STAGE(PG8_SB(1, 0), cB + kstep, voffB); PG8_STAGE(PG8_SA(1, 0), cA + kstep, voffA); PG8_STAGE(PG8_SB(1, 1), cB + hstepB + kstep, voffB);
;     PG8_WAIT_V(6); PG8_BAR;
.LBB0_1317:
	s_lshl_b32 s0, s10, 5
	s_mov_b64 s[10:11], 0x80
	s_and_b32 s14, s0, 0x60
	s_add_i32 m0, s28, 0x18000
	v_lshl_add_u64 v[6:7], v[6:7], 0, s[10:11]
	s_lshl_b32 s13, s4, 13
	s_lshl_b32 s15, s14, 7
	s_waitcnt vmcnt(2)
	s_barrier
	global_load_lds_dwordx4 v[6:7], off
	v_lshl_add_u64 v[4:5], v[4:5], 0, s[10:11]
	s_add_i32 m0, s28, 0x1a000
	s_add_i32 s36, s28, 0x8000
	s_add_i32 s37, s28, 0xa000
	global_load_lds_dwordx4 v[4:5], off
	v_lshl_add_u64 v[0:1], v[0:1], 0, s[10:11]
	s_mov_b32 m0, s36
	s_add_u32 s0, s18, 0xb0080
	global_load_lds_dwordx4 v[0:1], off
	v_lshl_add_u64 v[0:1], v[2:3], 0, s[10:11]
	s_mov_b32 m0, s37
	s_addc_u32 s1, s19, 0
	global_load_lds_dwordx4 v[0:1], off
	s_add_i32 m0, s28, 0x1c000
	v_lshl_add_u64 v[0:1], s[0:1], 0, v[130:131]
	global_load_lds_dwordx4 v[0:1], off
	v_lshl_add_u64 v[0:1], s[0:1], 0, v[134:135]
	s_add_i32 m0, s28, 0x1e000
	v_lshlrev_b32_e32 v2, 2, v184
	global_load_lds_dwordx4 v[0:1], off
	v_and_b32_e32 v0, 15, v184
	v_lshlrev_b32_e32 v1, 1, v10
	v_lshlrev_b32_e32 v3, 6, v184
	s_movk_i32 s0, 0x3c0
	v_lshl_or_b32 v148, s4, 6, v0
	v_lshl_or_b32 v0, v0, 6, v1
	v_and_b32_e32 v2, 32, v2
	v_and_or_b32 v1, v3, s0, v1
	v_bitop3_b32 v149, s15, v1, v2 bitop3:0xf6
	s_waitcnt vmcnt(6)
	s_cmpk_lt_u32 s12, 0x100
	v_add_u16_e32 v1, v8, v9
	v_bitop3_b32 v0, v0, s13, v2 bitop3:0xde
	s_cselect_b64 s[12:13], -1, 0
	v_lshrrev_b16_e32 v1, 1, v1
	s_add_i32 s39, 0, 0x10000
	s_add_i32 s40, 0, 0x14000
	s_sext_i32_i8 s44, s5
	s_ashr_i32 s38, s3, 31
	v_or_b32_e32 v150, s14, v10
	v_add_lshl_u32 v136, v11, v1, 1
	v_mov_b32_e32 v137, v131
	v_add_lshl_u32 v138, v12, v1, 1
	v_mov_b32_e32 v139, v131
	v_mov_b64_e32 v[140:141], 0x400
	v_mov_b64_e32 v[142:143], 0x3ff
	v_add_u32_e32 v151, s39, v149
	v_add_u32_e32 v152, s40, v149
	v_add_u32_e32 v153, 0, v0
	s_barrier
	s_mov_b32 s99, 0
	s_branch .LBB0_1320

; #define PG8_STAGE(bufoff, gbase, voff) do { _Pragma("unroll") for (int _i = 0; _i < 2; ++_i) \
;         __builtin_amdgcn_global_load_lds((const unsigned*)((const char*)(gbase) + (voff)[_i]), (LAS unsigned*)(lds + (bufoff) + ldsw + _i * 8192), 16, 0, 0); } while (0)
; #define PG8_LDA(dst, b, h) do { _Pragma("unroll") for (int m = 0; m < 4; ++m) _Pragma("unroll") for (int k = 0; k < 2; ++k) dst[m][k] = *(const LAS bf16x8*)(lds + PG8_SA(b, h) + aoff + m * 2048 + k * 1024); } while (0)
; #define PG8_LDB(dst, b, h) do { _Pragma("unroll") for (int n = 0; n < 2; ++n) _Pragma("unroll") for (int k = 0; k < 2; ++k) dst[n][k] = *(const LAS bf16x8*)(lds + PG8_SB(b, h) + boff + n * 2048 + k * 1024); } while (0)
; #define PG8_MMA(ai, bj, At, Bt) do { __builtin_amdgcn_s_setprio(1); _Pragma("unroll") for (int m = 0; m < 4; ++m) _Pragma("unroll") for (int n = 0; n < 2; ++n) _Pragma("unroll") for (int k = 0; k < 2; ++k) \
;         acc[ai][bj][m][n] = __builtin_amdgcn_mfma_f32_16x16x32_bf16(Bt[n][k], At[m][k], acc[ai][bj][m][n], 0, 0, 0); __builtin_amdgcn_s_setprio(0); } while (0)
; #define PG8_WAIT_V(n) asm volatile("s_waitcnt vmcnt(" #n ")" ::: "memory")
; template <class Epi, class Sched>
; DI void gemm_phase(LAS unsigned char* lds, const Gemm g, const Sched& S, const Epi& E) {
;     ...
;         const char* nA = has_next ? (const char*)(nxt.src ? g.A1 : g.A0) + (size_t)nxt.pm * tstepA : cA; const char* nB = has_next ? (const char*)(nxt.src ? g.B1 : g.B0) + (size_t)nxt.pn * tstepB : cB;
;         for (int t = 0; t < nt; t += 2) {
;             const bool last = (t == nt - 2);
;             const char* a1 = cA + (size_t)(t + 1) * kstep;
;             const char* a2 = last ? nA : cA + (size_t)(t + 2) * kstep; const char* b2 = last ? nB : cB + (size_t)(t + 2) * kstep;
;             const char* a3 = a2 + kstep; const char* b3 = b2 + kstep;
;             PG8_LDB(B0, 0, 0); PG8_LDB(B1, 0, 1); PG8_SCHED; PG8_LDA(At, 0, 0); PG8_STAGE(PG8_SA(1, 1), a1 + hstepA, voffA);
;             PG8_WAIT_V(8); PG8_WAIT_L(0); PG8_BAR; PG8_MMA(0, 0, At, B0); PG8_MMA(0, 1, At, B1); PG8_BAR; PG8_SCHED;
;             PG8_LDA(At, 0, 1); PG8_STAGE(PG8_SB(0, 0), b2, voffB); PG8_STAGE(PG8_SB(0, 1), b2 + hstepB, voffB); PG8_STAGE(PG8_SA(0, 0), a2, voffA);
;             PG8_WAIT_V(8); PG8_WAIT_L(0); PG8_BAR; PG8_MMA(1, 0, At, B0); PG8_MMA(1, 1, At, B1); PG8_BAR; PG8_SCHED;
.LBB0_1330:
	s_add_u32 s16, s16, 0xb0080
	s_addc_u32 s17, s17, 0
	s_add_u32 s45, s18, 0x100
	s_addc_u32 s46, s19, 0
	s_mov_b32 s47, -2
	ds_read_b128 v[144:147], v151
	ds_read_b128 v[154:157], v151 offset:1024
	ds_read_b128 v[158:161], v151 offset:2048
	ds_read_b128 v[162:165], v151 offset:3072
	ds_read_b128 v[166:169], v152
	ds_read_b128 v[170:173], v152 offset:1024
	ds_read_b128 v[174:177], v152 offset:2048
	ds_read_b128 v[178:181], v152 offset:3072
	s_add_u32 s18, s16, 0xfff50080
	s_addc_u32 s19, s17, -1
	s_cmp_eq_u32 s47, 40
	s_cselect_b32 s21, s5, s19
	s_cselect_b32 s20, s4, s18
	s_cselect_b32 s19, s15, s46
	s_cselect_b32 s18, s14, s45
	v_lshl_add_u64 v[214:215], s[16:17], 0, v[136:137]
	s_add_i32 m0, s28, 0xc000
	ds_read_b128 v[182:185], v153
	ds_read_b128 v[186:189], v153 offset:1024
	ds_read_b128 v[190:193], v153 offset:2048
	ds_read_b128 v[194:197], v153 offset:3072
	ds_read_b128 v[198:201], v153 offset:4096
	ds_read_b128 v[202:205], v153 offset:5120
	ds_read_b128 v[206:209], v153 offset:6144
	ds_read_b128 v[210:213], v153 offset:7168
	global_load_lds_dwordx4 v[214:215], off
	v_lshl_add_u64 v[214:215], s[16:17], 0, v[138:139]
	s_add_i32 m0, s28, 0xe000
	s_nop 0
	global_load_lds_dwordx4 v[214:215], off
	s_cmp_lg_u32 s99, 0
	s_cbranch_scc1 .Lpk6_w1
	s_waitcnt vmcnt(8)
.Lpk6_w1:
	s_waitcnt lgkmcnt(0)
	s_barrier
	s_setprio 1
	v_mfma_f32_16x16x32_bf16 v[124:127], v[144:147], v[182:185], 0
	v_mfma_f32_16x16x32_bf16 v[120:123], v[158:161], v[182:185], 0
	v_mfma_f32_16x16x32_bf16 v[108:111], v[144:147], v[190:193], 0
	v_mfma_f32_16x16x32_bf16 v[104:107], v[158:161], v[190:193], 0
	v_mfma_f32_16x16x32_bf16 v[92:95], v[144:147], v[198:201], 0
	v_mfma_f32_16x16x32_bf16 v[88:91], v[158:161], v[198:201], 0
	v_mfma_f32_16x16x32_bf16 v[76:79], v[144:147], v[206:209], 0
	v_mfma_f32_16x16x32_bf16 v[72:75], v[158:161], v[206:209], 0
	v_mfma_f32_16x16x32_bf16 v[124:127], v[154:157], v[186:189], v[124:127]
	v_mfma_f32_16x16x32_bf16 v[120:123], v[162:165], v[186:189], v[120:123]
	v_mfma_f32_16x16x32_bf16 v[108:111], v[154:157], v[194:197], v[108:111]
	v_mfma_f32_16x16x32_bf16 v[104:107], v[162:165], v[194:197], v[104:107]
	v_mfma_f32_16x16x32_bf16 v[92:95], v[154:157], v[202:205], v[92:95]
	v_mfma_f32_16x16x32_bf16 v[88:91], v[162:165], v[202:205], v[88:91]
	v_mfma_f32_16x16x32_bf16 v[76:79], v[154:157], v[210:213], v[76:79]
	v_mfma_f32_16x16x32_bf16 v[72:75], v[162:165], v[210:213], v[72:75]
	v_mfma_f32_16x16x32_bf16 v[116:119], v[166:169], v[182:185], 0
	v_mfma_f32_16x16x32_bf16 v[112:115], v[174:177], v[182:185], 0
	v_mfma_f32_16x16x32_bf16 v[100:103], v[166:169], v[190:193], 0
	v_mfma_f32_16x16x32_bf16 v[96:99], v[174:177], v[190:193], 0
	v_mfma_f32_16x16x32_bf16 v[84:87], v[166:169], v[198:201], 0
	v_mfma_f32_16x16x32_bf16 v[80:83], v[174:177], v[198:201], 0
	v_mfma_f32_16x16x32_bf16 v[68:71], v[166:169], v[206:209], 0
	v_mfma_f32_16x16x32_bf16 v[64:67], v[174:177], v[206:209], 0
	v_mfma_f32_16x16x32_bf16 v[116:119], v[170:173], v[186:189], v[116:119]
	v_mfma_f32_16x16x32_bf16 v[112:115], v[178:181], v[186:189], v[112:115]
	v_mfma_f32_16x16x32_bf16 v[100:103], v[170:173], v[194:197], v[100:103]
	v_mfma_f32_16x16x32_bf16 v[96:99], v[178:181], v[194:197], v[96:99]
	v_mfma_f32_16x16x32_bf16 v[84:87], v[170:173], v[202:205], v[84:87]
	v_mfma_f32_16x16x32_bf16 v[80:83], v[178:181], v[202:205], v[80:83]
	v_mfma_f32_16x16x32_bf16 v[68:71], v[170:173], v[210:213], v[68:71]
	v_mfma_f32_16x16x32_bf16 v[64:67], v[178:181], v[210:213], v[64:67]
	s_setprio 0
	s_barrier
	s_add_i32 s48, s39, s27
	v_lshl_add_u64 v[214:215], s[18:19], 0, v[130:131]
	s_mov_b32 m0, s48
	ds_read_b128 v[182:185], v153 offset:16384
	ds_read_b128 v[186:189], v153 offset:17408
	ds_read_b128 v[190:193], v153 offset:18432
	ds_read_b128 v[194:197], v153 offset:19456
	ds_read_b128 v[198:201], v153 offset:20480
	ds_read_b128 v[202:205], v153 offset:21504
	ds_read_b128 v[206:209], v153 offset:22528
	ds_read_b128 v[210:213], v153 offset:23552
	global_load_lds_dwordx4 v[214:215], off
	s_add_i32 m0, s48, 0x2000
	s_add_u32 s48, s18, 0xb0000
	v_lshl_add_u64 v[216:217], s[18:19], 0, v[134:135]
	s_addc_u32 s49, s19, 0
	s_add_i32 s50, s40, s27
	global_load_lds_dwordx4 v[216:217], off
	v_lshl_add_u64 v[218:219], s[48:49], 0, v[130:131]
	s_mov_b32 m0, s50
	v_lshl_add_u64 v[220:221], s[20:21], 0, v[132:133]
	global_load_lds_dwordx4 v[218:219], off
	v_lshl_add_u64 v[218:219], s[48:49], 0, v[134:135]
	s_add_i32 m0, s50, 0x2000
	s_nop 0
	global_load_lds_dwordx4 v[218:219], off
	v_lshl_add_u64 v[218:219], s[20:21], 0, v[128:129]
	s_mov_b32 m0, s28
	s_nop 0
	global_load_lds_dwordx4 v[218:219], off
	s_mov_b32 m0, s29
	s_nop 0
	global_load_lds_dwordx4 v[220:221], off
	s_cmp_lg_u32 s99, 0
	s_cbranch_scc1 .Lpk6_w2
	s_waitcnt vmcnt(8)
; #define PG8_STAGE(bufoff, gbase, voff) do { _Pragma("unroll") for (int _i = 0; _i < 2; ++_i) \
;         __builtin_amdgcn_global_load_lds((const unsigned*)((const char*)(gbase) + (voff)[_i]), (LAS unsigned*)(lds + (bufoff) + ldsw + _i * 8192), 16, 0, 0); } while (0)
; #define PG8_LDA(dst, b, h) do { _Pragma("unroll") for (int m = 0; m < 4; ++m) _Pragma("unroll") for (int k = 0; k < 2; ++k) dst[m][k] = *(const LAS bf16x8*)(lds + PG8_SA(b, h) + aoff + m * 2048 + k * 1024); } while (0)
; #define PG8_LDB(dst, b, h) do { _Pragma("unroll") for (int n = 0; n < 2; ++n) _Pragma("unroll") for (int k = 0; k < 2; ++k) dst[n][k] = *(const LAS bf16x8*)(lds + PG8_SB(b, h) + boff + n * 2048 + k * 1024); } while (0)
; #define PG8_MMA(ai, bj, At, Bt) do { __builtin_amdgcn_s_setprio(1); _Pragma("unroll") for (int m = 0; m < 4; ++m) _Pragma("unroll") for (int n = 0; n < 2; ++n) _Pragma("unroll") for (int k = 0; k < 2; ++k) \
;         acc[ai][bj][m][n] = __builtin_amdgcn_mfma_f32_16x16x32_bf16(Bt[n][k], At[m][k], acc[ai][bj][m][n], 0, 0, 0); __builtin_amdgcn_s_setprio(0); } while (0)
; #define PG8_WAIT_V(n) asm volatile("s_waitcnt vmcnt(" #n ")" ::: "memory")
; #define PG8_WAIT_L(n) asm volatile("s_waitcnt lgkmcnt(" #n ")" ::: "memory")
; #define PG8_BAR __builtin_amdgcn_s_barrier()
; #define PG8_SCHED __builtin_amdgcn_sched_barrier(0)
; template <class Epi, class Sched>
; DI void gemm_phase(LAS unsigned char* lds, const Gemm g, const Sched& S, const Epi& E) {
;     ...
;             PG8_WAIT_V(8); PG8_WAIT_L(0); PG8_BAR; PG8_MMA(1, 0, At, B0); PG8_MMA(1, 1, At, B1); PG8_BAR; PG8_SCHED;
;             PG8_LDB(B0, 1, 0); PG8_LDB(B1, 1, 1); PG8_SCHED; PG8_LDA(At, 1, 0); PG8_STAGE(PG8_SA(0, 1), a2 + hstepA, voffA);
;             PG8_WAIT_V(8); PG8_WAIT_L(0); PG8_BAR; PG8_MMA(0, 0, At, B0); PG8_MMA(0, 1, At, B1); PG8_BAR; PG8_SCHED;
.Lpk6_w2:
	s_mov_b32 s99, 0
	s_waitcnt lgkmcnt(0)
	s_barrier
	s_setprio 1
	v_mfma_f32_16x16x32_bf16 v[60:63], v[144:147], v[182:185], 0
	v_mfma_f32_16x16x32_bf16 v[56:59], v[158:161], v[182:185], 0
	v_mfma_f32_16x16x32_bf16 v[44:47], v[144:147], v[190:193], 0
	v_mfma_f32_16x16x32_bf16 v[40:43], v[158:161], v[190:193], 0
	v_mfma_f32_16x16x32_bf16 v[28:31], v[144:147], v[198:201], 0
	v_mfma_f32_16x16x32_bf16 v[24:27], v[158:161], v[198:201], 0
	v_mfma_f32_16x16x32_bf16 v[12:15], v[144:147], v[206:209], 0
	v_mfma_f32_16x16x32_bf16 v[8:11], v[158:161], v[206:209], 0
	v_mfma_f32_16x16x32_bf16 v[60:63], v[154:157], v[186:189], v[60:63]
	v_mfma_f32_16x16x32_bf16 v[56:59], v[162:165], v[186:189], v[56:59]
	v_mfma_f32_16x16x32_bf16 v[44:47], v[154:157], v[194:197], v[44:47]
	v_mfma_f32_16x16x32_bf16 v[40:43], v[162:165], v[194:197], v[40:43]
	v_mfma_f32_16x16x32_bf16 v[28:31], v[154:157], v[202:205], v[28:31]
	v_mfma_f32_16x16x32_bf16 v[24:27], v[162:165], v[202:205], v[24:27]
	v_mfma_f32_16x16x32_bf16 v[12:15], v[154:157], v[210:213], v[12:15]
	v_mfma_f32_16x16x32_bf16 v[8:11], v[162:165], v[210:213], v[8:11]
	v_mfma_f32_16x16x32_bf16 v[52:55], v[166:169], v[182:185], 0
	v_mfma_f32_16x16x32_bf16 v[48:51], v[174:177], v[182:185], 0
	v_mfma_f32_16x16x32_bf16 v[36:39], v[166:169], v[190:193], 0
	v_mfma_f32_16x16x32_bf16 v[32:35], v[174:177], v[190:193], 0
	v_mfma_f32_16x16x32_bf16 v[20:23], v[166:169], v[198:201], 0
	v_mfma_f32_16x16x32_bf16 v[16:19], v[174:177], v[198:201], 0
	v_mfma_f32_16x16x32_bf16 v[4:7], v[166:169], v[206:209], 0
	v_mfma_f32_16x16x32_bf16 v[0:3], v[174:177], v[206:209], 0
	v_mfma_f32_16x16x32_bf16 v[52:55], v[170:173], v[186:189], v[52:55]
	v_mfma_f32_16x16x32_bf16 v[48:51], v[178:181], v[186:189], v[48:51]
	v_mfma_f32_16x16x32_bf16 v[36:39], v[170:173], v[194:197], v[36:39]
	v_mfma_f32_16x16x32_bf16 v[32:35], v[178:181], v[194:197], v[32:35]
	v_mfma_f32_16x16x32_bf16 v[20:23], v[170:173], v[202:205], v[20:23]
	v_mfma_f32_16x16x32_bf16 v[16:19], v[178:181], v[202:205], v[16:19]
	v_mfma_f32_16x16x32_bf16 v[4:7], v[170:173], v[210:213], v[4:7]
	v_mfma_f32_16x16x32_bf16 v[0:3], v[178:181], v[210:213], v[0:3]
	s_setprio 0
	s_barrier
	s_add_i32 s48, 0, 0x18000
	s_add_i32 s49, 0, 0x1c000
	v_add_u32_e32 v162, s48, v149
	v_add_u32_e32 v178, s49, v149
	ds_read_b128 v[144:147], v162
	ds_read_b128 v[154:157], v162 offset:1024
	ds_read_b128 v[158:161], v162 offset:2048
	ds_read_b128 v[162:165], v162 offset:3072
	ds_read_b128 v[166:169], v178
	ds_read_b128 v[170:173], v178 offset:1024
	ds_read_b128 v[174:177], v178 offset:2048
	ds_read_b128 v[178:181], v178 offset:3072
	s_add_u32 s20, s20, 0xb0000
	s_addc_u32 s21, s21, 0
	s_mov_b32 m0, s33
	v_lshl_add_u64 v[222:223], s[20:21], 0, v[128:129]
	ds_read_b128 v[182:185], v153 offset:32768
	ds_read_b128 v[186:189], v153 offset:33792
	ds_read_b128 v[190:193], v153 offset:34816
	ds_read_b128 v[194:197], v153 offset:35840
	ds_read_b128 v[198:201], v153 offset:36864
	ds_read_b128 v[202:205], v153 offset:37888
	ds_read_b128 v[206:209], v153 offset:38912
	ds_read_b128 v[210:213], v153 offset:39936
	global_load_lds_dwordx4 v[222:223], off
	v_lshl_add_u64 v[222:223], s[20:21], 0, v[132:133]
	s_mov_b32 m0, s34
	s_nop 0
	global_load_lds_dwordx4 v[222:223], off
	s_waitcnt vmcnt(8)
	s_waitcnt lgkmcnt(0)
	s_barrier
	s_setprio 1
	v_mfma_f32_16x16x32_bf16 v[124:127], v[144:147], v[182:185], v[124:127]
	v_mfma_f32_16x16x32_bf16 v[120:123], v[158:161], v[182:185], v[120:123]
	v_mfma_f32_16x16x32_bf16 v[108:111], v[144:147], v[190:193], v[108:111]
	v_mfma_f32_16x16x32_bf16 v[104:107], v[158:161], v[190:193], v[104:107]
	v_mfma_f32_16x16x32_bf16 v[92:95], v[144:147], v[198:201], v[92:95]
	v_mfma_f32_16x16x32_bf16 v[88:91], v[158:161], v[198:201], v[88:91]
	v_mfma_f32_16x16x32_bf16 v[76:79], v[144:147], v[206:209], v[76:79]
	v_mfma_f32_16x16x32_bf16 v[72:75], v[158:161], v[206:209], v[72:75]
	v_mfma_f32_16x16x32_bf16 v[124:127], v[154:157], v[186:189], v[124:127]
	v_mfma_f32_16x16x32_bf16 v[120:123], v[162:165], v[186:189], v[120:123]
	v_mfma_f32_16x16x32_bf16 v[108:111], v[154:157], v[194:197], v[108:111]
	v_mfma_f32_16x16x32_bf16 v[104:107], v[162:165], v[194:197], v[104:107]
	v_mfma_f32_16x16x32_bf16 v[92:95], v[154:157], v[202:205], v[92:95]
	v_mfma_f32_16x16x32_bf16 v[88:91], v[162:165], v[202:205], v[88:91]
	v_mfma_f32_16x16x32_bf16 v[76:79], v[154:157], v[210:213], v[76:79]
	v_mfma_f32_16x16x32_bf16 v[72:75], v[162:165], v[210:213], v[72:75]
	v_mfma_f32_16x16x32_bf16 v[116:119], v[166:169], v[182:185], v[116:119]
	v_mfma_f32_16x16x32_bf16 v[112:115], v[174:177], v[182:185], v[112:115]
	v_mfma_f32_16x16x32_bf16 v[100:103], v[166:169], v[190:193], v[100:103]
	v_mfma_f32_16x16x32_bf16 v[96:99], v[174:177], v[190:193], v[96:99]
	v_mfma_f32_16x16x32_bf16 v[84:87], v[166:169], v[198:201], v[84:87]
	v_mfma_f32_16x16x32_bf16 v[80:83], v[174:177], v[198:201], v[80:83]
	v_mfma_f32_16x16x32_bf16 v[68:71], v[166:169], v[206:209], v[68:71]
	v_mfma_f32_16x16x32_bf16 v[64:67], v[174:177], v[206:209], v[64:67]
	v_mfma_f32_16x16x32_bf16 v[116:119], v[170:173], v[186:189], v[116:119]
	v_mfma_f32_16x16x32_bf16 v[112:115], v[178:181], v[186:189], v[112:115]
	v_mfma_f32_16x16x32_bf16 v[100:103], v[170:173], v[194:197], v[100:103]
	v_mfma_f32_16x16x32_bf16 v[96:99], v[178:181], v[194:197], v[96:99]
	v_mfma_f32_16x16x32_bf16 v[84:87], v[170:173], v[202:205], v[84:87]
	v_mfma_f32_16x16x32_bf16 v[80:83], v[178:181], v[202:205], v[80:83]
	v_mfma_f32_16x16x32_bf16 v[68:71], v[170:173], v[210:213], v[68:71]
	v_mfma_f32_16x16x32_bf16 v[64:67], v[178:181], v[210:213], v[64:67]
	s_setprio 0
	s_barrier
; #define PG8_STAGE(bufoff, gbase, voff) do { _Pragma("unroll") for (int _i = 0; _i < 2; ++_i) \
;         __builtin_amdgcn_global_load_lds((const unsigned*)((const char*)(gbase) + (voff)[_i]), (LAS unsigned*)(lds + (bufoff) + ldsw + _i * 8192), 16, 0, 0); } while (0)
; #define PG8_LDA(dst, b, h) do { _Pragma("unroll") for (int m = 0; m < 4; ++m) _Pragma("unroll") for (int k = 0; k < 2; ++k) dst[m][k] = *(const LAS bf16x8*)(lds + PG8_SA(b, h) + aoff + m * 2048 + k * 1024); } while (0)
; #define PG8_LDB(dst, b, h) do { _Pragma("unroll") for (int n = 0; n < 2; ++n) _Pragma("unroll") for (int k = 0; k < 2; ++k) dst[n][k] = *(const LAS bf16x8*)(lds + PG8_SB(b, h) + boff + n * 2048 + k * 1024); } while (0)
; #define PG8_MMA(ai, bj, At, Bt) do { __builtin_amdgcn_s_setprio(1); _Pragma("unroll") for (int m = 0; m < 4; ++m) _Pragma("unroll") for (int n = 0; n < 2; ++n) _Pragma("unroll") for (int k = 0; k < 2; ++k) \
;         acc[ai][bj][m][n] = __builtin_amdgcn_mfma_f32_16x16x32_bf16(Bt[n][k], At[m][k], acc[ai][bj][m][n], 0, 0, 0); __builtin_amdgcn_s_setprio(0); } while (0)
; #define PG8_WAIT_V(n) asm volatile("s_waitcnt vmcnt(" #n ")" ::: "memory")
; #define PG8_BAR __builtin_amdgcn_s_barrier()
; template <class Epi, class Sched>
; DI void gemm_phase(LAS unsigned char* lds, const Gemm g, const Sched& S, const Epi& E) {
;     ...
;             PG8_LDB(B0, 0, 0); PG8_LDB(B1, 0, 1); PG8_SCHED; PG8_LDA(At, 0, 0); PG8_STAGE(PG8_SA(1, 1), a1 + hstepA, voffA);
;             PG8_WAIT_V(8); PG8_WAIT_L(0); PG8_BAR; PG8_MMA(0, 0, At, B0); PG8_MMA(0, 1, At, B1); PG8_BAR; PG8_SCHED;
;             PG8_LDA(At, 0, 1); PG8_STAGE(PG8_SB(0, 0), b2, voffB); PG8_STAGE(PG8_SB(0, 1), b2 + hstepB, voffB); PG8_STAGE(PG8_SA(0, 0), a2, voffA);
;             PG8_WAIT_V(8); PG8_WAIT_L(0); PG8_BAR; PG8_MMA(1, 0, At, B0); PG8_MMA(1, 1, At, B1); PG8_BAR; PG8_SCHED;
;             PG8_LDB(B0, 1, 0); PG8_LDB(B1, 1, 1); PG8_SCHED; PG8_LDA(At, 1, 0); PG8_STAGE(PG8_SA(0, 1), a2 + hstepA, voffA);
;             PG8_WAIT_V(8); PG8_WAIT_L(0); PG8_BAR; PG8_MMA(0, 0, At, B0); PG8_MMA(0, 1, At, B1); PG8_BAR; PG8_SCHED;
;             PG8_LDA(At, 1, 1); PG8_STAGE(PG8_SB(1, 0), b3, voffB); PG8_STAGE(PG8_SB(1, 1), b3 + hstepB, voffB); PG8_STAGE(PG8_SA(1, 0), a3, voffA);
;             PG8_WAIT_V(8); PG8_WAIT_L(0); PG8_BAR; PG8_MMA(1, 0, At, B0); PG8_MMA(1, 1, At, B1); PG8_BAR; PG8_SCHED;
;         }
	s_add_i32 s20, s48, s27
	v_lshl_add_u64 v[214:215], v[214:215], 0, s[10:11]
	s_mov_b32 m0, s20
	ds_read_b128 v[182:185], v153 offset:49152
	ds_read_b128 v[186:189], v153 offset:50176
	ds_read_b128 v[190:193], v153 offset:51200
	ds_read_b128 v[194:197], v153 offset:52224
	ds_read_b128 v[198:201], v153 offset:53248
	ds_read_b128 v[202:205], v153 offset:54272
	ds_read_b128 v[206:209], v153 offset:55296
	ds_read_b128 v[210:213], v153 offset:56320
	global_load_lds_dwordx4 v[214:215], off
	s_add_i32 m0, s20, 0x2000
	s_add_u32 s18, s18, 0xb0080
	v_lshl_add_u64 v[214:215], v[216:217], 0, s[10:11]
	s_addc_u32 s19, s19, 0
	s_add_i32 s20, s49, s27
	global_load_lds_dwordx4 v[214:215], off
	v_lshl_add_u64 v[214:215], s[18:19], 0, v[130:131]
	s_mov_b32 m0, s20
	s_nop 0
	global_load_lds_dwordx4 v[214:215], off
	v_lshl_add_u64 v[214:215], s[18:19], 0, v[134:135]
	s_add_i32 m0, s20, 0x2000
	s_nop 0
	global_load_lds_dwordx4 v[214:215], off
	v_lshl_add_u64 v[214:215], v[218:219], 0, s[10:11]
	s_mov_b32 m0, s36
	s_nop 0
	global_load_lds_dwordx4 v[214:215], off
	v_lshl_add_u64 v[214:215], v[220:221], 0, s[10:11]
	s_mov_b32 m0, s37
	s_nop 0
	global_load_lds_dwordx4 v[214:215], off
	s_waitcnt vmcnt(8)
	s_waitcnt lgkmcnt(0)
	s_barrier
	s_setprio 1
	v_mfma_f32_16x16x32_bf16 v[60:63], v[144:147], v[182:185], v[60:63]
	v_mfma_f32_16x16x32_bf16 v[56:59], v[158:161], v[182:185], v[56:59]
	v_mfma_f32_16x16x32_bf16 v[44:47], v[144:147], v[190:193], v[44:47]
	v_mfma_f32_16x16x32_bf16 v[40:43], v[158:161], v[190:193], v[40:43]
	v_mfma_f32_16x16x32_bf16 v[28:31], v[144:147], v[198:201], v[28:31]
	v_mfma_f32_16x16x32_bf16 v[24:27], v[158:161], v[198:201], v[24:27]
	v_mfma_f32_16x16x32_bf16 v[12:15], v[144:147], v[206:209], v[12:15]
	v_mfma_f32_16x16x32_bf16 v[8:11], v[158:161], v[206:209], v[8:11]
	v_mfma_f32_16x16x32_bf16 v[60:63], v[154:157], v[186:189], v[60:63]
	v_mfma_f32_16x16x32_bf16 v[56:59], v[162:165], v[186:189], v[56:59]
	v_mfma_f32_16x16x32_bf16 v[44:47], v[154:157], v[194:197], v[44:47]
	v_mfma_f32_16x16x32_bf16 v[40:43], v[162:165], v[194:197], v[40:43]
	v_mfma_f32_16x16x32_bf16 v[28:31], v[154:157], v[202:205], v[28:31]
	v_mfma_f32_16x16x32_bf16 v[24:27], v[162:165], v[202:205], v[24:27]
	v_mfma_f32_16x16x32_bf16 v[12:15], v[154:157], v[210:213], v[12:15]
	v_mfma_f32_16x16x32_bf16 v[8:11], v[162:165], v[210:213], v[8:11]
	v_mfma_f32_16x16x32_bf16 v[52:55], v[166:169], v[182:185], v[52:55]
	v_mfma_f32_16x16x32_bf16 v[48:51], v[174:177], v[182:185], v[48:51]
	v_mfma_f32_16x16x32_bf16 v[36:39], v[166:169], v[190:193], v[36:39]
	v_mfma_f32_16x16x32_bf16 v[32:35], v[174:177], v[190:193], v[32:35]
	v_mfma_f32_16x16x32_bf16 v[20:23], v[166:169], v[198:201], v[20:23]
	v_mfma_f32_16x16x32_bf16 v[16:19], v[174:177], v[198:201], v[16:19]
	v_mfma_f32_16x16x32_bf16 v[4:7], v[166:169], v[206:209], v[4:7]
	v_mfma_f32_16x16x32_bf16 v[0:3], v[174:177], v[206:209], v[0:3]
	v_mfma_f32_16x16x32_bf16 v[52:55], v[170:173], v[186:189], v[52:55]
	v_mfma_f32_16x16x32_bf16 v[48:51], v[178:181], v[186:189], v[48:51]
	v_mfma_f32_16x16x32_bf16 v[36:39], v[170:173], v[194:197], v[36:39]
	v_mfma_f32_16x16x32_bf16 v[32:35], v[178:181], v[194:197], v[32:35]
	v_mfma_f32_16x16x32_bf16 v[20:23], v[170:173], v[202:205], v[20:23]
	v_mfma_f32_16x16x32_bf16 v[16:19], v[178:181], v[202:205], v[16:19]
	v_mfma_f32_16x16x32_bf16 v[4:7], v[170:173], v[210:213], v[4:7]
	v_mfma_f32_16x16x32_bf16 v[0:3], v[178:181], v[210:213], v[0:3]
	s_setprio 0
	s_barrier
	s_add_i32 s47, s47, 2
	s_add_u32 s16, s16, 0x100
	s_addc_u32 s17, s17, 0
	s_add_u32 s45, s45, 0x100
	s_addc_u32 s46, s46, 0
	s_cmp_gt_u32 s47, 41
.LBB0_1331:
	ds_read_b128 v[144:147], v151
	ds_read_b128 v[154:157], v151 offset:1024
	ds_read_b128 v[158:161], v151 offset:2048
	ds_read_b128 v[162:165], v151 offset:3072
	ds_read_b128 v[166:169], v152
	ds_read_b128 v[170:173], v152 offset:1024
	ds_read_b128 v[174:177], v152 offset:2048
	ds_read_b128 v[178:181], v152 offset:3072
	s_add_u32 s18, s16, 0xfff50080
	s_addc_u32 s19, s17, -1
	s_cmp_eq_u32 s47, 40
	s_cselect_b32 s21, s5, s19
	s_cselect_b32 s20, s4, s18
	s_cselect_b32 s19, s15, s46
	s_cselect_b32 s18, s14, s45
	v_lshl_add_u64 v[214:215], s[16:17], 0, v[136:137]
	s_add_i32 m0, s28, 0xc000
	ds_read_b128 v[182:185], v153
	ds_read_b128 v[186:189], v153 offset:1024
	ds_read_b128 v[190:193], v153 offset:2048
	ds_read_b128 v[194:197], v153 offset:3072
	ds_read_b128 v[198:201], v153 offset:4096
	ds_read_b128 v[202:205], v153 offset:5120
	ds_read_b128 v[206:209], v153 offset:6144
	ds_read_b128 v[210:213], v153 offset:7168
	global_load_lds_dwordx4 v[214:215], off
	v_lshl_add_u64 v[214:215], s[16:17], 0, v[138:139]
	s_add_i32 m0, s28, 0xe000
	s_nop 0
	global_load_lds_dwordx4 v[214:215], off
	s_waitcnt vmcnt(8)
	s_waitcnt lgkmcnt(0)
	s_barrier
; #define PG8_STAGE(bufoff, gbase, voff) do { _Pragma("unroll") for (int _i = 0; _i < 2; ++_i) \
;         __builtin_amdgcn_global_load_lds((const unsigned*)((const char*)(gbase) + (voff)[_i]), (LAS unsigned*)(lds + (bufoff) + ldsw + _i * 8192), 16, 0, 0); } while (0)
; #define PG8_LDA(dst, b, h) do { _Pragma("unroll") for (int m = 0; m < 4; ++m) _Pragma("unroll") for (int k = 0; k < 2; ++k) dst[m][k] = *(const LAS bf16x8*)(lds + PG8_SA(b, h) + aoff + m * 2048 + k * 1024); } while (0)
; #define PG8_MMA(ai, bj, At, Bt) do { __builtin_amdgcn_s_setprio(1); _Pragma("unroll") for (int m = 0; m < 4; ++m) _Pragma("unroll") for (int n = 0; n < 2; ++n) _Pragma("unroll") for (int k = 0; k < 2; ++k) \
;         acc[ai][bj][m][n] = __builtin_amdgcn_mfma_f32_16x16x32_bf16(Bt[n][k], At[m][k], acc[ai][bj][m][n], 0, 0, 0); __builtin_amdgcn_s_setprio(0); } while (0)
; #define PG8_WAIT_V(n) asm volatile("s_waitcnt vmcnt(" #n ")" ::: "memory")
; #define PG8_WAIT_L(n) asm volatile("s_waitcnt lgkmcnt(" #n ")" ::: "memory")
; #define PG8_BAR __builtin_amdgcn_s_barrier()
; #define PG8_SCHED __builtin_amdgcn_sched_barrier(0)
; template <class Epi, class Sched>
; DI void gemm_phase(LAS unsigned char* lds, const Gemm g, const Sched& S, const Epi& E) {
;     ...
;             PG8_WAIT_V(8); PG8_WAIT_L(0); PG8_BAR; PG8_MMA(0, 0, At, B0); PG8_MMA(0, 1, At, B1); PG8_BAR; PG8_SCHED;
;             PG8_LDA(At, 0, 1); PG8_STAGE(PG8_SB(0, 0), b2, voffB); PG8_STAGE(PG8_SB(0, 1), b2 + hstepB, voffB); PG8_STAGE(PG8_SA(0, 0), a2, voffA);
;             PG8_WAIT_V(8); PG8_WAIT_L(0); PG8_BAR; PG8_MMA(1, 0, At, B0); PG8_MMA(1, 1, At, B1); PG8_BAR; PG8_SCHED;
	s_setprio 1
	v_mfma_f32_16x16x32_bf16 v[124:127], v[144:147], v[182:185], v[124:127]
	v_mfma_f32_16x16x32_bf16 v[120:123], v[158:161], v[182:185], v[120:123]
	v_mfma_f32_16x16x32_bf16 v[108:111], v[144:147], v[190:193], v[108:111]
	v_mfma_f32_16x16x32_bf16 v[104:107], v[158:161], v[190:193], v[104:107]
	v_mfma_f32_16x16x32_bf16 v[92:95], v[144:147], v[198:201], v[92:95]
	v_mfma_f32_16x16x32_bf16 v[88:91], v[158:161], v[198:201], v[88:91]
	v_mfma_f32_16x16x32_bf16 v[76:79], v[144:147], v[206:209], v[76:79]
	v_mfma_f32_16x16x32_bf16 v[72:75], v[158:161], v[206:209], v[72:75]
	v_mfma_f32_16x16x32_bf16 v[124:127], v[154:157], v[186:189], v[124:127]
	v_mfma_f32_16x16x32_bf16 v[120:123], v[162:165], v[186:189], v[120:123]
	v_mfma_f32_16x16x32_bf16 v[108:111], v[154:157], v[194:197], v[108:111]
	v_mfma_f32_16x16x32_bf16 v[104:107], v[162:165], v[194:197], v[104:107]
	v_mfma_f32_16x16x32_bf16 v[92:95], v[154:157], v[202:205], v[92:95]
	v_mfma_f32_16x16x32_bf16 v[88:91], v[162:165], v[202:205], v[88:91]
	v_mfma_f32_16x16x32_bf16 v[76:79], v[154:157], v[210:213], v[76:79]
	v_mfma_f32_16x16x32_bf16 v[72:75], v[162:165], v[210:213], v[72:75]
	v_mfma_f32_16x16x32_bf16 v[116:119], v[166:169], v[182:185], v[116:119]
	v_mfma_f32_16x16x32_bf16 v[112:115], v[174:177], v[182:185], v[112:115]
	v_mfma_f32_16x16x32_bf16 v[100:103], v[166:169], v[190:193], v[100:103]
	v_mfma_f32_16x16x32_bf16 v[96:99], v[174:177], v[190:193], v[96:99]
	v_mfma_f32_16x16x32_bf16 v[84:87], v[166:169], v[198:201], v[84:87]
	v_mfma_f32_16x16x32_bf16 v[80:83], v[174:177], v[198:201], v[80:83]
	v_mfma_f32_16x16x32_bf16 v[68:71], v[166:169], v[206:209], v[68:71]
	v_mfma_f32_16x16x32_bf16 v[64:67], v[174:177], v[206:209], v[64:67]
	v_mfma_f32_16x16x32_bf16 v[116:119], v[170:173], v[186:189], v[116:119]
	v_mfma_f32_16x16x32_bf16 v[112:115], v[178:181], v[186:189], v[112:115]
	v_mfma_f32_16x16x32_bf16 v[100:103], v[170:173], v[194:197], v[100:103]
	v_mfma_f32_16x16x32_bf16 v[96:99], v[178:181], v[194:197], v[96:99]
	v_mfma_f32_16x16x32_bf16 v[84:87], v[170:173], v[202:205], v[84:87]
	v_mfma_f32_16x16x32_bf16 v[80:83], v[178:181], v[202:205], v[80:83]
	v_mfma_f32_16x16x32_bf16 v[68:71], v[170:173], v[210:213], v[68:71]
	v_mfma_f32_16x16x32_bf16 v[64:67], v[178:181], v[210:213], v[64:67]
	s_setprio 0
	s_barrier
	s_add_i32 s48, s39, s27
	v_lshl_add_u64 v[214:215], s[18:19], 0, v[130:131]
	s_mov_b32 m0, s48
	ds_read_b128 v[182:185], v153 offset:16384
	ds_read_b128 v[186:189], v153 offset:17408
	ds_read_b128 v[190:193], v153 offset:18432
	ds_read_b128 v[194:197], v153 offset:19456
	ds_read_b128 v[198:201], v153 offset:20480
	ds_read_b128 v[202:205], v153 offset:21504
	ds_read_b128 v[206:209], v153 offset:22528
	ds_read_b128 v[210:213], v153 offset:23552
	global_load_lds_dwordx4 v[214:215], off
	s_add_i32 m0, s48, 0x2000
	s_add_u32 s48, s18, 0xb0000
	v_lshl_add_u64 v[216:217], s[18:19], 0, v[134:135]
	s_addc_u32 s49, s19, 0
	s_add_i32 s50, s40, s27
	global_load_lds_dwordx4 v[216:217], off
	v_lshl_add_u64 v[218:219], s[48:49], 0, v[130:131]
	s_mov_b32 m0, s50
	v_lshl_add_u64 v[220:221], s[20:21], 0, v[132:133]
	global_load_lds_dwordx4 v[218:219], off
	v_lshl_add_u64 v[218:219], s[48:49], 0, v[134:135]
	s_add_i32 m0, s50, 0x2000
	s_nop 0
	global_load_lds_dwordx4 v[218:219], off
	v_lshl_add_u64 v[218:219], s[20:21], 0, v[128:129]
	s_mov_b32 m0, s28
	s_nop 0
	global_load_lds_dwordx4 v[218:219], off
	s_mov_b32 m0, s29
	s_nop 0
	global_load_lds_dwordx4 v[220:221], off
	s_waitcnt vmcnt(8)
	s_waitcnt lgkmcnt(0)
	s_barrier
	s_setprio 1
	v_mfma_f32_16x16x32_bf16 v[60:63], v[144:147], v[182:185], v[60:63]
	v_mfma_f32_16x16x32_bf16 v[56:59], v[158:161], v[182:185], v[56:59]
	v_mfma_f32_16x16x32_bf16 v[44:47], v[144:147], v[190:193], v[44:47]
	v_mfma_f32_16x16x32_bf16 v[40:43], v[158:161], v[190:193], v[40:43]
	v_mfma_f32_16x16x32_bf16 v[28:31], v[144:147], v[198:201], v[28:31]
	v_mfma_f32_16x16x32_bf16 v[24:27], v[158:161], v[198:201], v[24:27]
	v_mfma_f32_16x16x32_bf16 v[12:15], v[144:147], v[206:209], v[12:15]
	v_mfma_f32_16x16x32_bf16 v[8:11], v[158:161], v[206:209], v[8:11]
	v_mfma_f32_16x16x32_bf16 v[60:63], v[154:157], v[186:189], v[60:63]
	v_mfma_f32_16x16x32_bf16 v[56:59], v[162:165], v[186:189], v[56:59]
	v_mfma_f32_16x16x32_bf16 v[44:47], v[154:157], v[194:197], v[44:47]
	v_mfma_f32_16x16x32_bf16 v[40:43], v[162:165], v[194:197], v[40:43]
	v_mfma_f32_16x16x32_bf16 v[28:31], v[154:157], v[202:205], v[28:31]
	v_mfma_f32_16x16x32_bf16 v[24:27], v[162:165], v[202:205], v[24:27]
	v_mfma_f32_16x16x32_bf16 v[12:15], v[154:157], v[210:213], v[12:15]
	v_mfma_f32_16x16x32_bf16 v[8:11], v[162:165], v[210:213], v[8:11]
	v_mfma_f32_16x16x32_bf16 v[52:55], v[166:169], v[182:185], v[52:55]
	v_mfma_f32_16x16x32_bf16 v[48:51], v[174:177], v[182:185], v[48:51]
	v_mfma_f32_16x16x32_bf16 v[36:39], v[166:169], v[190:193], v[36:39]
	v_mfma_f32_16x16x32_bf16 v[32:35], v[174:177], v[190:193], v[32:35]
	v_mfma_f32_16x16x32_bf16 v[20:23], v[166:169], v[198:201], v[20:23]
	v_mfma_f32_16x16x32_bf16 v[16:19], v[174:177], v[198:201], v[16:19]
	v_mfma_f32_16x16x32_bf16 v[4:7], v[166:169], v[206:209], v[4:7]
	v_mfma_f32_16x16x32_bf16 v[0:3], v[174:177], v[206:209], v[0:3]
	v_mfma_f32_16x16x32_bf16 v[52:55], v[170:173], v[186:189], v[52:55]
	v_mfma_f32_16x16x32_bf16 v[48:51], v[178:181], v[186:189], v[48:51]
	v_mfma_f32_16x16x32_bf16 v[36:39], v[170:173], v[194:197], v[36:39]
	v_mfma_f32_16x16x32_bf16 v[32:35], v[178:181], v[194:197], v[32:35]
	v_mfma_f32_16x16x32_bf16 v[20:23], v[170:173], v[202:205], v[20:23]
	v_mfma_f32_16x16x32_bf16 v[16:19], v[178:181], v[202:205], v[16:19]
	v_mfma_f32_16x16x32_bf16 v[4:7], v[170:173], v[210:213], v[4:7]
	v_mfma_f32_16x16x32_bf16 v[0:3], v[178:181], v[210:213], v[0:3]
	s_setprio 0
	s_barrier
; #define PG8_STAGE(bufoff, gbase, voff) do { _Pragma("unroll") for (int _i = 0; _i < 2; ++_i) \
;         __builtin_amdgcn_global_load_lds((const unsigned*)((const char*)(gbase) + (voff)[_i]), (LAS unsigned*)(lds + (bufoff) + ldsw + _i * 8192), 16, 0, 0); } while (0)
; #define PG8_LDA(dst, b, h) do { _Pragma("unroll") for (int m = 0; m < 4; ++m) _Pragma("unroll") for (int k = 0; k < 2; ++k) dst[m][k] = *(const LAS bf16x8*)(lds + PG8_SA(b, h) + aoff + m * 2048 + k * 1024); } while (0)
; #define PG8_LDB(dst, b, h) do { _Pragma("unroll") for (int n = 0; n < 2; ++n) _Pragma("unroll") for (int k = 0; k < 2; ++k) dst[n][k] = *(const LAS bf16x8*)(lds + PG8_SB(b, h) + boff + n * 2048 + k * 1024); } while (0)
; #define PG8_MMA(ai, bj, At, Bt) do { __builtin_amdgcn_s_setprio(1); _Pragma("unroll") for (int m = 0; m < 4; ++m) _Pragma("unroll") for (int n = 0; n < 2; ++n) _Pragma("unroll") for (int k = 0; k < 2; ++k) \
;         acc[ai][bj][m][n] = __builtin_amdgcn_mfma_f32_16x16x32_bf16(Bt[n][k], At[m][k], acc[ai][bj][m][n], 0, 0, 0); __builtin_amdgcn_s_setprio(0); } while (0)
; #define PG8_WAIT_V(n) asm volatile("s_waitcnt vmcnt(" #n ")" ::: "memory")
; #define PG8_WAIT_L(n) asm volatile("s_waitcnt lgkmcnt(" #n ")" ::: "memory")
; #define PG8_BAR __builtin_amdgcn_s_barrier()
; #define PG8_SCHED __builtin_amdgcn_sched_barrier(0)
; template <class Epi, class Sched>
; DI void gemm_phase(LAS unsigned char* lds, const Gemm g, const Sched& S, const Epi& E) {
;     ...
;             PG8_LDB(B0, 1, 0); PG8_LDB(B1, 1, 1); PG8_SCHED; PG8_LDA(At, 1, 0); PG8_STAGE(PG8_SA(0, 1), a2 + hstepA, voffA);
;             PG8_WAIT_V(8); PG8_WAIT_L(0); PG8_BAR; PG8_MMA(0, 0, At, B0); PG8_MMA(0, 1, At, B1); PG8_BAR; PG8_SCHED;
	s_add_i32 s48, 0, 0x18000
	s_add_i32 s49, 0, 0x1c000
	v_add_u32_e32 v162, s48, v149
	v_add_u32_e32 v178, s49, v149
	ds_read_b128 v[144:147], v162
	ds_read_b128 v[154:157], v162 offset:1024
	ds_read_b128 v[158:161], v162 offset:2048
	ds_read_b128 v[162:165], v162 offset:3072
	ds_read_b128 v[166:169], v178
	ds_read_b128 v[170:173], v178 offset:1024
	ds_read_b128 v[174:177], v178 offset:2048
	ds_read_b128 v[178:181], v178 offset:3072
	s_add_u32 s20, s20, 0xb0000
	s_addc_u32 s21, s21, 0
	s_mov_b32 m0, s33
	v_lshl_add_u64 v[222:223], s[20:21], 0, v[128:129]
	ds_read_b128 v[182:185], v153 offset:32768
	ds_read_b128 v[186:189], v153 offset:33792
	ds_read_b128 v[190:193], v153 offset:34816
	ds_read_b128 v[194:197], v153 offset:35840
	ds_read_b128 v[198:201], v153 offset:36864
	ds_read_b128 v[202:205], v153 offset:37888
	ds_read_b128 v[206:209], v153 offset:38912
	ds_read_b128 v[210:213], v153 offset:39936
	global_load_lds_dwordx4 v[222:223], off
	v_lshl_add_u64 v[222:223], s[20:21], 0, v[132:133]
	s_mov_b32 m0, s34
	s_nop 0
	global_load_lds_dwordx4 v[222:223], off
	s_waitcnt vmcnt(8)
	s_waitcnt lgkmcnt(0)
	s_barrier
	s_setprio 1
	v_mfma_f32_16x16x32_bf16 v[124:127], v[144:147], v[182:185], v[124:127]
	v_mfma_f32_16x16x32_bf16 v[120:123], v[158:161], v[182:185], v[120:123]
	v_mfma_f32_16x16x32_bf16 v[108:111], v[144:147], v[190:193], v[108:111]
	v_mfma_f32_16x16x32_bf16 v[104:107], v[158:161], v[190:193], v[104:107]
	v_mfma_f32_16x16x32_bf16 v[92:95], v[144:147], v[198:201], v[92:95]
	v_mfma_f32_16x16x32_bf16 v[88:91], v[158:161], v[198:201], v[88:91]
	v_mfma_f32_16x16x32_bf16 v[76:79], v[144:147], v[206:209], v[76:79]
	v_mfma_f32_16x16x32_bf16 v[72:75], v[158:161], v[206:209], v[72:75]
	v_mfma_f32_16x16x32_bf16 v[124:127], v[154:157], v[186:189], v[124:127]
	v_mfma_f32_16x16x32_bf16 v[120:123], v[162:165], v[186:189], v[120:123]
	v_mfma_f32_16x16x32_bf16 v[108:111], v[154:157], v[194:197], v[108:111]
	v_mfma_f32_16x16x32_bf16 v[104:107], v[162:165], v[194:197], v[104:107]
	v_mfma_f32_16x16x32_bf16 v[92:95], v[154:157], v[202:205], v[92:95]
	v_mfma_f32_16x16x32_bf16 v[88:91], v[162:165], v[202:205], v[88:91]
	v_mfma_f32_16x16x32_bf16 v[76:79], v[154:157], v[210:213], v[76:79]
	v_mfma_f32_16x16x32_bf16 v[72:75], v[162:165], v[210:213], v[72:75]
	v_mfma_f32_16x16x32_bf16 v[116:119], v[166:169], v[182:185], v[116:119]
	v_mfma_f32_16x16x32_bf16 v[112:115], v[174:177], v[182:185], v[112:115]
	v_mfma_f32_16x16x32_bf16 v[100:103], v[166:169], v[190:193], v[100:103]
	v_mfma_f32_16x16x32_bf16 v[96:99], v[174:177], v[190:193], v[96:99]
	v_mfma_f32_16x16x32_bf16 v[84:87], v[166:169], v[198:201], v[84:87]
	v_mfma_f32_16x16x32_bf16 v[80:83], v[174:177], v[198:201], v[80:83]
	v_mfma_f32_16x16x32_bf16 v[68:71], v[166:169], v[206:209], v[68:71]
	v_mfma_f32_16x16x32_bf16 v[64:67], v[174:177], v[206:209], v[64:67]
	v_mfma_f32_16x16x32_bf16 v[116:119], v[170:173], v[186:189], v[116:119]
	v_mfma_f32_16x16x32_bf16 v[112:115], v[178:181], v[186:189], v[112:115]
	v_mfma_f32_16x16x32_bf16 v[100:103], v[170:173], v[194:197], v[100:103]
	v_mfma_f32_16x16x32_bf16 v[96:99], v[178:181], v[194:197], v[96:99]
	v_mfma_f32_16x16x32_bf16 v[84:87], v[170:173], v[202:205], v[84:87]
	v_mfma_f32_16x16x32_bf16 v[80:83], v[178:181], v[202:205], v[80:83]
	v_mfma_f32_16x16x32_bf16 v[68:71], v[170:173], v[210:213], v[68:71]
	v_mfma_f32_16x16x32_bf16 v[64:67], v[178:181], v[210:213], v[64:67]
	s_setprio 0
	s_barrier
; #define PG8_STAGE(bufoff, gbase, voff) do { _Pragma("unroll") for (int _i = 0; _i < 2; ++_i) \
;         __builtin_amdgcn_global_load_lds((const unsigned*)((const char*)(gbase) + (voff)[_i]), (LAS unsigned*)(lds + (bufoff) + ldsw + _i * 8192), 16, 0, 0); } while (0)
; #define PG8_LDA(dst, b, h) do { _Pragma("unroll") for (int m = 0; m < 4; ++m) _Pragma("unroll") for (int k = 0; k < 2; ++k) dst[m][k] = *(const LAS bf16x8*)(lds + PG8_SA(b, h) + aoff + m * 2048 + k * 1024); } while (0)
; #define PG8_MMA(ai, bj, At, Bt) do { __builtin_amdgcn_s_setprio(1); _Pragma("unroll") for (int m = 0; m < 4; ++m) _Pragma("unroll") for (int n = 0; n < 2; ++n) _Pragma("unroll") for (int k = 0; k < 2; ++k) \
;         acc[ai][bj][m][n] = __builtin_amdgcn_mfma_f32_16x16x32_bf16(Bt[n][k], At[m][k], acc[ai][bj][m][n], 0, 0, 0); __builtin_amdgcn_s_setprio(0); } while (0)
; #define PG8_WAIT_V(n) asm volatile("s_waitcnt vmcnt(" #n ")" ::: "memory")
; #define PG8_WAIT_L(n) asm volatile("s_waitcnt lgkmcnt(" #n ")" ::: "memory")
; #define PG8_BAR __builtin_amdgcn_s_barrier()
; #define PG8_SCHED __builtin_amdgcn_sched_barrier(0)
;     DI void pre(Pre& pr, const pg8::Unit& u, int wr, int fr) const { load_rows(pr, ssq, u, wr, fr); }
;     DI void pre(Pre& pr, const pg8::Unit& u, int wr, int fr) const { load_rows(pr, ssq, u, wr, fr); }
; template <class Epi, class Sched>
; DI void gemm_phase(LAS unsigned char* lds, const Gemm g, const Sched& S, const Epi& E) {
;     ...
;             PG8_LDA(At, 1, 1); PG8_STAGE(PG8_SB(1, 0), b3, voffB); PG8_STAGE(PG8_SB(1, 1), b3 + hstepB, voffB); PG8_STAGE(PG8_SA(1, 0), a3, voffA);
;             PG8_WAIT_V(8); PG8_WAIT_L(0); PG8_BAR; PG8_MMA(1, 0, At, B0); PG8_MMA(1, 1, At, B1); PG8_BAR; PG8_SCHED;
;         }
;         if (wr == 0) PG8_BAR;
;         E(acc, cur, wr, wc, fr, fq, pre);
;         if (!has_next) break;
	s_add_i32 s20, s48, s27
	v_lshl_add_u64 v[214:215], v[214:215], 0, s[10:11]
	s_mov_b32 m0, s20
	ds_read_b128 v[182:185], v153 offset:49152
	ds_read_b128 v[186:189], v153 offset:50176
	ds_read_b128 v[190:193], v153 offset:51200
	ds_read_b128 v[194:197], v153 offset:52224
	ds_read_b128 v[198:201], v153 offset:53248
	ds_read_b128 v[202:205], v153 offset:54272
	ds_read_b128 v[206:209], v153 offset:55296
	ds_read_b128 v[210:213], v153 offset:56320
	global_load_lds_dwordx4 v[214:215], off
	s_add_i32 m0, s20, 0x2000
	s_add_u32 s18, s18, 0xb0080
	v_lshl_add_u64 v[214:215], v[216:217], 0, s[10:11]
	s_addc_u32 s19, s19, 0
	s_add_i32 s20, s49, s27
	global_load_lds_dwordx4 v[214:215], off
	v_lshl_add_u64 v[214:215], s[18:19], 0, v[130:131]
	s_mov_b32 m0, s20
	s_nop 0
	global_load_lds_dwordx4 v[214:215], off
	v_lshl_add_u64 v[214:215], s[18:19], 0, v[134:135]
	s_add_i32 m0, s20, 0x2000
	s_nop 0
	global_load_lds_dwordx4 v[214:215], off
	v_lshl_add_u64 v[214:215], v[218:219], 0, s[10:11]
	s_mov_b32 m0, s36
	s_nop 0
	global_load_lds_dwordx4 v[214:215], off
	v_lshl_add_u64 v[214:215], v[220:221], 0, s[10:11]
	s_mov_b32 m0, s37
	s_nop 0
	global_load_lds_dwordx4 v[214:215], off
	s_waitcnt vmcnt(8)
	s_waitcnt lgkmcnt(0)
	s_barrier
	s_setprio 1
	v_mfma_f32_16x16x32_bf16 v[60:63], v[144:147], v[182:185], v[60:63]
	v_mfma_f32_16x16x32_bf16 v[56:59], v[158:161], v[182:185], v[56:59]
	v_mfma_f32_16x16x32_bf16 v[44:47], v[144:147], v[190:193], v[44:47]
	v_mfma_f32_16x16x32_bf16 v[40:43], v[158:161], v[190:193], v[40:43]
	v_mfma_f32_16x16x32_bf16 v[28:31], v[144:147], v[198:201], v[28:31]
	v_mfma_f32_16x16x32_bf16 v[24:27], v[158:161], v[198:201], v[24:27]
	v_mfma_f32_16x16x32_bf16 v[12:15], v[144:147], v[206:209], v[12:15]
	v_mfma_f32_16x16x32_bf16 v[8:11], v[158:161], v[206:209], v[8:11]
	v_mfma_f32_16x16x32_bf16 v[60:63], v[154:157], v[186:189], v[60:63]
	v_mfma_f32_16x16x32_bf16 v[56:59], v[162:165], v[186:189], v[56:59]
	v_mfma_f32_16x16x32_bf16 v[44:47], v[154:157], v[194:197], v[44:47]
	v_mfma_f32_16x16x32_bf16 v[40:43], v[162:165], v[194:197], v[40:43]
	v_mfma_f32_16x16x32_bf16 v[28:31], v[154:157], v[202:205], v[28:31]
	v_mfma_f32_16x16x32_bf16 v[24:27], v[162:165], v[202:205], v[24:27]
	v_mfma_f32_16x16x32_bf16 v[12:15], v[154:157], v[210:213], v[12:15]
	v_mfma_f32_16x16x32_bf16 v[8:11], v[162:165], v[210:213], v[8:11]
	v_mfma_f32_16x16x32_bf16 v[52:55], v[166:169], v[182:185], v[52:55]
	v_mfma_f32_16x16x32_bf16 v[48:51], v[174:177], v[182:185], v[48:51]
	v_mfma_f32_16x16x32_bf16 v[36:39], v[166:169], v[190:193], v[36:39]
	v_mfma_f32_16x16x32_bf16 v[32:35], v[174:177], v[190:193], v[32:35]
	v_mfma_f32_16x16x32_bf16 v[20:23], v[166:169], v[198:201], v[20:23]
	v_mfma_f32_16x16x32_bf16 v[16:19], v[174:177], v[198:201], v[16:19]
	v_mfma_f32_16x16x32_bf16 v[4:7], v[166:169], v[206:209], v[4:7]
	v_mfma_f32_16x16x32_bf16 v[0:3], v[174:177], v[206:209], v[0:3]
	v_mfma_f32_16x16x32_bf16 v[52:55], v[170:173], v[186:189], v[52:55]
	v_mfma_f32_16x16x32_bf16 v[48:51], v[178:181], v[186:189], v[48:51]
	v_mfma_f32_16x16x32_bf16 v[36:39], v[170:173], v[194:197], v[36:39]
	v_mfma_f32_16x16x32_bf16 v[32:35], v[178:181], v[194:197], v[32:35]
	v_mfma_f32_16x16x32_bf16 v[20:23], v[170:173], v[202:205], v[20:23]
	v_mfma_f32_16x16x32_bf16 v[16:19], v[178:181], v[202:205], v[16:19]
	v_mfma_f32_16x16x32_bf16 v[4:7], v[170:173], v[210:213], v[4:7]
	v_mfma_f32_16x16x32_bf16 v[0:3], v[178:181], v[210:213], v[0:3]
	s_setprio 0
	s_barrier
	s_add_i32 s47, s47, 2
	s_add_u32 s16, s16, 0x100
	s_addc_u32 s17, s17, 0
	s_add_u32 s45, s45, 0x100
	s_addc_u32 s46, s46, 0
	s_cmp_gt_u32 s47, 41
	s_cbranch_scc0 .LBB0_1331
	s_waitcnt vmcnt(0)
	s_mov_b32 s99, 1
	s_and_b64 vcc, exec, s[12:13]
	s_cbranch_vccz .LBB0_1334
	s_barrier
